# GEMM K-loops: no setprio; ds_read wait moved in front of the barrier so the MFMA block issues immediately on release
# baseline (speedup 1.0000x reference)
; #define PG8_STAGE(bufoff, gbase, voff) do { _Pragma("unroll") for (int _i = 0; _i < 2; ++_i) \
;         __builtin_amdgcn_global_load_lds((const unsigned*)((const char*)(gbase) + (voff)[_i]), (PG8_LAS unsigned*)(lds + (bufoff) + ldsw + _i * 8192), 16, 0, 0); } while (0)
; #define PG8_LDA(dst, b, h) do { _Pragma("unroll") for (int m = 0; m < 4; ++m) _Pragma("unroll") for (int k = 0; k < 2; ++k) dst[m][k] = *(const PG8_LAS bf16x8*)(lds + PG8_SA(b, h) + aoff + m * 2048 + k * 1024); } while (0)
; #define PG8_LDB(dst, b, h) do { _Pragma("unroll") for (int n = 0; n < 2; ++n) _Pragma("unroll") for (int k = 0; k < 2; ++k) dst[n][k] = *(const PG8_LAS bf16x8*)(lds + PG8_SB(b, h) + boff + n * 2048 + k * 1024); } while (0)
; #define PG8_MMA(ai, bj, At, Bt) do { __builtin_amdgcn_s_setprio(1); _Pragma("unroll") for (int m = 0; m < 4; ++m) _Pragma("unroll") for (int n = 0; n < 2; ++n) _Pragma("unroll") for (int k = 0; k < 2; ++k) \
;         acc[ai][bj][m][n] = __builtin_amdgcn_mfma_f32_16x16x32_bf16(Bt[n][k], At[m][k], acc[ai][bj][m][n], 0, 0, 0); __builtin_amdgcn_s_setprio(0); } while (0)
; #define PG8_WAIT_V(n) asm volatile("s_waitcnt vmcnt(" #n ")" ::: "memory")
; #define PG8_WAIT_L(n) asm volatile("s_waitcnt lgkmcnt(" #n ")" ::: "memory")
; #define PG8_BAR __builtin_amdgcn_s_barrier()
; #define PG8_SCHED __builtin_amdgcn_sched_barrier(0)
; template <class Epi, class Sched>
; __device__ __forceinline__ void gemm_phase(PG8_LAS unsigned char* lds, const Gemm g, const Sched& S, const Epi& E) {
;     ...
;             PG8_LDB(B0, 0, 0); PG8_SCHED; PG8_LDA(At, 0, 0); PG8_STAGE(PG8_SA(1, 1), a1 + hstep, voffA);
;             PG8_WAIT_L(8); PG8_BAR; PG8_WAIT_L(0); PG8_MMA(0, 0, At, B0); PG8_BAR; PG8_SCHED;
;             PG8_LDB(B1, 0, 1); PG8_STAGE(PG8_SB(0, 0), b2, voffB);
;             PG8_BAR; PG8_WAIT_L(0); PG8_MMA(0, 1, At, B1); PG8_BAR;
;             PG8_LDA(At, 0, 1); PG8_STAGE(PG8_SA(0, 0), a2, voffA);
;             PG8_BAR; PG8_WAIT_L(0); PG8_MMA(1, 0, At, B0); PG8_BAR; PG8_SCHED;
;             PG8_STAGE(PG8_SB(0, 1), b2 + hstep, voffB);
;             PG8_WAIT_V(6); PG8_BAR; PG8_MMA(1, 1, At, B1); PG8_BAR;
.LBB0_195:
	ds_read_b128 v[144:147], v151
	ds_read_b128 v[156:159], v151 offset:1024
	ds_read_b128 v[160:163], v151 offset:2048
	ds_read_b128 v[166:169], v151 offset:3072
	s_add_u32 s30, s28, 0xfffc0080
	s_addc_u32 s31, s29, -1
	s_cmp_eq_u32 s58, 12
	s_cselect_b32 s35, s17, s31
	s_cselect_b32 s34, s54, s30
	s_cselect_b32 s31, s15, s57
	s_cselect_b32 s30, s55, s56
	v_lshl_add_u64 v[174:175], s[28:29], 0, v[136:137]
	s_add_i32 m0, s27, 0xc000
	ds_read_b128 v[170:173], v153
	ds_read_b128 v[182:185], v153 offset:1024
	ds_read_b128 v[190:193], v153 offset:2048
	ds_read_b128 v[194:197], v153 offset:3072
	ds_read_b128 v[198:201], v153 offset:4096
	ds_read_b128 v[202:205], v153 offset:5120
	ds_read_b128 v[206:209], v153 offset:6144
	ds_read_b128 v[210:213], v153 offset:7168
	global_load_lds_dwordx4 v[174:175], off
	v_lshl_add_u64 v[174:175], s[28:29], 0, v[138:139]
	s_add_i32 m0, s27, 0xe000
	s_nop 0
	global_load_lds_dwordx4 v[174:175], off
	s_waitcnt lgkmcnt(0)
	s_barrier
	v_mfma_f32_16x16x32_bf16 v[124:127], v[144:147], v[170:173], v[124:127]
	v_mfma_f32_16x16x32_bf16 v[120:123], v[160:163], v[170:173], v[120:123]
	v_mfma_f32_16x16x32_bf16 v[108:111], v[144:147], v[190:193], v[108:111]
	v_mfma_f32_16x16x32_bf16 v[104:107], v[160:163], v[190:193], v[104:107]
	v_mfma_f32_16x16x32_bf16 v[92:95], v[144:147], v[198:201], v[92:95]
	v_mfma_f32_16x16x32_bf16 v[88:91], v[160:163], v[198:201], v[88:91]
	v_mfma_f32_16x16x32_bf16 v[76:79], v[144:147], v[206:209], v[76:79]
	v_mfma_f32_16x16x32_bf16 v[72:75], v[160:163], v[206:209], v[72:75]
	v_mfma_f32_16x16x32_bf16 v[124:127], v[156:159], v[182:185], v[124:127]
	v_mfma_f32_16x16x32_bf16 v[120:123], v[166:169], v[182:185], v[120:123]
	v_mfma_f32_16x16x32_bf16 v[108:111], v[156:159], v[194:197], v[108:111]
	v_mfma_f32_16x16x32_bf16 v[104:107], v[166:169], v[194:197], v[104:107]
	v_mfma_f32_16x16x32_bf16 v[92:95], v[156:159], v[202:205], v[92:95]
	v_mfma_f32_16x16x32_bf16 v[88:91], v[166:169], v[202:205], v[88:91]
	v_mfma_f32_16x16x32_bf16 v[76:79], v[156:159], v[210:213], v[76:79]
	v_mfma_f32_16x16x32_bf16 v[72:75], v[166:169], v[210:213], v[72:75]
	s_barrier
	s_add_i32 s59, s50, s40
	v_lshl_add_u64 v[174:175], s[30:31], 0, v[132:133]
	s_mov_b32 m0, s59
	ds_read_b128 v[214:217], v154
	ds_read_b128 v[218:221], v154 offset:1024
	ds_read_b128 v[222:225], v154 offset:2048
	ds_read_b128 v[226:229], v154 offset:3072
	global_load_lds_dwordx4 v[174:175], off
	v_lshl_add_u64 v[178:179], s[30:31], 0, v[128:129]
	s_add_i32 m0, s59, 0x2000
	s_nop 0
	global_load_lds_dwordx4 v[178:179], off
	s_waitcnt lgkmcnt(0)
	s_barrier
	v_mfma_f32_16x16x32_bf16 v[116:119], v[214:217], v[170:173], v[116:119]
	v_mfma_f32_16x16x32_bf16 v[112:115], v[222:225], v[170:173], v[112:115]
	v_mfma_f32_16x16x32_bf16 v[100:103], v[214:217], v[190:193], v[100:103]
	v_mfma_f32_16x16x32_bf16 v[96:99], v[222:225], v[190:193], v[96:99]
	v_mfma_f32_16x16x32_bf16 v[84:87], v[214:217], v[198:201], v[84:87]
	v_mfma_f32_16x16x32_bf16 v[80:83], v[222:225], v[198:201], v[80:83]
	v_mfma_f32_16x16x32_bf16 v[68:71], v[214:217], v[206:209], v[68:71]
	v_mfma_f32_16x16x32_bf16 v[64:67], v[222:225], v[206:209], v[64:67]
	v_mfma_f32_16x16x32_bf16 v[116:119], v[218:221], v[182:185], v[116:119]
	v_mfma_f32_16x16x32_bf16 v[112:115], v[226:229], v[182:185], v[112:115]
	v_mfma_f32_16x16x32_bf16 v[100:103], v[218:221], v[194:197], v[100:103]
	v_mfma_f32_16x16x32_bf16 v[96:99], v[226:229], v[194:197], v[96:99]
	v_mfma_f32_16x16x32_bf16 v[84:87], v[218:221], v[202:205], v[84:87]
	v_mfma_f32_16x16x32_bf16 v[80:83], v[226:229], v[202:205], v[80:83]
	v_mfma_f32_16x16x32_bf16 v[68:71], v[218:221], v[210:213], v[68:71]
	v_mfma_f32_16x16x32_bf16 v[64:67], v[226:229], v[210:213], v[64:67]
	s_mov_b32 m0, s27
	v_lshl_add_u64 v[186:187], s[34:35], 0, v[134:135]
	s_barrier
	ds_read_b128 v[170:173], v153 offset:16384
	ds_read_b128 v[182:185], v153 offset:17408
	ds_read_b128 v[190:193], v153 offset:18432
	ds_read_b128 v[194:197], v153 offset:19456
	ds_read_b128 v[198:201], v153 offset:20480
	ds_read_b128 v[202:205], v153 offset:21504
	ds_read_b128 v[206:209], v153 offset:22528
	ds_read_b128 v[210:213], v153 offset:23552
	global_load_lds_dwordx4 v[186:187], off
	v_lshl_add_u64 v[230:231], s[34:35], 0, v[130:131]
	s_mov_b32 m0, s43
	s_nop 0
	global_load_lds_dwordx4 v[230:231], off
	s_waitcnt lgkmcnt(0)
	s_barrier
	v_mfma_f32_16x16x32_bf16 v[60:63], v[144:147], v[170:173], v[60:63]
	v_mfma_f32_16x16x32_bf16 v[56:59], v[160:163], v[170:173], v[56:59]
	v_mfma_f32_16x16x32_bf16 v[44:47], v[144:147], v[190:193], v[44:47]
	v_mfma_f32_16x16x32_bf16 v[40:43], v[160:163], v[190:193], v[40:43]
	v_mfma_f32_16x16x32_bf16 v[28:31], v[144:147], v[198:201], v[28:31]
	v_mfma_f32_16x16x32_bf16 v[24:27], v[160:163], v[198:201], v[24:27]
	v_mfma_f32_16x16x32_bf16 v[12:15], v[144:147], v[206:209], v[12:15]
	v_mfma_f32_16x16x32_bf16 v[8:11], v[160:163], v[206:209], v[8:11]
	v_mfma_f32_16x16x32_bf16 v[60:63], v[156:159], v[182:185], v[60:63]
	v_mfma_f32_16x16x32_bf16 v[56:59], v[166:169], v[182:185], v[56:59]
	v_mfma_f32_16x16x32_bf16 v[44:47], v[156:159], v[194:197], v[44:47]
	v_mfma_f32_16x16x32_bf16 v[40:43], v[166:169], v[194:197], v[40:43]
	v_mfma_f32_16x16x32_bf16 v[28:31], v[156:159], v[202:205], v[28:31]
	v_mfma_f32_16x16x32_bf16 v[24:27], v[166:169], v[202:205], v[24:27]
	v_mfma_f32_16x16x32_bf16 v[12:15], v[156:159], v[210:213], v[12:15]
	v_mfma_f32_16x16x32_bf16 v[8:11], v[166:169], v[210:213], v[8:11]
	s_barrier
	s_add_u32 s60, s30, 0x40000
	s_addc_u32 s61, s31, 0
	s_add_i32 s59, s51, s40
	v_lshl_add_u64 v[144:145], s[60:61], 0, v[132:133]
	s_mov_b32 m0, s59
	s_nop 0
	global_load_lds_dwordx4 v[144:145], off
	v_lshl_add_u64 v[144:145], s[60:61], 0, v[128:129]
	s_add_i32 m0, s59, 0x2000
	s_nop 0
	global_load_lds_dwordx4 v[144:145], off
	s_waitcnt vmcnt(6)
	s_barrier
; #define PG8_STAGE(bufoff, gbase, voff) do { _Pragma("unroll") for (int _i = 0; _i < 2; ++_i) \
;         __builtin_amdgcn_global_load_lds((const unsigned*)((const char*)(gbase) + (voff)[_i]), (PG8_LAS unsigned*)(lds + (bufoff) + ldsw + _i * 8192), 16, 0, 0); } while (0)
; #define PG8_LDA(dst, b, h) do { _Pragma("unroll") for (int m = 0; m < 4; ++m) _Pragma("unroll") for (int k = 0; k < 2; ++k) dst[m][k] = *(const PG8_LAS bf16x8*)(lds + PG8_SA(b, h) + aoff + m * 2048 + k * 1024); } while (0)
; #define PG8_LDB(dst, b, h) do { _Pragma("unroll") for (int n = 0; n < 2; ++n) _Pragma("unroll") for (int k = 0; k < 2; ++k) dst[n][k] = *(const PG8_LAS bf16x8*)(lds + PG8_SB(b, h) + boff + n * 2048 + k * 1024); } while (0)
; #define PG8_MMA(ai, bj, At, Bt) do { __builtin_amdgcn_s_setprio(1); _Pragma("unroll") for (int m = 0; m < 4; ++m) _Pragma("unroll") for (int n = 0; n < 2; ++n) _Pragma("unroll") for (int k = 0; k < 2; ++k) \
;         acc[ai][bj][m][n] = __builtin_amdgcn_mfma_f32_16x16x32_bf16(Bt[n][k], At[m][k], acc[ai][bj][m][n], 0, 0, 0); __builtin_amdgcn_s_setprio(0); } while (0)
; #define PG8_WAIT_V(n) asm volatile("s_waitcnt vmcnt(" #n ")" ::: "memory")
; #define PG8_WAIT_L(n) asm volatile("s_waitcnt lgkmcnt(" #n ")" ::: "memory")
; #define PG8_BAR __builtin_amdgcn_s_barrier()
; #define PG8_SCHED __builtin_amdgcn_sched_barrier(0)
; template <class Epi, class Sched>
; __device__ __forceinline__ void gemm_phase(PG8_LAS unsigned char* lds, const Gemm g, const Sched& S, const Epi& E) {
;     ...
;             PG8_WAIT_V(6); PG8_BAR; PG8_MMA(1, 1, At, B1); PG8_BAR;
;             PG8_LDB(B0, 1, 0); PG8_SCHED; PG8_LDA(At, 1, 0); PG8_STAGE(PG8_SA(0, 1), a2 + hstep, voffA);
;             PG8_WAIT_L(8); PG8_BAR; PG8_WAIT_L(0); PG8_MMA(0, 0, At, B0); PG8_BAR; PG8_SCHED;
;             PG8_LDB(B1, 1, 1); PG8_STAGE(PG8_SB(1, 0), b3, voffB);
;             PG8_BAR; PG8_WAIT_L(0); PG8_MMA(0, 1, At, B1); PG8_BAR;
;             PG8_LDA(At, 1, 1); PG8_STAGE(PG8_SA(1, 0), a3, voffA);
;             PG8_BAR; PG8_WAIT_L(0); PG8_MMA(1, 0, At, B0); PG8_BAR; PG8_SCHED;
	v_mfma_f32_16x16x32_bf16 v[52:55], v[214:217], v[170:173], v[52:55]
	v_mfma_f32_16x16x32_bf16 v[48:51], v[222:225], v[170:173], v[48:51]
	v_mfma_f32_16x16x32_bf16 v[36:39], v[214:217], v[190:193], v[36:39]
	v_mfma_f32_16x16x32_bf16 v[32:35], v[222:225], v[190:193], v[32:35]
	v_mfma_f32_16x16x32_bf16 v[20:23], v[214:217], v[198:201], v[20:23]
	v_mfma_f32_16x16x32_bf16 v[16:19], v[222:225], v[198:201], v[16:19]
	v_mfma_f32_16x16x32_bf16 v[4:7], v[214:217], v[206:209], v[4:7]
	v_mfma_f32_16x16x32_bf16 v[0:3], v[222:225], v[206:209], v[0:3]
	v_mfma_f32_16x16x32_bf16 v[52:55], v[218:221], v[182:185], v[52:55]
	v_mfma_f32_16x16x32_bf16 v[48:51], v[226:229], v[182:185], v[48:51]
	v_mfma_f32_16x16x32_bf16 v[36:39], v[218:221], v[194:197], v[36:39]
	v_mfma_f32_16x16x32_bf16 v[32:35], v[226:229], v[194:197], v[32:35]
	v_mfma_f32_16x16x32_bf16 v[20:23], v[218:221], v[202:205], v[20:23]
	v_mfma_f32_16x16x32_bf16 v[16:19], v[226:229], v[202:205], v[16:19]
	v_mfma_f32_16x16x32_bf16 v[4:7], v[218:221], v[210:213], v[4:7]
	v_mfma_f32_16x16x32_bf16 v[0:3], v[226:229], v[210:213], v[0:3]
	s_add_i32 s59, 0, 0x18000
	v_add_u32_e32 v155, s59, v149
	s_barrier
	ds_read_b128 v[144:147], v155
	ds_read_b128 v[156:159], v155 offset:1024
	ds_read_b128 v[160:163], v155 offset:2048
	ds_read_b128 v[166:169], v155 offset:3072
	s_add_u32 s34, s34, 0x40000
	s_addc_u32 s35, s35, 0
	s_mov_b32 m0, s44
	v_lshl_add_u64 v[214:215], s[34:35], 0, v[134:135]
	ds_read_b128 v[170:173], v153 offset:32768
	ds_read_b128 v[182:185], v153 offset:33792
	ds_read_b128 v[190:193], v153 offset:34816
	ds_read_b128 v[194:197], v153 offset:35840
	ds_read_b128 v[198:201], v153 offset:36864
	ds_read_b128 v[202:205], v153 offset:37888
	ds_read_b128 v[206:209], v153 offset:38912
	ds_read_b128 v[210:213], v153 offset:39936
	global_load_lds_dwordx4 v[214:215], off
	v_lshl_add_u64 v[214:215], s[34:35], 0, v[130:131]
	s_mov_b32 m0, s45
	s_nop 0
	global_load_lds_dwordx4 v[214:215], off
	s_waitcnt lgkmcnt(0)
	s_barrier
	v_mfma_f32_16x16x32_bf16 v[124:127], v[144:147], v[170:173], v[124:127]
	v_mfma_f32_16x16x32_bf16 v[120:123], v[160:163], v[170:173], v[120:123]
	v_mfma_f32_16x16x32_bf16 v[108:111], v[144:147], v[190:193], v[108:111]
	v_mfma_f32_16x16x32_bf16 v[104:107], v[160:163], v[190:193], v[104:107]
	v_mfma_f32_16x16x32_bf16 v[92:95], v[144:147], v[198:201], v[92:95]
	v_mfma_f32_16x16x32_bf16 v[88:91], v[160:163], v[198:201], v[88:91]
	v_mfma_f32_16x16x32_bf16 v[76:79], v[144:147], v[206:209], v[76:79]
	v_mfma_f32_16x16x32_bf16 v[72:75], v[160:163], v[206:209], v[72:75]
	v_mfma_f32_16x16x32_bf16 v[124:127], v[156:159], v[182:185], v[124:127]
	v_mfma_f32_16x16x32_bf16 v[120:123], v[166:169], v[182:185], v[120:123]
	v_mfma_f32_16x16x32_bf16 v[108:111], v[156:159], v[194:197], v[108:111]
	v_mfma_f32_16x16x32_bf16 v[104:107], v[166:169], v[194:197], v[104:107]
	v_mfma_f32_16x16x32_bf16 v[92:95], v[156:159], v[202:205], v[92:95]
	v_mfma_f32_16x16x32_bf16 v[88:91], v[166:169], v[202:205], v[88:91]
	v_mfma_f32_16x16x32_bf16 v[76:79], v[156:159], v[210:213], v[76:79]
	v_mfma_f32_16x16x32_bf16 v[72:75], v[166:169], v[210:213], v[72:75]
	s_barrier
	s_add_i32 s34, 0, 0x1c000
	s_add_i32 s35, s59, s40
	v_add_u32_e32 v155, s34, v149
	v_lshl_add_u64 v[174:175], v[174:175], 0, s[10:11]
	s_mov_b32 m0, s35
	ds_read_b128 v[214:217], v155
	ds_read_b128 v[218:221], v155 offset:1024
	ds_read_b128 v[222:225], v155 offset:2048
	ds_read_b128 v[226:229], v155 offset:3072
	global_load_lds_dwordx4 v[174:175], off
	v_lshl_add_u64 v[174:175], v[178:179], 0, s[10:11]
	s_add_i32 m0, s35, 0x2000
	s_nop 0
	global_load_lds_dwordx4 v[174:175], off
	s_waitcnt lgkmcnt(0)
	s_barrier
	v_mfma_f32_16x16x32_bf16 v[116:119], v[214:217], v[170:173], v[116:119]
	v_mfma_f32_16x16x32_bf16 v[112:115], v[222:225], v[170:173], v[112:115]
	v_mfma_f32_16x16x32_bf16 v[100:103], v[214:217], v[190:193], v[100:103]
	v_mfma_f32_16x16x32_bf16 v[96:99], v[222:225], v[190:193], v[96:99]
	v_mfma_f32_16x16x32_bf16 v[84:87], v[214:217], v[198:201], v[84:87]
	v_mfma_f32_16x16x32_bf16 v[80:83], v[222:225], v[198:201], v[80:83]
	v_mfma_f32_16x16x32_bf16 v[68:71], v[214:217], v[206:209], v[68:71]
	v_mfma_f32_16x16x32_bf16 v[64:67], v[222:225], v[206:209], v[64:67]
	v_mfma_f32_16x16x32_bf16 v[116:119], v[218:221], v[182:185], v[116:119]
	v_mfma_f32_16x16x32_bf16 v[112:115], v[226:229], v[182:185], v[112:115]
	v_mfma_f32_16x16x32_bf16 v[100:103], v[218:221], v[194:197], v[100:103]
	v_mfma_f32_16x16x32_bf16 v[96:99], v[226:229], v[194:197], v[96:99]
	v_mfma_f32_16x16x32_bf16 v[84:87], v[218:221], v[202:205], v[84:87]
	v_mfma_f32_16x16x32_bf16 v[80:83], v[226:229], v[202:205], v[80:83]
	v_mfma_f32_16x16x32_bf16 v[68:71], v[218:221], v[210:213], v[68:71]
	v_mfma_f32_16x16x32_bf16 v[64:67], v[226:229], v[210:213], v[64:67]
	s_mov_b32 m0, s47
	v_lshl_add_u64 v[174:175], v[186:187], 0, s[10:11]
	s_barrier
	ds_read_b128 v[170:173], v153 offset:49152
	ds_read_b128 v[182:185], v153 offset:50176
	ds_read_b128 v[190:193], v153 offset:51200
	ds_read_b128 v[194:197], v153 offset:52224
	ds_read_b128 v[198:201], v153 offset:53248
	ds_read_b128 v[202:205], v153 offset:54272
	ds_read_b128 v[206:209], v153 offset:55296
	ds_read_b128 v[210:213], v153 offset:56320
	global_load_lds_dwordx4 v[174:175], off
	v_lshl_add_u64 v[174:175], v[230:231], 0, s[10:11]
	s_mov_b32 m0, s48
	s_nop 0
	global_load_lds_dwordx4 v[174:175], off
	s_waitcnt lgkmcnt(0)
	s_barrier
; __device__ __forceinline__ unsigned cvt_pk_bf16(float lo, float hi) { unsigned r; asm volatile("v_cvt_pk_bf16_f32 %0, %1, %2" : "=v"(r) : "v"(lo), "v"(hi)); return r; }
; #define PG8_STAGE(bufoff, gbase, voff) do { _Pragma("unroll") for (int _i = 0; _i < 2; ++_i) \
;         __builtin_amdgcn_global_load_lds((const unsigned*)((const char*)(gbase) + (voff)[_i]), (PG8_LAS unsigned*)(lds + (bufoff) + ldsw + _i * 8192), 16, 0, 0); } while (0)
; #define PG8_MMA(ai, bj, At, Bt) do { __builtin_amdgcn_s_setprio(1); _Pragma("unroll") for (int m = 0; m < 4; ++m) _Pragma("unroll") for (int n = 0; n < 2; ++n) _Pragma("unroll") for (int k = 0; k < 2; ++k) \
;         acc[ai][bj][m][n] = __builtin_amdgcn_mfma_f32_16x16x32_bf16(Bt[n][k], At[m][k], acc[ai][bj][m][n], 0, 0, 0); __builtin_amdgcn_s_setprio(0); } while (0)
; #define PG8_WAIT_V(n) asm volatile("s_waitcnt vmcnt(" #n ")" ::: "memory")
; #define PG8_WAIT_L(n) asm volatile("s_waitcnt lgkmcnt(" #n ")" ::: "memory")
; #define PG8_BAR __builtin_amdgcn_s_barrier()
; #define PG8_SCHED __builtin_amdgcn_sched_barrier(0)
;     __device__ __forceinline__ void operator()(const f32x4 (&acc)[2][2][4][2], const Unit& u, int wr, int wc, int fr, int fq) const {
;     ...
;         for (int ai = 0; ai < 2; ++ai)
; #pragma unroll
;             for (int m = 0; m < 4; ++m) { bf16_t* rowp = O + (size_t)(row0 + ai * HALF + m * 16) * ldc + col0;
;                 f32x4 v0, v1;
; #pragma unroll
;                 for (int j = 0; j < 1; ++j) { v0 = acc[ai][0][m][0] * sigmoid4(acc[ai][0][m][0]) * acc[ai][1][m][0]; v1 = acc[ai][0][m][1] * sigmoid4(acc[ai][0][m][1]) * acc[ai][1][m][1]; }
;                 u32x4 w; w.x = cvt_pk_bf16(v0[0], v0[1]); w.y = cvt_pk_bf16(v0[2], v0[3]); w.z = cvt_pk_bf16(v1[0], v1[1]); w.w = cvt_pk_bf16(v1[2], v1[3]);
;                 *(u32x4*)rowp = w; }
; template <class Epi, class Sched>
; __device__ __forceinline__ void gemm_phase(PG8_LAS unsigned char* lds, const Gemm g, const Sched& S, const Epi& E) {
;     ...
;             PG8_BAR; PG8_WAIT_L(0); PG8_MMA(1, 0, At, B0); PG8_BAR; PG8_SCHED;
;             PG8_STAGE(PG8_SB(1, 1), b3 + hstep, voffB);
;             PG8_WAIT_V(6); PG8_BAR; PG8_MMA(1, 1, At, B1); PG8_BAR;
;         }
	v_mfma_f32_16x16x32_bf16 v[60:63], v[144:147], v[170:173], v[60:63]
	v_mfma_f32_16x16x32_bf16 v[56:59], v[160:163], v[170:173], v[56:59]
	v_mfma_f32_16x16x32_bf16 v[44:47], v[144:147], v[190:193], v[44:47]
	v_mfma_f32_16x16x32_bf16 v[40:43], v[160:163], v[190:193], v[40:43]
	v_mfma_f32_16x16x32_bf16 v[28:31], v[144:147], v[198:201], v[28:31]
	v_mfma_f32_16x16x32_bf16 v[24:27], v[160:163], v[198:201], v[24:27]
	v_mfma_f32_16x16x32_bf16 v[12:15], v[144:147], v[206:209], v[12:15]
	v_mfma_f32_16x16x32_bf16 v[8:11], v[160:163], v[206:209], v[8:11]
	v_mfma_f32_16x16x32_bf16 v[60:63], v[156:159], v[182:185], v[60:63]
	v_mfma_f32_16x16x32_bf16 v[56:59], v[166:169], v[182:185], v[56:59]
	v_mfma_f32_16x16x32_bf16 v[44:47], v[156:159], v[194:197], v[44:47]
	v_mfma_f32_16x16x32_bf16 v[40:43], v[166:169], v[194:197], v[40:43]
	v_mfma_f32_16x16x32_bf16 v[28:31], v[156:159], v[202:205], v[28:31]
	v_mfma_f32_16x16x32_bf16 v[24:27], v[166:169], v[202:205], v[24:27]
	v_mfma_f32_16x16x32_bf16 v[12:15], v[156:159], v[210:213], v[12:15]
	v_mfma_f32_16x16x32_bf16 v[8:11], v[166:169], v[210:213], v[8:11]
	s_barrier
	s_add_u32 s30, s30, 0x40080
	s_addc_u32 s31, s31, 0
	s_add_i32 s34, s34, s40
	v_lshl_add_u64 v[144:145], s[30:31], 0, v[132:133]
	s_mov_b32 m0, s34
	s_nop 0
	global_load_lds_dwordx4 v[144:145], off
	v_lshl_add_u64 v[144:145], s[30:31], 0, v[128:129]
	s_add_i32 m0, s34, 0x2000
	s_nop 0
	global_load_lds_dwordx4 v[144:145], off
	s_waitcnt vmcnt(6)
	s_barrier
	v_mfma_f32_16x16x32_bf16 v[52:55], v[214:217], v[170:173], v[52:55]
	v_mfma_f32_16x16x32_bf16 v[48:51], v[222:225], v[170:173], v[48:51]
	v_mfma_f32_16x16x32_bf16 v[36:39], v[214:217], v[190:193], v[36:39]
	v_mfma_f32_16x16x32_bf16 v[32:35], v[222:225], v[190:193], v[32:35]
	v_mfma_f32_16x16x32_bf16 v[20:23], v[214:217], v[198:201], v[20:23]
	v_mfma_f32_16x16x32_bf16 v[16:19], v[222:225], v[198:201], v[16:19]
	v_mfma_f32_16x16x32_bf16 v[4:7], v[214:217], v[206:209], v[4:7]
	v_mfma_f32_16x16x32_bf16 v[0:3], v[222:225], v[206:209], v[0:3]
	v_mfma_f32_16x16x32_bf16 v[52:55], v[218:221], v[182:185], v[52:55]
	v_mfma_f32_16x16x32_bf16 v[48:51], v[226:229], v[182:185], v[48:51]
	v_mfma_f32_16x16x32_bf16 v[36:39], v[218:221], v[194:197], v[36:39]
	v_mfma_f32_16x16x32_bf16 v[32:35], v[226:229], v[194:197], v[32:35]
	v_mfma_f32_16x16x32_bf16 v[20:23], v[218:221], v[202:205], v[20:23]
	v_mfma_f32_16x16x32_bf16 v[16:19], v[226:229], v[202:205], v[16:19]
	v_mfma_f32_16x16x32_bf16 v[4:7], v[218:221], v[210:213], v[4:7]
	v_mfma_f32_16x16x32_bf16 v[0:3], v[226:229], v[210:213], v[0:3]
	s_add_i32 s58, s58, 2
	s_add_u32 s28, s28, 0x100
	s_addc_u32 s29, s29, 0
	s_add_u32 s56, s56, 0x100
	s_addc_u32 s57, s57, 0
	s_cmp_gt_u32 s58, 13
	s_barrier
	s_cbranch_scc0 .LBB0_195
	v_max_f32_e32 v144, v124, v124
	v_max_f32_e32 v144, 0xc1a00000, v144
	v_mul_f32_e32 v144, 0xbfb8aa3b, v144
	v_exp_f32_e32 v157, v144
	v_max_f32_e32 v144, v125, v125
	v_max_f32_e32 v144, 0xc1a00000, v144
	v_mul_f32_e32 v144, 0xbfb8aa3b, v144
	v_exp_f32_e32 v156, v144
	v_max_f32_e32 v144, v126, v126
	v_max_f32_e32 v144, 0xc1a00000, v144
	v_mul_f32_e32 v144, 0xbfb8aa3b, v144
	v_exp_f32_e32 v159, v144
	v_max_f32_e32 v144, v127, v127
	v_max_f32_e32 v144, 0xc1a00000, v144
	v_mul_f32_e32 v144, 0xbfb8aa3b, v144
	v_exp_f32_e32 v158, v144
	v_pk_add_f32 v[156:157], v[156:157], 1.0 op_sel_hi:[1,0]
	v_lshl_or_b32 v146, s53, 7, v150
	v_mov_b32_e32 v160, v157
	v_pk_add_f32 v[158:159], v[158:159], 1.0 op_sel_hi:[1,0]
	v_mov_b32_e32 v162, v156
	v_mov_b32_e32 v161, v159
	v_mov_b32_e32 v163, v158
	v_pk_mul_f32 v[160:161], v[160:161], v[162:163]
	v_lshl_add_u32 v155, s26, 8, v148
	v_mul_f32_e32 v162, v160, v161
	v_rcp_f32_e32 v166, v162
	v_ashrrev_i32_e32 v147, 31, v146
	v_mov_b64_e32 v[144:145], s[4:5]
	v_mad_i64_i32 v[162:163], s[28:29], v155, s52, v[144:145]
	v_mul_f32_e32 v160, v160, v166
	v_mul_f32_e32 v164, v161, v166
	v_pk_mul_f32 v[158:159], v[158:159], v[160:161] op_sel_hi:[1,0]
	v_max_f32_e32 v160, v120, v120
	v_max_f32_e32 v166, v122, v122
	v_max_f32_e32 v160, 0xc1a00000, v160
	v_max_f32_e32 v166, 0xc1a00000, v166
	v_mul_f32_e32 v160, 0xbfb8aa3b, v160
	v_mul_f32_e32 v166, 0xbfb8aa3b, v166
	v_exp_f32_e32 v161, v160
	v_max_f32_e32 v160, v121, v121
	v_exp_f32_e32 v167, v166
	v_max_f32_e32 v166, v123, v123
	v_max_f32_e32 v160, 0xc1a00000, v160
	v_max_f32_e32 v166, 0xc1a00000, v166
	v_mul_f32_e32 v160, 0xbfb8aa3b, v160
	v_mul_f32_e32 v166, 0xbfb8aa3b, v166
	v_exp_f32_e32 v160, v160
	v_exp_f32_e32 v166, v166
	v_pk_mul_f32 v[156:157], v[156:157], v[164:165] op_sel_hi:[1,0]
	v_pk_mul_f32 v[126:127], v[126:127], v[158:159]
	v_pk_mul_f32 v[124:125], v[124:125], v[156:157]
	v_pk_add_f32 v[156:157], v[160:161], 1.0 op_sel_hi:[1,0]
	v_pk_add_f32 v[160:161], v[166:167], 1.0 op_sel_hi:[1,0]
	v_mov_b32_e32 v166, v157
	v_mov_b32_e32 v167, v161
	v_mov_b32_e32 v168, v156
	v_mov_b32_e32 v169, v160
	v_pk_mul_f32 v[166:167], v[166:167], v[168:169]
	v_pk_mul_f32 v[118:119], v[126:127], v[118:119]
	v_mul_f32_e32 v164, v166, v167
	v_rcp_f32_e32 v164, v164
	v_pk_mul_f32 v[116:117], v[124:125], v[116:117]
	v_lshlrev_b64 v[146:147], 1, v[146:147]
	v_lshl_add_u64 v[162:163], v[162:163], 0, v[146:147]
	v_mul_f32_e32 v124, v167, v164
	v_mul_f32_e32 v126, v166, v164
	v_pk_mul_f32 v[126:127], v[160:161], v[126:127] op_sel_hi:[1,0]
	v_pk_mul_f32 v[124:125], v[156:157], v[124:125] op_sel_hi:[1,0]
	v_pk_mul_f32 v[122:123], v[122:123], v[126:127]
	v_pk_mul_f32 v[120:121], v[120:121], v[124:125]
	v_pk_mul_f32 v[122:123], v[122:123], v[114:115]
	v_pk_mul_f32 v[114:115], v[120:121], v[112:113]
	v_cvt_pk_bf16_f32 v112, v116, v117
	v_cvt_pk_bf16_f32 v113, v118, v119
	v_max_f32_e32 v116, v108, v108
; __device__ __forceinline__ unsigned cvt_pk_bf16(float lo, float hi) { unsigned r; asm volatile("v_cvt_pk_bf16_f32 %0, %1, %2" : "=v"(r) : "v"(lo), "v"(hi)); return r; }
; __device__ __forceinline__ f32x4 sigmoid4(f32x4 x) {
;     f32x4 d;
; #pragma unroll
;     for (int j = 0; j < 4; ++j) d[j] = 1.0f + __expf(-fmaxf(x[j], -20.0f));
;     const float p01 = d[0] * d[1], p23 = d[2] * d[3], r = __builtin_amdgcn_rcpf(p01 * p23), r01 = r * p23, r23 = r * p01;
;     return (f32x4){r01 * d[1], r01 * d[0], r23 * d[3], r23 * d[2]};
; }
;     __device__ __forceinline__ void operator()(const f32x4 (&acc)[2][2][4][2], const Unit& u, int wr, int wc, int fr, int fq) const {
;     ...
;         for (int ai = 0; ai < 2; ++ai)
; #pragma unroll
;             for (int m = 0; m < 4; ++m) { bf16_t* rowp = O + (size_t)(row0 + ai * HALF + m * 16) * ldc + col0;
;                 f32x4 v0, v1;
; #pragma unroll
;                 for (int j = 0; j < 1; ++j) { v0 = acc[ai][0][m][0] * sigmoid4(acc[ai][0][m][0]) * acc[ai][1][m][0]; v1 = acc[ai][0][m][1] * sigmoid4(acc[ai][0][m][1]) * acc[ai][1][m][1]; }
;                 u32x4 w; w.x = cvt_pk_bf16(v0[0], v0[1]); w.y = cvt_pk_bf16(v0[2], v0[3]); w.z = cvt_pk_bf16(v1[0], v1[1]); w.w = cvt_pk_bf16(v1[2], v1[3]);
;                 *(u32x4*)rowp = w; }
	v_max_f32_e32 v118, v110, v110
	v_max_f32_e32 v116, 0xc1a00000, v116
	v_max_f32_e32 v118, 0xc1a00000, v118
	v_mul_f32_e32 v116, 0xbfb8aa3b, v116
	v_mul_f32_e32 v118, 0xbfb8aa3b, v118
	v_exp_f32_e32 v117, v116
	v_max_f32_e32 v116, v109, v109
	v_exp_f32_e32 v119, v118
	v_max_f32_e32 v118, v111, v111
	v_max_f32_e32 v116, 0xc1a00000, v116
	v_max_f32_e32 v118, 0xc1a00000, v118
	v_mul_f32_e32 v116, 0xbfb8aa3b, v116
	v_mul_f32_e32 v118, 0xbfb8aa3b, v118
	v_exp_f32_e32 v116, v116
	v_exp_f32_e32 v118, v118
	v_cvt_pk_bf16_f32 v114, v114, v115
	v_cvt_pk_bf16_f32 v115, v122, v123
	global_store_dwordx4 v[162:163], v[112:115], off
	v_or_b32_e32 v120, 16, v155
	s_and_b64 vcc, exec, s[2:3]
	v_pk_add_f32 v[112:113], v[116:117], 1.0 op_sel_hi:[1,0]
	v_pk_add_f32 v[114:115], v[118:119], 1.0 op_sel_hi:[1,0]
	v_mov_b32_e32 v116, v113
	v_mov_b32_e32 v117, v115
	v_mov_b32_e32 v118, v112
	v_mov_b32_e32 v119, v114
	v_pk_mul_f32 v[116:117], v[116:117], v[118:119]
	s_mov_b32 s53, s14
	v_mul_f32_e32 v118, v116, v117
	v_rcp_f32_e32 v121, v118
	v_mad_i64_i32 v[118:119], s[28:29], v120, s52, v[144:145]
	v_lshl_add_u64 v[118:119], v[118:119], 0, v[146:147]
	v_mul_f32_e32 v116, v116, v121
	v_mul_f32_e32 v120, v117, v121
	v_pk_mul_f32 v[114:115], v[114:115], v[116:117] op_sel_hi:[1,0]
	v_max_f32_e32 v116, v104, v104
	v_max_f32_e32 v121, v106, v106
	v_max_f32_e32 v116, 0xc1a00000, v116
	v_max_f32_e32 v121, 0xc1a00000, v121
	v_mul_f32_e32 v116, 0xbfb8aa3b, v116
	v_mul_f32_e32 v121, 0xbfb8aa3b, v121
	v_exp_f32_e32 v117, v116
	v_max_f32_e32 v116, v105, v105
	v_exp_f32_e32 v123, v121
	v_max_f32_e32 v121, v107, v107
	v_max_f32_e32 v116, 0xc1a00000, v116
	v_max_f32_e32 v121, 0xc1a00000, v121
	v_mul_f32_e32 v116, 0xbfb8aa3b, v116
	v_mul_f32_e32 v121, 0xbfb8aa3b, v121
	v_exp_f32_e32 v116, v116
	v_exp_f32_e32 v122, v121
	v_pk_mul_f32 v[112:113], v[112:113], v[120:121] op_sel_hi:[1,0]
	v_pk_mul_f32 v[110:111], v[110:111], v[114:115]
	v_pk_mul_f32 v[108:109], v[108:109], v[112:113]
	v_pk_add_f32 v[112:113], v[116:117], 1.0 op_sel_hi:[1,0]
	v_pk_add_f32 v[116:117], v[122:123], 1.0 op_sel_hi:[1,0]
	v_mov_b32_e32 v120, v113
	v_mov_b32_e32 v121, v117
	v_mov_b32_e32 v122, v112
	v_mov_b32_e32 v123, v116
	v_pk_mul_f32 v[120:121], v[120:121], v[122:123]
	v_pk_mul_f32 v[102:103], v[110:111], v[102:103]
	v_mul_f32_e32 v122, v120, v121
	v_rcp_f32_e32 v122, v122
	v_pk_mul_f32 v[100:101], v[108:109], v[100:101]
	s_mov_b32 s26, s16
	s_mov_b64 s[30:31], s[24:25]
	v_mul_f32_e32 v108, v121, v122
	v_mul_f32_e32 v110, v120, v122
	v_pk_mul_f32 v[110:111], v[116:117], v[110:111] op_sel_hi:[1,0]
	v_pk_mul_f32 v[108:109], v[112:113], v[108:109] op_sel_hi:[1,0]
	v_pk_mul_f32 v[106:107], v[106:107], v[110:111]
	v_pk_mul_f32 v[104:105], v[104:105], v[108:109]
	v_pk_mul_f32 v[106:107], v[106:107], v[98:99]
	v_pk_mul_f32 v[98:99], v[104:105], v[96:97]
	v_cvt_pk_bf16_f32 v96, v100, v101
	v_cvt_pk_bf16_f32 v97, v102, v103
	v_max_f32_e32 v100, v92, v92
	v_max_f32_e32 v102, v94, v94
	v_max_f32_e32 v100, 0xc1a00000, v100
	v_max_f32_e32 v102, 0xc1a00000, v102
	v_mul_f32_e32 v100, 0xbfb8aa3b, v100
	v_mul_f32_e32 v102, 0xbfb8aa3b, v102
	v_exp_f32_e32 v101, v100
	v_max_f32_e32 v100, v93, v93
	v_exp_f32_e32 v103, v102
	v_max_f32_e32 v102, v95, v95
	v_max_f32_e32 v100, 0xc1a00000, v100
	v_max_f32_e32 v102, 0xc1a00000, v102
	v_mul_f32_e32 v100, 0xbfb8aa3b, v100
	v_mul_f32_e32 v102, 0xbfb8aa3b, v102
	v_exp_f32_e32 v100, v100
	v_exp_f32_e32 v102, v102
	v_cvt_pk_bf16_f32 v98, v98, v99
	v_cvt_pk_bf16_f32 v99, v106, v107
	global_store_dwordx4 v[118:119], v[96:99], off
	v_or_b32_e32 v104, 32, v155
	s_nop 0
	v_pk_add_f32 v[96:97], v[100:101], 1.0 op_sel_hi:[1,0]
	v_pk_add_f32 v[98:99], v[102:103], 1.0 op_sel_hi:[1,0]
	v_mov_b32_e32 v100, v97
	v_mov_b32_e32 v101, v99
	v_mov_b32_e32 v102, v96
	v_mov_b32_e32 v103, v98
	v_pk_mul_f32 v[100:101], v[100:101], v[102:103]
	s_nop 0
	v_mul_f32_e32 v102, v100, v101
	v_rcp_f32_e32 v105, v102
	v_mad_i64_i32 v[102:103], s[28:29], v104, s52, v[144:145]
	v_lshl_add_u64 v[102:103], v[102:103], 0, v[146:147]
	v_mul_f32_e32 v100, v100, v105
	v_mul_f32_e32 v104, v101, v105
	v_pk_mul_f32 v[98:99], v[98:99], v[100:101] op_sel_hi:[1,0]
	v_max_f32_e32 v100, v88, v88
	v_max_f32_e32 v105, v90, v90
	v_max_f32_e32 v100, 0xc1a00000, v100
	v_max_f32_e32 v105, 0xc1a00000, v105
	v_mul_f32_e32 v100, 0xbfb8aa3b, v100
	v_mul_f32_e32 v105, 0xbfb8aa3b, v105
	v_exp_f32_e32 v101, v100
	v_max_f32_e32 v100, v89, v89
	v_exp_f32_e32 v107, v105
	v_max_f32_e32 v105, v91, v91
	v_max_f32_e32 v100, 0xc1a00000, v100
	v_max_f32_e32 v105, 0xc1a00000, v105
	v_mul_f32_e32 v100, 0xbfb8aa3b, v100
	v_mul_f32_e32 v105, 0xbfb8aa3b, v105
	v_exp_f32_e32 v100, v100
	v_exp_f32_e32 v106, v105
	v_pk_mul_f32 v[96:97], v[96:97], v[104:105] op_sel_hi:[1,0]
	v_pk_mul_f32 v[94:95], v[94:95], v[98:99]
	v_pk_mul_f32 v[92:93], v[92:93], v[96:97]
	v_pk_add_f32 v[96:97], v[100:101], 1.0 op_sel_hi:[1,0]
	v_pk_add_f32 v[100:101], v[106:107], 1.0 op_sel_hi:[1,0]
	v_mov_b32_e32 v104, v97
	v_mov_b32_e32 v105, v101
	v_mov_b32_e32 v106, v96
	v_mov_b32_e32 v107, v100
	v_pk_mul_f32 v[104:105], v[104:105], v[106:107]
	v_pk_mul_f32 v[86:87], v[94:95], v[86:87]
	v_mul_f32_e32 v106, v104, v105
	v_rcp_f32_e32 v106, v106
	v_pk_mul_f32 v[84:85], v[92:93], v[84:85]
	v_mul_f32_e32 v92, v105, v106
	v_mul_f32_e32 v94, v104, v106
	v_pk_mul_f32 v[94:95], v[100:101], v[94:95] op_sel_hi:[1,0]
	v_pk_mul_f32 v[92:93], v[96:97], v[92:93] op_sel_hi:[1,0]
	v_pk_mul_f32 v[90:91], v[90:91], v[94:95]
	v_pk_mul_f32 v[88:89], v[88:89], v[92:93]
	v_pk_mul_f32 v[90:91], v[90:91], v[82:83]
	v_pk_mul_f32 v[82:83], v[88:89], v[80:81]
	v_cvt_pk_bf16_f32 v80, v84, v85
	v_cvt_pk_bf16_f32 v81, v86, v87
; __device__ __forceinline__ unsigned cvt_pk_bf16(float lo, float hi) { unsigned r; asm volatile("v_cvt_pk_bf16_f32 %0, %1, %2" : "=v"(r) : "v"(lo), "v"(hi)); return r; }
; __device__ __forceinline__ f32x4 sigmoid4(f32x4 x) {
;     f32x4 d;
; #pragma unroll
;     for (int j = 0; j < 4; ++j) d[j] = 1.0f + __expf(-fmaxf(x[j], -20.0f));
;     const float p01 = d[0] * d[1], p23 = d[2] * d[3], r = __builtin_amdgcn_rcpf(p01 * p23), r01 = r * p23, r23 = r * p01;
;     return (f32x4){r01 * d[1], r01 * d[0], r23 * d[3], r23 * d[2]};
; }
;     __device__ __forceinline__ void operator()(const f32x4 (&acc)[2][2][4][2], const Unit& u, int wr, int wc, int fr, int fq) const {
;     ...
;         for (int ai = 0; ai < 2; ++ai)
; #pragma unroll
;             for (int m = 0; m < 4; ++m) { bf16_t* rowp = O + (size_t)(row0 + ai * HALF + m * 16) * ldc + col0;
;                 f32x4 v0, v1;
; #pragma unroll
;                 for (int j = 0; j < 1; ++j) { v0 = acc[ai][0][m][0] * sigmoid4(acc[ai][0][m][0]) * acc[ai][1][m][0]; v1 = acc[ai][0][m][1] * sigmoid4(acc[ai][0][m][1]) * acc[ai][1][m][1]; }
;                 u32x4 w; w.x = cvt_pk_bf16(v0[0], v0[1]); w.y = cvt_pk_bf16(v0[2], v0[3]); w.z = cvt_pk_bf16(v1[0], v1[1]); w.w = cvt_pk_bf16(v1[2], v1[3]);
;                 *(u32x4*)rowp = w; }
	v_max_f32_e32 v84, v76, v76
	v_max_f32_e32 v86, v78, v78
	v_max_f32_e32 v84, 0xc1a00000, v84
	v_max_f32_e32 v86, 0xc1a00000, v86
	v_mul_f32_e32 v84, 0xbfb8aa3b, v84
	v_mul_f32_e32 v86, 0xbfb8aa3b, v86
	v_exp_f32_e32 v85, v84
	v_max_f32_e32 v84, v77, v77
	v_exp_f32_e32 v87, v86
	v_max_f32_e32 v86, v79, v79
	v_max_f32_e32 v84, 0xc1a00000, v84
	v_max_f32_e32 v86, 0xc1a00000, v86
	v_mul_f32_e32 v84, 0xbfb8aa3b, v84
	v_mul_f32_e32 v86, 0xbfb8aa3b, v86
	v_exp_f32_e32 v84, v84
	v_exp_f32_e32 v86, v86
	v_cvt_pk_bf16_f32 v82, v82, v83
	v_cvt_pk_bf16_f32 v83, v90, v91
	global_store_dwordx4 v[102:103], v[80:83], off
	v_or_b32_e32 v88, 48, v155
	s_nop 0
	v_pk_add_f32 v[80:81], v[84:85], 1.0 op_sel_hi:[1,0]
	v_pk_add_f32 v[82:83], v[86:87], 1.0 op_sel_hi:[1,0]
	v_mov_b32_e32 v84, v81
	v_mov_b32_e32 v85, v83
	v_mov_b32_e32 v86, v80
	v_mov_b32_e32 v87, v82
	v_pk_mul_f32 v[84:85], v[84:85], v[86:87]
	s_nop 0
	v_mul_f32_e32 v86, v84, v85
	v_rcp_f32_e32 v89, v86
	v_mad_i64_i32 v[86:87], s[28:29], v88, s52, v[144:145]
	v_lshl_add_u64 v[86:87], v[86:87], 0, v[146:147]
	v_mul_f32_e32 v84, v84, v89
	v_mul_f32_e32 v88, v85, v89
	v_pk_mul_f32 v[82:83], v[82:83], v[84:85] op_sel_hi:[1,0]
	v_max_f32_e32 v84, v72, v72
	v_max_f32_e32 v89, v74, v74
	v_max_f32_e32 v84, 0xc1a00000, v84
	v_max_f32_e32 v89, 0xc1a00000, v89
	v_mul_f32_e32 v84, 0xbfb8aa3b, v84
	v_mul_f32_e32 v89, 0xbfb8aa3b, v89
	v_exp_f32_e32 v85, v84
	v_max_f32_e32 v84, v73, v73
	v_exp_f32_e32 v91, v89
	v_max_f32_e32 v89, v75, v75
	v_max_f32_e32 v84, 0xc1a00000, v84
	v_max_f32_e32 v89, 0xc1a00000, v89
	v_mul_f32_e32 v84, 0xbfb8aa3b, v84
	v_mul_f32_e32 v89, 0xbfb8aa3b, v89
	v_exp_f32_e32 v84, v84
	v_exp_f32_e32 v90, v89
	v_pk_mul_f32 v[80:81], v[80:81], v[88:89] op_sel_hi:[1,0]
	v_pk_mul_f32 v[78:79], v[78:79], v[82:83]
	v_pk_mul_f32 v[76:77], v[76:77], v[80:81]
	v_pk_add_f32 v[80:81], v[84:85], 1.0 op_sel_hi:[1,0]
	v_pk_add_f32 v[84:85], v[90:91], 1.0 op_sel_hi:[1,0]
	v_mov_b32_e32 v88, v81
	v_mov_b32_e32 v89, v85
	v_mov_b32_e32 v90, v80
	v_mov_b32_e32 v91, v84
	v_pk_mul_f32 v[88:89], v[88:89], v[90:91]
	v_pk_mul_f32 v[70:71], v[78:79], v[70:71]
	v_mul_f32_e32 v90, v88, v89
	v_rcp_f32_e32 v90, v90
	v_pk_mul_f32 v[68:69], v[76:77], v[68:69]
	v_mul_f32_e32 v76, v89, v90
	v_mul_f32_e32 v78, v88, v90
	v_pk_mul_f32 v[78:79], v[84:85], v[78:79] op_sel_hi:[1,0]
	v_pk_mul_f32 v[76:77], v[80:81], v[76:77] op_sel_hi:[1,0]
	v_pk_mul_f32 v[74:75], v[74:75], v[78:79]
	v_pk_mul_f32 v[72:73], v[72:73], v[76:77]
	v_pk_mul_f32 v[74:75], v[74:75], v[66:67]
	v_pk_mul_f32 v[66:67], v[72:73], v[64:65]
	v_cvt_pk_bf16_f32 v64, v68, v69
	v_cvt_pk_bf16_f32 v65, v70, v71
	v_max_f32_e32 v68, v60, v60
	v_max_f32_e32 v70, v62, v62
	v_max_f32_e32 v68, 0xc1a00000, v68
	v_max_f32_e32 v70, 0xc1a00000, v70
	v_mul_f32_e32 v68, 0xbfb8aa3b, v68
	v_mul_f32_e32 v70, 0xbfb8aa3b, v70
	v_exp_f32_e32 v69, v68
	v_max_f32_e32 v68, v61, v61
	v_exp_f32_e32 v71, v70
	v_max_f32_e32 v70, v63, v63
	v_max_f32_e32 v68, 0xc1a00000, v68
	v_max_f32_e32 v70, 0xc1a00000, v70
	v_mul_f32_e32 v68, 0xbfb8aa3b, v68
	v_mul_f32_e32 v70, 0xbfb8aa3b, v70
	v_exp_f32_e32 v68, v68
	v_exp_f32_e32 v70, v70
	v_cvt_pk_bf16_f32 v66, v66, v67
	v_cvt_pk_bf16_f32 v67, v74, v75
	global_store_dwordx4 v[86:87], v[64:67], off
	v_add_u32_e32 v72, 0x80, v155
	s_nop 0
	v_pk_add_f32 v[64:65], v[68:69], 1.0 op_sel_hi:[1,0]
	v_pk_add_f32 v[66:67], v[70:71], 1.0 op_sel_hi:[1,0]
	v_mov_b32_e32 v68, v65
	v_mov_b32_e32 v69, v67
	v_mov_b32_e32 v70, v64
	v_mov_b32_e32 v71, v66
	v_pk_mul_f32 v[68:69], v[68:69], v[70:71]
	s_nop 0
	v_mul_f32_e32 v70, v68, v69
	v_rcp_f32_e32 v73, v70
	v_mad_i64_i32 v[70:71], s[28:29], v72, s52, v[144:145]
	v_lshl_add_u64 v[70:71], v[70:71], 0, v[146:147]
	v_mul_f32_e32 v68, v68, v73
	v_mul_f32_e32 v72, v69, v73
	v_pk_mul_f32 v[66:67], v[66:67], v[68:69] op_sel_hi:[1,0]
	v_max_f32_e32 v68, v56, v56
	v_max_f32_e32 v73, v58, v58
	v_max_f32_e32 v68, 0xc1a00000, v68
	v_max_f32_e32 v73, 0xc1a00000, v73
	v_mul_f32_e32 v68, 0xbfb8aa3b, v68
	v_mul_f32_e32 v73, 0xbfb8aa3b, v73
	v_exp_f32_e32 v69, v68
	v_max_f32_e32 v68, v57, v57
	v_exp_f32_e32 v75, v73
	v_max_f32_e32 v73, v59, v59
	v_max_f32_e32 v68, 0xc1a00000, v68
	v_max_f32_e32 v73, 0xc1a00000, v73
	v_mul_f32_e32 v68, 0xbfb8aa3b, v68
	v_mul_f32_e32 v73, 0xbfb8aa3b, v73
	v_exp_f32_e32 v68, v68
	v_exp_f32_e32 v74, v73
	v_pk_mul_f32 v[64:65], v[64:65], v[72:73] op_sel_hi:[1,0]
	v_pk_mul_f32 v[62:63], v[62:63], v[66:67]
	v_pk_mul_f32 v[60:61], v[60:61], v[64:65]
	v_pk_add_f32 v[64:65], v[68:69], 1.0 op_sel_hi:[1,0]
	v_pk_add_f32 v[68:69], v[74:75], 1.0 op_sel_hi:[1,0]
	v_mov_b32_e32 v72, v65
	v_mov_b32_e32 v73, v69
	v_mov_b32_e32 v74, v64
	v_mov_b32_e32 v75, v68
	v_pk_mul_f32 v[72:73], v[72:73], v[74:75]
	v_pk_mul_f32 v[54:55], v[62:63], v[54:55]
	v_mul_f32_e32 v74, v72, v73
	v_rcp_f32_e32 v74, v74
	v_pk_mul_f32 v[52:53], v[60:61], v[52:53]
	v_mul_f32_e32 v60, v73, v74
	v_mul_f32_e32 v62, v72, v74
	v_pk_mul_f32 v[62:63], v[68:69], v[62:63] op_sel_hi:[1,0]
	v_pk_mul_f32 v[60:61], v[64:65], v[60:61] op_sel_hi:[1,0]
	v_pk_mul_f32 v[58:59], v[58:59], v[62:63]
	v_pk_mul_f32 v[56:57], v[56:57], v[60:61]
	v_pk_mul_f32 v[58:59], v[58:59], v[50:51]
	v_pk_mul_f32 v[50:51], v[56:57], v[48:49]
	v_cvt_pk_bf16_f32 v48, v52, v53
	v_cvt_pk_bf16_f32 v49, v54, v55
	v_max_f32_e32 v52, v44, v44
	v_max_f32_e32 v54, v46, v46
	v_max_f32_e32 v52, 0xc1a00000, v52
	v_max_f32_e32 v54, 0xc1a00000, v54
	v_mul_f32_e32 v52, 0xbfb8aa3b, v52
	v_mul_f32_e32 v54, 0xbfb8aa3b, v54
	v_exp_f32_e32 v53, v52
	v_max_f32_e32 v52, v45, v45
	v_exp_f32_e32 v55, v54
	v_max_f32_e32 v54, v47, v47
	v_max_f32_e32 v52, 0xc1a00000, v52
	v_max_f32_e32 v54, 0xc1a00000, v54
; __device__ __forceinline__ unsigned cvt_pk_bf16(float lo, float hi) { unsigned r; asm volatile("v_cvt_pk_bf16_f32 %0, %1, %2" : "=v"(r) : "v"(lo), "v"(hi)); return r; }
; __device__ __forceinline__ f32x4 sigmoid4(f32x4 x) {
;     f32x4 d;
; #pragma unroll
;     for (int j = 0; j < 4; ++j) d[j] = 1.0f + __expf(-fmaxf(x[j], -20.0f));
;     const float p01 = d[0] * d[1], p23 = d[2] * d[3], r = __builtin_amdgcn_rcpf(p01 * p23), r01 = r * p23, r23 = r * p01;
;     return (f32x4){r01 * d[1], r01 * d[0], r23 * d[3], r23 * d[2]};
; }
;     __device__ __forceinline__ void operator()(const f32x4 (&acc)[2][2][4][2], const Unit& u, int wr, int wc, int fr, int fq) const {
;     ...
;         for (int ai = 0; ai < 2; ++ai)
; #pragma unroll
;             for (int m = 0; m < 4; ++m) { bf16_t* rowp = O + (size_t)(row0 + ai * HALF + m * 16) * ldc + col0;
;                 f32x4 v0, v1;
; #pragma unroll
;                 for (int j = 0; j < 1; ++j) { v0 = acc[ai][0][m][0] * sigmoid4(acc[ai][0][m][0]) * acc[ai][1][m][0]; v1 = acc[ai][0][m][1] * sigmoid4(acc[ai][0][m][1]) * acc[ai][1][m][1]; }
;                 u32x4 w; w.x = cvt_pk_bf16(v0[0], v0[1]); w.y = cvt_pk_bf16(v0[2], v0[3]); w.z = cvt_pk_bf16(v1[0], v1[1]); w.w = cvt_pk_bf16(v1[2], v1[3]);
;                 *(u32x4*)rowp = w; }
	v_mul_f32_e32 v52, 0xbfb8aa3b, v52
	v_mul_f32_e32 v54, 0xbfb8aa3b, v54
	v_exp_f32_e32 v52, v52
	v_exp_f32_e32 v54, v54
	v_cvt_pk_bf16_f32 v50, v50, v51
	v_cvt_pk_bf16_f32 v51, v58, v59
	global_store_dwordx4 v[70:71], v[48:51], off
	v_add_u32_e32 v56, 0x90, v155
	s_nop 0
	v_pk_add_f32 v[48:49], v[52:53], 1.0 op_sel_hi:[1,0]
	v_pk_add_f32 v[50:51], v[54:55], 1.0 op_sel_hi:[1,0]
	v_mov_b32_e32 v52, v49
	v_mov_b32_e32 v53, v51
	v_mov_b32_e32 v54, v48
	v_mov_b32_e32 v55, v50
	v_pk_mul_f32 v[52:53], v[52:53], v[54:55]
	s_nop 0
	v_mul_f32_e32 v54, v52, v53
	v_rcp_f32_e32 v57, v54
	v_mad_i64_i32 v[54:55], s[28:29], v56, s52, v[144:145]
	v_lshl_add_u64 v[54:55], v[54:55], 0, v[146:147]
	v_mul_f32_e32 v52, v52, v57
	v_mul_f32_e32 v56, v53, v57
	v_pk_mul_f32 v[50:51], v[50:51], v[52:53] op_sel_hi:[1,0]
	v_max_f32_e32 v52, v40, v40
	v_max_f32_e32 v57, v42, v42
	v_max_f32_e32 v52, 0xc1a00000, v52
	v_max_f32_e32 v57, 0xc1a00000, v57
	v_mul_f32_e32 v52, 0xbfb8aa3b, v52
	v_mul_f32_e32 v57, 0xbfb8aa3b, v57
	v_exp_f32_e32 v53, v52
	v_max_f32_e32 v52, v41, v41
	v_exp_f32_e32 v59, v57
	v_max_f32_e32 v57, v43, v43
	v_max_f32_e32 v52, 0xc1a00000, v52
	v_max_f32_e32 v57, 0xc1a00000, v57
	v_mul_f32_e32 v52, 0xbfb8aa3b, v52
	v_mul_f32_e32 v57, 0xbfb8aa3b, v57
	v_exp_f32_e32 v52, v52
	v_exp_f32_e32 v58, v57
	v_pk_mul_f32 v[48:49], v[48:49], v[56:57] op_sel_hi:[1,0]
	v_pk_mul_f32 v[46:47], v[46:47], v[50:51]
	v_pk_mul_f32 v[44:45], v[44:45], v[48:49]
	v_pk_add_f32 v[48:49], v[52:53], 1.0 op_sel_hi:[1,0]
	v_pk_add_f32 v[52:53], v[58:59], 1.0 op_sel_hi:[1,0]
	v_mov_b32_e32 v56, v49
	v_mov_b32_e32 v57, v53
	v_mov_b32_e32 v58, v48
	v_mov_b32_e32 v59, v52
	v_pk_mul_f32 v[56:57], v[56:57], v[58:59]
	v_pk_mul_f32 v[38:39], v[46:47], v[38:39]
	v_mul_f32_e32 v58, v56, v57
	v_rcp_f32_e32 v58, v58
	v_pk_mul_f32 v[36:37], v[44:45], v[36:37]
	v_mul_f32_e32 v44, v57, v58
	v_mul_f32_e32 v46, v56, v58
	v_pk_mul_f32 v[46:47], v[52:53], v[46:47] op_sel_hi:[1,0]
	v_pk_mul_f32 v[44:45], v[48:49], v[44:45] op_sel_hi:[1,0]
	v_pk_mul_f32 v[42:43], v[42:43], v[46:47]
	v_pk_mul_f32 v[40:41], v[40:41], v[44:45]
	v_pk_mul_f32 v[42:43], v[42:43], v[34:35]
	v_pk_mul_f32 v[34:35], v[40:41], v[32:33]
	v_cvt_pk_bf16_f32 v32, v36, v37
	v_cvt_pk_bf16_f32 v33, v38, v39
	v_max_f32_e32 v36, v28, v28
	v_max_f32_e32 v38, v30, v30
	v_max_f32_e32 v36, 0xc1a00000, v36
	v_max_f32_e32 v38, 0xc1a00000, v38
	v_mul_f32_e32 v36, 0xbfb8aa3b, v36
	v_mul_f32_e32 v38, 0xbfb8aa3b, v38
	v_exp_f32_e32 v37, v36
	v_max_f32_e32 v36, v29, v29
	v_exp_f32_e32 v39, v38
	v_max_f32_e32 v38, v31, v31
	v_max_f32_e32 v36, 0xc1a00000, v36
	v_max_f32_e32 v38, 0xc1a00000, v38
	v_mul_f32_e32 v36, 0xbfb8aa3b, v36
	v_mul_f32_e32 v38, 0xbfb8aa3b, v38
	v_exp_f32_e32 v36, v36
	v_exp_f32_e32 v38, v38
	v_cvt_pk_bf16_f32 v34, v34, v35
	v_cvt_pk_bf16_f32 v35, v42, v43
	global_store_dwordx4 v[54:55], v[32:35], off
	v_add_u32_e32 v40, 0xa0, v155
	s_nop 0
	v_pk_add_f32 v[32:33], v[36:37], 1.0 op_sel_hi:[1,0]
	v_pk_add_f32 v[34:35], v[38:39], 1.0 op_sel_hi:[1,0]
	v_mov_b32_e32 v36, v33
	v_mov_b32_e32 v37, v35
	v_mov_b32_e32 v38, v32
	v_mov_b32_e32 v39, v34
	v_pk_mul_f32 v[36:37], v[36:37], v[38:39]
	s_nop 0
	v_mul_f32_e32 v38, v36, v37
	v_rcp_f32_e32 v41, v38
	v_mad_i64_i32 v[38:39], s[28:29], v40, s52, v[144:145]
	v_lshl_add_u64 v[38:39], v[38:39], 0, v[146:147]
	v_mul_f32_e32 v36, v36, v41
	v_mul_f32_e32 v40, v37, v41
	v_pk_mul_f32 v[34:35], v[34:35], v[36:37] op_sel_hi:[1,0]
	v_max_f32_e32 v36, v24, v24
	v_max_f32_e32 v41, v26, v26
	v_max_f32_e32 v36, 0xc1a00000, v36
	v_max_f32_e32 v41, 0xc1a00000, v41
	v_mul_f32_e32 v36, 0xbfb8aa3b, v36
	v_mul_f32_e32 v41, 0xbfb8aa3b, v41
	v_exp_f32_e32 v37, v36
	v_max_f32_e32 v36, v25, v25
	v_exp_f32_e32 v43, v41
	v_max_f32_e32 v41, v27, v27
	v_max_f32_e32 v36, 0xc1a00000, v36
	v_max_f32_e32 v41, 0xc1a00000, v41
	v_mul_f32_e32 v36, 0xbfb8aa3b, v36
; __device__ __forceinline__ unsigned cvt_pk_bf16(float lo, float hi) { unsigned r; asm volatile("v_cvt_pk_bf16_f32 %0, %1, %2" : "=v"(r) : "v"(lo), "v"(hi)); return r; }
; __device__ __forceinline__ f32x4 sigmoid4(f32x4 x) {
;     f32x4 d;
; #pragma unroll
;     for (int j = 0; j < 4; ++j) d[j] = 1.0f + __expf(-fmaxf(x[j], -20.0f));
;     const float p01 = d[0] * d[1], p23 = d[2] * d[3], r = __builtin_amdgcn_rcpf(p01 * p23), r01 = r * p23, r23 = r * p01;
;     return (f32x4){r01 * d[1], r01 * d[0], r23 * d[3], r23 * d[2]};
; }
;     __device__ __forceinline__ void operator()(const f32x4 (&acc)[2][2][4][2], const Unit& u, int wr, int wc, int fr, int fq) const {
;     ...
;         for (int ai = 0; ai < 2; ++ai)
; #pragma unroll
;             for (int m = 0; m < 4; ++m) { bf16_t* rowp = O + (size_t)(row0 + ai * HALF + m * 16) * ldc + col0;
;                 f32x4 v0, v1;
; #pragma unroll
;                 for (int j = 0; j < 1; ++j) { v0 = acc[ai][0][m][0] * sigmoid4(acc[ai][0][m][0]) * acc[ai][1][m][0]; v1 = acc[ai][0][m][1] * sigmoid4(acc[ai][0][m][1]) * acc[ai][1][m][1]; }
;                 u32x4 w; w.x = cvt_pk_bf16(v0[0], v0[1]); w.y = cvt_pk_bf16(v0[2], v0[3]); w.z = cvt_pk_bf16(v1[0], v1[1]); w.w = cvt_pk_bf16(v1[2], v1[3]);
;                 *(u32x4*)rowp = w; }
	v_mul_f32_e32 v41, 0xbfb8aa3b, v41
	v_exp_f32_e32 v36, v36
	v_exp_f32_e32 v42, v41
	v_pk_mul_f32 v[32:33], v[32:33], v[40:41] op_sel_hi:[1,0]
	v_pk_mul_f32 v[30:31], v[30:31], v[34:35]
	v_pk_mul_f32 v[28:29], v[28:29], v[32:33]
	v_pk_add_f32 v[32:33], v[36:37], 1.0 op_sel_hi:[1,0]
	v_pk_add_f32 v[36:37], v[42:43], 1.0 op_sel_hi:[1,0]
	v_mov_b32_e32 v40, v33
	v_mov_b32_e32 v41, v37
	v_mov_b32_e32 v42, v32
	v_mov_b32_e32 v43, v36
	v_pk_mul_f32 v[40:41], v[40:41], v[42:43]
	v_pk_mul_f32 v[22:23], v[30:31], v[22:23]
	v_mul_f32_e32 v42, v40, v41
	v_rcp_f32_e32 v42, v42
	v_pk_mul_f32 v[20:21], v[28:29], v[20:21]
	v_mul_f32_e32 v28, v41, v42
	v_mul_f32_e32 v30, v40, v42
	v_pk_mul_f32 v[30:31], v[36:37], v[30:31] op_sel_hi:[1,0]
	v_pk_mul_f32 v[28:29], v[32:33], v[28:29] op_sel_hi:[1,0]
	v_pk_mul_f32 v[26:27], v[26:27], v[30:31]
	v_pk_mul_f32 v[24:25], v[24:25], v[28:29]
	v_pk_mul_f32 v[26:27], v[26:27], v[18:19]
	v_pk_mul_f32 v[18:19], v[24:25], v[16:17]
	v_cvt_pk_bf16_f32 v16, v20, v21
	v_cvt_pk_bf16_f32 v17, v22, v23
	v_max_f32_e32 v20, v12, v12
	v_max_f32_e32 v22, v14, v14
	v_max_f32_e32 v20, 0xc1a00000, v20
	v_max_f32_e32 v22, 0xc1a00000, v22
	v_mul_f32_e32 v20, 0xbfb8aa3b, v20
	v_mul_f32_e32 v22, 0xbfb8aa3b, v22
	v_exp_f32_e32 v21, v20
	v_max_f32_e32 v20, v13, v13
	v_exp_f32_e32 v23, v22
	v_max_f32_e32 v22, v15, v15
	v_max_f32_e32 v20, 0xc1a00000, v20
	v_max_f32_e32 v22, 0xc1a00000, v22
	v_mul_f32_e32 v20, 0xbfb8aa3b, v20
	v_mul_f32_e32 v22, 0xbfb8aa3b, v22
	v_exp_f32_e32 v20, v20
	v_exp_f32_e32 v22, v22
	v_cvt_pk_bf16_f32 v18, v18, v19
	v_cvt_pk_bf16_f32 v19, v26, v27
	global_store_dwordx4 v[38:39], v[16:19], off
	v_add_u32_e32 v24, 0xb0, v155
	s_nop 0
	v_pk_add_f32 v[16:17], v[20:21], 1.0 op_sel_hi:[1,0]
	v_pk_add_f32 v[18:19], v[22:23], 1.0 op_sel_hi:[1,0]
	v_mov_b32_e32 v20, v17
	v_mov_b32_e32 v21, v19
	v_mov_b32_e32 v22, v16
	v_mov_b32_e32 v23, v18
	v_pk_mul_f32 v[20:21], v[20:21], v[22:23]
	s_nop 0
	v_mul_f32_e32 v22, v20, v21
	v_rcp_f32_e32 v25, v22
	v_mad_i64_i32 v[22:23], s[28:29], v24, s52, v[144:145]
	v_lshl_add_u64 v[22:23], v[22:23], 0, v[146:147]
	v_mul_f32_e32 v20, v20, v25
	v_mul_f32_e32 v24, v21, v25
	v_pk_mul_f32 v[18:19], v[18:19], v[20:21] op_sel_hi:[1,0]
	v_max_f32_e32 v20, v8, v8
	v_max_f32_e32 v25, v10, v10
	v_max_f32_e32 v20, 0xc1a00000, v20
	v_max_f32_e32 v25, 0xc1a00000, v25
	v_mul_f32_e32 v20, 0xbfb8aa3b, v20
	v_mul_f32_e32 v25, 0xbfb8aa3b, v25
	v_exp_f32_e32 v21, v20
	v_max_f32_e32 v20, v9, v9
	v_exp_f32_e32 v27, v25
	v_max_f32_e32 v25, v11, v11
	v_max_f32_e32 v20, 0xc1a00000, v20
	v_max_f32_e32 v25, 0xc1a00000, v25
	v_mul_f32_e32 v20, 0xbfb8aa3b, v20
	v_mul_f32_e32 v25, 0xbfb8aa3b, v25
	v_exp_f32_e32 v20, v20
	v_exp_f32_e32 v26, v25
	v_pk_mul_f32 v[16:17], v[16:17], v[24:25] op_sel_hi:[1,0]
	v_pk_mul_f32 v[14:15], v[14:15], v[18:19]
	v_pk_mul_f32 v[12:13], v[12:13], v[16:17]
	v_pk_add_f32 v[16:17], v[20:21], 1.0 op_sel_hi:[1,0]
	v_pk_add_f32 v[20:21], v[26:27], 1.0 op_sel_hi:[1,0]
	v_mov_b32_e32 v24, v17
	v_mov_b32_e32 v25, v21
	v_mov_b32_e32 v26, v16
	v_mov_b32_e32 v27, v20
	v_pk_mul_f32 v[24:25], v[24:25], v[26:27]
	v_pk_mul_f32 v[6:7], v[14:15], v[6:7]
	v_mul_f32_e32 v26, v24, v25
	v_rcp_f32_e32 v26, v26
	v_pk_mul_f32 v[4:5], v[12:13], v[4:5]
	s_mov_b64 s[28:29], s[18:19]
	v_mul_f32_e32 v12, v25, v26
	v_mul_f32_e32 v14, v24, v26
	v_pk_mul_f32 v[14:15], v[20:21], v[14:15] op_sel_hi:[1,0]
	v_pk_mul_f32 v[12:13], v[16:17], v[12:13] op_sel_hi:[1,0]
	v_pk_mul_f32 v[10:11], v[10:11], v[14:15]
	v_pk_mul_f32 v[8:9], v[8:9], v[12:13]
	v_pk_mul_f32 v[10:11], v[10:11], v[2:3]
	v_pk_mul_f32 v[2:3], v[8:9], v[0:1]
	v_cvt_pk_bf16_f32 v0, v4, v5
	v_cvt_pk_bf16_f32 v1, v6, v7
	s_nop 0
	v_cvt_pk_bf16_f32 v2, v2, v3
	v_cvt_pk_bf16_f32 v3, v10, v11
	global_store_dwordx4 v[22:23], v[0:3], off
	s_cbranch_vccz .LBB0_192
	s_waitcnt vmcnt(0)
	s_cmpk_gt_u32 s37, 0xff
	s_cbranch_scc1 .LBB0_199
	s_barrier

; #define PG8_STAGE(bufoff, gbase, voff) do { _Pragma("unroll") for (int _i = 0; _i < 2; ++_i) \
;         __builtin_amdgcn_global_load_lds((const unsigned*)((const char*)(gbase) + (voff)[_i]), (PG8_LAS unsigned*)(lds + (bufoff) + ldsw + _i * 8192), 16, 0, 0); } while (0)
; #define PG8_LDA(dst, b, h) do { _Pragma("unroll") for (int m = 0; m < 4; ++m) _Pragma("unroll") for (int k = 0; k < 2; ++k) dst[m][k] = *(const PG8_LAS bf16x8*)(lds + PG8_SA(b, h) + aoff + m * 2048 + k * 1024); } while (0)
; #define PG8_LDB(dst, b, h) do { _Pragma("unroll") for (int n = 0; n < 2; ++n) _Pragma("unroll") for (int k = 0; k < 2; ++k) dst[n][k] = *(const PG8_LAS bf16x8*)(lds + PG8_SB(b, h) + boff + n * 2048 + k * 1024); } while (0)
; #define PG8_MMA(ai, bj, At, Bt) do { __builtin_amdgcn_s_setprio(1); _Pragma("unroll") for (int m = 0; m < 4; ++m) _Pragma("unroll") for (int n = 0; n < 2; ++n) _Pragma("unroll") for (int k = 0; k < 2; ++k) \
;         acc[ai][bj][m][n] = __builtin_amdgcn_mfma_f32_16x16x32_bf16(Bt[n][k], At[m][k], acc[ai][bj][m][n], 0, 0, 0); __builtin_amdgcn_s_setprio(0); } while (0)
; #define PG8_WAIT_V(n) asm volatile("s_waitcnt vmcnt(" #n ")" ::: "memory")
; #define PG8_WAIT_L(n) asm volatile("s_waitcnt lgkmcnt(" #n ")" ::: "memory")
; #define PG8_BAR __builtin_amdgcn_s_barrier()
; #define PG8_SCHED __builtin_amdgcn_sched_barrier(0)
; template <class Epi, class Sched>
; __device__ __forceinline__ void gemm_phase(PG8_LAS unsigned char* lds, const Gemm g, const Sched& S, const Epi& E) {
;     ...
;             PG8_LDB(B0, 0, 0); PG8_SCHED; PG8_LDA(At, 0, 0); PG8_STAGE(PG8_SA(1, 1), a1 + hstep, voffA);
;             PG8_WAIT_L(8); PG8_BAR; PG8_WAIT_L(0); PG8_MMA(0, 0, At, B0); PG8_BAR; PG8_SCHED;
;             PG8_LDB(B1, 0, 1); PG8_STAGE(PG8_SB(0, 0), b2, voffB);
;             PG8_BAR; PG8_WAIT_L(0); PG8_MMA(0, 1, At, B1); PG8_BAR;
;             PG8_LDA(At, 0, 1); PG8_STAGE(PG8_SA(0, 0), a2, voffA);
;             PG8_BAR; PG8_WAIT_L(0); PG8_MMA(1, 0, At, B0); PG8_BAR; PG8_SCHED;
;             PG8_STAGE(PG8_SB(0, 1), b2 + hstep, voffB);
;             PG8_WAIT_V(6); PG8_BAR; PG8_MMA(1, 1, At, B1); PG8_BAR;
.LBB0_286:
	ds_read_b128 v[154:157], v149
	ds_read_b128 v[158:161], v149 offset:1024
	ds_read_b128 v[166:169], v149 offset:2048
	ds_read_b128 v[170:173], v149 offset:3072
	s_add_u32 s24, s22, 0x100
	s_addc_u32 s25, s23, 0
	s_cmp_eq_u32 s57, 40
	s_cselect_b32 s29, s1, s25
	s_cselect_b32 s28, s0, s24
	s_cselect_b32 s27, s5, s56
	s_cselect_b32 s26, s4, s55
	v_lshl_add_u64 v[144:145], s[22:23], 0, v[136:137]
	s_add_i32 m0, s38, 0xc000
	ds_read_b128 v[182:185], v150
	ds_read_b128 v[190:193], v150 offset:1024
	ds_read_b128 v[194:197], v150 offset:2048
	ds_read_b128 v[198:201], v150 offset:3072
	ds_read_b128 v[202:205], v150 offset:4096
	ds_read_b128 v[206:209], v150 offset:5120
	ds_read_b128 v[210:213], v150 offset:6144
	ds_read_b128 v[214:217], v150 offset:7168
	global_load_lds_dwordx4 v[144:145], off
	v_lshl_add_u64 v[144:145], s[22:23], 0, v[138:139]
	s_add_i32 m0, s38, 0xe000
	s_nop 0
	global_load_lds_dwordx4 v[144:145], off
	s_waitcnt lgkmcnt(0)
	s_barrier
	v_mfma_f32_16x16x32_bf16 v[124:127], v[154:157], v[182:185], v[124:127]
	v_mfma_f32_16x16x32_bf16 v[120:123], v[166:169], v[182:185], v[120:123]
	v_mfma_f32_16x16x32_bf16 v[108:111], v[154:157], v[194:197], v[108:111]
	v_mfma_f32_16x16x32_bf16 v[104:107], v[166:169], v[194:197], v[104:107]
	v_mfma_f32_16x16x32_bf16 v[92:95], v[154:157], v[202:205], v[92:95]
	v_mfma_f32_16x16x32_bf16 v[88:91], v[166:169], v[202:205], v[88:91]
	v_mfma_f32_16x16x32_bf16 v[76:79], v[154:157], v[210:213], v[76:79]
	v_mfma_f32_16x16x32_bf16 v[72:75], v[166:169], v[210:213], v[72:75]
	v_mfma_f32_16x16x32_bf16 v[124:127], v[158:161], v[190:193], v[124:127]
	v_mfma_f32_16x16x32_bf16 v[120:123], v[170:173], v[190:193], v[120:123]
	v_mfma_f32_16x16x32_bf16 v[108:111], v[158:161], v[198:201], v[108:111]
	v_mfma_f32_16x16x32_bf16 v[104:107], v[170:173], v[198:201], v[104:107]
	v_mfma_f32_16x16x32_bf16 v[92:95], v[158:161], v[206:209], v[92:95]
	v_mfma_f32_16x16x32_bf16 v[88:91], v[170:173], v[206:209], v[88:91]
	v_mfma_f32_16x16x32_bf16 v[76:79], v[158:161], v[214:217], v[76:79]
	v_mfma_f32_16x16x32_bf16 v[72:75], v[170:173], v[214:217], v[72:75]
	s_barrier
	s_add_i32 s22, s46, s37
	v_lshl_add_u64 v[144:145], s[26:27], 0, v[130:131]
	s_mov_b32 m0, s22
	ds_read_b128 v[218:221], v151
	ds_read_b128 v[222:225], v151 offset:1024
	ds_read_b128 v[226:229], v151 offset:2048
	ds_read_b128 v[230:233], v151 offset:3072
	global_load_lds_dwordx4 v[144:145], off
	v_lshl_add_u64 v[162:163], s[26:27], 0, v[134:135]
	s_add_i32 m0, s22, 0x2000
	s_nop 0
	global_load_lds_dwordx4 v[162:163], off
	s_waitcnt lgkmcnt(0)
	s_barrier
	v_mfma_f32_16x16x32_bf16 v[116:119], v[218:221], v[182:185], v[116:119]
	v_mfma_f32_16x16x32_bf16 v[112:115], v[226:229], v[182:185], v[112:115]
	v_mfma_f32_16x16x32_bf16 v[100:103], v[218:221], v[194:197], v[100:103]
	v_mfma_f32_16x16x32_bf16 v[96:99], v[226:229], v[194:197], v[96:99]
	v_mfma_f32_16x16x32_bf16 v[84:87], v[218:221], v[202:205], v[84:87]
	v_mfma_f32_16x16x32_bf16 v[80:83], v[226:229], v[202:205], v[80:83]
	v_mfma_f32_16x16x32_bf16 v[68:71], v[218:221], v[210:213], v[68:71]
	v_mfma_f32_16x16x32_bf16 v[64:67], v[226:229], v[210:213], v[64:67]
	v_mfma_f32_16x16x32_bf16 v[116:119], v[222:225], v[190:193], v[116:119]
	v_mfma_f32_16x16x32_bf16 v[112:115], v[230:233], v[190:193], v[112:115]
	v_mfma_f32_16x16x32_bf16 v[100:103], v[222:225], v[198:201], v[100:103]
	v_mfma_f32_16x16x32_bf16 v[96:99], v[230:233], v[198:201], v[96:99]
	v_mfma_f32_16x16x32_bf16 v[84:87], v[222:225], v[206:209], v[84:87]
	v_mfma_f32_16x16x32_bf16 v[80:83], v[230:233], v[206:209], v[80:83]
	v_mfma_f32_16x16x32_bf16 v[68:71], v[222:225], v[214:217], v[68:71]
	v_mfma_f32_16x16x32_bf16 v[64:67], v[230:233], v[214:217], v[64:67]
	s_mov_b32 m0, s38
	v_lshl_add_u64 v[174:175], s[28:29], 0, v[128:129]
	s_barrier
	ds_read_b128 v[182:185], v150 offset:16384
	ds_read_b128 v[190:193], v150 offset:17408
	ds_read_b128 v[194:197], v150 offset:18432
	ds_read_b128 v[198:201], v150 offset:19456
	ds_read_b128 v[202:205], v150 offset:20480
	ds_read_b128 v[206:209], v150 offset:21504
	ds_read_b128 v[210:213], v150 offset:22528
	ds_read_b128 v[214:217], v150 offset:23552
	global_load_lds_dwordx4 v[174:175], off
	v_lshl_add_u64 v[178:179], s[28:29], 0, v[132:133]
	s_mov_b32 m0, s39
	s_nop 0
	global_load_lds_dwordx4 v[178:179], off
	s_waitcnt lgkmcnt(0)
	s_barrier
	v_mfma_f32_16x16x32_bf16 v[60:63], v[154:157], v[182:185], v[60:63]
	v_mfma_f32_16x16x32_bf16 v[56:59], v[166:169], v[182:185], v[56:59]
	v_mfma_f32_16x16x32_bf16 v[48:51], v[154:157], v[194:197], v[48:51]
	v_mfma_f32_16x16x32_bf16 v[40:43], v[166:169], v[194:197], v[40:43]
	v_mfma_f32_16x16x32_bf16 v[32:35], v[154:157], v[202:205], v[32:35]
	v_mfma_f32_16x16x32_bf16 v[24:27], v[166:169], v[202:205], v[24:27]
	v_mfma_f32_16x16x32_bf16 v[16:19], v[154:157], v[210:213], v[16:19]
	v_mfma_f32_16x16x32_bf16 v[8:11], v[166:169], v[210:213], v[8:11]
	v_mfma_f32_16x16x32_bf16 v[60:63], v[158:161], v[190:193], v[60:63]
	v_mfma_f32_16x16x32_bf16 v[56:59], v[170:173], v[190:193], v[56:59]
	v_mfma_f32_16x16x32_bf16 v[48:51], v[158:161], v[198:201], v[48:51]
	v_mfma_f32_16x16x32_bf16 v[40:43], v[170:173], v[198:201], v[40:43]
	v_mfma_f32_16x16x32_bf16 v[32:35], v[158:161], v[206:209], v[32:35]
	v_mfma_f32_16x16x32_bf16 v[24:27], v[170:173], v[206:209], v[24:27]
	v_mfma_f32_16x16x32_bf16 v[16:19], v[158:161], v[214:217], v[16:19]
	v_mfma_f32_16x16x32_bf16 v[8:11], v[170:173], v[214:217], v[8:11]
	s_barrier
	s_add_u32 s22, s26, 0xb0000
	s_addc_u32 s23, s27, 0
	s_add_i32 s58, s47, s37
	v_lshl_add_u64 v[154:155], s[22:23], 0, v[130:131]
	s_mov_b32 m0, s58
	s_nop 0
	global_load_lds_dwordx4 v[154:155], off
	v_lshl_add_u64 v[154:155], s[22:23], 0, v[134:135]
	s_add_i32 m0, s58, 0x2000
	s_nop 0
	global_load_lds_dwordx4 v[154:155], off
	s_waitcnt vmcnt(6)
	s_barrier
; #define PG8_STAGE(bufoff, gbase, voff) do { _Pragma("unroll") for (int _i = 0; _i < 2; ++_i) \
;         __builtin_amdgcn_global_load_lds((const unsigned*)((const char*)(gbase) + (voff)[_i]), (PG8_LAS unsigned*)(lds + (bufoff) + ldsw + _i * 8192), 16, 0, 0); } while (0)
; #define PG8_LDA(dst, b, h) do { _Pragma("unroll") for (int m = 0; m < 4; ++m) _Pragma("unroll") for (int k = 0; k < 2; ++k) dst[m][k] = *(const PG8_LAS bf16x8*)(lds + PG8_SA(b, h) + aoff + m * 2048 + k * 1024); } while (0)
; #define PG8_LDB(dst, b, h) do { _Pragma("unroll") for (int n = 0; n < 2; ++n) _Pragma("unroll") for (int k = 0; k < 2; ++k) dst[n][k] = *(const PG8_LAS bf16x8*)(lds + PG8_SB(b, h) + boff + n * 2048 + k * 1024); } while (0)
; #define PG8_MMA(ai, bj, At, Bt) do { __builtin_amdgcn_s_setprio(1); _Pragma("unroll") for (int m = 0; m < 4; ++m) _Pragma("unroll") for (int n = 0; n < 2; ++n) _Pragma("unroll") for (int k = 0; k < 2; ++k) \
;         acc[ai][bj][m][n] = __builtin_amdgcn_mfma_f32_16x16x32_bf16(Bt[n][k], At[m][k], acc[ai][bj][m][n], 0, 0, 0); __builtin_amdgcn_s_setprio(0); } while (0)
; #define PG8_WAIT_V(n) asm volatile("s_waitcnt vmcnt(" #n ")" ::: "memory")
; #define PG8_WAIT_L(n) asm volatile("s_waitcnt lgkmcnt(" #n ")" ::: "memory")
; #define PG8_BAR __builtin_amdgcn_s_barrier()
; #define PG8_SCHED __builtin_amdgcn_sched_barrier(0)
; template <class Epi, class Sched>
; __device__ __forceinline__ void gemm_phase(PG8_LAS unsigned char* lds, const Gemm g, const Sched& S, const Epi& E) {
;     ...
;             PG8_WAIT_V(6); PG8_BAR; PG8_MMA(1, 1, At, B1); PG8_BAR;
;             PG8_LDB(B0, 1, 0); PG8_SCHED; PG8_LDA(At, 1, 0); PG8_STAGE(PG8_SA(0, 1), a2 + hstep, voffA);
;             PG8_WAIT_L(8); PG8_BAR; PG8_WAIT_L(0); PG8_MMA(0, 0, At, B0); PG8_BAR; PG8_SCHED;
;             PG8_LDB(B1, 1, 1); PG8_STAGE(PG8_SB(1, 0), b3, voffB);
;             PG8_BAR; PG8_WAIT_L(0); PG8_MMA(0, 1, At, B1); PG8_BAR;
;             PG8_LDA(At, 1, 1); PG8_STAGE(PG8_SA(1, 0), a3, voffA);
;             PG8_BAR; PG8_WAIT_L(0); PG8_MMA(1, 0, At, B0); PG8_BAR; PG8_SCHED;
;             PG8_STAGE(PG8_SB(1, 1), b3 + hstep, voffB);
	v_mfma_f32_16x16x32_bf16 v[52:55], v[218:221], v[182:185], v[52:55]
	v_mfma_f32_16x16x32_bf16 v[44:47], v[226:229], v[182:185], v[44:47]
	v_mfma_f32_16x16x32_bf16 v[36:39], v[218:221], v[194:197], v[36:39]
	v_mfma_f32_16x16x32_bf16 v[28:31], v[226:229], v[194:197], v[28:31]
	v_mfma_f32_16x16x32_bf16 v[20:23], v[218:221], v[202:205], v[20:23]
	v_mfma_f32_16x16x32_bf16 v[12:15], v[226:229], v[202:205], v[12:15]
	v_mfma_f32_16x16x32_bf16 v[4:7], v[218:221], v[210:213], v[4:7]
	v_mfma_f32_16x16x32_bf16 v[0:3], v[226:229], v[210:213], v[0:3]
	v_mfma_f32_16x16x32_bf16 v[52:55], v[222:225], v[190:193], v[52:55]
	v_mfma_f32_16x16x32_bf16 v[44:47], v[230:233], v[190:193], v[44:47]
	v_mfma_f32_16x16x32_bf16 v[36:39], v[222:225], v[198:201], v[36:39]
	v_mfma_f32_16x16x32_bf16 v[28:31], v[230:233], v[198:201], v[28:31]
	v_mfma_f32_16x16x32_bf16 v[20:23], v[222:225], v[206:209], v[20:23]
	v_mfma_f32_16x16x32_bf16 v[12:15], v[230:233], v[206:209], v[12:15]
	v_mfma_f32_16x16x32_bf16 v[4:7], v[222:225], v[214:217], v[4:7]
	v_mfma_f32_16x16x32_bf16 v[0:3], v[230:233], v[214:217], v[0:3]
	s_add_i32 s58, 0, 0x18000
	v_add_u32_e32 v153, s58, v147
	s_barrier
	ds_read_b128 v[154:157], v153
	ds_read_b128 v[158:161], v153 offset:1024
	ds_read_b128 v[166:169], v153 offset:2048
	ds_read_b128 v[170:173], v153 offset:3072
	s_add_u32 s22, s28, 0xb0000
	s_addc_u32 s23, s29, 0
	s_mov_b32 m0, s40
	v_lshl_add_u64 v[186:187], s[22:23], 0, v[128:129]
	ds_read_b128 v[182:185], v150 offset:32768
	ds_read_b128 v[190:193], v150 offset:33792
	ds_read_b128 v[194:197], v150 offset:34816
	ds_read_b128 v[198:201], v150 offset:35840
	ds_read_b128 v[202:205], v150 offset:36864
	ds_read_b128 v[206:209], v150 offset:37888
	ds_read_b128 v[210:213], v150 offset:38912
	ds_read_b128 v[214:217], v150 offset:39936
	global_load_lds_dwordx4 v[186:187], off
	v_lshl_add_u64 v[186:187], s[22:23], 0, v[132:133]
	s_mov_b32 m0, s41
	s_nop 0
	global_load_lds_dwordx4 v[186:187], off
	s_waitcnt lgkmcnt(0)
	s_barrier
	v_mfma_f32_16x16x32_bf16 v[124:127], v[154:157], v[182:185], v[124:127]
	v_mfma_f32_16x16x32_bf16 v[120:123], v[166:169], v[182:185], v[120:123]
	v_mfma_f32_16x16x32_bf16 v[108:111], v[154:157], v[194:197], v[108:111]
	v_mfma_f32_16x16x32_bf16 v[104:107], v[166:169], v[194:197], v[104:107]
	v_mfma_f32_16x16x32_bf16 v[92:95], v[154:157], v[202:205], v[92:95]
	v_mfma_f32_16x16x32_bf16 v[88:91], v[166:169], v[202:205], v[88:91]
	v_mfma_f32_16x16x32_bf16 v[76:79], v[154:157], v[210:213], v[76:79]
	v_mfma_f32_16x16x32_bf16 v[72:75], v[166:169], v[210:213], v[72:75]
	v_mfma_f32_16x16x32_bf16 v[124:127], v[158:161], v[190:193], v[124:127]
	v_mfma_f32_16x16x32_bf16 v[120:123], v[170:173], v[190:193], v[120:123]
	v_mfma_f32_16x16x32_bf16 v[108:111], v[158:161], v[198:201], v[108:111]
	v_mfma_f32_16x16x32_bf16 v[104:107], v[170:173], v[198:201], v[104:107]
	v_mfma_f32_16x16x32_bf16 v[92:95], v[158:161], v[206:209], v[92:95]
	v_mfma_f32_16x16x32_bf16 v[88:91], v[170:173], v[206:209], v[88:91]
	v_mfma_f32_16x16x32_bf16 v[76:79], v[158:161], v[214:217], v[76:79]
	v_mfma_f32_16x16x32_bf16 v[72:75], v[170:173], v[214:217], v[72:75]
	s_barrier
	s_add_i32 s28, 0, 0x1c000
	s_add_i32 s22, s58, s37
	v_add_u32_e32 v153, s28, v147
	v_lshl_add_u64 v[144:145], v[144:145], 0, s[14:15]
	s_mov_b32 m0, s22
	ds_read_b128 v[218:221], v153
	ds_read_b128 v[222:225], v153 offset:1024
	ds_read_b128 v[226:229], v153 offset:2048
	ds_read_b128 v[230:233], v153 offset:3072
	global_load_lds_dwordx4 v[144:145], off
	v_lshl_add_u64 v[144:145], v[162:163], 0, s[14:15]
	s_add_i32 m0, s22, 0x2000
	s_nop 0
	global_load_lds_dwordx4 v[144:145], off
	s_waitcnt lgkmcnt(0)
	s_barrier
	v_mfma_f32_16x16x32_bf16 v[116:119], v[218:221], v[182:185], v[116:119]
	v_mfma_f32_16x16x32_bf16 v[112:115], v[226:229], v[182:185], v[112:115]
	v_mfma_f32_16x16x32_bf16 v[100:103], v[218:221], v[194:197], v[100:103]
	v_mfma_f32_16x16x32_bf16 v[96:99], v[226:229], v[194:197], v[96:99]
	v_mfma_f32_16x16x32_bf16 v[84:87], v[218:221], v[202:205], v[84:87]
	v_mfma_f32_16x16x32_bf16 v[80:83], v[226:229], v[202:205], v[80:83]
	v_mfma_f32_16x16x32_bf16 v[68:71], v[218:221], v[210:213], v[68:71]
	v_mfma_f32_16x16x32_bf16 v[64:67], v[226:229], v[210:213], v[64:67]
	v_mfma_f32_16x16x32_bf16 v[116:119], v[222:225], v[190:193], v[116:119]
	v_mfma_f32_16x16x32_bf16 v[112:115], v[230:233], v[190:193], v[112:115]
	v_mfma_f32_16x16x32_bf16 v[100:103], v[222:225], v[198:201], v[100:103]
	v_mfma_f32_16x16x32_bf16 v[96:99], v[230:233], v[198:201], v[96:99]
	v_mfma_f32_16x16x32_bf16 v[84:87], v[222:225], v[206:209], v[84:87]
	v_mfma_f32_16x16x32_bf16 v[80:83], v[230:233], v[206:209], v[80:83]
	v_mfma_f32_16x16x32_bf16 v[68:71], v[222:225], v[214:217], v[68:71]
	v_mfma_f32_16x16x32_bf16 v[64:67], v[230:233], v[214:217], v[64:67]
	s_mov_b32 m0, s43
	v_lshl_add_u64 v[144:145], v[174:175], 0, s[14:15]
	s_barrier
	ds_read_b128 v[182:185], v150 offset:49152
	ds_read_b128 v[190:193], v150 offset:50176
	ds_read_b128 v[194:197], v150 offset:51200
	ds_read_b128 v[198:201], v150 offset:52224
	ds_read_b128 v[202:205], v150 offset:53248
	ds_read_b128 v[206:209], v150 offset:54272
	ds_read_b128 v[210:213], v150 offset:55296
	ds_read_b128 v[214:217], v150 offset:56320
	global_load_lds_dwordx4 v[144:145], off
	v_lshl_add_u64 v[144:145], v[178:179], 0, s[14:15]
	s_mov_b32 m0, s44
	s_nop 0
	global_load_lds_dwordx4 v[144:145], off
	s_waitcnt lgkmcnt(0)
	s_barrier
; __device__ __forceinline__ unsigned cvt_pk_bf16(float lo, float hi) { unsigned r; asm volatile("v_cvt_pk_bf16_f32 %0, %1, %2" : "=v"(r) : "v"(lo), "v"(hi)); return r; }
; __device__ __forceinline__ float flogsig16(float x) { return (fminf(x, 0.f) - __logf(1.0f + __expf(-fabsf(x)))) * 0.0625f; }
; #define PG8_WAIT_V(n) asm volatile("s_waitcnt vmcnt(" #n ")" ::: "memory")
; #define PG8_WAIT_L(n) asm volatile("s_waitcnt lgkmcnt(" #n ")" ::: "memory")
;     __device__ __forceinline__ void operator()(const f32x4 (&acc)[2][2][4][2], const Unit& u, int wr, int wc, int fr, int fq) const {
;     ...
;         const int row0 = u.pm * BM + wr * 64 + fr, col0 = u.pn * BM + wc * 32 + 8 * fq, bcol0 = wc * 32 + 8 * fq;
;         f32x4 bv[2][2];
; #pragma unroll
;         for (int bj = 0; bj < 2; ++bj)
; #pragma unroll
;             for (int n = 0; n < 2; ++n) bv[bj][n] = bias ? *(const f32x4*)(bias + bcol0 + bj * HALF + 4 * n) : (f32x4){0.f, 0.f, 0.f, 0.f};
; #pragma unroll
;         for (int ai = 0; ai < 2; ++ai)
; #pragma unroll
;             for (int m = 0; m < 4; ++m) { bf16_t* rowp = O + (size_t)(row0 + ai * HALF + m * 16) * ldc + col0;
; #pragma unroll
;                 for (int bj = 0; bj < 2; ++bj) { f32x4 v0 = acc[ai][bj][m][0] + bv[bj][0], v1 = acc[ai][bj][m][1] + bv[bj][1];
;                     if (act == 1) {
; #pragma unroll
;                         for (int j = 0; j < 1; ++j) { v0 = v0 * sigmoid4(v0); v1 = v1 * sigmoid4(v1); } }
;                     else if (act == 2) {
; #pragma unroll
;                         for (int j = 0; j < 1; ++j) { v0 = sigmoid4(v0); v1 = sigmoid4(v1); } }
;                     else if (act == 3) {
; #pragma unroll
;                         for (int j = 0; j < 4; ++j) { v0[j] = flogsig16(v0[j]); v1[j] = flogsig16(v1[j]); } }
;                     u32x4 w; w.x = cvt_pk_bf16(v0[0], v0[1]); w.y = cvt_pk_bf16(v0[2], v0[3]); w.z = cvt_pk_bf16(v1[0], v1[1]); w.w = cvt_pk_bf16(v1[2], v1[3]);
;                     *(u32x4*)(rowp + bj * HALF) = w; } }
; template <class Epi, class Sched>
; __device__ __forceinline__ void gemm_phase(PG8_LAS unsigned char* lds, const Gemm g, const Sched& S, const Epi& E) {
;     ...
;             PG8_BAR; PG8_WAIT_L(0); PG8_MMA(1, 0, At, B0); PG8_BAR; PG8_SCHED;
;             PG8_STAGE(PG8_SB(1, 1), b3 + hstep, voffB);
;             PG8_WAIT_V(6); PG8_BAR; PG8_MMA(1, 1, At, B1); PG8_BAR;
	v_mfma_f32_16x16x32_bf16 v[60:63], v[154:157], v[182:185], v[60:63]
	v_mfma_f32_16x16x32_bf16 v[56:59], v[166:169], v[182:185], v[56:59]
	v_mfma_f32_16x16x32_bf16 v[48:51], v[154:157], v[194:197], v[48:51]
	v_mfma_f32_16x16x32_bf16 v[40:43], v[166:169], v[194:197], v[40:43]
	v_mfma_f32_16x16x32_bf16 v[32:35], v[154:157], v[202:205], v[32:35]
	v_mfma_f32_16x16x32_bf16 v[24:27], v[166:169], v[202:205], v[24:27]
	v_mfma_f32_16x16x32_bf16 v[16:19], v[154:157], v[210:213], v[16:19]
	v_mfma_f32_16x16x32_bf16 v[8:11], v[166:169], v[210:213], v[8:11]
	v_mfma_f32_16x16x32_bf16 v[60:63], v[158:161], v[190:193], v[60:63]
	v_mfma_f32_16x16x32_bf16 v[56:59], v[170:173], v[190:193], v[56:59]
	v_mfma_f32_16x16x32_bf16 v[48:51], v[158:161], v[198:201], v[48:51]
	v_mfma_f32_16x16x32_bf16 v[40:43], v[170:173], v[198:201], v[40:43]
	v_mfma_f32_16x16x32_bf16 v[32:35], v[158:161], v[206:209], v[32:35]
	v_mfma_f32_16x16x32_bf16 v[24:27], v[170:173], v[206:209], v[24:27]
	v_mfma_f32_16x16x32_bf16 v[16:19], v[158:161], v[214:217], v[16:19]
	v_mfma_f32_16x16x32_bf16 v[8:11], v[170:173], v[214:217], v[8:11]
	s_barrier
	s_add_u32 s22, s26, 0xb0080
	s_addc_u32 s23, s27, 0
	s_add_i32 s26, s28, s37
	v_lshl_add_u64 v[144:145], s[22:23], 0, v[130:131]
	s_mov_b32 m0, s26
	s_nop 0
	global_load_lds_dwordx4 v[144:145], off
	v_lshl_add_u64 v[144:145], s[22:23], 0, v[134:135]
	s_add_i32 m0, s26, 0x2000
	s_nop 0
	global_load_lds_dwordx4 v[144:145], off
	s_waitcnt vmcnt(6)
	s_barrier
	v_mfma_f32_16x16x32_bf16 v[52:55], v[218:221], v[182:185], v[52:55]
	v_mfma_f32_16x16x32_bf16 v[44:47], v[226:229], v[182:185], v[44:47]
	v_mfma_f32_16x16x32_bf16 v[36:39], v[218:221], v[194:197], v[36:39]
	v_mfma_f32_16x16x32_bf16 v[28:31], v[226:229], v[194:197], v[28:31]
	v_mfma_f32_16x16x32_bf16 v[20:23], v[218:221], v[202:205], v[20:23]
	v_mfma_f32_16x16x32_bf16 v[12:15], v[226:229], v[202:205], v[12:15]
	v_mfma_f32_16x16x32_bf16 v[4:7], v[218:221], v[210:213], v[4:7]
	v_mfma_f32_16x16x32_bf16 v[0:3], v[226:229], v[210:213], v[0:3]
	v_mfma_f32_16x16x32_bf16 v[52:55], v[222:225], v[190:193], v[52:55]
	v_mfma_f32_16x16x32_bf16 v[44:47], v[230:233], v[190:193], v[44:47]
	v_mfma_f32_16x16x32_bf16 v[36:39], v[222:225], v[198:201], v[36:39]
	v_mfma_f32_16x16x32_bf16 v[28:31], v[230:233], v[198:201], v[28:31]
	v_mfma_f32_16x16x32_bf16 v[20:23], v[222:225], v[206:209], v[20:23]
	v_mfma_f32_16x16x32_bf16 v[12:15], v[230:233], v[206:209], v[12:15]
	v_mfma_f32_16x16x32_bf16 v[4:7], v[222:225], v[214:217], v[4:7]
	v_mfma_f32_16x16x32_bf16 v[0:3], v[230:233], v[214:217], v[0:3]
	s_add_i32 s57, s57, 2
	s_add_u32 s55, s55, 0x100
	s_addc_u32 s56, s56, 0
	s_cmp_gt_u32 s57, 41
	s_mov_b64 s[22:23], s[24:25]
	s_barrier
	s_cbranch_scc0 .LBB0_286
	v_lshl_add_u32 v154, s53, 8, v146
	v_lshl_or_b32 v144, s54, 8, v148
	v_ashrrev_i32_e32 v155, 31, v154
	v_ashrrev_i32_e32 v145, 31, v144
	v_lshlrev_b64 v[156:157], 11, v[154:155]
	v_lshl_add_u64 v[156:157], s[10:11], 0, v[156:157]
	v_lshlrev_b64 v[158:159], 1, v[144:145]
	v_lshl_add_u64 v[144:145], v[156:157], 0, v[158:159]
	v_pk_add_f32 v[126:127], v[126:127], 0 op_sel_hi:[1,0]
	v_pk_add_f32 v[124:125], v[124:125], 0 op_sel_hi:[1,0]
	v_pk_add_f32 v[156:157], v[122:123], 0 op_sel_hi:[1,0]
	v_pk_add_f32 v[122:123], v[120:121], 0 op_sel_hi:[1,0]
	v_cvt_pk_bf16_f32 v120, v124, v125
	v_cvt_pk_bf16_f32 v121, v126, v127
	v_pk_add_f32 v[116:117], v[116:117], 0 op_sel_hi:[1,0]
	v_cvt_pk_bf16_f32 v122, v122, v123
	v_cvt_pk_bf16_f32 v123, v156, v157
	global_store_dwordx4 v[144:145], v[120:123], off
	v_pk_add_f32 v[118:119], v[118:119], 0 op_sel_hi:[1,0]
	v_pk_add_f32 v[110:111], v[110:111], 0 op_sel_hi:[1,0]
	v_pk_add_f32 v[120:121], v[114:115], 0 op_sel_hi:[1,0]
	v_pk_add_f32 v[114:115], v[112:113], 0 op_sel_hi:[1,0]
	v_cvt_pk_bf16_f32 v112, v116, v117
	v_cvt_pk_bf16_f32 v113, v118, v119
	v_pk_add_f32 v[108:109], v[108:109], 0 op_sel_hi:[1,0]
	v_cvt_pk_bf16_f32 v114, v114, v115
	v_cvt_pk_bf16_f32 v115, v120, v121
	global_store_dwordx4 v[144:145], v[112:115], off offset:256
	v_pk_add_f32 v[100:101], v[100:101], 0 op_sel_hi:[1,0]
	v_pk_add_f32 v[102:103], v[102:103], 0 op_sel_hi:[1,0]
	v_or_b32_e32 v112, 16, v154
	v_ashrrev_i32_e32 v113, 31, v112
	v_lshlrev_b64 v[112:113], 11, v[112:113]
	v_lshl_add_u64 v[112:113], s[10:11], 0, v[112:113]
	v_lshl_add_u64 v[112:113], v[112:113], 0, v[158:159]
	v_pk_add_f32 v[114:115], v[106:107], 0 op_sel_hi:[1,0]
	v_pk_add_f32 v[106:107], v[104:105], 0 op_sel_hi:[1,0]
	v_cvt_pk_bf16_f32 v104, v108, v109
	v_cvt_pk_bf16_f32 v105, v110, v111
	v_pk_add_f32 v[94:95], v[94:95], 0 op_sel_hi:[1,0]
	v_cvt_pk_bf16_f32 v106, v106, v107
	v_cvt_pk_bf16_f32 v107, v114, v115
	global_store_dwordx4 v[112:113], v[104:107], off
	v_pk_add_f32 v[92:93], v[92:93], 0 op_sel_hi:[1,0]
	v_pk_add_f32 v[84:85], v[84:85], 0 op_sel_hi:[1,0]
	v_pk_add_f32 v[104:105], v[98:99], 0 op_sel_hi:[1,0]
	v_pk_add_f32 v[98:99], v[96:97], 0 op_sel_hi:[1,0]
	v_cvt_pk_bf16_f32 v96, v100, v101
	v_cvt_pk_bf16_f32 v97, v102, v103
	v_pk_add_f32 v[86:87], v[86:87], 0 op_sel_hi:[1,0]
	v_cvt_pk_bf16_f32 v98, v98, v99
	v_cvt_pk_bf16_f32 v99, v104, v105
	global_store_dwordx4 v[112:113], v[96:99], off offset:256
	v_pk_add_f32 v[78:79], v[78:79], 0 op_sel_hi:[1,0]
	v_pk_add_f32 v[76:77], v[76:77], 0 op_sel_hi:[1,0]
	v_or_b32_e32 v96, 32, v154
	v_ashrrev_i32_e32 v97, 31, v96
	v_lshlrev_b64 v[96:97], 11, v[96:97]
	v_lshl_add_u64 v[96:97], s[10:11], 0, v[96:97]
	v_lshl_add_u64 v[96:97], v[96:97], 0, v[158:159]
; __device__ __forceinline__ unsigned cvt_pk_bf16(float lo, float hi) { unsigned r; asm volatile("v_cvt_pk_bf16_f32 %0, %1, %2" : "=v"(r) : "v"(lo), "v"(hi)); return r; }
; __device__ __forceinline__ float flogsig16(float x) { return (fminf(x, 0.f) - __logf(1.0f + __expf(-fabsf(x)))) * 0.0625f; }
; #define PG8_WAIT_V(n) asm volatile("s_waitcnt vmcnt(" #n ")" ::: "memory")
; #define PG8_BAR __builtin_amdgcn_s_barrier()
;     __device__ __forceinline__ void operator()(const f32x4 (&acc)[2][2][4][2], const Unit& u, int wr, int wc, int fr, int fq) const {
;     ...
;             for (int m = 0; m < 4; ++m) { bf16_t* rowp = O + (size_t)(row0 + ai * HALF + m * 16) * ldc + col0;
; #pragma unroll
;                 for (int bj = 0; bj < 2; ++bj) { f32x4 v0 = acc[ai][bj][m][0] + bv[bj][0], v1 = acc[ai][bj][m][1] + bv[bj][1];
;                     if (act == 1) {
; #pragma unroll
;                         for (int j = 0; j < 1; ++j) { v0 = v0 * sigmoid4(v0); v1 = v1 * sigmoid4(v1); } }
;                     else if (act == 2) {
; #pragma unroll
;                         for (int j = 0; j < 1; ++j) { v0 = sigmoid4(v0); v1 = sigmoid4(v1); } }
;                     else if (act == 3) {
; #pragma unroll
;                         for (int j = 0; j < 4; ++j) { v0[j] = flogsig16(v0[j]); v1[j] = flogsig16(v1[j]); } }
;                     u32x4 w; w.x = cvt_pk_bf16(v0[0], v0[1]); w.y = cvt_pk_bf16(v0[2], v0[3]); w.z = cvt_pk_bf16(v1[0], v1[1]); w.w = cvt_pk_bf16(v1[2], v1[3]);
;                     *(u32x4*)(rowp + bj * HALF) = w; } }
; template <class Epi, class Sched>
; __device__ __forceinline__ void gemm_phase(PG8_LAS unsigned char* lds, const Gemm g, const Sched& S, const Epi& E) {
;     ...
;         if constexpr (!Epi::AFTER_DRAIN) { E(acc, cur, wr, wc, fr, fq); S.done(cur); }
;         if (!has_next) break;
; #pragma unroll
;         for (int a = 0; a < 2; ++a)
; #pragma unroll
;             for (int b = 0; b < 2; ++b)
; #pragma unroll
;                 for (int m = 0; m < 4; ++m)
; #pragma unroll
;                     for (int n = 0; n < 2; ++n) acc[a][b][m][n] = (f32x4){0.f, 0.f, 0.f, 0.f};
;         cur = nxt; cA = nA; cB = nB; ++ui;
;     }
;     PG8_WAIT_V(0);
;     if (wr == 0) PG8_BAR;
	v_pk_add_f32 v[98:99], v[90:91], 0 op_sel_hi:[1,0]
	v_pk_add_f32 v[90:91], v[88:89], 0 op_sel_hi:[1,0]
	v_cvt_pk_bf16_f32 v88, v92, v93
	v_cvt_pk_bf16_f32 v89, v94, v95
	v_pk_add_f32 v[70:71], v[70:71], 0 op_sel_hi:[1,0]
	v_cvt_pk_bf16_f32 v90, v90, v91
	v_cvt_pk_bf16_f32 v91, v98, v99
	global_store_dwordx4 v[96:97], v[88:91], off
	v_pk_add_f32 v[68:69], v[68:69], 0 op_sel_hi:[1,0]
	s_mov_b64 s[22:23], 0x40000
	v_pk_add_f32 v[88:89], v[82:83], 0 op_sel_hi:[1,0]
	v_pk_add_f32 v[82:83], v[80:81], 0 op_sel_hi:[1,0]
	v_cvt_pk_bf16_f32 v80, v84, v85
	v_cvt_pk_bf16_f32 v81, v86, v87
	v_pk_add_f32 v[60:61], v[60:61], 0 op_sel_hi:[1,0]
	v_cvt_pk_bf16_f32 v82, v82, v83
	v_cvt_pk_bf16_f32 v83, v88, v89
	global_store_dwordx4 v[96:97], v[80:83], off offset:256
	v_pk_add_f32 v[62:63], v[62:63], 0 op_sel_hi:[1,0]
	v_pk_add_f32 v[54:55], v[54:55], 0 op_sel_hi:[1,0]
	v_or_b32_e32 v80, 48, v154
	v_ashrrev_i32_e32 v81, 31, v80
	v_lshlrev_b64 v[80:81], 11, v[80:81]
	v_lshl_add_u64 v[80:81], s[10:11], 0, v[80:81]
	v_lshl_add_u64 v[80:81], v[80:81], 0, v[158:159]
	v_pk_add_f32 v[82:83], v[74:75], 0 op_sel_hi:[1,0]
	v_pk_add_f32 v[74:75], v[72:73], 0 op_sel_hi:[1,0]
	v_cvt_pk_bf16_f32 v72, v76, v77
	v_cvt_pk_bf16_f32 v73, v78, v79
	v_pk_add_f32 v[52:53], v[52:53], 0 op_sel_hi:[1,0]
	v_cvt_pk_bf16_f32 v74, v74, v75
	v_cvt_pk_bf16_f32 v75, v82, v83
	global_store_dwordx4 v[80:81], v[72:75], off
	v_pk_add_f32 v[48:49], v[48:49], 0 op_sel_hi:[1,0]
	v_pk_add_f32 v[38:39], v[38:39], 0 op_sel_hi:[1,0]
	v_pk_add_f32 v[72:73], v[66:67], 0 op_sel_hi:[1,0]
	v_pk_add_f32 v[66:67], v[64:65], 0 op_sel_hi:[1,0]
	v_cvt_pk_bf16_f32 v64, v68, v69
	v_cvt_pk_bf16_f32 v65, v70, v71
	v_pk_add_f32 v[36:37], v[36:37], 0 op_sel_hi:[1,0]
	v_cvt_pk_bf16_f32 v66, v66, v67
	v_cvt_pk_bf16_f32 v67, v72, v73
	global_store_dwordx4 v[80:81], v[64:67], off offset:256
	v_pk_add_f32 v[32:33], v[32:33], 0 op_sel_hi:[1,0]
	v_pk_add_f32 v[22:23], v[22:23], 0 op_sel_hi:[1,0]
	v_lshl_add_u64 v[64:65], v[144:145], 0, s[22:23]
	s_mov_b32 s22, 0x40000
	v_pk_add_f32 v[66:67], v[58:59], 0 op_sel_hi:[1,0]
	v_pk_add_f32 v[58:59], v[56:57], 0 op_sel_hi:[1,0]
	v_cvt_pk_bf16_f32 v56, v60, v61
	v_add_co_u32_e32 v60, vcc, s22, v144
	v_cvt_pk_bf16_f32 v57, v62, v63
	v_cvt_pk_bf16_f32 v58, v58, v59
	v_cvt_pk_bf16_f32 v59, v66, v67
	s_mov_b64 s[22:23], 0x48000
	s_nop 0
	v_addc_co_u32_e32 v61, vcc, 0, v145, vcc
	global_store_dwordx4 v[60:61], v[56:59], off
	v_pk_add_f32 v[20:21], v[20:21], 0 op_sel_hi:[1,0]
	v_pk_add_f32 v[16:17], v[16:17], 0 op_sel_hi:[1,0]
	v_pk_add_f32 v[56:57], v[46:47], 0 op_sel_hi:[1,0]
	v_pk_add_f32 v[46:47], v[44:45], 0 op_sel_hi:[1,0]
	v_cvt_pk_bf16_f32 v44, v52, v53
	v_cvt_pk_bf16_f32 v45, v54, v55
	s_mov_b32 s54, s51
	v_cvt_pk_bf16_f32 v46, v46, v47
	v_cvt_pk_bf16_f32 v47, v56, v57
	global_store_dwordx4 v[64:65], v[44:47], off offset:256
	s_mov_b32 s53, s52
	s_mov_b64 s[24:25], s[4:5]
	v_pk_add_f32 v[46:47], v[50:51], 0 op_sel_hi:[1,0]
	v_pk_add_f32 v[50:51], v[42:43], 0 op_sel_hi:[1,0]
	v_pk_add_f32 v[42:43], v[40:41], 0 op_sel_hi:[1,0]
	v_cvt_pk_bf16_f32 v40, v48, v49
	v_cvt_pk_bf16_f32 v41, v46, v47
	v_add_co_u32_e32 v46, vcc, s48, v144
	v_cvt_pk_bf16_f32 v42, v42, v43
	v_cvt_pk_bf16_f32 v43, v50, v51
	v_lshl_add_u64 v[44:45], v[144:145], 0, s[22:23]
	s_nop 0
	v_addc_co_u32_e32 v47, vcc, 0, v145, vcc
	global_store_dwordx4 v[46:47], v[40:43], off
	s_mov_b64 s[22:23], s[0:1]
	v_pk_add_f32 v[6:7], v[6:7], 0 op_sel_hi:[1,0]
	v_pk_add_f32 v[40:41], v[30:31], 0 op_sel_hi:[1,0]
	v_pk_add_f32 v[30:31], v[28:29], 0 op_sel_hi:[1,0]
	v_cvt_pk_bf16_f32 v28, v36, v37
	v_cvt_pk_bf16_f32 v29, v38, v39
	v_pk_add_f32 v[4:5], v[4:5], 0 op_sel_hi:[1,0]
	v_cvt_pk_bf16_f32 v30, v30, v31
	v_cvt_pk_bf16_f32 v31, v40, v41
	global_store_dwordx4 v[44:45], v[28:31], off offset:256
	s_nop 1
	v_pk_add_f32 v[30:31], v[34:35], 0 op_sel_hi:[1,0]
	v_pk_add_f32 v[34:35], v[26:27], 0 op_sel_hi:[1,0]
	v_pk_add_f32 v[26:27], v[24:25], 0 op_sel_hi:[1,0]
	v_cvt_pk_bf16_f32 v24, v32, v33
	v_cvt_pk_bf16_f32 v25, v30, v31
	v_add_co_u32_e32 v30, vcc, s49, v144
	v_cvt_pk_bf16_f32 v26, v26, v27
	v_cvt_pk_bf16_f32 v27, v34, v35
	v_lshl_add_u64 v[28:29], v[144:145], 0, s[16:17]
	s_nop 0
	v_addc_co_u32_e32 v31, vcc, 0, v145, vcc
	global_store_dwordx4 v[30:31], v[24:27], off
	s_nop 1
	v_pk_add_f32 v[24:25], v[14:15], 0 op_sel_hi:[1,0]
	v_pk_add_f32 v[14:15], v[12:13], 0 op_sel_hi:[1,0]
	v_cvt_pk_bf16_f32 v12, v20, v21
	v_cvt_pk_bf16_f32 v13, v22, v23
	s_nop 0
	v_cvt_pk_bf16_f32 v14, v14, v15
	v_cvt_pk_bf16_f32 v15, v24, v25
	global_store_dwordx4 v[28:29], v[12:15], off offset:256
	s_nop 1
	v_pk_add_f32 v[14:15], v[18:19], 0 op_sel_hi:[1,0]
	v_pk_add_f32 v[18:19], v[10:11], 0 op_sel_hi:[1,0]
	v_pk_add_f32 v[10:11], v[8:9], 0 op_sel_hi:[1,0]
	v_cvt_pk_bf16_f32 v8, v16, v17
	v_cvt_pk_bf16_f32 v9, v14, v15
	v_add_co_u32_e32 v14, vcc, s50, v144
	v_lshl_add_u64 v[12:13], v[144:145], 0, s[18:19]
	s_nop 0
	v_addc_co_u32_e32 v15, vcc, 0, v145, vcc
	v_cvt_pk_bf16_f32 v10, v10, v11
	v_cvt_pk_bf16_f32 v11, v18, v19
	global_store_dwordx4 v[14:15], v[8:11], off
	s_and_b64 vcc, exec, s[2:3]
	s_nop 0
	v_pk_add_f32 v[8:9], v[2:3], 0 op_sel_hi:[1,0]
	v_pk_add_f32 v[2:3], v[0:1], 0 op_sel_hi:[1,0]
	v_cvt_pk_bf16_f32 v0, v4, v5
	v_cvt_pk_bf16_f32 v1, v6, v7
	s_nop 0
	v_cvt_pk_bf16_f32 v2, v2, v3
	v_cvt_pk_bf16_f32 v3, v8, v9
	global_store_dwordx4 v[12:13], v[0:3], off offset:256
	s_cbranch_vccz .LBB0_275
	s_waitcnt vmcnt(0)
	s_cmpk_gt_u32 s31, 0xff
	s_cbranch_scc1 .LBB0_290
	s_barrier

; #define PG8_STAGE(bufoff, gbase, voff) do { _Pragma("unroll") for (int _i = 0; _i < 2; ++_i) \
;         __builtin_amdgcn_global_load_lds((const unsigned*)((const char*)(gbase) + (voff)[_i]), (PG8_LAS unsigned*)(lds + (bufoff) + ldsw + _i * 8192), 16, 0, 0); } while (0)
; #define PG8_LDA(dst, b, h) do { _Pragma("unroll") for (int m = 0; m < 4; ++m) _Pragma("unroll") for (int k = 0; k < 2; ++k) dst[m][k] = *(const PG8_LAS bf16x8*)(lds + PG8_SA(b, h) + aoff + m * 2048 + k * 1024); } while (0)
; #define PG8_LDB(dst, b, h) do { _Pragma("unroll") for (int n = 0; n < 2; ++n) _Pragma("unroll") for (int k = 0; k < 2; ++k) dst[n][k] = *(const PG8_LAS bf16x8*)(lds + PG8_SB(b, h) + boff + n * 2048 + k * 1024); } while (0)
; #define PG8_MMA(ai, bj, At, Bt) do { __builtin_amdgcn_s_setprio(1); _Pragma("unroll") for (int m = 0; m < 4; ++m) _Pragma("unroll") for (int n = 0; n < 2; ++n) _Pragma("unroll") for (int k = 0; k < 2; ++k) \
;         acc[ai][bj][m][n] = __builtin_amdgcn_mfma_f32_16x16x32_bf16(Bt[n][k], At[m][k], acc[ai][bj][m][n], 0, 0, 0); __builtin_amdgcn_s_setprio(0); } while (0)
; #define PG8_WAIT_V(n) asm volatile("s_waitcnt vmcnt(" #n ")" ::: "memory")
; #define PG8_WAIT_L(n) asm volatile("s_waitcnt lgkmcnt(" #n ")" ::: "memory")
; #define PG8_BAR __builtin_amdgcn_s_barrier()
; #define PG8_SCHED __builtin_amdgcn_sched_barrier(0)
; template <class Epi, class Sched>
; __device__ __forceinline__ void gemm_phase(PG8_LAS unsigned char* lds, const Gemm g, const Sched& S, const Epi& E) {
;     ...
;             PG8_LDB(B0, 0, 0); PG8_SCHED; PG8_LDA(At, 0, 0); PG8_STAGE(PG8_SA(1, 1), a1 + hstep, voffA);
;             PG8_WAIT_L(8); PG8_BAR; PG8_WAIT_L(0); PG8_MMA(0, 0, At, B0); PG8_BAR; PG8_SCHED;
;             PG8_LDB(B1, 0, 1); PG8_STAGE(PG8_SB(0, 0), b2, voffB);
;             PG8_BAR; PG8_WAIT_L(0); PG8_MMA(0, 1, At, B1); PG8_BAR;
;             PG8_LDA(At, 0, 1); PG8_STAGE(PG8_SA(0, 0), a2, voffA);
;             PG8_BAR; PG8_WAIT_L(0); PG8_MMA(1, 0, At, B0); PG8_BAR; PG8_SCHED;
;             PG8_STAGE(PG8_SB(0, 1), b2 + hstep, voffB);
;             PG8_WAIT_V(6); PG8_BAR; PG8_MMA(1, 1, At, B1); PG8_BAR;
.LBB0_416:
	ds_read_b128 v[24:27], v186
	ds_read_b128 v[28:31], v186 offset:1024
	ds_read_b128 v[40:43], v186 offset:2048
	ds_read_b128 v[44:47], v186 offset:3072
	s_add_u32 s4, s0, 0xfffc0080
	s_addc_u32 s5, s1, -1
	s_cmp_eq_u32 s53, 12
	s_cselect_b32 s29, s7, s5
	s_cselect_b32 s28, s10, s4
	s_cselect_b32 s5, s19, s52
	s_cselect_b32 s4, s21, s51
	v_lshl_add_u64 v[174:175], s[0:1], 0, v[166:167]
	s_add_i32 m0, s27, 0xc000
	ds_read_b128 v[144:147], v187
	ds_read_b128 v[148:151], v187 offset:1024
	ds_read_b128 v[182:185], v187 offset:2048
	ds_read_b128 v[192:195], v187 offset:3072
	ds_read_b128 v[196:199], v187 offset:4096
	ds_read_b128 v[200:203], v187 offset:5120
	ds_read_b128 v[204:207], v187 offset:6144
	ds_read_b128 v[208:211], v187 offset:7168
	global_load_lds_dwordx4 v[174:175], off
	v_lshl_add_u64 v[174:175], s[0:1], 0, v[168:169]
	s_add_i32 m0, s27, 0xe000
	s_nop 0
	global_load_lds_dwordx4 v[174:175], off
	s_waitcnt lgkmcnt(0)
	s_barrier
	v_mfma_f32_16x16x32_bf16 v[140:143], v[24:27], v[144:147], v[140:143]
	v_mfma_f32_16x16x32_bf16 v[136:139], v[40:43], v[144:147], v[136:139]
	v_mfma_f32_16x16x32_bf16 v[124:127], v[24:27], v[182:185], v[124:127]
	v_mfma_f32_16x16x32_bf16 v[120:123], v[40:43], v[182:185], v[120:123]
	v_mfma_f32_16x16x32_bf16 v[108:111], v[24:27], v[196:199], v[108:111]
	v_mfma_f32_16x16x32_bf16 v[104:107], v[40:43], v[196:199], v[104:107]
	v_mfma_f32_16x16x32_bf16 v[92:95], v[24:27], v[204:207], v[92:95]
	v_mfma_f32_16x16x32_bf16 v[88:91], v[40:43], v[204:207], v[88:91]
	v_mfma_f32_16x16x32_bf16 v[140:143], v[28:31], v[148:151], v[140:143]
	v_mfma_f32_16x16x32_bf16 v[136:139], v[44:47], v[148:151], v[136:139]
	v_mfma_f32_16x16x32_bf16 v[124:127], v[28:31], v[192:195], v[124:127]
	v_mfma_f32_16x16x32_bf16 v[120:123], v[44:47], v[192:195], v[120:123]
	v_mfma_f32_16x16x32_bf16 v[108:111], v[28:31], v[200:203], v[108:111]
	v_mfma_f32_16x16x32_bf16 v[104:107], v[44:47], v[200:203], v[104:107]
	v_mfma_f32_16x16x32_bf16 v[92:95], v[28:31], v[208:211], v[92:95]
	v_mfma_f32_16x16x32_bf16 v[88:91], v[44:47], v[208:211], v[88:91]
	s_barrier
	s_add_i32 s54, s43, s35
	v_lshl_add_u64 v[174:175], s[4:5], 0, v[156:157]
	s_mov_b32 m0, s54
	ds_read_b128 v[212:215], v189
	ds_read_b128 v[216:219], v189 offset:1024
	ds_read_b128 v[220:223], v189 offset:2048
	ds_read_b128 v[224:227], v189 offset:3072
	global_load_lds_dwordx4 v[174:175], off
	v_lshl_add_u64 v[228:229], s[4:5], 0, v[160:161]
	s_add_i32 m0, s54, 0x2000
	s_nop 0
	global_load_lds_dwordx4 v[228:229], off
	s_waitcnt lgkmcnt(0)
	s_barrier
	v_mfma_f32_16x16x32_bf16 v[132:135], v[212:215], v[144:147], v[132:135]
	v_mfma_f32_16x16x32_bf16 v[128:131], v[220:223], v[144:147], v[128:131]
	v_mfma_f32_16x16x32_bf16 v[116:119], v[212:215], v[182:185], v[116:119]
	v_mfma_f32_16x16x32_bf16 v[112:115], v[220:223], v[182:185], v[112:115]
	v_mfma_f32_16x16x32_bf16 v[100:103], v[212:215], v[196:199], v[100:103]
	v_mfma_f32_16x16x32_bf16 v[96:99], v[220:223], v[196:199], v[96:99]
	v_mfma_f32_16x16x32_bf16 v[84:87], v[212:215], v[204:207], v[84:87]
	v_mfma_f32_16x16x32_bf16 v[80:83], v[220:223], v[204:207], v[80:83]
	v_mfma_f32_16x16x32_bf16 v[132:135], v[216:219], v[148:151], v[132:135]
	v_mfma_f32_16x16x32_bf16 v[128:131], v[224:227], v[148:151], v[128:131]
	v_mfma_f32_16x16x32_bf16 v[116:119], v[216:219], v[192:195], v[116:119]
	v_mfma_f32_16x16x32_bf16 v[112:115], v[224:227], v[192:195], v[112:115]
	v_mfma_f32_16x16x32_bf16 v[100:103], v[216:219], v[200:203], v[100:103]
	v_mfma_f32_16x16x32_bf16 v[96:99], v[224:227], v[200:203], v[96:99]
	v_mfma_f32_16x16x32_bf16 v[84:87], v[216:219], v[208:211], v[84:87]
	v_mfma_f32_16x16x32_bf16 v[80:83], v[224:227], v[208:211], v[80:83]
	s_mov_b32 m0, s27
	v_lshl_add_u64 v[230:231], s[28:29], 0, v[154:155]
	s_barrier
	ds_read_b128 v[144:147], v187 offset:16384
	ds_read_b128 v[148:151], v187 offset:17408
	ds_read_b128 v[182:185], v187 offset:18432
	ds_read_b128 v[192:195], v187 offset:19456
	ds_read_b128 v[196:199], v187 offset:20480
	ds_read_b128 v[200:203], v187 offset:21504
	ds_read_b128 v[204:207], v187 offset:22528
	ds_read_b128 v[208:211], v187 offset:23552
	global_load_lds_dwordx4 v[230:231], off
	v_lshl_add_u64 v[232:233], s[28:29], 0, v[158:159]
	s_mov_b32 m0, s36
	s_nop 0
	global_load_lds_dwordx4 v[232:233], off
	s_waitcnt lgkmcnt(0)
	s_barrier
	v_mfma_f32_16x16x32_bf16 v[76:79], v[24:27], v[144:147], v[76:79]
	v_mfma_f32_16x16x32_bf16 v[72:75], v[40:43], v[144:147], v[72:75]
	v_mfma_f32_16x16x32_bf16 v[60:63], v[24:27], v[182:185], v[60:63]
	v_mfma_f32_16x16x32_bf16 v[56:59], v[40:43], v[182:185], v[56:59]
	v_mfma_f32_16x16x32_bf16 v[36:39], v[24:27], v[196:199], v[36:39]
	v_mfma_f32_16x16x32_bf16 v[32:35], v[40:43], v[196:199], v[32:35]
	v_mfma_f32_16x16x32_bf16 v[12:15], v[24:27], v[204:207], v[12:15]
	v_mfma_f32_16x16x32_bf16 v[8:11], v[40:43], v[204:207], v[8:11]
	v_mfma_f32_16x16x32_bf16 v[76:79], v[28:31], v[148:151], v[76:79]
	v_mfma_f32_16x16x32_bf16 v[72:75], v[44:47], v[148:151], v[72:75]
	v_mfma_f32_16x16x32_bf16 v[60:63], v[28:31], v[192:195], v[60:63]
	v_mfma_f32_16x16x32_bf16 v[56:59], v[44:47], v[192:195], v[56:59]
	v_mfma_f32_16x16x32_bf16 v[36:39], v[28:31], v[200:203], v[36:39]
	v_mfma_f32_16x16x32_bf16 v[32:35], v[44:47], v[200:203], v[32:35]
	v_mfma_f32_16x16x32_bf16 v[12:15], v[28:31], v[208:211], v[12:15]
	v_mfma_f32_16x16x32_bf16 v[8:11], v[44:47], v[208:211], v[8:11]
	s_barrier
	s_add_u32 s54, s4, 0x40000
	s_addc_u32 s55, s5, 0
	s_add_i32 s56, s44, s35
	v_lshl_add_u64 v[24:25], s[54:55], 0, v[156:157]
	s_mov_b32 m0, s56
	s_nop 0
	global_load_lds_dwordx4 v[24:25], off
	v_lshl_add_u64 v[24:25], s[54:55], 0, v[160:161]
	s_add_i32 m0, s56, 0x2000
	s_nop 0
	global_load_lds_dwordx4 v[24:25], off
	s_waitcnt vmcnt(6)
	s_barrier
; #define PG8_STAGE(bufoff, gbase, voff) do { _Pragma("unroll") for (int _i = 0; _i < 2; ++_i) \
;         __builtin_amdgcn_global_load_lds((const unsigned*)((const char*)(gbase) + (voff)[_i]), (PG8_LAS unsigned*)(lds + (bufoff) + ldsw + _i * 8192), 16, 0, 0); } while (0)
; #define PG8_LDA(dst, b, h) do { _Pragma("unroll") for (int m = 0; m < 4; ++m) _Pragma("unroll") for (int k = 0; k < 2; ++k) dst[m][k] = *(const PG8_LAS bf16x8*)(lds + PG8_SA(b, h) + aoff + m * 2048 + k * 1024); } while (0)
; #define PG8_LDB(dst, b, h) do { _Pragma("unroll") for (int n = 0; n < 2; ++n) _Pragma("unroll") for (int k = 0; k < 2; ++k) dst[n][k] = *(const PG8_LAS bf16x8*)(lds + PG8_SB(b, h) + boff + n * 2048 + k * 1024); } while (0)
; #define PG8_MMA(ai, bj, At, Bt) do { __builtin_amdgcn_s_setprio(1); _Pragma("unroll") for (int m = 0; m < 4; ++m) _Pragma("unroll") for (int n = 0; n < 2; ++n) _Pragma("unroll") for (int k = 0; k < 2; ++k) \
;         acc[ai][bj][m][n] = __builtin_amdgcn_mfma_f32_16x16x32_bf16(Bt[n][k], At[m][k], acc[ai][bj][m][n], 0, 0, 0); __builtin_amdgcn_s_setprio(0); } while (0)
; #define PG8_WAIT_V(n) asm volatile("s_waitcnt vmcnt(" #n ")" ::: "memory")
; #define PG8_WAIT_L(n) asm volatile("s_waitcnt lgkmcnt(" #n ")" ::: "memory")
; #define PG8_BAR __builtin_amdgcn_s_barrier()
; #define PG8_SCHED __builtin_amdgcn_sched_barrier(0)
; template <class Epi, class Sched>
; __device__ __forceinline__ void gemm_phase(PG8_LAS unsigned char* lds, const Gemm g, const Sched& S, const Epi& E) {
;     ...
;             PG8_WAIT_V(6); PG8_BAR; PG8_MMA(1, 1, At, B1); PG8_BAR;
;             PG8_LDB(B0, 1, 0); PG8_SCHED; PG8_LDA(At, 1, 0); PG8_STAGE(PG8_SA(0, 1), a2 + hstep, voffA);
;             PG8_WAIT_L(8); PG8_BAR; PG8_WAIT_L(0); PG8_MMA(0, 0, At, B0); PG8_BAR; PG8_SCHED;
;             PG8_LDB(B1, 1, 1); PG8_STAGE(PG8_SB(1, 0), b3, voffB);
;             PG8_BAR; PG8_WAIT_L(0); PG8_MMA(0, 1, At, B1); PG8_BAR;
;             PG8_LDA(At, 1, 1); PG8_STAGE(PG8_SA(1, 0), a3, voffA);
;             PG8_BAR; PG8_WAIT_L(0); PG8_MMA(1, 0, At, B0); PG8_BAR; PG8_SCHED;
;             PG8_STAGE(PG8_SB(1, 1), b3 + hstep, voffB);
	v_mfma_f32_16x16x32_bf16 v[20:23], v[212:215], v[196:199], v[20:23]
	v_mfma_f32_16x16x32_bf16 v[16:19], v[220:223], v[196:199], v[16:19]
	v_mfma_f32_16x16x32_bf16 v[4:7], v[212:215], v[204:207], v[4:7]
	v_mfma_f32_16x16x32_bf16 v[0:3], v[220:223], v[204:207], v[0:3]
	v_mfma_f32_16x16x32_bf16 v[24:27], v[212:215], v[144:147], v[68:71]
	v_mfma_f32_16x16x32_bf16 v[28:31], v[220:223], v[144:147], v[64:67]
	v_mfma_f32_16x16x32_bf16 v[40:43], v[212:215], v[182:185], v[52:55]
	v_mfma_f32_16x16x32_bf16 v[44:47], v[220:223], v[182:185], v[48:51]
	v_mfma_f32_16x16x32_bf16 v[20:23], v[216:219], v[200:203], v[20:23]
	v_mfma_f32_16x16x32_bf16 v[16:19], v[224:227], v[200:203], v[16:19]
	v_mfma_f32_16x16x32_bf16 v[4:7], v[216:219], v[208:211], v[4:7]
	v_mfma_f32_16x16x32_bf16 v[0:3], v[224:227], v[208:211], v[0:3]
	v_mfma_f32_16x16x32_bf16 v[24:27], v[216:219], v[148:151], v[24:27]
	v_mfma_f32_16x16x32_bf16 v[28:31], v[224:227], v[148:151], v[28:31]
	v_mfma_f32_16x16x32_bf16 v[40:43], v[216:219], v[192:195], v[40:43]
	v_mfma_f32_16x16x32_bf16 v[44:47], v[224:227], v[192:195], v[44:47]
	s_add_i32 s54, 0, 0x18000
	v_add_u32_e32 v68, s54, v179
	s_barrier
	ds_read_b128 v[48:51], v68
	ds_read_b128 v[52:55], v68 offset:1024
	ds_read_b128 v[64:67], v68 offset:2048
	ds_read_b128 v[68:71], v68 offset:3072
	s_add_u32 s28, s28, 0x40000
	s_addc_u32 s29, s29, 0
	s_mov_b32 m0, s37
	v_lshl_add_u64 v[212:213], s[28:29], 0, v[154:155]
	ds_read_b128 v[144:147], v187 offset:32768
	ds_read_b128 v[148:151], v187 offset:33792
	ds_read_b128 v[182:185], v187 offset:34816
	ds_read_b128 v[192:195], v187 offset:35840
	ds_read_b128 v[196:199], v187 offset:36864
	ds_read_b128 v[200:203], v187 offset:37888
	ds_read_b128 v[204:207], v187 offset:38912
	ds_read_b128 v[208:211], v187 offset:39936
	global_load_lds_dwordx4 v[212:213], off
	v_lshl_add_u64 v[212:213], s[28:29], 0, v[158:159]
	s_mov_b32 m0, s38
	s_nop 0
	global_load_lds_dwordx4 v[212:213], off
	s_waitcnt lgkmcnt(0)
	s_barrier
	v_mfma_f32_16x16x32_bf16 v[140:143], v[48:51], v[144:147], v[140:143]
	v_mfma_f32_16x16x32_bf16 v[136:139], v[64:67], v[144:147], v[136:139]
	v_mfma_f32_16x16x32_bf16 v[124:127], v[48:51], v[182:185], v[124:127]
	v_mfma_f32_16x16x32_bf16 v[120:123], v[64:67], v[182:185], v[120:123]
	v_mfma_f32_16x16x32_bf16 v[108:111], v[48:51], v[196:199], v[108:111]
	v_mfma_f32_16x16x32_bf16 v[104:107], v[64:67], v[196:199], v[104:107]
	v_mfma_f32_16x16x32_bf16 v[92:95], v[48:51], v[204:207], v[92:95]
	v_mfma_f32_16x16x32_bf16 v[88:91], v[64:67], v[204:207], v[88:91]
	v_mfma_f32_16x16x32_bf16 v[140:143], v[52:55], v[148:151], v[140:143]
	v_mfma_f32_16x16x32_bf16 v[136:139], v[68:71], v[148:151], v[136:139]
	v_mfma_f32_16x16x32_bf16 v[124:127], v[52:55], v[192:195], v[124:127]
	v_mfma_f32_16x16x32_bf16 v[120:123], v[68:71], v[192:195], v[120:123]
	v_mfma_f32_16x16x32_bf16 v[108:111], v[52:55], v[200:203], v[108:111]
	v_mfma_f32_16x16x32_bf16 v[104:107], v[68:71], v[200:203], v[104:107]
	v_mfma_f32_16x16x32_bf16 v[92:95], v[52:55], v[208:211], v[92:95]
	v_mfma_f32_16x16x32_bf16 v[88:91], v[68:71], v[208:211], v[88:91]
	s_barrier
	s_add_i32 s28, 0, 0x1c000
	s_add_i32 s29, s54, s35
	v_add_u32_e32 v162, s28, v179
	v_lshl_add_u64 v[174:175], v[174:175], 0, s[14:15]
	s_mov_b32 m0, s29
	ds_read_b128 v[212:215], v162
	ds_read_b128 v[216:219], v162 offset:1024
	ds_read_b128 v[220:223], v162 offset:2048
	ds_read_b128 v[224:227], v162 offset:3072
	global_load_lds_dwordx4 v[174:175], off
	v_lshl_add_u64 v[174:175], v[228:229], 0, s[14:15]
	s_add_i32 m0, s29, 0x2000
	s_nop 0
	global_load_lds_dwordx4 v[174:175], off
	s_waitcnt lgkmcnt(0)
	s_barrier
	v_mfma_f32_16x16x32_bf16 v[132:135], v[212:215], v[144:147], v[132:135]
	v_mfma_f32_16x16x32_bf16 v[128:131], v[220:223], v[144:147], v[128:131]
	v_mfma_f32_16x16x32_bf16 v[116:119], v[212:215], v[182:185], v[116:119]
	v_mfma_f32_16x16x32_bf16 v[112:115], v[220:223], v[182:185], v[112:115]
	v_mfma_f32_16x16x32_bf16 v[100:103], v[212:215], v[196:199], v[100:103]
	v_mfma_f32_16x16x32_bf16 v[96:99], v[220:223], v[196:199], v[96:99]
	v_mfma_f32_16x16x32_bf16 v[84:87], v[212:215], v[204:207], v[84:87]
	v_mfma_f32_16x16x32_bf16 v[80:83], v[220:223], v[204:207], v[80:83]
	v_mfma_f32_16x16x32_bf16 v[132:135], v[216:219], v[148:151], v[132:135]
	v_mfma_f32_16x16x32_bf16 v[128:131], v[224:227], v[148:151], v[128:131]
	v_mfma_f32_16x16x32_bf16 v[116:119], v[216:219], v[192:195], v[116:119]
	v_mfma_f32_16x16x32_bf16 v[112:115], v[224:227], v[192:195], v[112:115]
	v_mfma_f32_16x16x32_bf16 v[100:103], v[216:219], v[200:203], v[100:103]
	v_mfma_f32_16x16x32_bf16 v[96:99], v[224:227], v[200:203], v[96:99]
	v_mfma_f32_16x16x32_bf16 v[84:87], v[216:219], v[208:211], v[84:87]
	v_mfma_f32_16x16x32_bf16 v[80:83], v[224:227], v[208:211], v[80:83]
	s_mov_b32 m0, s39
	v_lshl_add_u64 v[174:175], v[230:231], 0, s[14:15]
	s_barrier
; #define PG8_STAGE(bufoff, gbase, voff) do { _Pragma("unroll") for (int _i = 0; _i < 2; ++_i) \
;         __builtin_amdgcn_global_load_lds((const unsigned*)((const char*)(gbase) + (voff)[_i]), (PG8_LAS unsigned*)(lds + (bufoff) + ldsw + _i * 8192), 16, 0, 0); } while (0)
; #define PG8_LDA(dst, b, h) do { _Pragma("unroll") for (int m = 0; m < 4; ++m) _Pragma("unroll") for (int k = 0; k < 2; ++k) dst[m][k] = *(const PG8_LAS bf16x8*)(lds + PG8_SA(b, h) + aoff + m * 2048 + k * 1024); } while (0)
; #define PG8_LDB(dst, b, h) do { _Pragma("unroll") for (int n = 0; n < 2; ++n) _Pragma("unroll") for (int k = 0; k < 2; ++k) dst[n][k] = *(const PG8_LAS bf16x8*)(lds + PG8_SB(b, h) + boff + n * 2048 + k * 1024); } while (0)
; #define PG8_WAIT_V(n) asm volatile("s_waitcnt vmcnt(" #n ")" ::: "memory")
; #define PG8_WAIT_L(n) asm volatile("s_waitcnt lgkmcnt(" #n ")" ::: "memory")
; #define PG8_BAR __builtin_amdgcn_s_barrier()
; #define PG8_SCHED __builtin_amdgcn_sched_barrier(0)
;     __device__ __forceinline__ void operator()(const f32x4 (&acc)[2][2][4][2], const Unit& u, int wr, int wc, int fr, int fq) const {
;     ...
;         if (mode == 1) { if (u.pn >= 8 && u.pn < 12) act = 1; else if (u.pn >= 12) { act = 3; bias = (u.pn >= 14) ? bias_b + (u.pn - 14) * 256 : bias_f + (u.pn - 12) * 256; } }
;         else if (mode == 2) { if (u.pn >= 6) act = 2; }
;         const int row0 = u.pm * BM + wr * 64 + fr, col0 = u.pn * BM + wc * 32 + 8 * fq, bcol0 = wc * 32 + 8 * fq;
;         f32x4 bv[2][2];
; #pragma unroll
;         for (int bj = 0; bj < 2; ++bj)
; #pragma unroll
;             for (int n = 0; n < 2; ++n) bv[bj][n] = bias ? *(const f32x4*)(bias + bcol0 + bj * HALF + 4 * n) : (f32x4){0.f, 0.f, 0.f, 0.f};
; template <class Epi, class Sched>
; __device__ __forceinline__ void gemm_phase(PG8_LAS unsigned char* lds, const Gemm g, const Sched& S, const Epi& E) {
;     ...
;             PG8_WAIT_L(8); PG8_BAR; PG8_WAIT_L(0); PG8_MMA(0, 0, At, B0); PG8_BAR; PG8_SCHED;
;             PG8_LDB(B1, 1, 1); PG8_STAGE(PG8_SB(1, 0), b3, voffB);
;             PG8_BAR; PG8_WAIT_L(0); PG8_MMA(0, 1, At, B1); PG8_BAR;
;             PG8_LDA(At, 1, 1); PG8_STAGE(PG8_SA(1, 0), a3, voffA);
;             PG8_BAR; PG8_WAIT_L(0); PG8_MMA(1, 0, At, B0); PG8_BAR; PG8_SCHED;
;             PG8_STAGE(PG8_SB(1, 1), b3 + hstep, voffB);
;             PG8_WAIT_V(6); PG8_BAR; PG8_MMA(1, 1, At, B1); PG8_BAR;
	ds_read_b128 v[144:147], v187 offset:49152
	ds_read_b128 v[148:151], v187 offset:50176
	ds_read_b128 v[182:185], v187 offset:51200
	ds_read_b128 v[192:195], v187 offset:52224
	ds_read_b128 v[196:199], v187 offset:53248
	ds_read_b128 v[200:203], v187 offset:54272
	ds_read_b128 v[204:207], v187 offset:55296
	ds_read_b128 v[208:211], v187 offset:56320
	global_load_lds_dwordx4 v[174:175], off
	v_lshl_add_u64 v[174:175], v[232:233], 0, s[14:15]
	s_mov_b32 m0, s40
	s_nop 0
	global_load_lds_dwordx4 v[174:175], off
	s_waitcnt lgkmcnt(0)
	s_barrier
	v_mfma_f32_16x16x32_bf16 v[76:79], v[48:51], v[144:147], v[76:79]
	v_mfma_f32_16x16x32_bf16 v[72:75], v[64:67], v[144:147], v[72:75]
	v_mfma_f32_16x16x32_bf16 v[60:63], v[48:51], v[182:185], v[60:63]
	v_mfma_f32_16x16x32_bf16 v[56:59], v[64:67], v[182:185], v[56:59]
	v_mfma_f32_16x16x32_bf16 v[36:39], v[48:51], v[196:199], v[36:39]
	v_mfma_f32_16x16x32_bf16 v[32:35], v[64:67], v[196:199], v[32:35]
	v_mfma_f32_16x16x32_bf16 v[12:15], v[48:51], v[204:207], v[12:15]
	v_mfma_f32_16x16x32_bf16 v[8:11], v[64:67], v[204:207], v[8:11]
	v_mfma_f32_16x16x32_bf16 v[76:79], v[52:55], v[148:151], v[76:79]
	v_mfma_f32_16x16x32_bf16 v[72:75], v[68:71], v[148:151], v[72:75]
	v_mfma_f32_16x16x32_bf16 v[60:63], v[52:55], v[192:195], v[60:63]
	v_mfma_f32_16x16x32_bf16 v[56:59], v[68:71], v[192:195], v[56:59]
	v_mfma_f32_16x16x32_bf16 v[36:39], v[52:55], v[200:203], v[36:39]
	v_mfma_f32_16x16x32_bf16 v[32:35], v[68:71], v[200:203], v[32:35]
	v_mfma_f32_16x16x32_bf16 v[12:15], v[52:55], v[208:211], v[12:15]
	v_mfma_f32_16x16x32_bf16 v[8:11], v[68:71], v[208:211], v[8:11]
	s_barrier
	s_add_u32 s4, s4, 0x40080
	s_addc_u32 s5, s5, 0
	s_add_i32 s28, s28, s35
	v_lshl_add_u64 v[48:49], s[4:5], 0, v[156:157]
	s_mov_b32 m0, s28
	s_nop 0
	global_load_lds_dwordx4 v[48:49], off
	v_lshl_add_u64 v[48:49], s[4:5], 0, v[160:161]
	s_add_i32 m0, s28, 0x2000
	s_nop 0
	global_load_lds_dwordx4 v[48:49], off
	s_waitcnt vmcnt(6)
	s_barrier
	v_mfma_f32_16x16x32_bf16 v[24:27], v[212:215], v[144:147], v[24:27]
	v_mfma_f32_16x16x32_bf16 v[68:71], v[216:219], v[148:151], v[24:27]
	v_mfma_f32_16x16x32_bf16 v[24:27], v[220:223], v[144:147], v[28:31]
	v_mfma_f32_16x16x32_bf16 v[64:67], v[224:227], v[148:151], v[24:27]
	v_mfma_f32_16x16x32_bf16 v[24:27], v[212:215], v[182:185], v[40:43]
	v_mfma_f32_16x16x32_bf16 v[52:55], v[216:219], v[192:195], v[24:27]
	v_mfma_f32_16x16x32_bf16 v[24:27], v[220:223], v[182:185], v[44:47]
	v_mfma_f32_16x16x32_bf16 v[20:23], v[212:215], v[196:199], v[20:23]
	v_mfma_f32_16x16x32_bf16 v[16:19], v[220:223], v[196:199], v[16:19]
	v_mfma_f32_16x16x32_bf16 v[4:7], v[212:215], v[204:207], v[4:7]
	v_mfma_f32_16x16x32_bf16 v[0:3], v[220:223], v[204:207], v[0:3]
	v_mfma_f32_16x16x32_bf16 v[48:51], v[224:227], v[192:195], v[24:27]
	v_mfma_f32_16x16x32_bf16 v[20:23], v[216:219], v[200:203], v[20:23]
	v_mfma_f32_16x16x32_bf16 v[16:19], v[224:227], v[200:203], v[16:19]
	v_mfma_f32_16x16x32_bf16 v[4:7], v[216:219], v[208:211], v[4:7]
	v_mfma_f32_16x16x32_bf16 v[0:3], v[224:227], v[208:211], v[0:3]
	s_add_i32 s53, s53, 2
	s_add_u32 s0, s0, 0x100
	s_addc_u32 s1, s1, 0
	s_add_u32 s51, s51, 0x100
	s_addc_u32 s52, s52, 0
	s_cmp_gt_u32 s53, 13
	s_barrier
	s_cbranch_scc0 .LBB0_416
	s_cmp_gt_i32 s26, 11
	s_cselect_b64 s[4:5], -1, 0
	s_cmp_lt_i32 s26, 12
	s_mov_b64 s[0:1], 0
	s_cbranch_scc1 .LBB0_422
	s_lshl_b32 s10, s26, 8
	s_cmp_lt_u32 s26, 14
	s_mov_b64 s[28:29], -1
	s_cbranch_scc0 .LBB0_420
	s_lshl_b64 s[0:1], s[10:11], 2
	v_readlane_b32 s52, v245, 0
	v_readlane_b32 s53, v245, 1
	s_add_u32 s0, s52, s0
	s_addc_u32 s1, s53, s1
	s_add_u32 s0, s0, 0xffffd000
	v_readlane_b32 s54, v245, 2
	v_readlane_b32 s55, v245, 3
	v_readlane_b32 s56, v245, 4
	v_readlane_b32 s57, v245, 5
	v_readlane_b32 s58, v245, 6
	v_readlane_b32 s59, v245, 7
	v_readlane_b32 s60, v245, 8
	v_readlane_b32 s61, v245, 9
	v_readlane_b32 s62, v245, 10
	v_readlane_b32 s63, v245, 11
	v_readlane_b32 s64, v245, 12
	v_readlane_b32 s65, v245, 13
	v_readlane_b32 s66, v245, 14
	v_readlane_b32 s67, v245, 15
	s_addc_u32 s1, s1, -1
	s_mov_b64 s[28:29], 0

; #define PG8_STAGE(bufoff, gbase, voff) do { _Pragma("unroll") for (int _i = 0; _i < 2; ++_i) \
;         __builtin_amdgcn_global_load_lds((const unsigned*)((const char*)(gbase) + (voff)[_i]), (PG8_LAS unsigned*)(lds + (bufoff) + ldsw + _i * 8192), 16, 0, 0); } while (0)
; #define PG8_LDA(dst, b, h) do { _Pragma("unroll") for (int m = 0; m < 4; ++m) _Pragma("unroll") for (int k = 0; k < 2; ++k) dst[m][k] = *(const PG8_LAS bf16x8*)(lds + PG8_SA(b, h) + aoff + m * 2048 + k * 1024); } while (0)
; #define PG8_LDB(dst, b, h) do { _Pragma("unroll") for (int n = 0; n < 2; ++n) _Pragma("unroll") for (int k = 0; k < 2; ++k) dst[n][k] = *(const PG8_LAS bf16x8*)(lds + PG8_SB(b, h) + boff + n * 2048 + k * 1024); } while (0)
; #define PG8_MMA(ai, bj, At, Bt) do { __builtin_amdgcn_s_setprio(1); _Pragma("unroll") for (int m = 0; m < 4; ++m) _Pragma("unroll") for (int n = 0; n < 2; ++n) _Pragma("unroll") for (int k = 0; k < 2; ++k) \
;         acc[ai][bj][m][n] = __builtin_amdgcn_mfma_f32_16x16x32_bf16(Bt[n][k], At[m][k], acc[ai][bj][m][n], 0, 0, 0); __builtin_amdgcn_s_setprio(0); } while (0)
; #define PG8_WAIT_V(n) asm volatile("s_waitcnt vmcnt(" #n ")" ::: "memory")
; #define PG8_WAIT_L(n) asm volatile("s_waitcnt lgkmcnt(" #n ")" ::: "memory")
; #define PG8_BAR __builtin_amdgcn_s_barrier()
; #define PG8_SCHED __builtin_amdgcn_sched_barrier(0)
; template <class Epi, class Sched>
; __device__ __forceinline__ void gemm_phase(PG8_LAS unsigned char* lds, const Gemm g, const Sched& S, const Epi& E) {
;     ...
;             PG8_LDB(B0, 0, 0); PG8_SCHED; PG8_LDA(At, 0, 0); PG8_STAGE(PG8_SA(1, 1), a1 + hstep, voffA);
;             PG8_WAIT_L(8); PG8_BAR; PG8_WAIT_L(0); PG8_MMA(0, 0, At, B0); PG8_BAR; PG8_SCHED;
;             PG8_LDB(B1, 0, 1); PG8_STAGE(PG8_SB(0, 0), b2, voffB);
;             PG8_BAR; PG8_WAIT_L(0); PG8_MMA(0, 1, At, B1); PG8_BAR;
;             PG8_LDA(At, 0, 1); PG8_STAGE(PG8_SA(0, 0), a2, voffA);
;             PG8_BAR; PG8_WAIT_L(0); PG8_MMA(1, 0, At, B0); PG8_BAR; PG8_SCHED;
;             PG8_STAGE(PG8_SB(0, 1), b2 + hstep, voffB);
;             PG8_WAIT_V(6); PG8_BAR; PG8_MMA(1, 1, At, B1); PG8_BAR;
.LBB0_724:
	ds_read_b128 v[144:147], v151
	ds_read_b128 v[156:159], v151 offset:1024
	ds_read_b128 v[160:163], v151 offset:2048
	ds_read_b128 v[166:169], v151 offset:3072
	s_add_u32 s20, s18, 0xfffc0080
	s_addc_u32 s21, s19, -1
	s_cmp_eq_u32 s48, 12
	s_cselect_b32 s23, s5, s21
	s_cselect_b32 s22, s11, s20
	s_cselect_b32 s21, s9, s47
	s_cselect_b32 s20, s45, s46
	v_lshl_add_u64 v[174:175], s[18:19], 0, v[136:137]
	s_add_i32 m0, s17, 0xc000
	ds_read_b128 v[170:173], v153
	ds_read_b128 v[182:185], v153 offset:1024
	ds_read_b128 v[190:193], v153 offset:2048
	ds_read_b128 v[194:197], v153 offset:3072
	ds_read_b128 v[198:201], v153 offset:4096
	ds_read_b128 v[202:205], v153 offset:5120
	ds_read_b128 v[206:209], v153 offset:6144
	ds_read_b128 v[210:213], v153 offset:7168
	global_load_lds_dwordx4 v[174:175], off
	v_lshl_add_u64 v[174:175], s[18:19], 0, v[138:139]
	s_add_i32 m0, s17, 0xe000
	s_nop 0
	global_load_lds_dwordx4 v[174:175], off
	s_waitcnt lgkmcnt(0)
	s_barrier
	v_mfma_f32_16x16x32_bf16 v[124:127], v[144:147], v[170:173], v[124:127]
	v_mfma_f32_16x16x32_bf16 v[120:123], v[160:163], v[170:173], v[120:123]
	v_mfma_f32_16x16x32_bf16 v[108:111], v[144:147], v[190:193], v[108:111]
	v_mfma_f32_16x16x32_bf16 v[104:107], v[160:163], v[190:193], v[104:107]
	v_mfma_f32_16x16x32_bf16 v[92:95], v[144:147], v[198:201], v[92:95]
	v_mfma_f32_16x16x32_bf16 v[88:91], v[160:163], v[198:201], v[88:91]
	v_mfma_f32_16x16x32_bf16 v[76:79], v[144:147], v[206:209], v[76:79]
	v_mfma_f32_16x16x32_bf16 v[72:75], v[160:163], v[206:209], v[72:75]
	v_mfma_f32_16x16x32_bf16 v[124:127], v[156:159], v[182:185], v[124:127]
	v_mfma_f32_16x16x32_bf16 v[120:123], v[166:169], v[182:185], v[120:123]
	v_mfma_f32_16x16x32_bf16 v[108:111], v[156:159], v[194:197], v[108:111]
	v_mfma_f32_16x16x32_bf16 v[104:107], v[166:169], v[194:197], v[104:107]
	v_mfma_f32_16x16x32_bf16 v[92:95], v[156:159], v[202:205], v[92:95]
	v_mfma_f32_16x16x32_bf16 v[88:91], v[166:169], v[202:205], v[88:91]
	v_mfma_f32_16x16x32_bf16 v[76:79], v[156:159], v[210:213], v[76:79]
	v_mfma_f32_16x16x32_bf16 v[72:75], v[166:169], v[210:213], v[72:75]
	s_barrier
	s_add_i32 s49, s42, s30
	v_lshl_add_u64 v[174:175], s[20:21], 0, v[130:131]
	s_mov_b32 m0, s49
	ds_read_b128 v[214:217], v154
	ds_read_b128 v[218:221], v154 offset:1024
	ds_read_b128 v[222:225], v154 offset:2048
	ds_read_b128 v[226:229], v154 offset:3072
	global_load_lds_dwordx4 v[174:175], off
	v_lshl_add_u64 v[186:187], s[20:21], 0, v[134:135]
	s_add_i32 m0, s49, 0x2000
	s_nop 0
	global_load_lds_dwordx4 v[186:187], off
	s_waitcnt lgkmcnt(0)
	s_barrier
	v_mfma_f32_16x16x32_bf16 v[116:119], v[214:217], v[170:173], v[116:119]
	v_mfma_f32_16x16x32_bf16 v[112:115], v[222:225], v[170:173], v[112:115]
	v_mfma_f32_16x16x32_bf16 v[100:103], v[214:217], v[190:193], v[100:103]
	v_mfma_f32_16x16x32_bf16 v[96:99], v[222:225], v[190:193], v[96:99]
	v_mfma_f32_16x16x32_bf16 v[84:87], v[214:217], v[198:201], v[84:87]
	v_mfma_f32_16x16x32_bf16 v[80:83], v[222:225], v[198:201], v[80:83]
	v_mfma_f32_16x16x32_bf16 v[68:71], v[214:217], v[206:209], v[68:71]
	v_mfma_f32_16x16x32_bf16 v[64:67], v[222:225], v[206:209], v[64:67]
	v_mfma_f32_16x16x32_bf16 v[116:119], v[218:221], v[182:185], v[116:119]
	v_mfma_f32_16x16x32_bf16 v[112:115], v[226:229], v[182:185], v[112:115]
	v_mfma_f32_16x16x32_bf16 v[100:103], v[218:221], v[194:197], v[100:103]
	v_mfma_f32_16x16x32_bf16 v[96:99], v[226:229], v[194:197], v[96:99]
	v_mfma_f32_16x16x32_bf16 v[84:87], v[218:221], v[202:205], v[84:87]
	v_mfma_f32_16x16x32_bf16 v[80:83], v[226:229], v[202:205], v[80:83]
	v_mfma_f32_16x16x32_bf16 v[68:71], v[218:221], v[210:213], v[68:71]
	v_mfma_f32_16x16x32_bf16 v[64:67], v[226:229], v[210:213], v[64:67]
	s_mov_b32 m0, s17
	v_lshl_add_u64 v[230:231], s[22:23], 0, v[128:129]
	s_barrier
	ds_read_b128 v[170:173], v153 offset:16384
	ds_read_b128 v[182:185], v153 offset:17408
	ds_read_b128 v[190:193], v153 offset:18432
	ds_read_b128 v[194:197], v153 offset:19456
	ds_read_b128 v[198:201], v153 offset:20480
	ds_read_b128 v[202:205], v153 offset:21504
	ds_read_b128 v[206:209], v153 offset:22528
	ds_read_b128 v[210:213], v153 offset:23552
	global_load_lds_dwordx4 v[230:231], off
	v_lshl_add_u64 v[232:233], s[22:23], 0, v[132:133]
	s_mov_b32 m0, s31
	s_nop 0
	global_load_lds_dwordx4 v[232:233], off
	s_waitcnt lgkmcnt(0)
	s_barrier
	v_mfma_f32_16x16x32_bf16 v[60:63], v[144:147], v[170:173], v[60:63]
	v_mfma_f32_16x16x32_bf16 v[56:59], v[160:163], v[170:173], v[56:59]
	v_mfma_f32_16x16x32_bf16 v[44:47], v[144:147], v[190:193], v[44:47]
	v_mfma_f32_16x16x32_bf16 v[40:43], v[160:163], v[190:193], v[40:43]
	v_mfma_f32_16x16x32_bf16 v[28:31], v[144:147], v[198:201], v[28:31]
	v_mfma_f32_16x16x32_bf16 v[24:27], v[160:163], v[198:201], v[24:27]
	v_mfma_f32_16x16x32_bf16 v[12:15], v[144:147], v[206:209], v[12:15]
	v_mfma_f32_16x16x32_bf16 v[8:11], v[160:163], v[206:209], v[8:11]
	v_mfma_f32_16x16x32_bf16 v[60:63], v[156:159], v[182:185], v[60:63]
	v_mfma_f32_16x16x32_bf16 v[56:59], v[166:169], v[182:185], v[56:59]
	v_mfma_f32_16x16x32_bf16 v[44:47], v[156:159], v[194:197], v[44:47]
	v_mfma_f32_16x16x32_bf16 v[40:43], v[166:169], v[194:197], v[40:43]
	v_mfma_f32_16x16x32_bf16 v[28:31], v[156:159], v[202:205], v[28:31]
	v_mfma_f32_16x16x32_bf16 v[24:27], v[166:169], v[202:205], v[24:27]
	v_mfma_f32_16x16x32_bf16 v[12:15], v[156:159], v[210:213], v[12:15]
	v_mfma_f32_16x16x32_bf16 v[8:11], v[166:169], v[210:213], v[8:11]
	s_barrier
	s_add_u32 s50, s20, 0x40000
	s_addc_u32 s51, s21, 0
	s_add_i32 s49, s43, s30
	v_lshl_add_u64 v[144:145], s[50:51], 0, v[130:131]
	s_mov_b32 m0, s49
	s_nop 0
	global_load_lds_dwordx4 v[144:145], off
	v_lshl_add_u64 v[144:145], s[50:51], 0, v[134:135]
	s_add_i32 m0, s49, 0x2000
	s_nop 0
	global_load_lds_dwordx4 v[144:145], off
	s_waitcnt vmcnt(6)
	s_barrier
; #define PG8_STAGE(bufoff, gbase, voff) do { _Pragma("unroll") for (int _i = 0; _i < 2; ++_i) \
;         __builtin_amdgcn_global_load_lds((const unsigned*)((const char*)(gbase) + (voff)[_i]), (PG8_LAS unsigned*)(lds + (bufoff) + ldsw + _i * 8192), 16, 0, 0); } while (0)
; #define PG8_LDA(dst, b, h) do { _Pragma("unroll") for (int m = 0; m < 4; ++m) _Pragma("unroll") for (int k = 0; k < 2; ++k) dst[m][k] = *(const PG8_LAS bf16x8*)(lds + PG8_SA(b, h) + aoff + m * 2048 + k * 1024); } while (0)
; #define PG8_LDB(dst, b, h) do { _Pragma("unroll") for (int n = 0; n < 2; ++n) _Pragma("unroll") for (int k = 0; k < 2; ++k) dst[n][k] = *(const PG8_LAS bf16x8*)(lds + PG8_SB(b, h) + boff + n * 2048 + k * 1024); } while (0)
; #define PG8_MMA(ai, bj, At, Bt) do { __builtin_amdgcn_s_setprio(1); _Pragma("unroll") for (int m = 0; m < 4; ++m) _Pragma("unroll") for (int n = 0; n < 2; ++n) _Pragma("unroll") for (int k = 0; k < 2; ++k) \
;         acc[ai][bj][m][n] = __builtin_amdgcn_mfma_f32_16x16x32_bf16(Bt[n][k], At[m][k], acc[ai][bj][m][n], 0, 0, 0); __builtin_amdgcn_s_setprio(0); } while (0)
; #define PG8_WAIT_V(n) asm volatile("s_waitcnt vmcnt(" #n ")" ::: "memory")
; #define PG8_WAIT_L(n) asm volatile("s_waitcnt lgkmcnt(" #n ")" ::: "memory")
; #define PG8_BAR __builtin_amdgcn_s_barrier()
; #define PG8_SCHED __builtin_amdgcn_sched_barrier(0)
; template <class Epi, class Sched>
; __device__ __forceinline__ void gemm_phase(PG8_LAS unsigned char* lds, const Gemm g, const Sched& S, const Epi& E) {
;     ...
;             PG8_WAIT_V(6); PG8_BAR; PG8_MMA(1, 1, At, B1); PG8_BAR;
;             PG8_LDB(B0, 1, 0); PG8_SCHED; PG8_LDA(At, 1, 0); PG8_STAGE(PG8_SA(0, 1), a2 + hstep, voffA);
;             PG8_WAIT_L(8); PG8_BAR; PG8_WAIT_L(0); PG8_MMA(0, 0, At, B0); PG8_BAR; PG8_SCHED;
;             PG8_LDB(B1, 1, 1); PG8_STAGE(PG8_SB(1, 0), b3, voffB);
;             PG8_BAR; PG8_WAIT_L(0); PG8_MMA(0, 1, At, B1); PG8_BAR;
;             PG8_LDA(At, 1, 1); PG8_STAGE(PG8_SA(1, 0), a3, voffA);
;             PG8_BAR; PG8_WAIT_L(0); PG8_MMA(1, 0, At, B0); PG8_BAR; PG8_SCHED;
;             PG8_STAGE(PG8_SB(1, 1), b3 + hstep, voffB);
	v_mfma_f32_16x16x32_bf16 v[52:55], v[214:217], v[170:173], v[52:55]
	v_mfma_f32_16x16x32_bf16 v[48:51], v[222:225], v[170:173], v[48:51]
	v_mfma_f32_16x16x32_bf16 v[36:39], v[214:217], v[190:193], v[36:39]
	v_mfma_f32_16x16x32_bf16 v[32:35], v[222:225], v[190:193], v[32:35]
	v_mfma_f32_16x16x32_bf16 v[20:23], v[214:217], v[198:201], v[20:23]
	v_mfma_f32_16x16x32_bf16 v[16:19], v[222:225], v[198:201], v[16:19]
	v_mfma_f32_16x16x32_bf16 v[4:7], v[214:217], v[206:209], v[4:7]
	v_mfma_f32_16x16x32_bf16 v[0:3], v[222:225], v[206:209], v[0:3]
	v_mfma_f32_16x16x32_bf16 v[52:55], v[218:221], v[182:185], v[52:55]
	v_mfma_f32_16x16x32_bf16 v[48:51], v[226:229], v[182:185], v[48:51]
	v_mfma_f32_16x16x32_bf16 v[36:39], v[218:221], v[194:197], v[36:39]
	v_mfma_f32_16x16x32_bf16 v[32:35], v[226:229], v[194:197], v[32:35]
	v_mfma_f32_16x16x32_bf16 v[20:23], v[218:221], v[202:205], v[20:23]
	v_mfma_f32_16x16x32_bf16 v[16:19], v[226:229], v[202:205], v[16:19]
	v_mfma_f32_16x16x32_bf16 v[4:7], v[218:221], v[210:213], v[4:7]
	v_mfma_f32_16x16x32_bf16 v[0:3], v[226:229], v[210:213], v[0:3]
	s_add_i32 s49, 0, 0x18000
	v_add_u32_e32 v155, s49, v149
	s_barrier
	ds_read_b128 v[144:147], v155
	ds_read_b128 v[156:159], v155 offset:1024
	ds_read_b128 v[160:163], v155 offset:2048
	ds_read_b128 v[166:169], v155 offset:3072
	s_add_u32 s22, s22, 0x40000
	s_addc_u32 s23, s23, 0
	s_mov_b32 m0, s34
	v_lshl_add_u64 v[214:215], s[22:23], 0, v[128:129]
	ds_read_b128 v[170:173], v153 offset:32768
	ds_read_b128 v[182:185], v153 offset:33792
	ds_read_b128 v[190:193], v153 offset:34816
	ds_read_b128 v[194:197], v153 offset:35840
	ds_read_b128 v[198:201], v153 offset:36864
	ds_read_b128 v[202:205], v153 offset:37888
	ds_read_b128 v[206:209], v153 offset:38912
	ds_read_b128 v[210:213], v153 offset:39936
	global_load_lds_dwordx4 v[214:215], off
	v_lshl_add_u64 v[214:215], s[22:23], 0, v[132:133]
	s_mov_b32 m0, s35
	s_nop 0
	global_load_lds_dwordx4 v[214:215], off
	s_waitcnt lgkmcnt(0)
	s_barrier
	v_mfma_f32_16x16x32_bf16 v[124:127], v[144:147], v[170:173], v[124:127]
	v_mfma_f32_16x16x32_bf16 v[120:123], v[160:163], v[170:173], v[120:123]
	v_mfma_f32_16x16x32_bf16 v[108:111], v[144:147], v[190:193], v[108:111]
	v_mfma_f32_16x16x32_bf16 v[104:107], v[160:163], v[190:193], v[104:107]
	v_mfma_f32_16x16x32_bf16 v[92:95], v[144:147], v[198:201], v[92:95]
	v_mfma_f32_16x16x32_bf16 v[88:91], v[160:163], v[198:201], v[88:91]
	v_mfma_f32_16x16x32_bf16 v[76:79], v[144:147], v[206:209], v[76:79]
	v_mfma_f32_16x16x32_bf16 v[72:75], v[160:163], v[206:209], v[72:75]
	v_mfma_f32_16x16x32_bf16 v[124:127], v[156:159], v[182:185], v[124:127]
	v_mfma_f32_16x16x32_bf16 v[120:123], v[166:169], v[182:185], v[120:123]
	v_mfma_f32_16x16x32_bf16 v[108:111], v[156:159], v[194:197], v[108:111]
	v_mfma_f32_16x16x32_bf16 v[104:107], v[166:169], v[194:197], v[104:107]
	v_mfma_f32_16x16x32_bf16 v[92:95], v[156:159], v[202:205], v[92:95]
	v_mfma_f32_16x16x32_bf16 v[88:91], v[166:169], v[202:205], v[88:91]
	v_mfma_f32_16x16x32_bf16 v[76:79], v[156:159], v[210:213], v[76:79]
	v_mfma_f32_16x16x32_bf16 v[72:75], v[166:169], v[210:213], v[72:75]
	s_barrier
	s_add_i32 s22, 0, 0x1c000
	s_add_i32 s23, s49, s30
	v_add_u32_e32 v155, s22, v149
	v_lshl_add_u64 v[174:175], v[174:175], 0, s[6:7]
	s_mov_b32 m0, s23
	ds_read_b128 v[214:217], v155
	ds_read_b128 v[218:221], v155 offset:1024
	ds_read_b128 v[222:225], v155 offset:2048
	ds_read_b128 v[226:229], v155 offset:3072
	global_load_lds_dwordx4 v[174:175], off
	v_lshl_add_u64 v[174:175], v[186:187], 0, s[6:7]
	s_add_i32 m0, s23, 0x2000
	s_nop 0
	global_load_lds_dwordx4 v[174:175], off
	s_waitcnt lgkmcnt(0)
	s_barrier
	v_mfma_f32_16x16x32_bf16 v[116:119], v[214:217], v[170:173], v[116:119]
	v_mfma_f32_16x16x32_bf16 v[112:115], v[222:225], v[170:173], v[112:115]
	v_mfma_f32_16x16x32_bf16 v[100:103], v[214:217], v[190:193], v[100:103]
	v_mfma_f32_16x16x32_bf16 v[96:99], v[222:225], v[190:193], v[96:99]
	v_mfma_f32_16x16x32_bf16 v[84:87], v[214:217], v[198:201], v[84:87]
	v_mfma_f32_16x16x32_bf16 v[80:83], v[222:225], v[198:201], v[80:83]
	v_mfma_f32_16x16x32_bf16 v[68:71], v[214:217], v[206:209], v[68:71]
	v_mfma_f32_16x16x32_bf16 v[64:67], v[222:225], v[206:209], v[64:67]
	v_mfma_f32_16x16x32_bf16 v[116:119], v[218:221], v[182:185], v[116:119]
	v_mfma_f32_16x16x32_bf16 v[112:115], v[226:229], v[182:185], v[112:115]
	v_mfma_f32_16x16x32_bf16 v[100:103], v[218:221], v[194:197], v[100:103]
	v_mfma_f32_16x16x32_bf16 v[96:99], v[226:229], v[194:197], v[96:99]
	v_mfma_f32_16x16x32_bf16 v[84:87], v[218:221], v[202:205], v[84:87]
	v_mfma_f32_16x16x32_bf16 v[80:83], v[226:229], v[202:205], v[80:83]
	v_mfma_f32_16x16x32_bf16 v[68:71], v[218:221], v[210:213], v[68:71]
	v_mfma_f32_16x16x32_bf16 v[64:67], v[226:229], v[210:213], v[64:67]
	s_mov_b32 m0, s37
	v_lshl_add_u64 v[174:175], v[230:231], 0, s[6:7]
	s_barrier
	ds_read_b128 v[170:173], v153 offset:49152
	ds_read_b128 v[182:185], v153 offset:50176
	ds_read_b128 v[190:193], v153 offset:51200
	ds_read_b128 v[194:197], v153 offset:52224
	ds_read_b128 v[198:201], v153 offset:53248
	ds_read_b128 v[202:205], v153 offset:54272
	ds_read_b128 v[206:209], v153 offset:55296
	ds_read_b128 v[210:213], v153 offset:56320
	global_load_lds_dwordx4 v[174:175], off
	v_lshl_add_u64 v[174:175], v[232:233], 0, s[6:7]
	s_mov_b32 m0, s38
	s_nop 0
	global_load_lds_dwordx4 v[174:175], off
	s_waitcnt lgkmcnt(0)
	s_barrier
; #define PG8_STAGE(bufoff, gbase, voff) do { _Pragma("unroll") for (int _i = 0; _i < 2; ++_i) \
;         __builtin_amdgcn_global_load_lds((const unsigned*)((const char*)(gbase) + (voff)[_i]), (PG8_LAS unsigned*)(lds + (bufoff) + ldsw + _i * 8192), 16, 0, 0); } while (0)
; #define PG8_LDA(dst, b, h) do { _Pragma("unroll") for (int m = 0; m < 4; ++m) _Pragma("unroll") for (int k = 0; k < 2; ++k) dst[m][k] = *(const PG8_LAS bf16x8*)(lds + PG8_SA(b, h) + aoff + m * 2048 + k * 1024); } while (0)
; #define PG8_LDB(dst, b, h) do { _Pragma("unroll") for (int n = 0; n < 2; ++n) _Pragma("unroll") for (int k = 0; k < 2; ++k) dst[n][k] = *(const PG8_LAS bf16x8*)(lds + PG8_SB(b, h) + boff + n * 2048 + k * 1024); } while (0)
; #define PG8_MMA(ai, bj, At, Bt) do { __builtin_amdgcn_s_setprio(1); _Pragma("unroll") for (int m = 0; m < 4; ++m) _Pragma("unroll") for (int n = 0; n < 2; ++n) _Pragma("unroll") for (int k = 0; k < 2; ++k) \
;         acc[ai][bj][m][n] = __builtin_amdgcn_mfma_f32_16x16x32_bf16(Bt[n][k], At[m][k], acc[ai][bj][m][n], 0, 0, 0); __builtin_amdgcn_s_setprio(0); } while (0)
; #define PG8_WAIT_V(n) asm volatile("s_waitcnt vmcnt(" #n ")" ::: "memory")
; #define PG8_WAIT_L(n) asm volatile("s_waitcnt lgkmcnt(" #n ")" ::: "memory")
; #define PG8_BAR __builtin_amdgcn_s_barrier()
; #define PG8_SCHED __builtin_amdgcn_sched_barrier(0)
; __device__ __forceinline__ f32x4 sigmoid4(f32x4 x) {
;     f32x4 d;
; #pragma unroll
;     for (int j = 0; j < 4; ++j) d[j] = 1.0f + __expf(-fmaxf(x[j], -20.0f));
;     const float p01 = d[0] * d[1], p23 = d[2] * d[3], r = __builtin_amdgcn_rcpf(p01 * p23), r01 = r * p23, r23 = r * p01;
;     return (f32x4){r01 * d[1], r01 * d[0], r23 * d[3], r23 * d[2]};
; }
; template <class Epi, class Sched>
; __device__ __forceinline__ void gemm_phase(PG8_LAS unsigned char* lds, const Gemm g, const Sched& S, const Epi& E) {
;     ...
;             PG8_WAIT_L(8); PG8_BAR; PG8_WAIT_L(0); PG8_MMA(0, 0, At, B0); PG8_BAR; PG8_SCHED;
;             PG8_LDB(B1, 1, 1); PG8_STAGE(PG8_SB(1, 0), b3, voffB);
;             PG8_BAR; PG8_WAIT_L(0); PG8_MMA(0, 1, At, B1); PG8_BAR;
;             PG8_LDA(At, 1, 1); PG8_STAGE(PG8_SA(1, 0), a3, voffA);
;             PG8_BAR; PG8_WAIT_L(0); PG8_MMA(1, 0, At, B0); PG8_BAR; PG8_SCHED;
;             PG8_STAGE(PG8_SB(1, 1), b3 + hstep, voffB);
;             PG8_WAIT_V(6); PG8_BAR; PG8_MMA(1, 1, At, B1); PG8_BAR;
	v_mfma_f32_16x16x32_bf16 v[60:63], v[144:147], v[170:173], v[60:63]
	v_mfma_f32_16x16x32_bf16 v[56:59], v[160:163], v[170:173], v[56:59]
	v_mfma_f32_16x16x32_bf16 v[44:47], v[144:147], v[190:193], v[44:47]
	v_mfma_f32_16x16x32_bf16 v[40:43], v[160:163], v[190:193], v[40:43]
	v_mfma_f32_16x16x32_bf16 v[28:31], v[144:147], v[198:201], v[28:31]
	v_mfma_f32_16x16x32_bf16 v[24:27], v[160:163], v[198:201], v[24:27]
	v_mfma_f32_16x16x32_bf16 v[12:15], v[144:147], v[206:209], v[12:15]
	v_mfma_f32_16x16x32_bf16 v[8:11], v[160:163], v[206:209], v[8:11]
	v_mfma_f32_16x16x32_bf16 v[60:63], v[156:159], v[182:185], v[60:63]
	v_mfma_f32_16x16x32_bf16 v[56:59], v[166:169], v[182:185], v[56:59]
	v_mfma_f32_16x16x32_bf16 v[44:47], v[156:159], v[194:197], v[44:47]
	v_mfma_f32_16x16x32_bf16 v[40:43], v[166:169], v[194:197], v[40:43]
	v_mfma_f32_16x16x32_bf16 v[28:31], v[156:159], v[202:205], v[28:31]
	v_mfma_f32_16x16x32_bf16 v[24:27], v[166:169], v[202:205], v[24:27]
	v_mfma_f32_16x16x32_bf16 v[12:15], v[156:159], v[210:213], v[12:15]
	v_mfma_f32_16x16x32_bf16 v[8:11], v[166:169], v[210:213], v[8:11]
	s_barrier
	s_add_u32 s20, s20, 0x40080
	s_addc_u32 s21, s21, 0
	s_add_i32 s22, s22, s30
	v_lshl_add_u64 v[144:145], s[20:21], 0, v[130:131]
	s_mov_b32 m0, s22
	s_nop 0
	global_load_lds_dwordx4 v[144:145], off
	v_lshl_add_u64 v[144:145], s[20:21], 0, v[134:135]
	s_add_i32 m0, s22, 0x2000
	s_nop 0
	global_load_lds_dwordx4 v[144:145], off
	s_waitcnt vmcnt(6)
	s_barrier
	v_mfma_f32_16x16x32_bf16 v[52:55], v[214:217], v[170:173], v[52:55]
	v_mfma_f32_16x16x32_bf16 v[48:51], v[222:225], v[170:173], v[48:51]
	v_mfma_f32_16x16x32_bf16 v[36:39], v[214:217], v[190:193], v[36:39]
	v_mfma_f32_16x16x32_bf16 v[32:35], v[222:225], v[190:193], v[32:35]
	v_mfma_f32_16x16x32_bf16 v[20:23], v[214:217], v[198:201], v[20:23]
	v_mfma_f32_16x16x32_bf16 v[16:19], v[222:225], v[198:201], v[16:19]
	v_mfma_f32_16x16x32_bf16 v[4:7], v[214:217], v[206:209], v[4:7]
	v_mfma_f32_16x16x32_bf16 v[0:3], v[222:225], v[206:209], v[0:3]
	v_mfma_f32_16x16x32_bf16 v[52:55], v[218:221], v[182:185], v[52:55]
	v_mfma_f32_16x16x32_bf16 v[48:51], v[226:229], v[182:185], v[48:51]
	v_mfma_f32_16x16x32_bf16 v[36:39], v[218:221], v[194:197], v[36:39]
	v_mfma_f32_16x16x32_bf16 v[32:35], v[226:229], v[194:197], v[32:35]
	v_mfma_f32_16x16x32_bf16 v[20:23], v[218:221], v[202:205], v[20:23]
	v_mfma_f32_16x16x32_bf16 v[16:19], v[226:229], v[202:205], v[16:19]
	v_mfma_f32_16x16x32_bf16 v[4:7], v[218:221], v[210:213], v[4:7]
	v_mfma_f32_16x16x32_bf16 v[0:3], v[226:229], v[210:213], v[0:3]
	s_add_i32 s48, s48, 2
	s_add_u32 s18, s18, 0x100
	s_addc_u32 s19, s19, 0
	s_add_u32 s46, s46, 0x100
	s_addc_u32 s47, s47, 0
	s_cmp_gt_u32 s48, 13
	s_barrier
	s_cbranch_scc0 .LBB0_724
	s_cmp_gt_i32 s4, 5
	s_cselect_b64 s[18:19], -1, 0
	s_cmp_lt_i32 s4, 6
	v_pk_add_f32 v[144:145], v[126:127], 0 op_sel_hi:[1,0]
	v_pk_add_f32 v[146:147], v[124:125], 0 op_sel_hi:[1,0]
	v_pk_add_f32 v[124:125], v[122:123], 0 op_sel_hi:[1,0]
	v_pk_add_f32 v[126:127], v[120:121], 0 op_sel_hi:[1,0]
	s_cbranch_scc1 .LBB0_727
	v_max_f32_e32 v122, v144, v144
	v_max_f32_e32 v122, 0xc1a00000, v122
	v_mul_f32_e32 v122, 0xbfb8aa3b, v122
	v_max_f32_e32 v120, v146, v146
	v_max_f32_e32 v121, v147, v147
	v_exp_f32_e32 v123, v122
	v_max_f32_e32 v122, v145, v145
	v_max_f32_e32 v120, 0xc1a00000, v120
	v_max_f32_e32 v121, 0xc1a00000, v121
	v_max_f32_e32 v122, 0xc1a00000, v122
	v_mul_f32_e32 v120, 0xbfb8aa3b, v120
	v_mul_f32_e32 v121, 0xbfb8aa3b, v121
	v_mul_f32_e32 v122, 0xbfb8aa3b, v122
	v_exp_f32_e32 v120, v120
	v_exp_f32_e32 v121, v121
	v_exp_f32_e32 v122, v122
	v_max_f32_e32 v124, v124, v124
	v_max_f32_e32 v124, 0xc1a00000, v124
	v_pk_add_f32 v[120:121], v[120:121], 1.0 op_sel_hi:[1,0]
	v_pk_add_f32 v[122:123], v[122:123], 1.0 op_sel_hi:[1,0]
	v_mov_b32_e32 v144, v120
	v_mov_b32_e32 v145, v123
	v_pk_mov_b32 v[146:147], v[120:121], v[122:123] op_sel:[1,0]
	v_mul_f32_e32 v124, 0xbfb8aa3b, v124
	v_pk_mul_f32 v[144:145], v[144:145], v[146:147]
	v_max_f32_e32 v126, v126, v126
	v_max_f32_e32 v127, v127, v127
	v_exp_f32_e32 v147, v124
	v_max_f32_e32 v124, v125, v125
	v_max_f32_e32 v126, 0xc1a00000, v126
	v_max_f32_e32 v127, 0xc1a00000, v127
	v_max_f32_e32 v124, 0xc1a00000, v124
	v_mul_f32_e32 v146, v144, v145
	v_mul_f32_e32 v126, 0xbfb8aa3b, v126
	v_mul_f32_e32 v127, 0xbfb8aa3b, v127
	v_mul_f32_e32 v124, 0xbfb8aa3b, v124
	v_rcp_f32_e32 v155, v146
	v_exp_f32_e32 v126, v126
	v_exp_f32_e32 v127, v127
	v_exp_f32_e32 v146, v124
	v_mul_f32_e32 v124, v145, v155
	v_mul_f32_e32 v144, v144, v155
	v_pk_add_f32 v[126:127], v[126:127], 1.0 op_sel_hi:[1,0]
	v_pk_add_f32 v[156:157], v[146:147], 1.0 op_sel_hi:[1,0]
	v_mov_b32_e32 v146, v126
	v_mov_b32_e32 v147, v157
	v_pk_mov_b32 v[158:159], v[126:127], v[156:157] op_sel:[1,0]
	v_pk_mul_f32 v[144:145], v[122:123], v[144:145] op_sel_hi:[1,0]
	v_pk_mul_f32 v[158:159], v[146:147], v[158:159]
	s_nop 0
	v_mul_f32_e32 v125, v158, v159
	v_rcp_f32_e32 v125, v125
	s_nop 0
	v_pk_mul_f32 v[146:147], v[120:121], v[124:125] op_sel:[1,0] op_sel_hi:[0,0]
	v_mul_f32_e32 v120, v159, v125
	v_mul_f32_e32 v122, v158, v125
	v_pk_mul_f32 v[124:125], v[156:157], v[122:123] op_sel_hi:[1,0]
	v_pk_mul_f32 v[126:127], v[126:127], v[120:121] op_sel:[1,0] op_sel_hi:[0,0]

; #define PG8_STAGE(bufoff, gbase, voff) do { _Pragma("unroll") for (int _i = 0; _i < 2; ++_i) \
;         __builtin_amdgcn_global_load_lds((const unsigned*)((const char*)(gbase) + (voff)[_i]), (PG8_LAS unsigned*)(lds + (bufoff) + ldsw + _i * 8192), 16, 0, 0); } while (0)
; #define PG8_LDA(dst, b, h) do { _Pragma("unroll") for (int m = 0; m < 4; ++m) _Pragma("unroll") for (int k = 0; k < 2; ++k) dst[m][k] = *(const PG8_LAS bf16x8*)(lds + PG8_SA(b, h) + aoff + m * 2048 + k * 1024); } while (0)
; #define PG8_LDB(dst, b, h) do { _Pragma("unroll") for (int n = 0; n < 2; ++n) _Pragma("unroll") for (int k = 0; k < 2; ++k) dst[n][k] = *(const PG8_LAS bf16x8*)(lds + PG8_SB(b, h) + boff + n * 2048 + k * 1024); } while (0)
; #define PG8_MMA(ai, bj, At, Bt) do { __builtin_amdgcn_s_setprio(1); _Pragma("unroll") for (int m = 0; m < 4; ++m) _Pragma("unroll") for (int n = 0; n < 2; ++n) _Pragma("unroll") for (int k = 0; k < 2; ++k) \
;         acc[ai][bj][m][n] = __builtin_amdgcn_mfma_f32_16x16x32_bf16(Bt[n][k], At[m][k], acc[ai][bj][m][n], 0, 0, 0); __builtin_amdgcn_s_setprio(0); } while (0)
; #define PG8_WAIT_V(n) asm volatile("s_waitcnt vmcnt(" #n ")" ::: "memory")
; #define PG8_WAIT_L(n) asm volatile("s_waitcnt lgkmcnt(" #n ")" ::: "memory")
; #define PG8_BAR __builtin_amdgcn_s_barrier()
; #define PG8_SCHED __builtin_amdgcn_sched_barrier(0)
; template <class Epi, class Sched>
; __device__ __forceinline__ void gemm_phase(PG8_LAS unsigned char* lds, const Gemm g, const Sched& S, const Epi& E) {
;     ...
;             PG8_LDB(B0, 0, 0); PG8_SCHED; PG8_LDA(At, 0, 0); PG8_STAGE(PG8_SA(1, 1), a1 + hstep, voffA);
;             PG8_WAIT_L(8); PG8_BAR; PG8_WAIT_L(0); PG8_MMA(0, 0, At, B0); PG8_BAR; PG8_SCHED;
;             PG8_LDB(B1, 0, 1); PG8_STAGE(PG8_SB(0, 0), b2, voffB);
;             PG8_BAR; PG8_WAIT_L(0); PG8_MMA(0, 1, At, B1); PG8_BAR;
;             PG8_LDA(At, 0, 1); PG8_STAGE(PG8_SA(0, 0), a2, voffA);
;             PG8_BAR; PG8_WAIT_L(0); PG8_MMA(1, 0, At, B0); PG8_BAR; PG8_SCHED;
;             PG8_STAGE(PG8_SB(0, 1), b2 + hstep, voffB);
;             PG8_WAIT_V(6); PG8_BAR; PG8_MMA(1, 1, At, B1); PG8_BAR;
.LBB0_991:
	ds_read_b128 v[144:147], v153
	ds_read_b128 v[156:159], v153 offset:1024
	ds_read_b128 v[160:163], v153 offset:2048
	ds_read_b128 v[164:167], v153 offset:3072
	s_add_u32 s20, s18, 0xfffc0080
	s_addc_u32 s21, s19, -1
	s_cmp_eq_u32 s47, 12
	s_cselect_b32 s23, s11, s21
	s_cselect_b32 s22, s43, s20
	s_cselect_b32 s21, s9, s46
	s_cselect_b32 s20, s44, s45
	v_lshl_add_u64 v[148:149], s[18:19], 0, v[136:137]
	s_add_i32 m0, s17, 0xc000
	ds_read_b128 v[168:171], v154
	ds_read_b128 v[172:175], v154 offset:1024
	ds_read_b128 v[182:185], v154 offset:2048
	ds_read_b128 v[190:193], v154 offset:3072
	ds_read_b128 v[194:197], v154 offset:4096
	ds_read_b128 v[198:201], v154 offset:5120
	ds_read_b128 v[202:205], v154 offset:6144
	ds_read_b128 v[206:209], v154 offset:7168
	global_load_lds_dwordx4 v[148:149], off
	v_lshl_add_u64 v[148:149], s[18:19], 0, v[138:139]
	s_add_i32 m0, s17, 0xe000
	s_nop 0
	global_load_lds_dwordx4 v[148:149], off
	s_waitcnt lgkmcnt(0)
	s_barrier
	v_mfma_f32_16x16x32_bf16 v[124:127], v[144:147], v[168:171], v[124:127]
	v_mfma_f32_16x16x32_bf16 v[120:123], v[160:163], v[168:171], v[120:123]
	v_mfma_f32_16x16x32_bf16 v[112:115], v[144:147], v[182:185], v[112:115]
	v_mfma_f32_16x16x32_bf16 v[104:107], v[160:163], v[182:185], v[104:107]
	v_mfma_f32_16x16x32_bf16 v[96:99], v[144:147], v[194:197], v[96:99]
	v_mfma_f32_16x16x32_bf16 v[88:91], v[160:163], v[194:197], v[88:91]
	v_mfma_f32_16x16x32_bf16 v[80:83], v[144:147], v[202:205], v[80:83]
	v_mfma_f32_16x16x32_bf16 v[72:75], v[160:163], v[202:205], v[72:75]
	v_mfma_f32_16x16x32_bf16 v[124:127], v[156:159], v[172:175], v[124:127]
	v_mfma_f32_16x16x32_bf16 v[120:123], v[164:167], v[172:175], v[120:123]
	v_mfma_f32_16x16x32_bf16 v[112:115], v[156:159], v[190:193], v[112:115]
	v_mfma_f32_16x16x32_bf16 v[104:107], v[164:167], v[190:193], v[104:107]
	v_mfma_f32_16x16x32_bf16 v[96:99], v[156:159], v[198:201], v[96:99]
	v_mfma_f32_16x16x32_bf16 v[88:91], v[164:167], v[198:201], v[88:91]
	v_mfma_f32_16x16x32_bf16 v[80:83], v[156:159], v[206:209], v[80:83]
	v_mfma_f32_16x16x32_bf16 v[72:75], v[164:167], v[206:209], v[72:75]
	s_barrier
	s_add_i32 s48, s39, s29
	v_lshl_add_u64 v[148:149], s[20:21], 0, v[130:131]
	s_mov_b32 m0, s48
	ds_read_b128 v[210:213], v155
	ds_read_b128 v[214:217], v155 offset:1024
	ds_read_b128 v[218:221], v155 offset:2048
	ds_read_b128 v[222:225], v155 offset:3072
	global_load_lds_dwordx4 v[148:149], off
	v_lshl_add_u64 v[186:187], s[20:21], 0, v[134:135]
	s_add_i32 m0, s48, 0x2000
	s_nop 0
	global_load_lds_dwordx4 v[186:187], off
	s_waitcnt lgkmcnt(0)
	s_barrier
	v_mfma_f32_16x16x32_bf16 v[116:119], v[210:213], v[168:171], v[116:119]
	v_mfma_f32_16x16x32_bf16 v[108:111], v[218:221], v[168:171], v[108:111]
	v_mfma_f32_16x16x32_bf16 v[100:103], v[210:213], v[182:185], v[100:103]
	v_mfma_f32_16x16x32_bf16 v[92:95], v[218:221], v[182:185], v[92:95]
	v_mfma_f32_16x16x32_bf16 v[84:87], v[210:213], v[194:197], v[84:87]
	v_mfma_f32_16x16x32_bf16 v[76:79], v[218:221], v[194:197], v[76:79]
	v_mfma_f32_16x16x32_bf16 v[68:71], v[210:213], v[202:205], v[68:71]
	v_mfma_f32_16x16x32_bf16 v[64:67], v[218:221], v[202:205], v[64:67]
	v_mfma_f32_16x16x32_bf16 v[116:119], v[214:217], v[172:175], v[116:119]
	v_mfma_f32_16x16x32_bf16 v[108:111], v[222:225], v[172:175], v[108:111]
	v_mfma_f32_16x16x32_bf16 v[100:103], v[214:217], v[190:193], v[100:103]
	v_mfma_f32_16x16x32_bf16 v[92:95], v[222:225], v[190:193], v[92:95]
	v_mfma_f32_16x16x32_bf16 v[84:87], v[214:217], v[198:201], v[84:87]
	v_mfma_f32_16x16x32_bf16 v[76:79], v[222:225], v[198:201], v[76:79]
	v_mfma_f32_16x16x32_bf16 v[68:71], v[214:217], v[206:209], v[68:71]
	v_mfma_f32_16x16x32_bf16 v[64:67], v[222:225], v[206:209], v[64:67]
	s_mov_b32 m0, s17
	v_lshl_add_u64 v[226:227], s[22:23], 0, v[128:129]
	s_barrier
	ds_read_b128 v[168:171], v154 offset:16384
	ds_read_b128 v[172:175], v154 offset:17408
	ds_read_b128 v[182:185], v154 offset:18432
	ds_read_b128 v[190:193], v154 offset:19456
	ds_read_b128 v[194:197], v154 offset:20480
	ds_read_b128 v[198:201], v154 offset:21504
	ds_read_b128 v[202:205], v154 offset:22528
	ds_read_b128 v[206:209], v154 offset:23552
	global_load_lds_dwordx4 v[226:227], off
	v_lshl_add_u64 v[228:229], s[22:23], 0, v[132:133]
	s_mov_b32 m0, s30
	s_nop 0
	global_load_lds_dwordx4 v[228:229], off
	s_waitcnt lgkmcnt(0)
	s_barrier
	v_mfma_f32_16x16x32_bf16 v[60:63], v[144:147], v[168:171], v[60:63]
	v_mfma_f32_16x16x32_bf16 v[56:59], v[160:163], v[168:171], v[56:59]
	v_mfma_f32_16x16x32_bf16 v[48:51], v[144:147], v[182:185], v[48:51]
	v_mfma_f32_16x16x32_bf16 v[40:43], v[160:163], v[182:185], v[40:43]
	v_mfma_f32_16x16x32_bf16 v[32:35], v[144:147], v[194:197], v[32:35]
	v_mfma_f32_16x16x32_bf16 v[24:27], v[160:163], v[194:197], v[24:27]
	v_mfma_f32_16x16x32_bf16 v[16:19], v[144:147], v[202:205], v[16:19]
	v_mfma_f32_16x16x32_bf16 v[8:11], v[160:163], v[202:205], v[8:11]
	v_mfma_f32_16x16x32_bf16 v[60:63], v[156:159], v[172:175], v[60:63]
	v_mfma_f32_16x16x32_bf16 v[56:59], v[164:167], v[172:175], v[56:59]
	v_mfma_f32_16x16x32_bf16 v[48:51], v[156:159], v[190:193], v[48:51]
	v_mfma_f32_16x16x32_bf16 v[40:43], v[164:167], v[190:193], v[40:43]
	v_mfma_f32_16x16x32_bf16 v[32:35], v[156:159], v[198:201], v[32:35]
	v_mfma_f32_16x16x32_bf16 v[24:27], v[164:167], v[198:201], v[24:27]
	v_mfma_f32_16x16x32_bf16 v[16:19], v[156:159], v[206:209], v[16:19]
	v_mfma_f32_16x16x32_bf16 v[8:11], v[164:167], v[206:209], v[8:11]
	s_barrier
	s_add_u32 s48, s20, 0x40000
	s_addc_u32 s49, s21, 0
	s_add_i32 s50, s40, s29
	v_lshl_add_u64 v[144:145], s[48:49], 0, v[130:131]
	s_mov_b32 m0, s50
	s_nop 0
	global_load_lds_dwordx4 v[144:145], off
	v_lshl_add_u64 v[144:145], s[48:49], 0, v[134:135]
	s_add_i32 m0, s50, 0x2000
	s_nop 0
	global_load_lds_dwordx4 v[144:145], off
	s_waitcnt vmcnt(6)
	s_barrier
; #define PG8_STAGE(bufoff, gbase, voff) do { _Pragma("unroll") for (int _i = 0; _i < 2; ++_i) \
;         __builtin_amdgcn_global_load_lds((const unsigned*)((const char*)(gbase) + (voff)[_i]), (PG8_LAS unsigned*)(lds + (bufoff) + ldsw + _i * 8192), 16, 0, 0); } while (0)
; #define PG8_LDA(dst, b, h) do { _Pragma("unroll") for (int m = 0; m < 4; ++m) _Pragma("unroll") for (int k = 0; k < 2; ++k) dst[m][k] = *(const PG8_LAS bf16x8*)(lds + PG8_SA(b, h) + aoff + m * 2048 + k * 1024); } while (0)
; #define PG8_LDB(dst, b, h) do { _Pragma("unroll") for (int n = 0; n < 2; ++n) _Pragma("unroll") for (int k = 0; k < 2; ++k) dst[n][k] = *(const PG8_LAS bf16x8*)(lds + PG8_SB(b, h) + boff + n * 2048 + k * 1024); } while (0)
; #define PG8_MMA(ai, bj, At, Bt) do { __builtin_amdgcn_s_setprio(1); _Pragma("unroll") for (int m = 0; m < 4; ++m) _Pragma("unroll") for (int n = 0; n < 2; ++n) _Pragma("unroll") for (int k = 0; k < 2; ++k) \
;         acc[ai][bj][m][n] = __builtin_amdgcn_mfma_f32_16x16x32_bf16(Bt[n][k], At[m][k], acc[ai][bj][m][n], 0, 0, 0); __builtin_amdgcn_s_setprio(0); } while (0)
; #define PG8_WAIT_V(n) asm volatile("s_waitcnt vmcnt(" #n ")" ::: "memory")
; #define PG8_WAIT_L(n) asm volatile("s_waitcnt lgkmcnt(" #n ")" ::: "memory")
; #define PG8_BAR __builtin_amdgcn_s_barrier()
; #define PG8_SCHED __builtin_amdgcn_sched_barrier(0)
; template <class Epi, class Sched>
; __device__ __forceinline__ void gemm_phase(PG8_LAS unsigned char* lds, const Gemm g, const Sched& S, const Epi& E) {
;     ...
;             PG8_WAIT_V(6); PG8_BAR; PG8_MMA(1, 1, At, B1); PG8_BAR;
;             PG8_LDB(B0, 1, 0); PG8_SCHED; PG8_LDA(At, 1, 0); PG8_STAGE(PG8_SA(0, 1), a2 + hstep, voffA);
;             PG8_WAIT_L(8); PG8_BAR; PG8_WAIT_L(0); PG8_MMA(0, 0, At, B0); PG8_BAR; PG8_SCHED;
;             PG8_LDB(B1, 1, 1); PG8_STAGE(PG8_SB(1, 0), b3, voffB);
;             PG8_BAR; PG8_WAIT_L(0); PG8_MMA(0, 1, At, B1); PG8_BAR;
;             PG8_LDA(At, 1, 1); PG8_STAGE(PG8_SA(1, 0), a3, voffA);
;             PG8_BAR; PG8_WAIT_L(0); PG8_MMA(1, 0, At, B0); PG8_BAR; PG8_SCHED;
;             PG8_STAGE(PG8_SB(1, 1), b3 + hstep, voffB);
	v_mfma_f32_16x16x32_bf16 v[52:55], v[210:213], v[168:171], v[52:55]
	v_mfma_f32_16x16x32_bf16 v[44:47], v[218:221], v[168:171], v[44:47]
	v_mfma_f32_16x16x32_bf16 v[36:39], v[210:213], v[182:185], v[36:39]
	v_mfma_f32_16x16x32_bf16 v[28:31], v[218:221], v[182:185], v[28:31]
	v_mfma_f32_16x16x32_bf16 v[20:23], v[210:213], v[194:197], v[20:23]
	v_mfma_f32_16x16x32_bf16 v[12:15], v[218:221], v[194:197], v[12:15]
	v_mfma_f32_16x16x32_bf16 v[4:7], v[210:213], v[202:205], v[4:7]
	v_mfma_f32_16x16x32_bf16 v[0:3], v[218:221], v[202:205], v[0:3]
	v_mfma_f32_16x16x32_bf16 v[52:55], v[214:217], v[172:175], v[52:55]
	v_mfma_f32_16x16x32_bf16 v[44:47], v[222:225], v[172:175], v[44:47]
	v_mfma_f32_16x16x32_bf16 v[36:39], v[214:217], v[190:193], v[36:39]
	v_mfma_f32_16x16x32_bf16 v[28:31], v[222:225], v[190:193], v[28:31]
	v_mfma_f32_16x16x32_bf16 v[20:23], v[214:217], v[198:201], v[20:23]
	v_mfma_f32_16x16x32_bf16 v[12:15], v[222:225], v[198:201], v[12:15]
	v_mfma_f32_16x16x32_bf16 v[4:7], v[214:217], v[206:209], v[4:7]
	v_mfma_f32_16x16x32_bf16 v[0:3], v[222:225], v[206:209], v[0:3]
	s_add_i32 s48, 0, 0x18000
	v_add_u32_e32 v164, s48, v151
	s_barrier
	ds_read_b128 v[144:147], v164
	ds_read_b128 v[156:159], v164 offset:1024
	ds_read_b128 v[160:163], v164 offset:2048
	ds_read_b128 v[164:167], v164 offset:3072
	s_add_u32 s22, s22, 0x40000
	s_addc_u32 s23, s23, 0
	s_mov_b32 m0, s31
	v_lshl_add_u64 v[210:211], s[22:23], 0, v[128:129]
	ds_read_b128 v[168:171], v154 offset:32768
	ds_read_b128 v[172:175], v154 offset:33792
	ds_read_b128 v[182:185], v154 offset:34816
	ds_read_b128 v[190:193], v154 offset:35840
	ds_read_b128 v[194:197], v154 offset:36864
	ds_read_b128 v[198:201], v154 offset:37888
	ds_read_b128 v[202:205], v154 offset:38912
	ds_read_b128 v[206:209], v154 offset:39936
	global_load_lds_dwordx4 v[210:211], off
	v_lshl_add_u64 v[210:211], s[22:23], 0, v[132:133]
	s_mov_b32 m0, s34
	s_nop 0
	global_load_lds_dwordx4 v[210:211], off
	s_waitcnt lgkmcnt(0)
	s_barrier
	v_mfma_f32_16x16x32_bf16 v[124:127], v[144:147], v[168:171], v[124:127]
	v_mfma_f32_16x16x32_bf16 v[120:123], v[160:163], v[168:171], v[120:123]
	v_mfma_f32_16x16x32_bf16 v[112:115], v[144:147], v[182:185], v[112:115]
	v_mfma_f32_16x16x32_bf16 v[104:107], v[160:163], v[182:185], v[104:107]
	v_mfma_f32_16x16x32_bf16 v[96:99], v[144:147], v[194:197], v[96:99]
	v_mfma_f32_16x16x32_bf16 v[88:91], v[160:163], v[194:197], v[88:91]
	v_mfma_f32_16x16x32_bf16 v[80:83], v[144:147], v[202:205], v[80:83]
	v_mfma_f32_16x16x32_bf16 v[72:75], v[160:163], v[202:205], v[72:75]
	v_mfma_f32_16x16x32_bf16 v[124:127], v[156:159], v[172:175], v[124:127]
	v_mfma_f32_16x16x32_bf16 v[120:123], v[164:167], v[172:175], v[120:123]
	v_mfma_f32_16x16x32_bf16 v[112:115], v[156:159], v[190:193], v[112:115]
	v_mfma_f32_16x16x32_bf16 v[104:107], v[164:167], v[190:193], v[104:107]
	v_mfma_f32_16x16x32_bf16 v[96:99], v[156:159], v[198:201], v[96:99]
	v_mfma_f32_16x16x32_bf16 v[88:91], v[164:167], v[198:201], v[88:91]
	v_mfma_f32_16x16x32_bf16 v[80:83], v[156:159], v[206:209], v[80:83]
	v_mfma_f32_16x16x32_bf16 v[72:75], v[164:167], v[206:209], v[72:75]
	s_barrier
	s_add_i32 s22, 0, 0x1c000
	s_add_i32 s23, s48, s29
	v_add_u32_e32 v179, s22, v151
	v_lshl_add_u64 v[148:149], v[148:149], 0, s[6:7]
	s_mov_b32 m0, s23
	ds_read_b128 v[210:213], v179
	ds_read_b128 v[214:217], v179 offset:1024
	ds_read_b128 v[218:221], v179 offset:2048
	ds_read_b128 v[222:225], v179 offset:3072
	global_load_lds_dwordx4 v[148:149], off
	v_lshl_add_u64 v[148:149], v[186:187], 0, s[6:7]
	s_add_i32 m0, s23, 0x2000
	s_nop 0
	global_load_lds_dwordx4 v[148:149], off
	s_waitcnt lgkmcnt(0)
	s_barrier
	v_mfma_f32_16x16x32_bf16 v[116:119], v[210:213], v[168:171], v[116:119]
	v_mfma_f32_16x16x32_bf16 v[108:111], v[218:221], v[168:171], v[108:111]
	v_mfma_f32_16x16x32_bf16 v[100:103], v[210:213], v[182:185], v[100:103]
	v_mfma_f32_16x16x32_bf16 v[92:95], v[218:221], v[182:185], v[92:95]
	v_mfma_f32_16x16x32_bf16 v[84:87], v[210:213], v[194:197], v[84:87]
	v_mfma_f32_16x16x32_bf16 v[76:79], v[218:221], v[194:197], v[76:79]
	v_mfma_f32_16x16x32_bf16 v[68:71], v[210:213], v[202:205], v[68:71]
	v_mfma_f32_16x16x32_bf16 v[64:67], v[218:221], v[202:205], v[64:67]
	v_mfma_f32_16x16x32_bf16 v[116:119], v[214:217], v[172:175], v[116:119]
	v_mfma_f32_16x16x32_bf16 v[108:111], v[222:225], v[172:175], v[108:111]
	v_mfma_f32_16x16x32_bf16 v[100:103], v[214:217], v[190:193], v[100:103]
	v_mfma_f32_16x16x32_bf16 v[92:95], v[222:225], v[190:193], v[92:95]
	v_mfma_f32_16x16x32_bf16 v[84:87], v[214:217], v[198:201], v[84:87]
	v_mfma_f32_16x16x32_bf16 v[76:79], v[222:225], v[198:201], v[76:79]
	v_mfma_f32_16x16x32_bf16 v[68:71], v[214:217], v[206:209], v[68:71]
	v_mfma_f32_16x16x32_bf16 v[64:67], v[222:225], v[206:209], v[64:67]
	s_mov_b32 m0, s36
	v_lshl_add_u64 v[148:149], v[226:227], 0, s[6:7]
	s_barrier
	ds_read_b128 v[168:171], v154 offset:49152
	ds_read_b128 v[172:175], v154 offset:50176
	ds_read_b128 v[182:185], v154 offset:51200
	ds_read_b128 v[190:193], v154 offset:52224
	ds_read_b128 v[194:197], v154 offset:53248
	ds_read_b128 v[198:201], v154 offset:54272
	ds_read_b128 v[202:205], v154 offset:55296
	ds_read_b128 v[206:209], v154 offset:56320
	global_load_lds_dwordx4 v[148:149], off
	v_lshl_add_u64 v[148:149], v[228:229], 0, s[6:7]
	s_mov_b32 m0, s37
	s_nop 0
	global_load_lds_dwordx4 v[148:149], off
	s_waitcnt lgkmcnt(0)
	s_barrier
; __device__ __forceinline__ unsigned cvt_pk_bf16(float lo, float hi) { unsigned r; asm volatile("v_cvt_pk_bf16_f32 %0, %1, %2" : "=v"(r) : "v"(lo), "v"(hi)); return r; }
; __device__ __forceinline__ float bf_lo(unsigned u) { return __uint_as_float(u << 16); }
; __device__ __forceinline__ float bf_hi(unsigned u) { return __uint_as_float(u & 0xffff0000u); }
; #define PG8_WAIT_V(n) asm volatile("s_waitcnt vmcnt(" #n ")" ::: "memory")
; #define PG8_WAIT_L(n) asm volatile("s_waitcnt lgkmcnt(" #n ")" ::: "memory")
; #define PG8_BAR __builtin_amdgcn_s_barrier()
;     __device__ __forceinline__ void operator()(const f32x4 (&acc)[2][2][4][2], const Unit& u, int wr, int wc, int fr, int fq) const {
;         const int row0 = u.pm * BM + wr * 64 + fr, col0 = u.pn * BM + wc * 32 + 8 * fq;
; #pragma unroll
;         for (int ai = 0; ai < 2; ++ai)
; #pragma unroll
;             for (int m = 0; m < 4; ++m) { const size_t r = (size_t)(row0 + ai * HALF + m * 16); bf16_t* rowp = O + r * ldc + col0; const bf16_t* gp = G + r * ldg + col0;
; #pragma unroll
;                 for (int bj = 0; bj < 2; ++bj) { const u32x4 gw = *(const u32x4*)(gp + bj * HALF);
;                     f32x4 v0 = acc[ai][bj][m][0], v1 = acc[ai][bj][m][1];
;                     v0[0] *= bf_lo(gw.x); v0[1] *= bf_hi(gw.x); v0[2] *= bf_lo(gw.y); v0[3] *= bf_hi(gw.y);
;                     v1[0] *= bf_lo(gw.z); v1[1] *= bf_hi(gw.z); v1[2] *= bf_lo(gw.w); v1[3] *= bf_hi(gw.w);
;                     if (ACCUM) { const u32x4 pw = *(const u32x4*)(rowp + bj * HALF);
;                         v0[0] += bf_lo(pw.x); v0[1] += bf_hi(pw.x); v0[2] += bf_lo(pw.y); v0[3] += bf_hi(pw.y);
;                         v1[0] += bf_lo(pw.z); v1[1] += bf_hi(pw.z); v1[2] += bf_lo(pw.w); v1[3] += bf_hi(pw.w); }
;                     u32x4 w; w.x = cvt_pk_bf16(v0[0], v0[1]); w.y = cvt_pk_bf16(v0[2], v0[3]); w.z = cvt_pk_bf16(v1[0], v1[1]); w.w = cvt_pk_bf16(v1[2], v1[3]);
;                     *(u32x4*)(rowp + bj * HALF) = w; } }
; template <class Epi, class Sched>
; __device__ __forceinline__ void gemm_phase(PG8_LAS unsigned char* lds, const Gemm g, const Sched& S, const Epi& E) {
;     ...
;             PG8_BAR; PG8_WAIT_L(0); PG8_MMA(1, 0, At, B0); PG8_BAR; PG8_SCHED;
;             PG8_STAGE(PG8_SB(1, 1), b3 + hstep, voffB);
;             PG8_WAIT_V(6); PG8_BAR; PG8_MMA(1, 1, At, B1); PG8_BAR;
	v_mfma_f32_16x16x32_bf16 v[60:63], v[144:147], v[168:171], v[60:63]
	v_mfma_f32_16x16x32_bf16 v[56:59], v[160:163], v[168:171], v[56:59]
	v_mfma_f32_16x16x32_bf16 v[48:51], v[144:147], v[182:185], v[48:51]
	v_mfma_f32_16x16x32_bf16 v[40:43], v[160:163], v[182:185], v[40:43]
	v_mfma_f32_16x16x32_bf16 v[32:35], v[144:147], v[194:197], v[32:35]
	v_mfma_f32_16x16x32_bf16 v[24:27], v[160:163], v[194:197], v[24:27]
	v_mfma_f32_16x16x32_bf16 v[16:19], v[144:147], v[202:205], v[16:19]
	v_mfma_f32_16x16x32_bf16 v[8:11], v[160:163], v[202:205], v[8:11]
	v_mfma_f32_16x16x32_bf16 v[60:63], v[156:159], v[172:175], v[60:63]
	v_mfma_f32_16x16x32_bf16 v[56:59], v[164:167], v[172:175], v[56:59]
	v_mfma_f32_16x16x32_bf16 v[48:51], v[156:159], v[190:193], v[48:51]
	v_mfma_f32_16x16x32_bf16 v[40:43], v[164:167], v[190:193], v[40:43]
	v_mfma_f32_16x16x32_bf16 v[32:35], v[156:159], v[198:201], v[32:35]
	v_mfma_f32_16x16x32_bf16 v[24:27], v[164:167], v[198:201], v[24:27]
	v_mfma_f32_16x16x32_bf16 v[16:19], v[156:159], v[206:209], v[16:19]
	v_mfma_f32_16x16x32_bf16 v[8:11], v[164:167], v[206:209], v[8:11]
	s_barrier
	s_add_u32 s20, s20, 0x40080
	s_addc_u32 s21, s21, 0
	s_add_i32 s22, s22, s29
	v_lshl_add_u64 v[144:145], s[20:21], 0, v[130:131]
	s_mov_b32 m0, s22
	s_nop 0
	global_load_lds_dwordx4 v[144:145], off
	v_lshl_add_u64 v[144:145], s[20:21], 0, v[134:135]
	s_add_i32 m0, s22, 0x2000
	s_nop 0
	global_load_lds_dwordx4 v[144:145], off
	s_waitcnt vmcnt(6)
	s_barrier
	v_mfma_f32_16x16x32_bf16 v[52:55], v[210:213], v[168:171], v[52:55]
	v_mfma_f32_16x16x32_bf16 v[44:47], v[218:221], v[168:171], v[44:47]
	v_mfma_f32_16x16x32_bf16 v[36:39], v[210:213], v[182:185], v[36:39]
	v_mfma_f32_16x16x32_bf16 v[28:31], v[218:221], v[182:185], v[28:31]
	v_mfma_f32_16x16x32_bf16 v[20:23], v[210:213], v[194:197], v[20:23]
	v_mfma_f32_16x16x32_bf16 v[12:15], v[218:221], v[194:197], v[12:15]
	v_mfma_f32_16x16x32_bf16 v[4:7], v[210:213], v[202:205], v[4:7]
	v_mfma_f32_16x16x32_bf16 v[0:3], v[218:221], v[202:205], v[0:3]
	v_mfma_f32_16x16x32_bf16 v[52:55], v[214:217], v[172:175], v[52:55]
	v_mfma_f32_16x16x32_bf16 v[44:47], v[222:225], v[172:175], v[44:47]
	v_mfma_f32_16x16x32_bf16 v[36:39], v[214:217], v[190:193], v[36:39]
	v_mfma_f32_16x16x32_bf16 v[28:31], v[222:225], v[190:193], v[28:31]
	v_mfma_f32_16x16x32_bf16 v[20:23], v[214:217], v[198:201], v[20:23]
	v_mfma_f32_16x16x32_bf16 v[12:15], v[222:225], v[198:201], v[12:15]
	v_mfma_f32_16x16x32_bf16 v[4:7], v[214:217], v[206:209], v[4:7]
	v_mfma_f32_16x16x32_bf16 v[0:3], v[222:225], v[206:209], v[0:3]
	s_add_i32 s47, s47, 2
	s_add_u32 s18, s18, 0x100
	s_addc_u32 s19, s19, 0
	s_add_u32 s45, s45, 0x100
	s_addc_u32 s46, s46, 0
	s_cmp_gt_u32 s47, 13
	s_barrier
	s_cbranch_scc0 .LBB0_991
	v_lshl_or_b32 v144, s42, 8, v152
	v_lshl_add_u32 v146, s16, 8, v150
	v_ashrrev_i32_e32 v145, 31, v144
	v_mov_b64_e32 v[148:149], s[4:5]
	v_lshlrev_b64 v[144:145], 1, v[144:145]
	v_mad_i64_i32 v[156:157], s[18:19], v146, s41, v[148:149]
	v_lshl_add_u64 v[160:161], v[156:157], 0, v[144:145]
	global_load_dwordx4 v[156:159], v[160:161], off offset:3072
	s_and_b64 vcc, exec, s[2:3]
	s_mov_b32 s42, s8
	s_mov_b32 s16, s10
	s_mov_b64 s[20:21], s[14:15]
	s_waitcnt vmcnt(0)
	v_lshlrev_b32_e32 v147, 16, v156
	v_and_b32_e32 v156, 0xffff0000, v156
	v_lshlrev_b32_e32 v162, 16, v157
	v_and_b32_e32 v157, 0xffff0000, v157
	v_lshlrev_b32_e32 v164, 16, v159
	v_and_b32_e32 v159, 0xffff0000, v159
	v_lshlrev_b32_e32 v163, 16, v158
	v_and_b32_e32 v158, 0xffff0000, v158
	v_mul_f32_e32 v124, v124, v147
	v_mul_f32_e32 v125, v125, v156
	v_mul_f32_e32 v126, v126, v162
	v_mul_f32_e32 v127, v127, v157
	v_mul_f32_e32 v123, v123, v159
	v_mul_f32_e32 v147, v120, v163
	v_mul_f32_e32 v156, v121, v158
	v_mul_f32_e32 v157, v122, v164
	v_cvt_pk_bf16_f32 v120, v124, v125
	v_cvt_pk_bf16_f32 v121, v126, v127
	v_cvt_pk_bf16_f32 v122, v147, v156
	v_cvt_pk_bf16_f32 v123, v157, v123
	global_load_dwordx4 v[124:127], v[160:161], off offset:3328
	v_ashrrev_i32_e32 v147, 31, v146
	v_lshlrev_b64 v[158:159], 11, v[146:147]
	v_lshl_add_u64 v[158:159], s[0:1], 0, v[158:159]
	v_or_b32_e32 v156, 16, v146
	v_lshl_add_u64 v[158:159], v[158:159], 0, v[144:145]
	v_mad_i64_i32 v[160:161], s[18:19], v156, s41, v[148:149]
	global_store_dwordx4 v[158:159], v[120:123], off
	v_lshl_add_u64 v[160:161], v[160:161], 0, v[144:145]
	v_ashrrev_i32_e32 v157, 31, v156
	s_waitcnt vmcnt(0)
	v_lshlrev_b32_e32 v120, 16, v124
	v_and_b32_e32 v121, 0xffff0000, v124
	v_lshlrev_b32_e32 v122, 16, v125
	v_and_b32_e32 v123, 0xffff0000, v125
	v_lshlrev_b32_e32 v124, 16, v126
	v_and_b32_e32 v125, 0xffff0000, v126
	v_lshlrev_b32_e32 v126, 16, v127
	v_and_b32_e32 v127, 0xffff0000, v127
	v_mul_f32_e32 v116, v116, v120
	v_mul_f32_e32 v117, v117, v121
	v_mul_f32_e32 v118, v118, v122
	v_mul_f32_e32 v119, v119, v123
	v_mul_f32_e32 v111, v111, v127
	v_mul_f32_e32 v120, v108, v124
	v_mul_f32_e32 v121, v109, v125
	v_mul_f32_e32 v122, v110, v126
	v_cvt_pk_bf16_f32 v108, v116, v117
	v_cvt_pk_bf16_f32 v109, v118, v119
	v_cvt_pk_bf16_f32 v110, v120, v121
	v_cvt_pk_bf16_f32 v111, v122, v111
	global_load_dwordx4 v[116:119], v[160:161], off offset:3072
	s_nop 0
	global_store_dwordx4 v[158:159], v[108:111], off offset:256
	s_waitcnt vmcnt(0)
; __device__ __forceinline__ unsigned cvt_pk_bf16(float lo, float hi) { unsigned r; asm volatile("v_cvt_pk_bf16_f32 %0, %1, %2" : "=v"(r) : "v"(lo), "v"(hi)); return r; }
; __device__ __forceinline__ float bf_lo(unsigned u) { return __uint_as_float(u << 16); }
; __device__ __forceinline__ float bf_hi(unsigned u) { return __uint_as_float(u & 0xffff0000u); }
;     __device__ __forceinline__ void operator()(const f32x4 (&acc)[2][2][4][2], const Unit& u, int wr, int wc, int fr, int fq) const {
;     ...
;             for (int m = 0; m < 4; ++m) { const size_t r = (size_t)(row0 + ai * HALF + m * 16); bf16_t* rowp = O + r * ldc + col0; const bf16_t* gp = G + r * ldg + col0;
; #pragma unroll
;                 for (int bj = 0; bj < 2; ++bj) { const u32x4 gw = *(const u32x4*)(gp + bj * HALF);
;                     f32x4 v0 = acc[ai][bj][m][0], v1 = acc[ai][bj][m][1];
;                     v0[0] *= bf_lo(gw.x); v0[1] *= bf_hi(gw.x); v0[2] *= bf_lo(gw.y); v0[3] *= bf_hi(gw.y);
;                     v1[0] *= bf_lo(gw.z); v1[1] *= bf_hi(gw.z); v1[2] *= bf_lo(gw.w); v1[3] *= bf_hi(gw.w);
;                     if (ACCUM) { const u32x4 pw = *(const u32x4*)(rowp + bj * HALF);
;                         v0[0] += bf_lo(pw.x); v0[1] += bf_hi(pw.x); v0[2] += bf_lo(pw.y); v0[3] += bf_hi(pw.y);
;                         v1[0] += bf_lo(pw.z); v1[1] += bf_hi(pw.z); v1[2] += bf_lo(pw.w); v1[3] += bf_hi(pw.w); }
;                     u32x4 w; w.x = cvt_pk_bf16(v0[0], v0[1]); w.y = cvt_pk_bf16(v0[2], v0[3]); w.z = cvt_pk_bf16(v1[0], v1[1]); w.w = cvt_pk_bf16(v1[2], v1[3]);
;                     *(u32x4*)(rowp + bj * HALF) = w; } }
	s_nop 0
	v_lshlrev_b32_e32 v108, 16, v116
	v_and_b32_e32 v109, 0xffff0000, v116
	v_lshlrev_b32_e32 v110, 16, v117
	v_and_b32_e32 v111, 0xffff0000, v117
	v_lshlrev_b32_e32 v116, 16, v118
	v_and_b32_e32 v117, 0xffff0000, v118
	v_lshlrev_b32_e32 v118, 16, v119
	v_and_b32_e32 v119, 0xffff0000, v119
	v_mul_f32_e32 v108, v112, v108
	v_mul_f32_e32 v109, v113, v109
	v_mul_f32_e32 v110, v114, v110
	v_mul_f32_e32 v111, v115, v111
	v_mul_f32_e32 v107, v107, v119
	v_mul_f32_e32 v112, v104, v116
	v_mul_f32_e32 v113, v105, v117
	v_mul_f32_e32 v114, v106, v118
	v_cvt_pk_bf16_f32 v104, v108, v109
	v_cvt_pk_bf16_f32 v105, v110, v111
	v_cvt_pk_bf16_f32 v106, v112, v113
	v_cvt_pk_bf16_f32 v107, v114, v107
	global_load_dwordx4 v[108:111], v[160:161], off offset:3328
	v_lshlrev_b64 v[116:117], 11, v[156:157]
	v_lshl_add_u64 v[116:117], s[0:1], 0, v[116:117]
	v_or_b32_e32 v112, 32, v146
	v_lshl_add_u64 v[116:117], v[116:117], 0, v[144:145]
	v_mad_i64_i32 v[114:115], s[18:19], v112, s41, v[148:149]
	global_store_dwordx4 v[116:117], v[104:107], off
	v_lshl_add_u64 v[114:115], v[114:115], 0, v[144:145]
	v_ashrrev_i32_e32 v113, 31, v112
	s_waitcnt vmcnt(0)
	v_lshlrev_b32_e32 v104, 16, v108
	v_and_b32_e32 v105, 0xffff0000, v108
	v_lshlrev_b32_e32 v106, 16, v109
	v_and_b32_e32 v107, 0xffff0000, v109
	v_lshlrev_b32_e32 v108, 16, v110
	v_and_b32_e32 v109, 0xffff0000, v110
	v_lshlrev_b32_e32 v110, 16, v111
	v_and_b32_e32 v111, 0xffff0000, v111
	v_mul_f32_e32 v100, v100, v104
	v_mul_f32_e32 v101, v101, v105
	v_mul_f32_e32 v102, v102, v106
	v_mul_f32_e32 v103, v103, v107
	v_mul_f32_e32 v95, v95, v111
	v_mul_f32_e32 v104, v92, v108
	v_mul_f32_e32 v105, v93, v109
	v_mul_f32_e32 v106, v94, v110
	v_cvt_pk_bf16_f32 v92, v100, v101
	v_cvt_pk_bf16_f32 v93, v102, v103
	v_cvt_pk_bf16_f32 v94, v104, v105
	v_cvt_pk_bf16_f32 v95, v106, v95
	global_load_dwordx4 v[100:103], v[114:115], off offset:3072
	s_nop 0
	global_store_dwordx4 v[116:117], v[92:95], off offset:256
	s_waitcnt vmcnt(0)
	s_nop 0
	v_lshlrev_b32_e32 v92, 16, v100
	v_and_b32_e32 v93, 0xffff0000, v100
	v_lshlrev_b32_e32 v94, 16, v101
	v_and_b32_e32 v95, 0xffff0000, v101
	v_lshlrev_b32_e32 v100, 16, v102
	v_and_b32_e32 v101, 0xffff0000, v102
	v_lshlrev_b32_e32 v102, 16, v103
	v_and_b32_e32 v103, 0xffff0000, v103
	v_mul_f32_e32 v92, v96, v92
	v_mul_f32_e32 v93, v97, v93
	v_mul_f32_e32 v94, v98, v94
	v_mul_f32_e32 v95, v99, v95
	v_mul_f32_e32 v91, v91, v103
	v_mul_f32_e32 v96, v88, v100
	v_mul_f32_e32 v97, v89, v101
	v_mul_f32_e32 v98, v90, v102
	v_cvt_pk_bf16_f32 v88, v92, v93
	v_cvt_pk_bf16_f32 v89, v94, v95
	v_cvt_pk_bf16_f32 v90, v96, v97
	v_cvt_pk_bf16_f32 v91, v98, v91
	global_load_dwordx4 v[92:95], v[114:115], off offset:3328
	v_lshlrev_b64 v[100:101], 11, v[112:113]
	v_lshl_add_u64 v[100:101], s[0:1], 0, v[100:101]
	v_or_b32_e32 v96, 48, v146
	v_lshl_add_u64 v[100:101], v[100:101], 0, v[144:145]
	v_mad_i64_i32 v[98:99], s[18:19], v96, s41, v[148:149]
	global_store_dwordx4 v[100:101], v[88:91], off
	v_lshl_add_u64 v[98:99], v[98:99], 0, v[144:145]
	v_ashrrev_i32_e32 v97, 31, v96
	s_waitcnt vmcnt(0)
	v_lshlrev_b32_e32 v88, 16, v92
	v_and_b32_e32 v89, 0xffff0000, v92
	v_lshlrev_b32_e32 v90, 16, v93
	v_and_b32_e32 v91, 0xffff0000, v93
	v_lshlrev_b32_e32 v92, 16, v94
	v_and_b32_e32 v93, 0xffff0000, v94
	v_lshlrev_b32_e32 v94, 16, v95
	v_and_b32_e32 v95, 0xffff0000, v95
	v_mul_f32_e32 v84, v84, v88
	v_mul_f32_e32 v85, v85, v89
	v_mul_f32_e32 v86, v86, v90
	v_mul_f32_e32 v87, v87, v91
	v_mul_f32_e32 v79, v79, v95
	v_mul_f32_e32 v88, v76, v92
	v_mul_f32_e32 v89, v77, v93
	v_mul_f32_e32 v90, v78, v94
	v_cvt_pk_bf16_f32 v76, v84, v85
	v_cvt_pk_bf16_f32 v77, v86, v87
	v_cvt_pk_bf16_f32 v78, v88, v89
	v_cvt_pk_bf16_f32 v79, v90, v79
	global_load_dwordx4 v[84:87], v[98:99], off offset:3072
	s_nop 0
	global_store_dwordx4 v[100:101], v[76:79], off offset:256
	s_waitcnt vmcnt(0)
	s_nop 0
	v_lshlrev_b32_e32 v76, 16, v84
	v_and_b32_e32 v77, 0xffff0000, v84
	v_lshlrev_b32_e32 v78, 16, v85
	v_and_b32_e32 v79, 0xffff0000, v85
	v_lshlrev_b32_e32 v84, 16, v86
	v_and_b32_e32 v85, 0xffff0000, v86
	v_lshlrev_b32_e32 v86, 16, v87
	v_and_b32_e32 v87, 0xffff0000, v87
	v_mul_f32_e32 v76, v80, v76
	v_mul_f32_e32 v77, v81, v77
	v_mul_f32_e32 v78, v82, v78
	v_mul_f32_e32 v79, v83, v79
	v_mul_f32_e32 v75, v75, v87
	v_mul_f32_e32 v80, v72, v84
	v_mul_f32_e32 v81, v73, v85
	v_mul_f32_e32 v82, v74, v86
	v_cvt_pk_bf16_f32 v72, v76, v77
	v_cvt_pk_bf16_f32 v73, v78, v79
	v_cvt_pk_bf16_f32 v74, v80, v81
	v_cvt_pk_bf16_f32 v75, v82, v75
	global_load_dwordx4 v[76:79], v[98:99], off offset:3328
	v_lshlrev_b64 v[84:85], 11, v[96:97]
	v_lshl_add_u64 v[84:85], s[0:1], 0, v[84:85]
	v_add_u32_e32 v80, 0x80, v146
	v_lshl_add_u64 v[84:85], v[84:85], 0, v[144:145]
	v_mad_i64_i32 v[82:83], s[18:19], v80, s41, v[148:149]
	global_store_dwordx4 v[84:85], v[72:75], off
	v_lshl_add_u64 v[82:83], v[82:83], 0, v[144:145]
	v_ashrrev_i32_e32 v81, 31, v80
	s_waitcnt vmcnt(0)
	v_lshlrev_b32_e32 v72, 16, v76
	v_and_b32_e32 v73, 0xffff0000, v76
	v_lshlrev_b32_e32 v74, 16, v77
	v_and_b32_e32 v75, 0xffff0000, v77
	v_lshlrev_b32_e32 v76, 16, v78
	v_and_b32_e32 v77, 0xffff0000, v78
	v_lshlrev_b32_e32 v78, 16, v79
	v_and_b32_e32 v79, 0xffff0000, v79
	v_mul_f32_e32 v68, v68, v72
	v_mul_f32_e32 v69, v69, v73
	v_mul_f32_e32 v70, v70, v74
	v_mul_f32_e32 v71, v71, v75
	v_mul_f32_e32 v67, v67, v79
	v_mul_f32_e32 v72, v64, v76
	v_mul_f32_e32 v73, v65, v77
	v_mul_f32_e32 v74, v66, v78
	v_cvt_pk_bf16_f32 v64, v68, v69
	v_cvt_pk_bf16_f32 v65, v70, v71
	v_cvt_pk_bf16_f32 v66, v72, v73
	v_cvt_pk_bf16_f32 v67, v74, v67
	global_load_dwordx4 v[68:71], v[82:83], off offset:3072
	s_nop 0
	global_store_dwordx4 v[84:85], v[64:67], off offset:256
	s_waitcnt vmcnt(0)
; __device__ __forceinline__ unsigned cvt_pk_bf16(float lo, float hi) { unsigned r; asm volatile("v_cvt_pk_bf16_f32 %0, %1, %2" : "=v"(r) : "v"(lo), "v"(hi)); return r; }
; __device__ __forceinline__ float bf_lo(unsigned u) { return __uint_as_float(u << 16); }
; __device__ __forceinline__ float bf_hi(unsigned u) { return __uint_as_float(u & 0xffff0000u); }
;     __device__ __forceinline__ void operator()(const f32x4 (&acc)[2][2][4][2], const Unit& u, int wr, int wc, int fr, int fq) const {
;     ...
;             for (int m = 0; m < 4; ++m) { const size_t r = (size_t)(row0 + ai * HALF + m * 16); bf16_t* rowp = O + r * ldc + col0; const bf16_t* gp = G + r * ldg + col0;
; #pragma unroll
;                 for (int bj = 0; bj < 2; ++bj) { const u32x4 gw = *(const u32x4*)(gp + bj * HALF);
;                     f32x4 v0 = acc[ai][bj][m][0], v1 = acc[ai][bj][m][1];
;                     v0[0] *= bf_lo(gw.x); v0[1] *= bf_hi(gw.x); v0[2] *= bf_lo(gw.y); v0[3] *= bf_hi(gw.y);
;                     v1[0] *= bf_lo(gw.z); v1[1] *= bf_hi(gw.z); v1[2] *= bf_lo(gw.w); v1[3] *= bf_hi(gw.w);
;                     if (ACCUM) { const u32x4 pw = *(const u32x4*)(rowp + bj * HALF);
;                         v0[0] += bf_lo(pw.x); v0[1] += bf_hi(pw.x); v0[2] += bf_lo(pw.y); v0[3] += bf_hi(pw.y);
;                         v1[0] += bf_lo(pw.z); v1[1] += bf_hi(pw.z); v1[2] += bf_lo(pw.w); v1[3] += bf_hi(pw.w); }
;                     u32x4 w; w.x = cvt_pk_bf16(v0[0], v0[1]); w.y = cvt_pk_bf16(v0[2], v0[3]); w.z = cvt_pk_bf16(v1[0], v1[1]); w.w = cvt_pk_bf16(v1[2], v1[3]);
;                     *(u32x4*)(rowp + bj * HALF) = w; } }
	s_nop 0
	v_lshlrev_b32_e32 v64, 16, v68
	v_and_b32_e32 v65, 0xffff0000, v68
	v_lshlrev_b32_e32 v66, 16, v69
	v_and_b32_e32 v67, 0xffff0000, v69
	v_lshlrev_b32_e32 v68, 16, v70
	v_and_b32_e32 v69, 0xffff0000, v70
	v_lshlrev_b32_e32 v70, 16, v71
	v_and_b32_e32 v71, 0xffff0000, v71
	v_mul_f32_e32 v60, v60, v64
	v_mul_f32_e32 v61, v61, v65
	v_mul_f32_e32 v62, v62, v66
	v_mul_f32_e32 v63, v63, v67
	v_mul_f32_e32 v59, v59, v71
	v_mul_f32_e32 v64, v56, v68
	v_mul_f32_e32 v65, v57, v69
	v_mul_f32_e32 v66, v58, v70
	v_cvt_pk_bf16_f32 v56, v60, v61
	v_cvt_pk_bf16_f32 v57, v62, v63
	v_cvt_pk_bf16_f32 v58, v64, v65
	v_cvt_pk_bf16_f32 v59, v66, v59
	global_load_dwordx4 v[60:63], v[82:83], off offset:3328
	v_lshlrev_b64 v[68:69], 11, v[80:81]
	v_lshl_add_u64 v[68:69], s[0:1], 0, v[68:69]
	v_add_u32_e32 v64, 0x90, v146
	v_lshl_add_u64 v[68:69], v[68:69], 0, v[144:145]
	v_mad_i64_i32 v[66:67], s[18:19], v64, s41, v[148:149]
	global_store_dwordx4 v[68:69], v[56:59], off
	v_lshl_add_u64 v[66:67], v[66:67], 0, v[144:145]
	v_ashrrev_i32_e32 v65, 31, v64
	s_waitcnt vmcnt(0)
	v_lshlrev_b32_e32 v56, 16, v60
	v_and_b32_e32 v57, 0xffff0000, v60
	v_lshlrev_b32_e32 v58, 16, v61
	v_and_b32_e32 v59, 0xffff0000, v61
	v_lshlrev_b32_e32 v60, 16, v62
	v_and_b32_e32 v61, 0xffff0000, v62
	v_lshlrev_b32_e32 v62, 16, v63
	v_and_b32_e32 v63, 0xffff0000, v63
	v_mul_f32_e32 v52, v52, v56
	v_mul_f32_e32 v53, v53, v57
	v_mul_f32_e32 v54, v54, v58
	v_mul_f32_e32 v55, v55, v59
	v_mul_f32_e32 v47, v47, v63
	v_mul_f32_e32 v56, v44, v60
	v_mul_f32_e32 v57, v45, v61
	v_mul_f32_e32 v58, v46, v62
	v_cvt_pk_bf16_f32 v44, v52, v53
	v_cvt_pk_bf16_f32 v45, v54, v55
	v_cvt_pk_bf16_f32 v46, v56, v57
	v_cvt_pk_bf16_f32 v47, v58, v47
	global_load_dwordx4 v[52:55], v[66:67], off offset:3072
	s_nop 0
	global_store_dwordx4 v[68:69], v[44:47], off offset:256
	s_waitcnt vmcnt(0)
	s_nop 0
	v_lshlrev_b32_e32 v44, 16, v52
	v_and_b32_e32 v45, 0xffff0000, v52
	v_lshlrev_b32_e32 v46, 16, v53
	v_and_b32_e32 v47, 0xffff0000, v53
	v_lshlrev_b32_e32 v52, 16, v54
	v_and_b32_e32 v53, 0xffff0000, v54
	v_lshlrev_b32_e32 v54, 16, v55
	v_and_b32_e32 v55, 0xffff0000, v55
	v_mul_f32_e32 v44, v48, v44
	v_mul_f32_e32 v45, v49, v45
	v_mul_f32_e32 v46, v50, v46
	v_mul_f32_e32 v47, v51, v47
	v_mul_f32_e32 v43, v43, v55
	v_mul_f32_e32 v48, v40, v52
	v_mul_f32_e32 v49, v41, v53
	v_mul_f32_e32 v50, v42, v54
	v_cvt_pk_bf16_f32 v40, v44, v45
	v_cvt_pk_bf16_f32 v41, v46, v47
	v_cvt_pk_bf16_f32 v42, v48, v49
	v_cvt_pk_bf16_f32 v43, v50, v43
	global_load_dwordx4 v[44:47], v[66:67], off offset:3328
	v_lshlrev_b64 v[52:53], 11, v[64:65]
	v_lshl_add_u64 v[52:53], s[0:1], 0, v[52:53]
	v_add_u32_e32 v48, 0xa0, v146
	v_lshl_add_u64 v[52:53], v[52:53], 0, v[144:145]
	v_mad_i64_i32 v[50:51], s[18:19], v48, s41, v[148:149]
	global_store_dwordx4 v[52:53], v[40:43], off
	v_lshl_add_u64 v[50:51], v[50:51], 0, v[144:145]
	v_ashrrev_i32_e32 v49, 31, v48
	s_waitcnt vmcnt(0)
	v_lshlrev_b32_e32 v40, 16, v44
	v_and_b32_e32 v41, 0xffff0000, v44
	v_lshlrev_b32_e32 v42, 16, v45
	v_and_b32_e32 v43, 0xffff0000, v45
	v_lshlrev_b32_e32 v44, 16, v46
	v_and_b32_e32 v45, 0xffff0000, v46
	v_lshlrev_b32_e32 v46, 16, v47
	v_and_b32_e32 v47, 0xffff0000, v47
	v_mul_f32_e32 v36, v36, v40
	v_mul_f32_e32 v37, v37, v41
	v_mul_f32_e32 v38, v38, v42
	v_mul_f32_e32 v39, v39, v43
	v_mul_f32_e32 v31, v31, v47
	v_mul_f32_e32 v40, v28, v44
	v_mul_f32_e32 v41, v29, v45
	v_mul_f32_e32 v42, v30, v46
	v_cvt_pk_bf16_f32 v28, v36, v37
	v_cvt_pk_bf16_f32 v29, v38, v39
	v_cvt_pk_bf16_f32 v30, v40, v41
	v_cvt_pk_bf16_f32 v31, v42, v31
	global_load_dwordx4 v[36:39], v[50:51], off offset:3072
	s_nop 0
	global_store_dwordx4 v[52:53], v[28:31], off offset:256
	s_waitcnt vmcnt(0)
; __device__ __forceinline__ unsigned cvt_pk_bf16(float lo, float hi) { unsigned r; asm volatile("v_cvt_pk_bf16_f32 %0, %1, %2" : "=v"(r) : "v"(lo), "v"(hi)); return r; }
; __device__ __forceinline__ float bf_lo(unsigned u) { return __uint_as_float(u << 16); }
; __device__ __forceinline__ float bf_hi(unsigned u) { return __uint_as_float(u & 0xffff0000u); }
; #define PG8_WAIT_V(n) asm volatile("s_waitcnt vmcnt(" #n ")" ::: "memory")
;     __device__ __forceinline__ void operator()(const f32x4 (&acc)[2][2][4][2], const Unit& u, int wr, int wc, int fr, int fq) const {
;     ...
;             for (int m = 0; m < 4; ++m) { const size_t r = (size_t)(row0 + ai * HALF + m * 16); bf16_t* rowp = O + r * ldc + col0; const bf16_t* gp = G + r * ldg + col0;
; #pragma unroll
;                 for (int bj = 0; bj < 2; ++bj) { const u32x4 gw = *(const u32x4*)(gp + bj * HALF);
;                     f32x4 v0 = acc[ai][bj][m][0], v1 = acc[ai][bj][m][1];
;                     v0[0] *= bf_lo(gw.x); v0[1] *= bf_hi(gw.x); v0[2] *= bf_lo(gw.y); v0[3] *= bf_hi(gw.y);
;                     v1[0] *= bf_lo(gw.z); v1[1] *= bf_hi(gw.z); v1[2] *= bf_lo(gw.w); v1[3] *= bf_hi(gw.w);
;                     if (ACCUM) { const u32x4 pw = *(const u32x4*)(rowp + bj * HALF);
;                         v0[0] += bf_lo(pw.x); v0[1] += bf_hi(pw.x); v0[2] += bf_lo(pw.y); v0[3] += bf_hi(pw.y);
;                         v1[0] += bf_lo(pw.z); v1[1] += bf_hi(pw.z); v1[2] += bf_lo(pw.w); v1[3] += bf_hi(pw.w); }
;                     u32x4 w; w.x = cvt_pk_bf16(v0[0], v0[1]); w.y = cvt_pk_bf16(v0[2], v0[3]); w.z = cvt_pk_bf16(v1[0], v1[1]); w.w = cvt_pk_bf16(v1[2], v1[3]);
;                     *(u32x4*)(rowp + bj * HALF) = w; } }
; template <class Epi, class Sched>
; __device__ __forceinline__ void gemm_phase(PG8_LAS unsigned char* lds, const Gemm g, const Sched& S, const Epi& E) {
;     ...
;         if constexpr (!Epi::AFTER_DRAIN) { E(acc, cur, wr, wc, fr, fq); S.done(cur); }
;         if (!has_next) break;
; #pragma unroll
;         for (int a = 0; a < 2; ++a)
; #pragma unroll
;             for (int b = 0; b < 2; ++b)
; #pragma unroll
;                 for (int m = 0; m < 4; ++m)
; #pragma unroll
;                     for (int n = 0; n < 2; ++n) acc[a][b][m][n] = (f32x4){0.f, 0.f, 0.f, 0.f};
;         cur = nxt; cA = nA; cB = nB; ++ui;
;     }
;     PG8_WAIT_V(0);
;     if (wr == 0) PG8_BAR;
	s_nop 0
	v_lshlrev_b32_e32 v28, 16, v36
	v_and_b32_e32 v29, 0xffff0000, v36
	v_lshlrev_b32_e32 v30, 16, v37
	v_and_b32_e32 v31, 0xffff0000, v37
	v_lshlrev_b32_e32 v36, 16, v38
	v_and_b32_e32 v37, 0xffff0000, v38
	v_lshlrev_b32_e32 v38, 16, v39
	v_and_b32_e32 v39, 0xffff0000, v39
	v_mul_f32_e32 v28, v32, v28
	v_mul_f32_e32 v29, v33, v29
	v_mul_f32_e32 v30, v34, v30
	v_mul_f32_e32 v31, v35, v31
	v_mul_f32_e32 v27, v27, v39
	v_mul_f32_e32 v32, v24, v36
	v_mul_f32_e32 v33, v25, v37
	v_mul_f32_e32 v34, v26, v38
	v_cvt_pk_bf16_f32 v24, v28, v29
	v_cvt_pk_bf16_f32 v25, v30, v31
	v_cvt_pk_bf16_f32 v26, v32, v33
	v_cvt_pk_bf16_f32 v27, v34, v27
	global_load_dwordx4 v[28:31], v[50:51], off offset:3328
	v_lshlrev_b64 v[36:37], 11, v[48:49]
	v_lshl_add_u64 v[36:37], s[0:1], 0, v[36:37]
	v_add_u32_e32 v32, 0xb0, v146
	v_lshl_add_u64 v[36:37], v[36:37], 0, v[144:145]
	v_mad_i64_i32 v[34:35], s[18:19], v32, s41, v[148:149]
	global_store_dwordx4 v[36:37], v[24:27], off
	v_lshl_add_u64 v[34:35], v[34:35], 0, v[144:145]
	v_ashrrev_i32_e32 v33, 31, v32
	s_mov_b64 s[18:19], s[12:13]
	s_waitcnt vmcnt(0)
	v_lshlrev_b32_e32 v24, 16, v28
	v_and_b32_e32 v25, 0xffff0000, v28
	v_lshlrev_b32_e32 v26, 16, v29
	v_and_b32_e32 v27, 0xffff0000, v29
	v_lshlrev_b32_e32 v28, 16, v30
	v_and_b32_e32 v29, 0xffff0000, v30
	v_lshlrev_b32_e32 v30, 16, v31
	v_and_b32_e32 v31, 0xffff0000, v31
	v_mul_f32_e32 v20, v20, v24
	v_mul_f32_e32 v21, v21, v25
	v_mul_f32_e32 v22, v22, v26
	v_mul_f32_e32 v23, v23, v27
	v_mul_f32_e32 v15, v15, v31
	v_mul_f32_e32 v24, v12, v28
	v_mul_f32_e32 v25, v13, v29
	v_mul_f32_e32 v26, v14, v30
	v_cvt_pk_bf16_f32 v12, v20, v21
	v_cvt_pk_bf16_f32 v13, v22, v23
	v_cvt_pk_bf16_f32 v14, v24, v25
	v_cvt_pk_bf16_f32 v15, v26, v15
	global_load_dwordx4 v[20:23], v[34:35], off offset:3072
	s_nop 0
	global_store_dwordx4 v[36:37], v[12:15], off offset:256
	s_waitcnt vmcnt(0)
	s_nop 0
	v_lshlrev_b32_e32 v12, 16, v20
	v_and_b32_e32 v13, 0xffff0000, v20
	v_lshlrev_b32_e32 v14, 16, v21
	v_and_b32_e32 v15, 0xffff0000, v21
	v_lshlrev_b32_e32 v20, 16, v22
	v_and_b32_e32 v21, 0xffff0000, v22
	v_lshlrev_b32_e32 v22, 16, v23
	v_and_b32_e32 v23, 0xffff0000, v23
	v_mul_f32_e32 v12, v16, v12
	v_mul_f32_e32 v13, v17, v13
	v_mul_f32_e32 v14, v18, v14
	v_mul_f32_e32 v15, v19, v15
	v_mul_f32_e32 v11, v11, v23
	v_mul_f32_e32 v16, v8, v20
	v_mul_f32_e32 v17, v9, v21
	v_mul_f32_e32 v18, v10, v22
	v_cvt_pk_bf16_f32 v8, v12, v13
	v_cvt_pk_bf16_f32 v9, v14, v15
	v_cvt_pk_bf16_f32 v10, v16, v17
	v_cvt_pk_bf16_f32 v11, v18, v11
	global_load_dwordx4 v[12:15], v[34:35], off offset:3328
	v_lshlrev_b64 v[16:17], 11, v[32:33]
	v_lshl_add_u64 v[16:17], s[0:1], 0, v[16:17]
	v_lshl_add_u64 v[16:17], v[16:17], 0, v[144:145]
	global_store_dwordx4 v[16:17], v[8:11], off
	s_waitcnt vmcnt(0)
	s_nop 0
	v_lshlrev_b32_e32 v8, 16, v12
	v_and_b32_e32 v9, 0xffff0000, v12
	v_lshlrev_b32_e32 v10, 16, v13
	v_and_b32_e32 v11, 0xffff0000, v13
	v_lshlrev_b32_e32 v12, 16, v14
	v_and_b32_e32 v13, 0xffff0000, v14
	v_lshlrev_b32_e32 v14, 16, v15
	v_and_b32_e32 v15, 0xffff0000, v15
	v_mul_f32_e32 v3, v3, v15
	v_mul_f32_e32 v4, v4, v8
	v_mul_f32_e32 v5, v5, v9
	v_mul_f32_e32 v6, v6, v10
	v_mul_f32_e32 v7, v7, v11
	v_mul_f32_e32 v8, v0, v12
	v_mul_f32_e32 v9, v1, v13
	v_mul_f32_e32 v10, v2, v14
	v_cvt_pk_bf16_f32 v0, v4, v5
	v_cvt_pk_bf16_f32 v1, v6, v7
	v_cvt_pk_bf16_f32 v2, v8, v9
	v_cvt_pk_bf16_f32 v3, v10, v3
	global_store_dwordx4 v[16:17], v[0:3], off offset:256
	s_cbranch_vccz .LBB0_984
	s_waitcnt vmcnt(0)
	s_cmpk_gt_u32 s25, 0xff
	s_cbranch_scc1 .LBB0_995
	s_barrier

; #define PG8_STAGE(bufoff, gbase, voff) do { _Pragma("unroll") for (int _i = 0; _i < 2; ++_i) \
;         __builtin_amdgcn_global_load_lds((const unsigned*)((const char*)(gbase) + (voff)[_i]), (PG8_LAS unsigned*)(lds + (bufoff) + ldsw + _i * 8192), 16, 0, 0); } while (0)
; #define PG8_LDA(dst, b, h) do { _Pragma("unroll") for (int m = 0; m < 4; ++m) _Pragma("unroll") for (int k = 0; k < 2; ++k) dst[m][k] = *(const PG8_LAS bf16x8*)(lds + PG8_SA(b, h) + aoff + m * 2048 + k * 1024); } while (0)
; #define PG8_LDB(dst, b, h) do { _Pragma("unroll") for (int n = 0; n < 2; ++n) _Pragma("unroll") for (int k = 0; k < 2; ++k) dst[n][k] = *(const PG8_LAS bf16x8*)(lds + PG8_SB(b, h) + boff + n * 2048 + k * 1024); } while (0)
; #define PG8_MMA(ai, bj, At, Bt) do { __builtin_amdgcn_s_setprio(1); _Pragma("unroll") for (int m = 0; m < 4; ++m) _Pragma("unroll") for (int n = 0; n < 2; ++n) _Pragma("unroll") for (int k = 0; k < 2; ++k) \
;         acc[ai][bj][m][n] = __builtin_amdgcn_mfma_f32_16x16x32_bf16(Bt[n][k], At[m][k], acc[ai][bj][m][n], 0, 0, 0); __builtin_amdgcn_s_setprio(0); } while (0)
; #define PG8_WAIT_V(n) asm volatile("s_waitcnt vmcnt(" #n ")" ::: "memory")
; #define PG8_WAIT_L(n) asm volatile("s_waitcnt lgkmcnt(" #n ")" ::: "memory")
; #define PG8_BAR __builtin_amdgcn_s_barrier()
; #define PG8_SCHED __builtin_amdgcn_sched_barrier(0)
; template <class Epi, class Sched>
; __device__ __forceinline__ void gemm_phase(PG8_LAS unsigned char* lds, const Gemm g, const Sched& S, const Epi& E) {
;     ...
;             PG8_LDB(B0, 0, 0); PG8_SCHED; PG8_LDA(At, 0, 0); PG8_STAGE(PG8_SA(1, 1), a1 + hstep, voffA);
;             PG8_WAIT_L(8); PG8_BAR; PG8_WAIT_L(0); PG8_MMA(0, 0, At, B0); PG8_BAR; PG8_SCHED;
;             PG8_LDB(B1, 0, 1); PG8_STAGE(PG8_SB(0, 0), b2, voffB);
;             PG8_BAR; PG8_WAIT_L(0); PG8_MMA(0, 1, At, B1); PG8_BAR;
;             PG8_LDA(At, 0, 1); PG8_STAGE(PG8_SA(0, 0), a2, voffA);
;             PG8_BAR; PG8_WAIT_L(0); PG8_MMA(1, 0, At, B0); PG8_BAR; PG8_SCHED;
;             PG8_STAGE(PG8_SB(0, 1), b2 + hstep, voffB);
;             PG8_WAIT_V(6); PG8_BAR; PG8_MMA(1, 1, At, B1); PG8_BAR;
.LBB0_1011:
	ds_read_b128 v[144:147], v153
	ds_read_b128 v[156:159], v153 offset:1024
	ds_read_b128 v[160:163], v153 offset:2048
	ds_read_b128 v[164:167], v153 offset:3072
	s_add_u32 s20, s18, 0xfffc0080
	s_addc_u32 s21, s19, -1
	s_cmp_eq_u32 s47, 12
	s_cselect_b32 s23, s11, s21
	s_cselect_b32 s22, s43, s20
	s_cselect_b32 s21, s9, s46
	s_cselect_b32 s20, s44, s45
	v_lshl_add_u64 v[148:149], s[18:19], 0, v[136:137]
	s_add_i32 m0, s17, 0xc000
	ds_read_b128 v[168:171], v154
	ds_read_b128 v[172:175], v154 offset:1024
	ds_read_b128 v[182:185], v154 offset:2048
	ds_read_b128 v[190:193], v154 offset:3072
	ds_read_b128 v[194:197], v154 offset:4096
	ds_read_b128 v[198:201], v154 offset:5120
	ds_read_b128 v[202:205], v154 offset:6144
	ds_read_b128 v[206:209], v154 offset:7168
	global_load_lds_dwordx4 v[148:149], off
	v_lshl_add_u64 v[148:149], s[18:19], 0, v[138:139]
	s_add_i32 m0, s17, 0xe000
	s_nop 0
	global_load_lds_dwordx4 v[148:149], off
	s_waitcnt lgkmcnt(0)
	s_barrier
	v_mfma_f32_16x16x32_bf16 v[124:127], v[144:147], v[168:171], v[124:127]
	v_mfma_f32_16x16x32_bf16 v[120:123], v[160:163], v[168:171], v[120:123]
	v_mfma_f32_16x16x32_bf16 v[108:111], v[144:147], v[182:185], v[108:111]
	v_mfma_f32_16x16x32_bf16 v[104:107], v[160:163], v[182:185], v[104:107]
	v_mfma_f32_16x16x32_bf16 v[92:95], v[144:147], v[194:197], v[92:95]
	v_mfma_f32_16x16x32_bf16 v[88:91], v[160:163], v[194:197], v[88:91]
	v_mfma_f32_16x16x32_bf16 v[76:79], v[144:147], v[202:205], v[76:79]
	v_mfma_f32_16x16x32_bf16 v[72:75], v[160:163], v[202:205], v[72:75]
	v_mfma_f32_16x16x32_bf16 v[124:127], v[156:159], v[172:175], v[124:127]
	v_mfma_f32_16x16x32_bf16 v[120:123], v[164:167], v[172:175], v[120:123]
	v_mfma_f32_16x16x32_bf16 v[108:111], v[156:159], v[190:193], v[108:111]
	v_mfma_f32_16x16x32_bf16 v[104:107], v[164:167], v[190:193], v[104:107]
	v_mfma_f32_16x16x32_bf16 v[92:95], v[156:159], v[198:201], v[92:95]
	v_mfma_f32_16x16x32_bf16 v[88:91], v[164:167], v[198:201], v[88:91]
	v_mfma_f32_16x16x32_bf16 v[76:79], v[156:159], v[206:209], v[76:79]
	v_mfma_f32_16x16x32_bf16 v[72:75], v[164:167], v[206:209], v[72:75]
	s_barrier
	s_add_i32 s48, s39, s29
	v_lshl_add_u64 v[148:149], s[20:21], 0, v[130:131]
	s_mov_b32 m0, s48
	ds_read_b128 v[210:213], v155
	ds_read_b128 v[214:217], v155 offset:1024
	ds_read_b128 v[218:221], v155 offset:2048
	ds_read_b128 v[222:225], v155 offset:3072
	global_load_lds_dwordx4 v[148:149], off
	v_lshl_add_u64 v[186:187], s[20:21], 0, v[134:135]
	s_add_i32 m0, s48, 0x2000
	s_nop 0
	global_load_lds_dwordx4 v[186:187], off
	s_waitcnt lgkmcnt(0)
	s_barrier
	v_mfma_f32_16x16x32_bf16 v[116:119], v[210:213], v[168:171], v[116:119]
	v_mfma_f32_16x16x32_bf16 v[112:115], v[218:221], v[168:171], v[112:115]
	v_mfma_f32_16x16x32_bf16 v[100:103], v[210:213], v[182:185], v[100:103]
	v_mfma_f32_16x16x32_bf16 v[96:99], v[218:221], v[182:185], v[96:99]
	v_mfma_f32_16x16x32_bf16 v[84:87], v[210:213], v[194:197], v[84:87]
	v_mfma_f32_16x16x32_bf16 v[80:83], v[218:221], v[194:197], v[80:83]
	v_mfma_f32_16x16x32_bf16 v[68:71], v[210:213], v[202:205], v[68:71]
	v_mfma_f32_16x16x32_bf16 v[64:67], v[218:221], v[202:205], v[64:67]
	v_mfma_f32_16x16x32_bf16 v[116:119], v[214:217], v[172:175], v[116:119]
	v_mfma_f32_16x16x32_bf16 v[112:115], v[222:225], v[172:175], v[112:115]
	v_mfma_f32_16x16x32_bf16 v[100:103], v[214:217], v[190:193], v[100:103]
	v_mfma_f32_16x16x32_bf16 v[96:99], v[222:225], v[190:193], v[96:99]
	v_mfma_f32_16x16x32_bf16 v[84:87], v[214:217], v[198:201], v[84:87]
	v_mfma_f32_16x16x32_bf16 v[80:83], v[222:225], v[198:201], v[80:83]
	v_mfma_f32_16x16x32_bf16 v[68:71], v[214:217], v[206:209], v[68:71]
	v_mfma_f32_16x16x32_bf16 v[64:67], v[222:225], v[206:209], v[64:67]
	s_mov_b32 m0, s17
	v_lshl_add_u64 v[226:227], s[22:23], 0, v[128:129]
	s_barrier
	ds_read_b128 v[168:171], v154 offset:16384
	ds_read_b128 v[172:175], v154 offset:17408
	ds_read_b128 v[182:185], v154 offset:18432
	ds_read_b128 v[190:193], v154 offset:19456
	ds_read_b128 v[194:197], v154 offset:20480
	ds_read_b128 v[198:201], v154 offset:21504
	ds_read_b128 v[202:205], v154 offset:22528
	ds_read_b128 v[206:209], v154 offset:23552
	global_load_lds_dwordx4 v[226:227], off
	v_lshl_add_u64 v[228:229], s[22:23], 0, v[132:133]
	s_mov_b32 m0, s30
	s_nop 0
	global_load_lds_dwordx4 v[228:229], off
	s_waitcnt lgkmcnt(0)
	s_barrier
	v_mfma_f32_16x16x32_bf16 v[60:63], v[144:147], v[168:171], v[60:63]
	v_mfma_f32_16x16x32_bf16 v[56:59], v[160:163], v[168:171], v[56:59]
	v_mfma_f32_16x16x32_bf16 v[44:47], v[144:147], v[182:185], v[44:47]
	v_mfma_f32_16x16x32_bf16 v[40:43], v[160:163], v[182:185], v[40:43]
	v_mfma_f32_16x16x32_bf16 v[28:31], v[144:147], v[194:197], v[28:31]
	v_mfma_f32_16x16x32_bf16 v[24:27], v[160:163], v[194:197], v[24:27]
	v_mfma_f32_16x16x32_bf16 v[12:15], v[144:147], v[202:205], v[12:15]
	v_mfma_f32_16x16x32_bf16 v[8:11], v[160:163], v[202:205], v[8:11]
	v_mfma_f32_16x16x32_bf16 v[60:63], v[156:159], v[172:175], v[60:63]
	v_mfma_f32_16x16x32_bf16 v[56:59], v[164:167], v[172:175], v[56:59]
	v_mfma_f32_16x16x32_bf16 v[44:47], v[156:159], v[190:193], v[44:47]
	v_mfma_f32_16x16x32_bf16 v[40:43], v[164:167], v[190:193], v[40:43]
	v_mfma_f32_16x16x32_bf16 v[28:31], v[156:159], v[198:201], v[28:31]
	v_mfma_f32_16x16x32_bf16 v[24:27], v[164:167], v[198:201], v[24:27]
	v_mfma_f32_16x16x32_bf16 v[12:15], v[156:159], v[206:209], v[12:15]
	v_mfma_f32_16x16x32_bf16 v[8:11], v[164:167], v[206:209], v[8:11]
	s_barrier
	s_add_u32 s48, s20, 0x40000
	s_addc_u32 s49, s21, 0
	s_add_i32 s50, s40, s29
	v_lshl_add_u64 v[144:145], s[48:49], 0, v[130:131]
	s_mov_b32 m0, s50
	s_nop 0
	global_load_lds_dwordx4 v[144:145], off
	v_lshl_add_u64 v[144:145], s[48:49], 0, v[134:135]
	s_add_i32 m0, s50, 0x2000
	s_nop 0
	global_load_lds_dwordx4 v[144:145], off
	s_waitcnt vmcnt(6)
	s_barrier
; #define PG8_STAGE(bufoff, gbase, voff) do { _Pragma("unroll") for (int _i = 0; _i < 2; ++_i) \
;         __builtin_amdgcn_global_load_lds((const unsigned*)((const char*)(gbase) + (voff)[_i]), (PG8_LAS unsigned*)(lds + (bufoff) + ldsw + _i * 8192), 16, 0, 0); } while (0)
; #define PG8_LDA(dst, b, h) do { _Pragma("unroll") for (int m = 0; m < 4; ++m) _Pragma("unroll") for (int k = 0; k < 2; ++k) dst[m][k] = *(const PG8_LAS bf16x8*)(lds + PG8_SA(b, h) + aoff + m * 2048 + k * 1024); } while (0)
; #define PG8_LDB(dst, b, h) do { _Pragma("unroll") for (int n = 0; n < 2; ++n) _Pragma("unroll") for (int k = 0; k < 2; ++k) dst[n][k] = *(const PG8_LAS bf16x8*)(lds + PG8_SB(b, h) + boff + n * 2048 + k * 1024); } while (0)
; #define PG8_MMA(ai, bj, At, Bt) do { __builtin_amdgcn_s_setprio(1); _Pragma("unroll") for (int m = 0; m < 4; ++m) _Pragma("unroll") for (int n = 0; n < 2; ++n) _Pragma("unroll") for (int k = 0; k < 2; ++k) \
;         acc[ai][bj][m][n] = __builtin_amdgcn_mfma_f32_16x16x32_bf16(Bt[n][k], At[m][k], acc[ai][bj][m][n], 0, 0, 0); __builtin_amdgcn_s_setprio(0); } while (0)
; #define PG8_WAIT_V(n) asm volatile("s_waitcnt vmcnt(" #n ")" ::: "memory")
; #define PG8_WAIT_L(n) asm volatile("s_waitcnt lgkmcnt(" #n ")" ::: "memory")
; #define PG8_BAR __builtin_amdgcn_s_barrier()
; #define PG8_SCHED __builtin_amdgcn_sched_barrier(0)
; template <class Epi, class Sched>
; __device__ __forceinline__ void gemm_phase(PG8_LAS unsigned char* lds, const Gemm g, const Sched& S, const Epi& E) {
;     ...
;             PG8_WAIT_V(6); PG8_BAR; PG8_MMA(1, 1, At, B1); PG8_BAR;
;             PG8_LDB(B0, 1, 0); PG8_SCHED; PG8_LDA(At, 1, 0); PG8_STAGE(PG8_SA(0, 1), a2 + hstep, voffA);
;             PG8_WAIT_L(8); PG8_BAR; PG8_WAIT_L(0); PG8_MMA(0, 0, At, B0); PG8_BAR; PG8_SCHED;
;             PG8_LDB(B1, 1, 1); PG8_STAGE(PG8_SB(1, 0), b3, voffB);
;             PG8_BAR; PG8_WAIT_L(0); PG8_MMA(0, 1, At, B1); PG8_BAR;
;             PG8_LDA(At, 1, 1); PG8_STAGE(PG8_SA(1, 0), a3, voffA);
;             PG8_BAR; PG8_WAIT_L(0); PG8_MMA(1, 0, At, B0); PG8_BAR; PG8_SCHED;
;             PG8_STAGE(PG8_SB(1, 1), b3 + hstep, voffB);
	v_mfma_f32_16x16x32_bf16 v[52:55], v[210:213], v[168:171], v[52:55]
	v_mfma_f32_16x16x32_bf16 v[48:51], v[218:221], v[168:171], v[48:51]
	v_mfma_f32_16x16x32_bf16 v[36:39], v[210:213], v[182:185], v[36:39]
	v_mfma_f32_16x16x32_bf16 v[32:35], v[218:221], v[182:185], v[32:35]
	v_mfma_f32_16x16x32_bf16 v[20:23], v[210:213], v[194:197], v[20:23]
	v_mfma_f32_16x16x32_bf16 v[16:19], v[218:221], v[194:197], v[16:19]
	v_mfma_f32_16x16x32_bf16 v[4:7], v[210:213], v[202:205], v[4:7]
	v_mfma_f32_16x16x32_bf16 v[0:3], v[218:221], v[202:205], v[0:3]
	v_mfma_f32_16x16x32_bf16 v[52:55], v[214:217], v[172:175], v[52:55]
	v_mfma_f32_16x16x32_bf16 v[48:51], v[222:225], v[172:175], v[48:51]
	v_mfma_f32_16x16x32_bf16 v[36:39], v[214:217], v[190:193], v[36:39]
	v_mfma_f32_16x16x32_bf16 v[32:35], v[222:225], v[190:193], v[32:35]
	v_mfma_f32_16x16x32_bf16 v[20:23], v[214:217], v[198:201], v[20:23]
	v_mfma_f32_16x16x32_bf16 v[16:19], v[222:225], v[198:201], v[16:19]
	v_mfma_f32_16x16x32_bf16 v[4:7], v[214:217], v[206:209], v[4:7]
	v_mfma_f32_16x16x32_bf16 v[0:3], v[222:225], v[206:209], v[0:3]
	s_add_i32 s48, 0, 0x18000
	v_add_u32_e32 v164, s48, v151
	s_barrier
	ds_read_b128 v[144:147], v164
	ds_read_b128 v[156:159], v164 offset:1024
	ds_read_b128 v[160:163], v164 offset:2048
	ds_read_b128 v[164:167], v164 offset:3072
	s_add_u32 s22, s22, 0x40000
	s_addc_u32 s23, s23, 0
	s_mov_b32 m0, s31
	v_lshl_add_u64 v[210:211], s[22:23], 0, v[128:129]
	ds_read_b128 v[168:171], v154 offset:32768
	ds_read_b128 v[172:175], v154 offset:33792
	ds_read_b128 v[182:185], v154 offset:34816
	ds_read_b128 v[190:193], v154 offset:35840
	ds_read_b128 v[194:197], v154 offset:36864
	ds_read_b128 v[198:201], v154 offset:37888
	ds_read_b128 v[202:205], v154 offset:38912
	ds_read_b128 v[206:209], v154 offset:39936
	global_load_lds_dwordx4 v[210:211], off
	v_lshl_add_u64 v[210:211], s[22:23], 0, v[132:133]
	s_mov_b32 m0, s34
	s_nop 0
	global_load_lds_dwordx4 v[210:211], off
	s_waitcnt lgkmcnt(0)
	s_barrier
	v_mfma_f32_16x16x32_bf16 v[124:127], v[144:147], v[168:171], v[124:127]
	v_mfma_f32_16x16x32_bf16 v[120:123], v[160:163], v[168:171], v[120:123]
	v_mfma_f32_16x16x32_bf16 v[108:111], v[144:147], v[182:185], v[108:111]
	v_mfma_f32_16x16x32_bf16 v[104:107], v[160:163], v[182:185], v[104:107]
	v_mfma_f32_16x16x32_bf16 v[92:95], v[144:147], v[194:197], v[92:95]
	v_mfma_f32_16x16x32_bf16 v[88:91], v[160:163], v[194:197], v[88:91]
	v_mfma_f32_16x16x32_bf16 v[76:79], v[144:147], v[202:205], v[76:79]
	v_mfma_f32_16x16x32_bf16 v[72:75], v[160:163], v[202:205], v[72:75]
	v_mfma_f32_16x16x32_bf16 v[124:127], v[156:159], v[172:175], v[124:127]
	v_mfma_f32_16x16x32_bf16 v[120:123], v[164:167], v[172:175], v[120:123]
	v_mfma_f32_16x16x32_bf16 v[108:111], v[156:159], v[190:193], v[108:111]
	v_mfma_f32_16x16x32_bf16 v[104:107], v[164:167], v[190:193], v[104:107]
	v_mfma_f32_16x16x32_bf16 v[92:95], v[156:159], v[198:201], v[92:95]
	v_mfma_f32_16x16x32_bf16 v[88:91], v[164:167], v[198:201], v[88:91]
	v_mfma_f32_16x16x32_bf16 v[76:79], v[156:159], v[206:209], v[76:79]
	v_mfma_f32_16x16x32_bf16 v[72:75], v[164:167], v[206:209], v[72:75]
	s_barrier
	s_add_i32 s22, 0, 0x1c000
	s_add_i32 s23, s48, s29
	v_add_u32_e32 v179, s22, v151
	v_lshl_add_u64 v[148:149], v[148:149], 0, s[6:7]
	s_mov_b32 m0, s23
	ds_read_b128 v[210:213], v179
	ds_read_b128 v[214:217], v179 offset:1024
	ds_read_b128 v[218:221], v179 offset:2048
	ds_read_b128 v[222:225], v179 offset:3072
	global_load_lds_dwordx4 v[148:149], off
	v_lshl_add_u64 v[148:149], v[186:187], 0, s[6:7]
	s_add_i32 m0, s23, 0x2000
	s_nop 0
	global_load_lds_dwordx4 v[148:149], off
	s_waitcnt lgkmcnt(0)
	s_barrier
	v_mfma_f32_16x16x32_bf16 v[116:119], v[210:213], v[168:171], v[116:119]
	v_mfma_f32_16x16x32_bf16 v[112:115], v[218:221], v[168:171], v[112:115]
	v_mfma_f32_16x16x32_bf16 v[100:103], v[210:213], v[182:185], v[100:103]
	v_mfma_f32_16x16x32_bf16 v[96:99], v[218:221], v[182:185], v[96:99]
	v_mfma_f32_16x16x32_bf16 v[84:87], v[210:213], v[194:197], v[84:87]
	v_mfma_f32_16x16x32_bf16 v[80:83], v[218:221], v[194:197], v[80:83]
	v_mfma_f32_16x16x32_bf16 v[68:71], v[210:213], v[202:205], v[68:71]
	v_mfma_f32_16x16x32_bf16 v[64:67], v[218:221], v[202:205], v[64:67]
	v_mfma_f32_16x16x32_bf16 v[116:119], v[214:217], v[172:175], v[116:119]
	v_mfma_f32_16x16x32_bf16 v[112:115], v[222:225], v[172:175], v[112:115]
	v_mfma_f32_16x16x32_bf16 v[100:103], v[214:217], v[190:193], v[100:103]
	v_mfma_f32_16x16x32_bf16 v[96:99], v[222:225], v[190:193], v[96:99]
	v_mfma_f32_16x16x32_bf16 v[84:87], v[214:217], v[198:201], v[84:87]
	v_mfma_f32_16x16x32_bf16 v[80:83], v[222:225], v[198:201], v[80:83]
	v_mfma_f32_16x16x32_bf16 v[68:71], v[214:217], v[206:209], v[68:71]
	v_mfma_f32_16x16x32_bf16 v[64:67], v[222:225], v[206:209], v[64:67]
	s_mov_b32 m0, s36
	v_lshl_add_u64 v[148:149], v[226:227], 0, s[6:7]
	s_barrier
	ds_read_b128 v[168:171], v154 offset:49152
	ds_read_b128 v[172:175], v154 offset:50176
	ds_read_b128 v[182:185], v154 offset:51200
	ds_read_b128 v[190:193], v154 offset:52224
	ds_read_b128 v[194:197], v154 offset:53248
	ds_read_b128 v[198:201], v154 offset:54272
	ds_read_b128 v[202:205], v154 offset:55296
	ds_read_b128 v[206:209], v154 offset:56320
	global_load_lds_dwordx4 v[148:149], off
	v_lshl_add_u64 v[148:149], v[228:229], 0, s[6:7]
	s_mov_b32 m0, s37
	s_nop 0
	global_load_lds_dwordx4 v[148:149], off
	s_waitcnt lgkmcnt(0)
	s_barrier
; __device__ __forceinline__ unsigned cvt_pk_bf16(float lo, float hi) { unsigned r; asm volatile("v_cvt_pk_bf16_f32 %0, %1, %2" : "=v"(r) : "v"(lo), "v"(hi)); return r; }
; __device__ __forceinline__ float bf_lo(unsigned u) { return __uint_as_float(u << 16); }
; __device__ __forceinline__ float bf_hi(unsigned u) { return __uint_as_float(u & 0xffff0000u); }
; #define PG8_WAIT_V(n) asm volatile("s_waitcnt vmcnt(" #n ")" ::: "memory")
; #define PG8_WAIT_L(n) asm volatile("s_waitcnt lgkmcnt(" #n ")" ::: "memory")
; #define PG8_BAR __builtin_amdgcn_s_barrier()
;     __device__ __forceinline__ void operator()(const f32x4 (&acc)[2][2][4][2], const Unit& u, int wr, int wc, int fr, int fq) const {
;         const int row0 = u.pm * BM + wr * 64 + fr, col0 = u.pn * BM + wc * 32 + 8 * fq;
; #pragma unroll
;         for (int ai = 0; ai < 2; ++ai)
; #pragma unroll
;             for (int m = 0; m < 4; ++m) { const size_t r = (size_t)(row0 + ai * HALF + m * 16); bf16_t* rowp = O + r * ldc + col0; const bf16_t* gp = G + r * ldg + col0;
; #pragma unroll
;                 for (int bj = 0; bj < 2; ++bj) { const u32x4 gw = *(const u32x4*)(gp + bj * HALF);
;                     f32x4 v0 = acc[ai][bj][m][0], v1 = acc[ai][bj][m][1];
;                     v0[0] *= bf_lo(gw.x); v0[1] *= bf_hi(gw.x); v0[2] *= bf_lo(gw.y); v0[3] *= bf_hi(gw.y);
;                     v1[0] *= bf_lo(gw.z); v1[1] *= bf_hi(gw.z); v1[2] *= bf_lo(gw.w); v1[3] *= bf_hi(gw.w);
;                     if (ACCUM) { const u32x4 pw = *(const u32x4*)(rowp + bj * HALF);
;                         v0[0] += bf_lo(pw.x); v0[1] += bf_hi(pw.x); v0[2] += bf_lo(pw.y); v0[3] += bf_hi(pw.y);
;                         v1[0] += bf_lo(pw.z); v1[1] += bf_hi(pw.z); v1[2] += bf_lo(pw.w); v1[3] += bf_hi(pw.w); }
;                     u32x4 w; w.x = cvt_pk_bf16(v0[0], v0[1]); w.y = cvt_pk_bf16(v0[2], v0[3]); w.z = cvt_pk_bf16(v1[0], v1[1]); w.w = cvt_pk_bf16(v1[2], v1[3]);
;                     *(u32x4*)(rowp + bj * HALF) = w; } }
; template <class Epi, class Sched>
; __device__ __forceinline__ void gemm_phase(PG8_LAS unsigned char* lds, const Gemm g, const Sched& S, const Epi& E) {
;     ...
;             PG8_BAR; PG8_WAIT_L(0); PG8_MMA(1, 0, At, B0); PG8_BAR; PG8_SCHED;
;             PG8_STAGE(PG8_SB(1, 1), b3 + hstep, voffB);
;             PG8_WAIT_V(6); PG8_BAR; PG8_MMA(1, 1, At, B1); PG8_BAR;
	v_mfma_f32_16x16x32_bf16 v[60:63], v[144:147], v[168:171], v[60:63]
	v_mfma_f32_16x16x32_bf16 v[56:59], v[160:163], v[168:171], v[56:59]
	v_mfma_f32_16x16x32_bf16 v[44:47], v[144:147], v[182:185], v[44:47]
	v_mfma_f32_16x16x32_bf16 v[40:43], v[160:163], v[182:185], v[40:43]
	v_mfma_f32_16x16x32_bf16 v[28:31], v[144:147], v[194:197], v[28:31]
	v_mfma_f32_16x16x32_bf16 v[24:27], v[160:163], v[194:197], v[24:27]
	v_mfma_f32_16x16x32_bf16 v[12:15], v[144:147], v[202:205], v[12:15]
	v_mfma_f32_16x16x32_bf16 v[8:11], v[160:163], v[202:205], v[8:11]
	v_mfma_f32_16x16x32_bf16 v[60:63], v[156:159], v[172:175], v[60:63]
	v_mfma_f32_16x16x32_bf16 v[56:59], v[164:167], v[172:175], v[56:59]
	v_mfma_f32_16x16x32_bf16 v[44:47], v[156:159], v[190:193], v[44:47]
	v_mfma_f32_16x16x32_bf16 v[40:43], v[164:167], v[190:193], v[40:43]
	v_mfma_f32_16x16x32_bf16 v[28:31], v[156:159], v[198:201], v[28:31]
	v_mfma_f32_16x16x32_bf16 v[24:27], v[164:167], v[198:201], v[24:27]
	v_mfma_f32_16x16x32_bf16 v[12:15], v[156:159], v[206:209], v[12:15]
	v_mfma_f32_16x16x32_bf16 v[8:11], v[164:167], v[206:209], v[8:11]
	s_barrier
	s_add_u32 s20, s20, 0x40080
	s_addc_u32 s21, s21, 0
	s_add_i32 s22, s22, s29
	v_lshl_add_u64 v[144:145], s[20:21], 0, v[130:131]
	s_mov_b32 m0, s22
	s_nop 0
	global_load_lds_dwordx4 v[144:145], off
	v_lshl_add_u64 v[144:145], s[20:21], 0, v[134:135]
	s_add_i32 m0, s22, 0x2000
	s_nop 0
	global_load_lds_dwordx4 v[144:145], off
	s_waitcnt vmcnt(6)
	s_barrier
	v_mfma_f32_16x16x32_bf16 v[52:55], v[210:213], v[168:171], v[52:55]
	v_mfma_f32_16x16x32_bf16 v[48:51], v[218:221], v[168:171], v[48:51]
	v_mfma_f32_16x16x32_bf16 v[36:39], v[210:213], v[182:185], v[36:39]
	v_mfma_f32_16x16x32_bf16 v[32:35], v[218:221], v[182:185], v[32:35]
	v_mfma_f32_16x16x32_bf16 v[20:23], v[210:213], v[194:197], v[20:23]
	v_mfma_f32_16x16x32_bf16 v[16:19], v[218:221], v[194:197], v[16:19]
	v_mfma_f32_16x16x32_bf16 v[4:7], v[210:213], v[202:205], v[4:7]
	v_mfma_f32_16x16x32_bf16 v[0:3], v[218:221], v[202:205], v[0:3]
	v_mfma_f32_16x16x32_bf16 v[52:55], v[214:217], v[172:175], v[52:55]
	v_mfma_f32_16x16x32_bf16 v[48:51], v[222:225], v[172:175], v[48:51]
	v_mfma_f32_16x16x32_bf16 v[36:39], v[214:217], v[190:193], v[36:39]
	v_mfma_f32_16x16x32_bf16 v[32:35], v[222:225], v[190:193], v[32:35]
	v_mfma_f32_16x16x32_bf16 v[20:23], v[214:217], v[198:201], v[20:23]
	v_mfma_f32_16x16x32_bf16 v[16:19], v[222:225], v[198:201], v[16:19]
	v_mfma_f32_16x16x32_bf16 v[4:7], v[214:217], v[206:209], v[4:7]
	v_mfma_f32_16x16x32_bf16 v[0:3], v[222:225], v[206:209], v[0:3]
	s_add_i32 s47, s47, 2
	s_add_u32 s18, s18, 0x100
	s_addc_u32 s19, s19, 0
	s_add_u32 s45, s45, 0x100
	s_addc_u32 s46, s46, 0
	s_cmp_gt_u32 s47, 13
	s_barrier
	s_cbranch_scc0 .LBB0_1011
	v_lshl_add_u32 v146, s16, 8, v150
	v_lshl_or_b32 v144, s42, 8, v152
	v_ashrrev_i32_e32 v147, 31, v146
	v_ashrrev_i32_e32 v145, 31, v144
	v_mov_b64_e32 v[148:149], s[4:5]
	v_lshlrev_b64 v[160:161], 11, v[146:147]
	v_lshlrev_b64 v[144:145], 1, v[144:145]
	v_mad_i64_i32 v[156:157], s[18:19], v146, s41, v[148:149]
	v_lshl_add_u64 v[160:161], s[0:1], 0, v[160:161]
	v_lshl_add_u64 v[164:165], v[156:157], 0, v[144:145]
	v_lshl_add_u64 v[166:167], v[160:161], 0, v[144:145]
	global_load_dwordx4 v[156:159], v[164:165], off
	global_load_dwordx4 v[160:163], v[166:167], off
	s_and_b64 vcc, exec, s[2:3]
	s_mov_b32 s42, s8
	s_mov_b32 s16, s10
	s_mov_b64 s[20:21], s[14:15]
	s_waitcnt vmcnt(0)
	v_lshlrev_b32_e32 v147, 16, v156
	v_and_b32_e32 v156, 0xffff0000, v156
	v_lshlrev_b32_e32 v168, 16, v157
	v_and_b32_e32 v157, 0xffff0000, v157
	v_lshlrev_b32_e32 v169, 16, v158
	v_and_b32_e32 v158, 0xffff0000, v158
	v_lshlrev_b32_e32 v170, 16, v159
	v_and_b32_e32 v159, 0xffff0000, v159
	v_lshlrev_b32_e32 v171, 16, v160
	v_and_b32_e32 v160, 0xffff0000, v160
	v_lshlrev_b32_e32 v172, 16, v161
	v_and_b32_e32 v161, 0xffff0000, v161
	v_lshlrev_b32_e32 v173, 16, v162
	v_and_b32_e32 v162, 0xffff0000, v162
	v_lshlrev_b32_e32 v174, 16, v163
	v_and_b32_e32 v163, 0xffff0000, v163
	v_fmac_f32_e32 v171, v124, v147
	v_fmac_f32_e32 v160, v125, v156
	v_fmac_f32_e32 v172, v126, v168
	v_fmac_f32_e32 v161, v127, v157
	v_fmac_f32_e32 v173, v120, v169
	v_fmac_f32_e32 v162, v121, v158
	v_fmac_f32_e32 v174, v122, v170
	v_fmac_f32_e32 v163, v123, v159
	v_cvt_pk_bf16_f32 v120, v171, v160
	v_cvt_pk_bf16_f32 v121, v172, v161
	v_cvt_pk_bf16_f32 v122, v173, v162
	v_cvt_pk_bf16_f32 v123, v174, v163
	global_load_dwordx4 v[124:127], v[164:165], off offset:256
	global_load_dwordx4 v[156:159], v[166:167], off offset:256
	v_or_b32_e32 v160, 16, v146
	global_store_dwordx4 v[166:167], v[120:123], off
	v_mad_i64_i32 v[162:163], s[18:19], v160, s41, v[148:149]
	v_lshl_add_u64 v[162:163], v[162:163], 0, v[144:145]
	s_waitcnt vmcnt(0)
	v_lshlrev_b32_e32 v122, 16, v125
	v_lshlrev_b32_e32 v161, 16, v157
	v_lshlrev_b32_e32 v120, 16, v124
	v_and_b32_e32 v121, 0xffff0000, v124
	v_and_b32_e32 v123, 0xffff0000, v125
	v_lshlrev_b32_e32 v124, 16, v126
	v_and_b32_e32 v125, 0xffff0000, v126
	v_lshlrev_b32_e32 v147, 16, v156
	v_and_b32_e32 v156, 0xffff0000, v156
	v_and_b32_e32 v157, 0xffff0000, v157
	v_lshlrev_b32_e32 v164, 16, v158
	v_and_b32_e32 v158, 0xffff0000, v158
	v_fmac_f32_e32 v161, v118, v122
	v_fmac_f32_e32 v147, v116, v120
	v_fmac_f32_e32 v156, v117, v121
	v_fmac_f32_e32 v157, v119, v123
	v_fmac_f32_e32 v164, v112, v124
	v_fmac_f32_e32 v158, v113, v125
	v_cvt_pk_bf16_f32 v112, v147, v156
	v_cvt_pk_bf16_f32 v113, v161, v157
	v_ashrrev_i32_e32 v161, 31, v160
	v_lshlrev_b64 v[120:121], 11, v[160:161]
	v_lshl_add_u64 v[120:121], s[0:1], 0, v[120:121]
	v_lshlrev_b32_e32 v126, 16, v127
	v_and_b32_e32 v127, 0xffff0000, v127
	v_lshlrev_b32_e32 v165, 16, v159
	v_and_b32_e32 v159, 0xffff0000, v159
	v_lshl_add_u64 v[124:125], v[120:121], 0, v[144:145]
	v_fmac_f32_e32 v165, v114, v126
	v_fmac_f32_e32 v159, v115, v127
	v_cvt_pk_bf16_f32 v114, v164, v158
	v_cvt_pk_bf16_f32 v115, v165, v159
	global_load_dwordx4 v[116:119], v[162:163], off
	global_load_dwordx4 v[120:123], v[124:125], off
	s_waitcnt vmcnt(0)
; __device__ __forceinline__ unsigned cvt_pk_bf16(float lo, float hi) { unsigned r; asm volatile("v_cvt_pk_bf16_f32 %0, %1, %2" : "=v"(r) : "v"(lo), "v"(hi)); return r; }
; __device__ __forceinline__ float bf_lo(unsigned u) { return __uint_as_float(u << 16); }
; __device__ __forceinline__ float bf_hi(unsigned u) { return __uint_as_float(u & 0xffff0000u); }
;     __device__ __forceinline__ void operator()(const f32x4 (&acc)[2][2][4][2], const Unit& u, int wr, int wc, int fr, int fq) const {
;     ...
;             for (int m = 0; m < 4; ++m) { const size_t r = (size_t)(row0 + ai * HALF + m * 16); bf16_t* rowp = O + r * ldc + col0; const bf16_t* gp = G + r * ldg + col0;
; #pragma unroll
;                 for (int bj = 0; bj < 2; ++bj) { const u32x4 gw = *(const u32x4*)(gp + bj * HALF);
;                     f32x4 v0 = acc[ai][bj][m][0], v1 = acc[ai][bj][m][1];
;                     v0[0] *= bf_lo(gw.x); v0[1] *= bf_hi(gw.x); v0[2] *= bf_lo(gw.y); v0[3] *= bf_hi(gw.y);
;                     v1[0] *= bf_lo(gw.z); v1[1] *= bf_hi(gw.z); v1[2] *= bf_lo(gw.w); v1[3] *= bf_hi(gw.w);
;                     if (ACCUM) { const u32x4 pw = *(const u32x4*)(rowp + bj * HALF);
;                         v0[0] += bf_lo(pw.x); v0[1] += bf_hi(pw.x); v0[2] += bf_lo(pw.y); v0[3] += bf_hi(pw.y);
;                         v1[0] += bf_lo(pw.z); v1[1] += bf_hi(pw.z); v1[2] += bf_lo(pw.w); v1[3] += bf_hi(pw.w); }
;                     u32x4 w; w.x = cvt_pk_bf16(v0[0], v0[1]); w.y = cvt_pk_bf16(v0[2], v0[3]); w.z = cvt_pk_bf16(v1[0], v1[1]); w.w = cvt_pk_bf16(v1[2], v1[3]);
;                     *(u32x4*)(rowp + bj * HALF) = w; } }
	v_lshlrev_b32_e32 v126, 16, v120
	global_store_dwordx4 v[166:167], v[112:115], off offset:256
	v_and_b32_e32 v120, 0xffff0000, v120
	v_lshlrev_b32_e32 v127, 16, v121
	v_lshlrev_b32_e32 v112, 16, v116
	v_and_b32_e32 v113, 0xffff0000, v116
	v_lshlrev_b32_e32 v114, 16, v117
	v_and_b32_e32 v115, 0xffff0000, v117
	v_lshlrev_b32_e32 v116, 16, v118
	v_and_b32_e32 v117, 0xffff0000, v118
	v_lshlrev_b32_e32 v118, 16, v119
	v_and_b32_e32 v119, 0xffff0000, v119
	v_and_b32_e32 v121, 0xffff0000, v121
	v_lshlrev_b32_e32 v147, 16, v122
	v_and_b32_e32 v122, 0xffff0000, v122
	v_lshlrev_b32_e32 v156, 16, v123
	v_and_b32_e32 v123, 0xffff0000, v123
	v_fmac_f32_e32 v126, v108, v112
	v_fmac_f32_e32 v120, v109, v113
	v_fmac_f32_e32 v127, v110, v114
	v_fmac_f32_e32 v121, v111, v115
	v_fmac_f32_e32 v147, v104, v116
	v_fmac_f32_e32 v122, v105, v117
	v_fmac_f32_e32 v156, v106, v118
	v_fmac_f32_e32 v123, v107, v119
	v_cvt_pk_bf16_f32 v104, v126, v120
	v_cvt_pk_bf16_f32 v105, v127, v121
	v_cvt_pk_bf16_f32 v106, v147, v122
	v_cvt_pk_bf16_f32 v107, v156, v123
	global_load_dwordx4 v[108:111], v[162:163], off offset:256
	global_load_dwordx4 v[112:115], v[124:125], off offset:256
	v_or_b32_e32 v116, 32, v146
	global_store_dwordx4 v[124:125], v[104:107], off
	v_mad_i64_i32 v[118:119], s[18:19], v116, s41, v[148:149]
	v_lshl_add_u64 v[118:119], v[118:119], 0, v[144:145]
	s_waitcnt vmcnt(0)
	v_lshlrev_b32_e32 v104, 16, v108
	v_lshlrev_b32_e32 v117, 16, v112
	v_and_b32_e32 v105, 0xffff0000, v108
	v_lshlrev_b32_e32 v108, 16, v110
	v_and_b32_e32 v112, 0xffff0000, v112
	v_lshlrev_b32_e32 v121, 16, v114
	v_fmac_f32_e32 v117, v100, v104
	v_fmac_f32_e32 v112, v101, v105
	v_fmac_f32_e32 v121, v96, v108
	v_cvt_pk_bf16_f32 v96, v117, v112
	v_ashrrev_i32_e32 v117, 31, v116
	v_lshlrev_b64 v[104:105], 11, v[116:117]
	v_lshlrev_b32_e32 v106, 16, v109
	v_and_b32_e32 v107, 0xffff0000, v109
	v_and_b32_e32 v109, 0xffff0000, v110
	v_and_b32_e32 v114, 0xffff0000, v114
	v_lshl_add_u64 v[104:105], s[0:1], 0, v[104:105]
	v_lshlrev_b32_e32 v110, 16, v111
	v_and_b32_e32 v111, 0xffff0000, v111
	v_lshlrev_b32_e32 v120, 16, v113
	v_and_b32_e32 v113, 0xffff0000, v113
	v_lshlrev_b32_e32 v122, 16, v115
	v_and_b32_e32 v115, 0xffff0000, v115
	v_fmac_f32_e32 v114, v97, v109
	v_lshl_add_u64 v[108:109], v[104:105], 0, v[144:145]
	v_fmac_f32_e32 v120, v102, v106
	v_fmac_f32_e32 v113, v103, v107
	v_fmac_f32_e32 v122, v98, v110
	v_fmac_f32_e32 v115, v99, v111
	v_cvt_pk_bf16_f32 v97, v120, v113
	v_cvt_pk_bf16_f32 v98, v121, v114
	v_cvt_pk_bf16_f32 v99, v122, v115
	global_load_dwordx4 v[100:103], v[118:119], off
	global_load_dwordx4 v[104:107], v[108:109], off
	s_waitcnt vmcnt(0)
	v_lshlrev_b32_e32 v110, 16, v104
	global_store_dwordx4 v[124:125], v[96:99], off offset:256
	v_and_b32_e32 v104, 0xffff0000, v104
	v_lshlrev_b32_e32 v111, 16, v105
	v_lshlrev_b32_e32 v96, 16, v100
	v_and_b32_e32 v97, 0xffff0000, v100
	v_lshlrev_b32_e32 v98, 16, v101
	v_and_b32_e32 v99, 0xffff0000, v101
	v_lshlrev_b32_e32 v100, 16, v102
	v_and_b32_e32 v101, 0xffff0000, v102
	v_lshlrev_b32_e32 v102, 16, v103
	v_and_b32_e32 v103, 0xffff0000, v103
	v_and_b32_e32 v105, 0xffff0000, v105
	v_lshlrev_b32_e32 v112, 16, v106
	v_and_b32_e32 v106, 0xffff0000, v106
	v_lshlrev_b32_e32 v113, 16, v107
	v_and_b32_e32 v107, 0xffff0000, v107
	v_fmac_f32_e32 v110, v92, v96
	v_fmac_f32_e32 v104, v93, v97
	v_fmac_f32_e32 v111, v94, v98
	v_fmac_f32_e32 v105, v95, v99
	v_fmac_f32_e32 v112, v88, v100
	v_fmac_f32_e32 v106, v89, v101
	v_fmac_f32_e32 v113, v90, v102
	v_fmac_f32_e32 v107, v91, v103
	v_cvt_pk_bf16_f32 v88, v110, v104
	v_cvt_pk_bf16_f32 v89, v111, v105
	v_cvt_pk_bf16_f32 v90, v112, v106
	v_cvt_pk_bf16_f32 v91, v113, v107
	global_load_dwordx4 v[92:95], v[118:119], off offset:256
	global_load_dwordx4 v[96:99], v[108:109], off offset:256
	v_or_b32_e32 v100, 48, v146
	global_store_dwordx4 v[108:109], v[88:91], off
	v_mad_i64_i32 v[102:103], s[18:19], v100, s41, v[148:149]
	v_lshl_add_u64 v[102:103], v[102:103], 0, v[144:145]
	s_waitcnt vmcnt(0)
	v_lshlrev_b32_e32 v88, 16, v92
	v_lshlrev_b32_e32 v101, 16, v96
	v_and_b32_e32 v89, 0xffff0000, v92
	v_lshlrev_b32_e32 v92, 16, v94
	v_and_b32_e32 v96, 0xffff0000, v96
	v_lshlrev_b32_e32 v105, 16, v98
	v_fmac_f32_e32 v101, v84, v88
	v_fmac_f32_e32 v96, v85, v89
	v_fmac_f32_e32 v105, v80, v92
	v_cvt_pk_bf16_f32 v80, v101, v96
	v_ashrrev_i32_e32 v101, 31, v100
	v_lshlrev_b64 v[88:89], 11, v[100:101]
	v_lshlrev_b32_e32 v90, 16, v93
	v_and_b32_e32 v91, 0xffff0000, v93
	v_and_b32_e32 v93, 0xffff0000, v94
	v_and_b32_e32 v98, 0xffff0000, v98
	v_lshl_add_u64 v[88:89], s[0:1], 0, v[88:89]
	v_lshlrev_b32_e32 v94, 16, v95
	v_and_b32_e32 v95, 0xffff0000, v95
	v_lshlrev_b32_e32 v104, 16, v97
	v_and_b32_e32 v97, 0xffff0000, v97
	v_lshlrev_b32_e32 v106, 16, v99
	v_and_b32_e32 v99, 0xffff0000, v99
	v_fmac_f32_e32 v98, v81, v93
	v_lshl_add_u64 v[92:93], v[88:89], 0, v[144:145]
	v_fmac_f32_e32 v104, v86, v90
	v_fmac_f32_e32 v97, v87, v91
	v_fmac_f32_e32 v106, v82, v94
	v_fmac_f32_e32 v99, v83, v95
	v_cvt_pk_bf16_f32 v81, v104, v97
	v_cvt_pk_bf16_f32 v82, v105, v98
	v_cvt_pk_bf16_f32 v83, v106, v99
	global_load_dwordx4 v[84:87], v[102:103], off
	global_load_dwordx4 v[88:91], v[92:93], off
	s_waitcnt vmcnt(0)
; __device__ __forceinline__ unsigned cvt_pk_bf16(float lo, float hi) { unsigned r; asm volatile("v_cvt_pk_bf16_f32 %0, %1, %2" : "=v"(r) : "v"(lo), "v"(hi)); return r; }
; __device__ __forceinline__ float bf_lo(unsigned u) { return __uint_as_float(u << 16); }
; __device__ __forceinline__ float bf_hi(unsigned u) { return __uint_as_float(u & 0xffff0000u); }
;     __device__ __forceinline__ void operator()(const f32x4 (&acc)[2][2][4][2], const Unit& u, int wr, int wc, int fr, int fq) const {
;     ...
;             for (int m = 0; m < 4; ++m) { const size_t r = (size_t)(row0 + ai * HALF + m * 16); bf16_t* rowp = O + r * ldc + col0; const bf16_t* gp = G + r * ldg + col0;
; #pragma unroll
;                 for (int bj = 0; bj < 2; ++bj) { const u32x4 gw = *(const u32x4*)(gp + bj * HALF);
;                     f32x4 v0 = acc[ai][bj][m][0], v1 = acc[ai][bj][m][1];
;                     v0[0] *= bf_lo(gw.x); v0[1] *= bf_hi(gw.x); v0[2] *= bf_lo(gw.y); v0[3] *= bf_hi(gw.y);
;                     v1[0] *= bf_lo(gw.z); v1[1] *= bf_hi(gw.z); v1[2] *= bf_lo(gw.w); v1[3] *= bf_hi(gw.w);
;                     if (ACCUM) { const u32x4 pw = *(const u32x4*)(rowp + bj * HALF);
;                         v0[0] += bf_lo(pw.x); v0[1] += bf_hi(pw.x); v0[2] += bf_lo(pw.y); v0[3] += bf_hi(pw.y);
;                         v1[0] += bf_lo(pw.z); v1[1] += bf_hi(pw.z); v1[2] += bf_lo(pw.w); v1[3] += bf_hi(pw.w); }
;                     u32x4 w; w.x = cvt_pk_bf16(v0[0], v0[1]); w.y = cvt_pk_bf16(v0[2], v0[3]); w.z = cvt_pk_bf16(v1[0], v1[1]); w.w = cvt_pk_bf16(v1[2], v1[3]);
;                     *(u32x4*)(rowp + bj * HALF) = w; } }
	v_lshlrev_b32_e32 v94, 16, v88
	global_store_dwordx4 v[108:109], v[80:83], off offset:256
	v_and_b32_e32 v88, 0xffff0000, v88
	v_lshlrev_b32_e32 v95, 16, v89
	v_lshlrev_b32_e32 v80, 16, v84
	v_and_b32_e32 v81, 0xffff0000, v84
	v_lshlrev_b32_e32 v82, 16, v85
	v_and_b32_e32 v83, 0xffff0000, v85
	v_lshlrev_b32_e32 v84, 16, v86
	v_and_b32_e32 v85, 0xffff0000, v86
	v_lshlrev_b32_e32 v86, 16, v87
	v_and_b32_e32 v87, 0xffff0000, v87
	v_and_b32_e32 v89, 0xffff0000, v89
	v_lshlrev_b32_e32 v96, 16, v90
	v_and_b32_e32 v90, 0xffff0000, v90
	v_lshlrev_b32_e32 v97, 16, v91
	v_and_b32_e32 v91, 0xffff0000, v91
	v_fmac_f32_e32 v94, v76, v80
	v_fmac_f32_e32 v88, v77, v81
	v_fmac_f32_e32 v95, v78, v82
	v_fmac_f32_e32 v89, v79, v83
	v_fmac_f32_e32 v96, v72, v84
	v_fmac_f32_e32 v90, v73, v85
	v_fmac_f32_e32 v97, v74, v86
	v_fmac_f32_e32 v91, v75, v87
	v_cvt_pk_bf16_f32 v72, v94, v88
	v_cvt_pk_bf16_f32 v73, v95, v89
	v_cvt_pk_bf16_f32 v74, v96, v90
	v_cvt_pk_bf16_f32 v75, v97, v91
	global_load_dwordx4 v[76:79], v[102:103], off offset:256
	global_load_dwordx4 v[80:83], v[92:93], off offset:256
	v_add_u32_e32 v84, 0x80, v146
	global_store_dwordx4 v[92:93], v[72:75], off
	v_mad_i64_i32 v[86:87], s[18:19], v84, s41, v[148:149]
	v_lshl_add_u64 v[86:87], v[86:87], 0, v[144:145]
	s_waitcnt vmcnt(0)
	v_lshlrev_b32_e32 v72, 16, v76
	v_lshlrev_b32_e32 v85, 16, v80
	v_and_b32_e32 v73, 0xffff0000, v76
	v_lshlrev_b32_e32 v76, 16, v78
	v_and_b32_e32 v80, 0xffff0000, v80
	v_lshlrev_b32_e32 v89, 16, v82
	v_fmac_f32_e32 v85, v68, v72
	v_fmac_f32_e32 v80, v69, v73
	v_fmac_f32_e32 v89, v64, v76
	v_cvt_pk_bf16_f32 v64, v85, v80
	v_ashrrev_i32_e32 v85, 31, v84
	v_lshlrev_b64 v[72:73], 11, v[84:85]
	v_lshlrev_b32_e32 v74, 16, v77
	v_and_b32_e32 v75, 0xffff0000, v77
	v_and_b32_e32 v77, 0xffff0000, v78
	v_and_b32_e32 v82, 0xffff0000, v82
	v_lshl_add_u64 v[72:73], s[0:1], 0, v[72:73]
	v_lshlrev_b32_e32 v78, 16, v79
	v_and_b32_e32 v79, 0xffff0000, v79
	v_lshlrev_b32_e32 v88, 16, v81
	v_and_b32_e32 v81, 0xffff0000, v81
	v_lshlrev_b32_e32 v90, 16, v83
	v_and_b32_e32 v83, 0xffff0000, v83
	v_fmac_f32_e32 v82, v65, v77
	v_lshl_add_u64 v[76:77], v[72:73], 0, v[144:145]
	v_fmac_f32_e32 v88, v70, v74
	v_fmac_f32_e32 v81, v71, v75
	v_fmac_f32_e32 v90, v66, v78
	v_fmac_f32_e32 v83, v67, v79
	v_cvt_pk_bf16_f32 v65, v88, v81
	v_cvt_pk_bf16_f32 v66, v89, v82
	v_cvt_pk_bf16_f32 v67, v90, v83
	global_load_dwordx4 v[68:71], v[86:87], off
	global_load_dwordx4 v[72:75], v[76:77], off
	s_waitcnt vmcnt(0)
	v_lshlrev_b32_e32 v78, 16, v72
	global_store_dwordx4 v[92:93], v[64:67], off offset:256
	v_and_b32_e32 v72, 0xffff0000, v72
	v_lshlrev_b32_e32 v79, 16, v73
	v_lshlrev_b32_e32 v64, 16, v68
	v_and_b32_e32 v65, 0xffff0000, v68
	v_lshlrev_b32_e32 v66, 16, v69
	v_and_b32_e32 v67, 0xffff0000, v69
	v_lshlrev_b32_e32 v68, 16, v70
	v_and_b32_e32 v69, 0xffff0000, v70
	v_lshlrev_b32_e32 v70, 16, v71
	v_and_b32_e32 v71, 0xffff0000, v71
	v_and_b32_e32 v73, 0xffff0000, v73
	v_lshlrev_b32_e32 v80, 16, v74
	v_and_b32_e32 v74, 0xffff0000, v74
	v_lshlrev_b32_e32 v81, 16, v75
	v_and_b32_e32 v75, 0xffff0000, v75
	v_fmac_f32_e32 v78, v60, v64
	v_fmac_f32_e32 v72, v61, v65
	v_fmac_f32_e32 v79, v62, v66
	v_fmac_f32_e32 v73, v63, v67
	v_fmac_f32_e32 v80, v56, v68
	v_fmac_f32_e32 v74, v57, v69
	v_fmac_f32_e32 v81, v58, v70
	v_fmac_f32_e32 v75, v59, v71
	v_cvt_pk_bf16_f32 v56, v78, v72
	v_cvt_pk_bf16_f32 v57, v79, v73
	v_cvt_pk_bf16_f32 v58, v80, v74
	v_cvt_pk_bf16_f32 v59, v81, v75
	global_load_dwordx4 v[60:63], v[86:87], off offset:256
	global_load_dwordx4 v[64:67], v[76:77], off offset:256
	v_add_u32_e32 v68, 0x90, v146
	global_store_dwordx4 v[76:77], v[56:59], off
	v_mad_i64_i32 v[70:71], s[18:19], v68, s41, v[148:149]
	v_lshl_add_u64 v[70:71], v[70:71], 0, v[144:145]
	s_waitcnt vmcnt(0)
	v_lshlrev_b32_e32 v56, 16, v60
	v_lshlrev_b32_e32 v69, 16, v64
	v_and_b32_e32 v57, 0xffff0000, v60
	v_lshlrev_b32_e32 v60, 16, v62
	v_and_b32_e32 v64, 0xffff0000, v64
	v_lshlrev_b32_e32 v73, 16, v66
	v_fmac_f32_e32 v69, v52, v56
	v_fmac_f32_e32 v64, v53, v57
	v_fmac_f32_e32 v73, v48, v60
	v_cvt_pk_bf16_f32 v48, v69, v64
	v_ashrrev_i32_e32 v69, 31, v68
	v_lshlrev_b64 v[56:57], 11, v[68:69]
	v_lshlrev_b32_e32 v58, 16, v61
	v_and_b32_e32 v59, 0xffff0000, v61
	v_and_b32_e32 v61, 0xffff0000, v62
	v_and_b32_e32 v66, 0xffff0000, v66
	v_lshl_add_u64 v[56:57], s[0:1], 0, v[56:57]
	v_lshlrev_b32_e32 v62, 16, v63
	v_and_b32_e32 v63, 0xffff0000, v63
	v_lshlrev_b32_e32 v72, 16, v65
	v_and_b32_e32 v65, 0xffff0000, v65
	v_lshlrev_b32_e32 v74, 16, v67
	v_and_b32_e32 v67, 0xffff0000, v67
	v_fmac_f32_e32 v66, v49, v61
	v_lshl_add_u64 v[60:61], v[56:57], 0, v[144:145]
	v_fmac_f32_e32 v72, v54, v58
	v_fmac_f32_e32 v65, v55, v59
	v_fmac_f32_e32 v74, v50, v62
	v_fmac_f32_e32 v67, v51, v63
	v_cvt_pk_bf16_f32 v49, v72, v65
	v_cvt_pk_bf16_f32 v50, v73, v66
	v_cvt_pk_bf16_f32 v51, v74, v67
	global_load_dwordx4 v[52:55], v[70:71], off
	global_load_dwordx4 v[56:59], v[60:61], off
	s_waitcnt vmcnt(0)
	v_lshlrev_b32_e32 v62, 16, v56
	global_store_dwordx4 v[76:77], v[48:51], off offset:256
	v_and_b32_e32 v56, 0xffff0000, v56
	v_lshlrev_b32_e32 v63, 16, v57
	v_lshlrev_b32_e32 v48, 16, v52
	v_and_b32_e32 v49, 0xffff0000, v52
	v_lshlrev_b32_e32 v50, 16, v53
	v_and_b32_e32 v51, 0xffff0000, v53
	v_lshlrev_b32_e32 v52, 16, v54
	v_and_b32_e32 v53, 0xffff0000, v54
	v_lshlrev_b32_e32 v54, 16, v55
	v_and_b32_e32 v55, 0xffff0000, v55
	v_and_b32_e32 v57, 0xffff0000, v57
	v_lshlrev_b32_e32 v64, 16, v58
	v_and_b32_e32 v58, 0xffff0000, v58
	v_lshlrev_b32_e32 v65, 16, v59
	v_and_b32_e32 v59, 0xffff0000, v59
	v_fmac_f32_e32 v62, v44, v48
	v_fmac_f32_e32 v56, v45, v49
	v_fmac_f32_e32 v63, v46, v50
	v_fmac_f32_e32 v57, v47, v51
	v_fmac_f32_e32 v64, v40, v52
	v_fmac_f32_e32 v58, v41, v53
	v_fmac_f32_e32 v65, v42, v54
	v_fmac_f32_e32 v59, v43, v55
	v_cvt_pk_bf16_f32 v40, v62, v56
	v_cvt_pk_bf16_f32 v41, v63, v57
	v_cvt_pk_bf16_f32 v42, v64, v58
	v_cvt_pk_bf16_f32 v43, v65, v59
	global_load_dwordx4 v[44:47], v[70:71], off offset:256
	global_load_dwordx4 v[48:51], v[60:61], off offset:256
	v_add_u32_e32 v52, 0xa0, v146
	global_store_dwordx4 v[60:61], v[40:43], off
	v_mad_i64_i32 v[54:55], s[18:19], v52, s41, v[148:149]
	v_lshl_add_u64 v[54:55], v[54:55], 0, v[144:145]
	s_waitcnt vmcnt(0)
; __device__ __forceinline__ unsigned cvt_pk_bf16(float lo, float hi) { unsigned r; asm volatile("v_cvt_pk_bf16_f32 %0, %1, %2" : "=v"(r) : "v"(lo), "v"(hi)); return r; }
; __device__ __forceinline__ float bf_lo(unsigned u) { return __uint_as_float(u << 16); }
; __device__ __forceinline__ float bf_hi(unsigned u) { return __uint_as_float(u & 0xffff0000u); }
; #define PG8_WAIT_V(n) asm volatile("s_waitcnt vmcnt(" #n ")" ::: "memory")
;     __device__ __forceinline__ void operator()(const f32x4 (&acc)[2][2][4][2], const Unit& u, int wr, int wc, int fr, int fq) const {
;     ...
;             for (int m = 0; m < 4; ++m) { const size_t r = (size_t)(row0 + ai * HALF + m * 16); bf16_t* rowp = O + r * ldc + col0; const bf16_t* gp = G + r * ldg + col0;
; #pragma unroll
;                 for (int bj = 0; bj < 2; ++bj) { const u32x4 gw = *(const u32x4*)(gp + bj * HALF);
;                     f32x4 v0 = acc[ai][bj][m][0], v1 = acc[ai][bj][m][1];
;                     v0[0] *= bf_lo(gw.x); v0[1] *= bf_hi(gw.x); v0[2] *= bf_lo(gw.y); v0[3] *= bf_hi(gw.y);
;                     v1[0] *= bf_lo(gw.z); v1[1] *= bf_hi(gw.z); v1[2] *= bf_lo(gw.w); v1[3] *= bf_hi(gw.w);
;                     if (ACCUM) { const u32x4 pw = *(const u32x4*)(rowp + bj * HALF);
;                         v0[0] += bf_lo(pw.x); v0[1] += bf_hi(pw.x); v0[2] += bf_lo(pw.y); v0[3] += bf_hi(pw.y);
;                         v1[0] += bf_lo(pw.z); v1[1] += bf_hi(pw.z); v1[2] += bf_lo(pw.w); v1[3] += bf_hi(pw.w); }
;                     u32x4 w; w.x = cvt_pk_bf16(v0[0], v0[1]); w.y = cvt_pk_bf16(v0[2], v0[3]); w.z = cvt_pk_bf16(v1[0], v1[1]); w.w = cvt_pk_bf16(v1[2], v1[3]);
;                     *(u32x4*)(rowp + bj * HALF) = w; } }
; template <class Epi, class Sched>
; __device__ __forceinline__ void gemm_phase(PG8_LAS unsigned char* lds, const Gemm g, const Sched& S, const Epi& E) {
;     ...
;         if constexpr (!Epi::AFTER_DRAIN) { E(acc, cur, wr, wc, fr, fq); S.done(cur); }
;         if (!has_next) break;
; #pragma unroll
;         for (int a = 0; a < 2; ++a)
; #pragma unroll
;             for (int b = 0; b < 2; ++b)
; #pragma unroll
;                 for (int m = 0; m < 4; ++m)
; #pragma unroll
;                     for (int n = 0; n < 2; ++n) acc[a][b][m][n] = (f32x4){0.f, 0.f, 0.f, 0.f};
;         cur = nxt; cA = nA; cB = nB; ++ui;
;     }
;     PG8_WAIT_V(0);
;     if (wr == 0) PG8_BAR;
	v_lshlrev_b32_e32 v40, 16, v44
	v_lshlrev_b32_e32 v53, 16, v48
	v_and_b32_e32 v41, 0xffff0000, v44
	v_lshlrev_b32_e32 v44, 16, v46
	v_and_b32_e32 v48, 0xffff0000, v48
	v_lshlrev_b32_e32 v57, 16, v50
	v_fmac_f32_e32 v53, v36, v40
	v_fmac_f32_e32 v48, v37, v41
	v_fmac_f32_e32 v57, v32, v44
	v_cvt_pk_bf16_f32 v32, v53, v48
	v_ashrrev_i32_e32 v53, 31, v52
	v_lshlrev_b64 v[40:41], 11, v[52:53]
	v_lshlrev_b32_e32 v42, 16, v45
	v_and_b32_e32 v43, 0xffff0000, v45
	v_and_b32_e32 v45, 0xffff0000, v46
	v_and_b32_e32 v50, 0xffff0000, v50
	v_lshl_add_u64 v[40:41], s[0:1], 0, v[40:41]
	v_lshlrev_b32_e32 v46, 16, v47
	v_and_b32_e32 v47, 0xffff0000, v47
	v_lshlrev_b32_e32 v56, 16, v49
	v_and_b32_e32 v49, 0xffff0000, v49
	v_lshlrev_b32_e32 v58, 16, v51
	v_and_b32_e32 v51, 0xffff0000, v51
	v_fmac_f32_e32 v50, v33, v45
	v_lshl_add_u64 v[44:45], v[40:41], 0, v[144:145]
	v_fmac_f32_e32 v56, v38, v42
	v_fmac_f32_e32 v49, v39, v43
	v_fmac_f32_e32 v58, v34, v46
	v_fmac_f32_e32 v51, v35, v47
	v_cvt_pk_bf16_f32 v33, v56, v49
	v_cvt_pk_bf16_f32 v34, v57, v50
	v_cvt_pk_bf16_f32 v35, v58, v51
	global_load_dwordx4 v[36:39], v[54:55], off
	global_load_dwordx4 v[40:43], v[44:45], off
	s_waitcnt vmcnt(0)
	v_lshlrev_b32_e32 v46, 16, v40
	global_store_dwordx4 v[60:61], v[32:35], off offset:256
	v_and_b32_e32 v40, 0xffff0000, v40
	v_lshlrev_b32_e32 v47, 16, v41
	v_lshlrev_b32_e32 v32, 16, v36
	v_and_b32_e32 v33, 0xffff0000, v36
	v_lshlrev_b32_e32 v34, 16, v37
	v_and_b32_e32 v35, 0xffff0000, v37
	v_lshlrev_b32_e32 v36, 16, v38
	v_and_b32_e32 v37, 0xffff0000, v38
	v_lshlrev_b32_e32 v38, 16, v39
	v_and_b32_e32 v39, 0xffff0000, v39
	v_and_b32_e32 v41, 0xffff0000, v41
	v_lshlrev_b32_e32 v48, 16, v42
	v_and_b32_e32 v42, 0xffff0000, v42
	v_lshlrev_b32_e32 v49, 16, v43
	v_and_b32_e32 v43, 0xffff0000, v43
	v_fmac_f32_e32 v46, v28, v32
	v_fmac_f32_e32 v40, v29, v33
	v_fmac_f32_e32 v47, v30, v34
	v_fmac_f32_e32 v41, v31, v35
	v_fmac_f32_e32 v48, v24, v36
	v_fmac_f32_e32 v42, v25, v37
	v_fmac_f32_e32 v49, v26, v38
	v_fmac_f32_e32 v43, v27, v39
	v_cvt_pk_bf16_f32 v24, v46, v40
	v_cvt_pk_bf16_f32 v25, v47, v41
	v_cvt_pk_bf16_f32 v26, v48, v42
	v_cvt_pk_bf16_f32 v27, v49, v43
	global_load_dwordx4 v[28:31], v[54:55], off offset:256
	global_load_dwordx4 v[32:35], v[44:45], off offset:256
	v_add_u32_e32 v36, 0xb0, v146
	global_store_dwordx4 v[44:45], v[24:27], off
	v_mad_i64_i32 v[38:39], s[18:19], v36, s41, v[148:149]
	v_lshl_add_u64 v[38:39], v[38:39], 0, v[144:145]
	s_mov_b64 s[18:19], s[12:13]
	s_waitcnt vmcnt(0)
	v_lshlrev_b32_e32 v24, 16, v28
	v_lshlrev_b32_e32 v37, 16, v32
	v_and_b32_e32 v25, 0xffff0000, v28
	v_lshlrev_b32_e32 v28, 16, v30
	v_and_b32_e32 v32, 0xffff0000, v32
	v_lshlrev_b32_e32 v41, 16, v34
	v_fmac_f32_e32 v37, v20, v24
	v_fmac_f32_e32 v32, v21, v25
	v_fmac_f32_e32 v41, v16, v28
	v_cvt_pk_bf16_f32 v16, v37, v32
	v_ashrrev_i32_e32 v37, 31, v36
	v_lshlrev_b64 v[24:25], 11, v[36:37]
	v_lshlrev_b32_e32 v26, 16, v29
	v_and_b32_e32 v27, 0xffff0000, v29
	v_and_b32_e32 v29, 0xffff0000, v30
	v_and_b32_e32 v34, 0xffff0000, v34
	v_lshl_add_u64 v[24:25], s[0:1], 0, v[24:25]
	v_lshlrev_b32_e32 v30, 16, v31
	v_and_b32_e32 v31, 0xffff0000, v31
	v_lshlrev_b32_e32 v40, 16, v33
	v_and_b32_e32 v33, 0xffff0000, v33
	v_lshlrev_b32_e32 v42, 16, v35
	v_and_b32_e32 v35, 0xffff0000, v35
	v_fmac_f32_e32 v34, v17, v29
	v_lshl_add_u64 v[28:29], v[24:25], 0, v[144:145]
	v_fmac_f32_e32 v40, v22, v26
	v_fmac_f32_e32 v33, v23, v27
	v_fmac_f32_e32 v42, v18, v30
	v_fmac_f32_e32 v35, v19, v31
	v_cvt_pk_bf16_f32 v17, v40, v33
	v_cvt_pk_bf16_f32 v18, v41, v34
	v_cvt_pk_bf16_f32 v19, v42, v35
	global_load_dwordx4 v[20:23], v[38:39], off
	global_load_dwordx4 v[24:27], v[28:29], off
	s_waitcnt vmcnt(0)
	v_lshlrev_b32_e32 v30, 16, v24
	global_store_dwordx4 v[44:45], v[16:19], off offset:256
	v_and_b32_e32 v24, 0xffff0000, v24
	v_lshlrev_b32_e32 v31, 16, v25
	v_lshlrev_b32_e32 v16, 16, v20
	v_and_b32_e32 v17, 0xffff0000, v20
	v_lshlrev_b32_e32 v18, 16, v21
	v_and_b32_e32 v19, 0xffff0000, v21
	v_lshlrev_b32_e32 v20, 16, v22
	v_and_b32_e32 v21, 0xffff0000, v22
	v_lshlrev_b32_e32 v22, 16, v23
	v_and_b32_e32 v23, 0xffff0000, v23
	v_and_b32_e32 v25, 0xffff0000, v25
	v_lshlrev_b32_e32 v32, 16, v26
	v_and_b32_e32 v26, 0xffff0000, v26
	v_lshlrev_b32_e32 v33, 16, v27
	v_and_b32_e32 v27, 0xffff0000, v27
	v_fmac_f32_e32 v30, v12, v16
	v_fmac_f32_e32 v24, v13, v17
	v_fmac_f32_e32 v31, v14, v18
	v_fmac_f32_e32 v25, v15, v19
	v_fmac_f32_e32 v32, v8, v20
	v_fmac_f32_e32 v26, v9, v21
	v_fmac_f32_e32 v33, v10, v22
	v_fmac_f32_e32 v27, v11, v23
	v_cvt_pk_bf16_f32 v8, v30, v24
	v_cvt_pk_bf16_f32 v9, v31, v25
	v_cvt_pk_bf16_f32 v10, v32, v26
	v_cvt_pk_bf16_f32 v11, v33, v27
	global_load_dwordx4 v[12:15], v[38:39], off offset:256
	global_load_dwordx4 v[16:19], v[28:29], off offset:256
	s_waitcnt vmcnt(0)
	v_lshlrev_b32_e32 v20, 16, v16
	global_store_dwordx4 v[28:29], v[8:11], off
	v_and_b32_e32 v16, 0xffff0000, v16
	v_lshlrev_b32_e32 v21, 16, v17
	v_lshlrev_b32_e32 v8, 16, v12
	v_and_b32_e32 v9, 0xffff0000, v12
	v_lshlrev_b32_e32 v10, 16, v13
	v_and_b32_e32 v11, 0xffff0000, v13
	v_lshlrev_b32_e32 v12, 16, v14
	v_and_b32_e32 v13, 0xffff0000, v14
	v_lshlrev_b32_e32 v14, 16, v15
	v_and_b32_e32 v15, 0xffff0000, v15
	v_and_b32_e32 v17, 0xffff0000, v17
	v_lshlrev_b32_e32 v22, 16, v18
	v_and_b32_e32 v18, 0xffff0000, v18
	v_lshlrev_b32_e32 v23, 16, v19
	v_and_b32_e32 v19, 0xffff0000, v19
	v_fmac_f32_e32 v20, v4, v8
	v_fmac_f32_e32 v16, v5, v9
	v_fmac_f32_e32 v21, v6, v10
	v_fmac_f32_e32 v17, v7, v11
	v_fmac_f32_e32 v22, v0, v12
	v_fmac_f32_e32 v18, v1, v13
	v_fmac_f32_e32 v23, v2, v14
	v_fmac_f32_e32 v19, v3, v15
	v_cvt_pk_bf16_f32 v0, v20, v16
	v_cvt_pk_bf16_f32 v1, v21, v17
	v_cvt_pk_bf16_f32 v2, v22, v18
	v_cvt_pk_bf16_f32 v3, v23, v19
	global_store_dwordx4 v[28:29], v[0:3], off offset:256
	s_cbranch_vccz .LBB0_1004
	s_waitcnt vmcnt(0)
	s_cmpk_gt_u32 s25, 0xff
	s_cbranch_scc1 .LBB0_1015
	s_barrier

; #define PG8_STAGE(bufoff, gbase, voff) do { _Pragma("unroll") for (int _i = 0; _i < 2; ++_i) \
;         __builtin_amdgcn_global_load_lds((const unsigned*)((const char*)(gbase) + (voff)[_i]), (PG8_LAS unsigned*)(lds + (bufoff) + ldsw + _i * 8192), 16, 0, 0); } while (0)
; #define PG8_LDA(dst, b, h) do { _Pragma("unroll") for (int m = 0; m < 4; ++m) _Pragma("unroll") for (int k = 0; k < 2; ++k) dst[m][k] = *(const PG8_LAS bf16x8*)(lds + PG8_SA(b, h) + aoff + m * 2048 + k * 1024); } while (0)
; #define PG8_LDB(dst, b, h) do { _Pragma("unroll") for (int n = 0; n < 2; ++n) _Pragma("unroll") for (int k = 0; k < 2; ++k) dst[n][k] = *(const PG8_LAS bf16x8*)(lds + PG8_SB(b, h) + boff + n * 2048 + k * 1024); } while (0)
; #define PG8_MMA(ai, bj, At, Bt) do { __builtin_amdgcn_s_setprio(1); _Pragma("unroll") for (int m = 0; m < 4; ++m) _Pragma("unroll") for (int n = 0; n < 2; ++n) _Pragma("unroll") for (int k = 0; k < 2; ++k) \
;         acc[ai][bj][m][n] = __builtin_amdgcn_mfma_f32_16x16x32_bf16(Bt[n][k], At[m][k], acc[ai][bj][m][n], 0, 0, 0); __builtin_amdgcn_s_setprio(0); } while (0)
; #define PG8_WAIT_V(n) asm volatile("s_waitcnt vmcnt(" #n ")" ::: "memory")
; #define PG8_WAIT_L(n) asm volatile("s_waitcnt lgkmcnt(" #n ")" ::: "memory")
; template <class Epi, class Sched>
; __device__ __forceinline__ void gemm_phase(PG8_LAS unsigned char* lds, const Gemm g, const Sched& S, const Epi& E) {
;     ...
;             const bool last = (t == nt - 2);
;             const char* a1 = cA + (size_t)(t + 1) * kstep;
;             const char* a2 = last ? nA : cA + (size_t)(t + 2) * kstep; const char* b2 = last ? nB : cB + (size_t)(t + 2) * kstep;
;             const char* a3 = a2 + kstep; const char* b3 = b2 + kstep;
;             if (last && has_next) S.a_ready(nxt);
;             PG8_LDB(B0, 0, 0); PG8_SCHED; PG8_LDA(At, 0, 0); PG8_STAGE(PG8_SA(1, 1), a1 + hstep, voffA);
;             PG8_WAIT_L(8); PG8_BAR; PG8_WAIT_L(0); PG8_MMA(0, 0, At, B0); PG8_BAR; PG8_SCHED;
;             PG8_LDB(B1, 0, 1); PG8_STAGE(PG8_SB(0, 0), b2, voffB);
;             PG8_BAR; PG8_WAIT_L(0); PG8_MMA(0, 1, At, B1); PG8_BAR;
;             PG8_LDA(At, 0, 1); PG8_STAGE(PG8_SA(0, 0), a2, voffA);
;             PG8_BAR; PG8_WAIT_L(0); PG8_MMA(1, 0, At, B0); PG8_BAR; PG8_SCHED;
;             PG8_STAGE(PG8_SB(0, 1), b2 + hstep, voffB);
;             PG8_WAIT_V(6); PG8_BAR; PG8_MMA(1, 1, At, B1); PG8_BAR;
.LBB0_1083:
	ds_read_b128 v[152:155], v149
	ds_read_b128 v[156:159], v149 offset:1024
	ds_read_b128 v[160:163], v149 offset:2048
	ds_read_b128 v[164:167], v149 offset:3072
	s_add_u32 s26, s24, 0xfffc0080
	s_addc_u32 s27, s25, -1
	s_cmp_eq_u32 s56, 12
	s_cselect_b32 s29, s17, s27
	s_cselect_b32 s28, s52, s26
	s_cselect_b32 s27, s15, s55
	s_cselect_b32 s26, s53, s54
	v_lshl_add_u64 v[144:145], s[24:25], 0, v[136:137]
	s_add_i32 m0, s23, 0xc000
	ds_read_b128 v[168:171], v150
	ds_read_b128 v[172:175], v150 offset:1024
	ds_read_b128 v[182:185], v150 offset:2048
	ds_read_b128 v[190:193], v150 offset:3072
	ds_read_b128 v[194:197], v150 offset:4096
	ds_read_b128 v[198:201], v150 offset:5120
	ds_read_b128 v[202:205], v150 offset:6144
	ds_read_b128 v[206:209], v150 offset:7168
	global_load_lds_dwordx4 v[144:145], off
	v_lshl_add_u64 v[144:145], s[24:25], 0, v[138:139]
	s_add_i32 m0, s23, 0xe000
	s_nop 0
	global_load_lds_dwordx4 v[144:145], off
	s_waitcnt lgkmcnt(0)
	s_barrier
	v_mfma_f32_16x16x32_bf16 v[124:127], v[152:155], v[168:171], v[124:127]
	v_mfma_f32_16x16x32_bf16 v[120:123], v[160:163], v[168:171], v[120:123]
	v_mfma_f32_16x16x32_bf16 v[108:111], v[152:155], v[182:185], v[108:111]
	v_mfma_f32_16x16x32_bf16 v[104:107], v[160:163], v[182:185], v[104:107]
	v_mfma_f32_16x16x32_bf16 v[92:95], v[152:155], v[194:197], v[92:95]
	v_mfma_f32_16x16x32_bf16 v[88:91], v[160:163], v[194:197], v[88:91]
	v_mfma_f32_16x16x32_bf16 v[76:79], v[152:155], v[202:205], v[76:79]
	v_mfma_f32_16x16x32_bf16 v[72:75], v[160:163], v[202:205], v[72:75]
	v_mfma_f32_16x16x32_bf16 v[124:127], v[156:159], v[172:175], v[124:127]
	v_mfma_f32_16x16x32_bf16 v[120:123], v[164:167], v[172:175], v[120:123]
	v_mfma_f32_16x16x32_bf16 v[108:111], v[156:159], v[190:193], v[108:111]
	v_mfma_f32_16x16x32_bf16 v[104:107], v[164:167], v[190:193], v[104:107]
	v_mfma_f32_16x16x32_bf16 v[92:95], v[156:159], v[198:201], v[92:95]
	v_mfma_f32_16x16x32_bf16 v[88:91], v[164:167], v[198:201], v[88:91]
	v_mfma_f32_16x16x32_bf16 v[76:79], v[156:159], v[206:209], v[76:79]
	v_mfma_f32_16x16x32_bf16 v[72:75], v[164:167], v[206:209], v[72:75]
	s_barrier
	s_add_i32 s57, s45, s37
	v_lshl_add_u64 v[144:145], s[26:27], 0, v[130:131]
	s_mov_b32 m0, s57
	ds_read_b128 v[210:213], v151
	ds_read_b128 v[214:217], v151 offset:1024
	ds_read_b128 v[218:221], v151 offset:2048
	ds_read_b128 v[222:225], v151 offset:3072
	global_load_lds_dwordx4 v[144:145], off
	v_lshl_add_u64 v[186:187], s[26:27], 0, v[134:135]
	s_add_i32 m0, s57, 0x2000
	s_nop 0
	global_load_lds_dwordx4 v[186:187], off
	s_waitcnt lgkmcnt(0)
	s_barrier
	v_mfma_f32_16x16x32_bf16 v[116:119], v[210:213], v[168:171], v[116:119]
	v_mfma_f32_16x16x32_bf16 v[112:115], v[218:221], v[168:171], v[112:115]
	v_mfma_f32_16x16x32_bf16 v[100:103], v[210:213], v[182:185], v[100:103]
	v_mfma_f32_16x16x32_bf16 v[96:99], v[218:221], v[182:185], v[96:99]
	v_mfma_f32_16x16x32_bf16 v[84:87], v[210:213], v[194:197], v[84:87]
	v_mfma_f32_16x16x32_bf16 v[80:83], v[218:221], v[194:197], v[80:83]
	v_mfma_f32_16x16x32_bf16 v[68:71], v[210:213], v[202:205], v[68:71]
	v_mfma_f32_16x16x32_bf16 v[64:67], v[218:221], v[202:205], v[64:67]
	v_mfma_f32_16x16x32_bf16 v[116:119], v[214:217], v[172:175], v[116:119]
	v_mfma_f32_16x16x32_bf16 v[112:115], v[222:225], v[172:175], v[112:115]
	v_mfma_f32_16x16x32_bf16 v[100:103], v[214:217], v[190:193], v[100:103]
	v_mfma_f32_16x16x32_bf16 v[96:99], v[222:225], v[190:193], v[96:99]
	v_mfma_f32_16x16x32_bf16 v[84:87], v[214:217], v[198:201], v[84:87]
	v_mfma_f32_16x16x32_bf16 v[80:83], v[222:225], v[198:201], v[80:83]
	v_mfma_f32_16x16x32_bf16 v[68:71], v[214:217], v[206:209], v[68:71]
	v_mfma_f32_16x16x32_bf16 v[64:67], v[222:225], v[206:209], v[64:67]
	s_mov_b32 m0, s23
	v_lshl_add_u64 v[226:227], s[28:29], 0, v[128:129]
	s_barrier
	ds_read_b128 v[168:171], v150 offset:16384
	ds_read_b128 v[172:175], v150 offset:17408
	ds_read_b128 v[182:185], v150 offset:18432
	ds_read_b128 v[190:193], v150 offset:19456
	ds_read_b128 v[194:197], v150 offset:20480
	ds_read_b128 v[198:201], v150 offset:21504
	ds_read_b128 v[202:205], v150 offset:22528
	ds_read_b128 v[206:209], v150 offset:23552
	global_load_lds_dwordx4 v[226:227], off
	v_lshl_add_u64 v[228:229], s[28:29], 0, v[132:133]
	s_mov_b32 m0, s38
	s_nop 0
	global_load_lds_dwordx4 v[228:229], off
	s_waitcnt lgkmcnt(0)
	s_barrier
	v_mfma_f32_16x16x32_bf16 v[60:63], v[152:155], v[168:171], v[60:63]
	v_mfma_f32_16x16x32_bf16 v[56:59], v[160:163], v[168:171], v[56:59]
	v_mfma_f32_16x16x32_bf16 v[48:51], v[152:155], v[182:185], v[48:51]
	v_mfma_f32_16x16x32_bf16 v[40:43], v[160:163], v[182:185], v[40:43]
	v_mfma_f32_16x16x32_bf16 v[32:35], v[152:155], v[194:197], v[32:35]
	v_mfma_f32_16x16x32_bf16 v[24:27], v[160:163], v[194:197], v[24:27]
	v_mfma_f32_16x16x32_bf16 v[16:19], v[152:155], v[202:205], v[16:19]
	v_mfma_f32_16x16x32_bf16 v[8:11], v[160:163], v[202:205], v[8:11]
	v_mfma_f32_16x16x32_bf16 v[60:63], v[156:159], v[172:175], v[60:63]
	v_mfma_f32_16x16x32_bf16 v[56:59], v[164:167], v[172:175], v[56:59]
	v_mfma_f32_16x16x32_bf16 v[48:51], v[156:159], v[190:193], v[48:51]
	v_mfma_f32_16x16x32_bf16 v[40:43], v[164:167], v[190:193], v[40:43]
	v_mfma_f32_16x16x32_bf16 v[32:35], v[156:159], v[198:201], v[32:35]
	v_mfma_f32_16x16x32_bf16 v[24:27], v[164:167], v[198:201], v[24:27]
	v_mfma_f32_16x16x32_bf16 v[16:19], v[156:159], v[206:209], v[16:19]
	v_mfma_f32_16x16x32_bf16 v[8:11], v[164:167], v[206:209], v[8:11]
	s_barrier
	s_add_u32 s58, s26, 0x40000
	s_addc_u32 s59, s27, 0
	s_add_i32 s57, s46, s37
	v_lshl_add_u64 v[152:153], s[58:59], 0, v[130:131]
	s_mov_b32 m0, s57
	s_nop 0
	global_load_lds_dwordx4 v[152:153], off
	v_lshl_add_u64 v[152:153], s[58:59], 0, v[134:135]
	s_add_i32 m0, s57, 0x2000
	s_nop 0
	global_load_lds_dwordx4 v[152:153], off
	s_waitcnt vmcnt(6)
	s_barrier
; #define PG8_STAGE(bufoff, gbase, voff) do { _Pragma("unroll") for (int _i = 0; _i < 2; ++_i) \
;         __builtin_amdgcn_global_load_lds((const unsigned*)((const char*)(gbase) + (voff)[_i]), (PG8_LAS unsigned*)(lds + (bufoff) + ldsw + _i * 8192), 16, 0, 0); } while (0)
; #define PG8_LDA(dst, b, h) do { _Pragma("unroll") for (int m = 0; m < 4; ++m) _Pragma("unroll") for (int k = 0; k < 2; ++k) dst[m][k] = *(const PG8_LAS bf16x8*)(lds + PG8_SA(b, h) + aoff + m * 2048 + k * 1024); } while (0)
; #define PG8_LDB(dst, b, h) do { _Pragma("unroll") for (int n = 0; n < 2; ++n) _Pragma("unroll") for (int k = 0; k < 2; ++k) dst[n][k] = *(const PG8_LAS bf16x8*)(lds + PG8_SB(b, h) + boff + n * 2048 + k * 1024); } while (0)
; #define PG8_MMA(ai, bj, At, Bt) do { __builtin_amdgcn_s_setprio(1); _Pragma("unroll") for (int m = 0; m < 4; ++m) _Pragma("unroll") for (int n = 0; n < 2; ++n) _Pragma("unroll") for (int k = 0; k < 2; ++k) \
;         acc[ai][bj][m][n] = __builtin_amdgcn_mfma_f32_16x16x32_bf16(Bt[n][k], At[m][k], acc[ai][bj][m][n], 0, 0, 0); __builtin_amdgcn_s_setprio(0); } while (0)
; #define PG8_WAIT_V(n) asm volatile("s_waitcnt vmcnt(" #n ")" ::: "memory")
; #define PG8_WAIT_L(n) asm volatile("s_waitcnt lgkmcnt(" #n ")" ::: "memory")
; #define PG8_BAR __builtin_amdgcn_s_barrier()
; #define PG8_SCHED __builtin_amdgcn_sched_barrier(0)
; template <class Epi, class Sched>
; __device__ __forceinline__ void gemm_phase(PG8_LAS unsigned char* lds, const Gemm g, const Sched& S, const Epi& E) {
;     ...
;             PG8_WAIT_V(6); PG8_BAR; PG8_MMA(1, 1, At, B1); PG8_BAR;
;             PG8_LDB(B0, 1, 0); PG8_SCHED; PG8_LDA(At, 1, 0); PG8_STAGE(PG8_SA(0, 1), a2 + hstep, voffA);
;             PG8_WAIT_L(8); PG8_BAR; PG8_WAIT_L(0); PG8_MMA(0, 0, At, B0); PG8_BAR; PG8_SCHED;
;             PG8_LDB(B1, 1, 1); PG8_STAGE(PG8_SB(1, 0), b3, voffB);
;             PG8_BAR; PG8_WAIT_L(0); PG8_MMA(0, 1, At, B1); PG8_BAR;
;             PG8_LDA(At, 1, 1); PG8_STAGE(PG8_SA(1, 0), a3, voffA);
;             PG8_BAR; PG8_WAIT_L(0); PG8_MMA(1, 0, At, B0); PG8_BAR; PG8_SCHED;
;             PG8_STAGE(PG8_SB(1, 1), b3 + hstep, voffB);
	v_mfma_f32_16x16x32_bf16 v[52:55], v[210:213], v[168:171], v[52:55]
	v_mfma_f32_16x16x32_bf16 v[44:47], v[218:221], v[168:171], v[44:47]
	v_mfma_f32_16x16x32_bf16 v[36:39], v[210:213], v[182:185], v[36:39]
	v_mfma_f32_16x16x32_bf16 v[28:31], v[218:221], v[182:185], v[28:31]
	v_mfma_f32_16x16x32_bf16 v[20:23], v[210:213], v[194:197], v[20:23]
	v_mfma_f32_16x16x32_bf16 v[12:15], v[218:221], v[194:197], v[12:15]
	v_mfma_f32_16x16x32_bf16 v[4:7], v[210:213], v[202:205], v[4:7]
	v_mfma_f32_16x16x32_bf16 v[0:3], v[218:221], v[202:205], v[0:3]
	v_mfma_f32_16x16x32_bf16 v[52:55], v[214:217], v[172:175], v[52:55]
	v_mfma_f32_16x16x32_bf16 v[44:47], v[222:225], v[172:175], v[44:47]
	v_mfma_f32_16x16x32_bf16 v[36:39], v[214:217], v[190:193], v[36:39]
	v_mfma_f32_16x16x32_bf16 v[28:31], v[222:225], v[190:193], v[28:31]
	v_mfma_f32_16x16x32_bf16 v[20:23], v[214:217], v[198:201], v[20:23]
	v_mfma_f32_16x16x32_bf16 v[12:15], v[222:225], v[198:201], v[12:15]
	v_mfma_f32_16x16x32_bf16 v[4:7], v[214:217], v[206:209], v[4:7]
	v_mfma_f32_16x16x32_bf16 v[0:3], v[222:225], v[206:209], v[0:3]
	s_add_i32 s57, 0, 0x18000
	v_add_u32_e32 v164, s57, v147
	s_barrier
	ds_read_b128 v[152:155], v164
	ds_read_b128 v[156:159], v164 offset:1024
	ds_read_b128 v[160:163], v164 offset:2048
	ds_read_b128 v[164:167], v164 offset:3072
	s_add_u32 s28, s28, 0x40000
	s_addc_u32 s29, s29, 0
	s_mov_b32 m0, s39
	v_lshl_add_u64 v[210:211], s[28:29], 0, v[128:129]
	ds_read_b128 v[168:171], v150 offset:32768
	ds_read_b128 v[172:175], v150 offset:33792
	ds_read_b128 v[182:185], v150 offset:34816
	ds_read_b128 v[190:193], v150 offset:35840
	ds_read_b128 v[194:197], v150 offset:36864
	ds_read_b128 v[198:201], v150 offset:37888
	ds_read_b128 v[202:205], v150 offset:38912
	ds_read_b128 v[206:209], v150 offset:39936
	global_load_lds_dwordx4 v[210:211], off
	v_lshl_add_u64 v[210:211], s[28:29], 0, v[132:133]
	s_mov_b32 m0, s40
	s_nop 0
	global_load_lds_dwordx4 v[210:211], off
	s_waitcnt lgkmcnt(0)
	s_barrier
	v_mfma_f32_16x16x32_bf16 v[124:127], v[152:155], v[168:171], v[124:127]
	v_mfma_f32_16x16x32_bf16 v[120:123], v[160:163], v[168:171], v[120:123]
	v_mfma_f32_16x16x32_bf16 v[108:111], v[152:155], v[182:185], v[108:111]
	v_mfma_f32_16x16x32_bf16 v[104:107], v[160:163], v[182:185], v[104:107]
	v_mfma_f32_16x16x32_bf16 v[92:95], v[152:155], v[194:197], v[92:95]
	v_mfma_f32_16x16x32_bf16 v[88:91], v[160:163], v[194:197], v[88:91]
	v_mfma_f32_16x16x32_bf16 v[76:79], v[152:155], v[202:205], v[76:79]
	v_mfma_f32_16x16x32_bf16 v[72:75], v[160:163], v[202:205], v[72:75]
	v_mfma_f32_16x16x32_bf16 v[124:127], v[156:159], v[172:175], v[124:127]
	v_mfma_f32_16x16x32_bf16 v[120:123], v[164:167], v[172:175], v[120:123]
	v_mfma_f32_16x16x32_bf16 v[108:111], v[156:159], v[190:193], v[108:111]
	v_mfma_f32_16x16x32_bf16 v[104:107], v[164:167], v[190:193], v[104:107]
	v_mfma_f32_16x16x32_bf16 v[92:95], v[156:159], v[198:201], v[92:95]
	v_mfma_f32_16x16x32_bf16 v[88:91], v[164:167], v[198:201], v[88:91]
	v_mfma_f32_16x16x32_bf16 v[76:79], v[156:159], v[206:209], v[76:79]
	v_mfma_f32_16x16x32_bf16 v[72:75], v[164:167], v[206:209], v[72:75]
	s_barrier
	s_add_i32 s28, 0, 0x1c000
	s_add_i32 s29, s57, s37
	v_add_u32_e32 v179, s28, v147
	v_lshl_add_u64 v[144:145], v[144:145], 0, s[6:7]
	s_mov_b32 m0, s29
	ds_read_b128 v[210:213], v179
	ds_read_b128 v[214:217], v179 offset:1024
	ds_read_b128 v[218:221], v179 offset:2048
	ds_read_b128 v[222:225], v179 offset:3072
	global_load_lds_dwordx4 v[144:145], off
	v_lshl_add_u64 v[144:145], v[186:187], 0, s[6:7]
	s_add_i32 m0, s29, 0x2000
	s_nop 0
	global_load_lds_dwordx4 v[144:145], off
	s_waitcnt lgkmcnt(0)
	s_barrier
	v_mfma_f32_16x16x32_bf16 v[116:119], v[210:213], v[168:171], v[116:119]
	v_mfma_f32_16x16x32_bf16 v[112:115], v[218:221], v[168:171], v[112:115]
	v_mfma_f32_16x16x32_bf16 v[100:103], v[210:213], v[182:185], v[100:103]
	v_mfma_f32_16x16x32_bf16 v[96:99], v[218:221], v[182:185], v[96:99]
	v_mfma_f32_16x16x32_bf16 v[84:87], v[210:213], v[194:197], v[84:87]
	v_mfma_f32_16x16x32_bf16 v[80:83], v[218:221], v[194:197], v[80:83]
	v_mfma_f32_16x16x32_bf16 v[68:71], v[210:213], v[202:205], v[68:71]
	v_mfma_f32_16x16x32_bf16 v[64:67], v[218:221], v[202:205], v[64:67]
	v_mfma_f32_16x16x32_bf16 v[116:119], v[214:217], v[172:175], v[116:119]
	v_mfma_f32_16x16x32_bf16 v[112:115], v[222:225], v[172:175], v[112:115]
	v_mfma_f32_16x16x32_bf16 v[100:103], v[214:217], v[190:193], v[100:103]
	v_mfma_f32_16x16x32_bf16 v[96:99], v[222:225], v[190:193], v[96:99]
	v_mfma_f32_16x16x32_bf16 v[84:87], v[214:217], v[198:201], v[84:87]
	v_mfma_f32_16x16x32_bf16 v[80:83], v[222:225], v[198:201], v[80:83]
	v_mfma_f32_16x16x32_bf16 v[68:71], v[214:217], v[206:209], v[68:71]
	v_mfma_f32_16x16x32_bf16 v[64:67], v[222:225], v[206:209], v[64:67]
	s_mov_b32 m0, s42
	v_lshl_add_u64 v[144:145], v[226:227], 0, s[6:7]
	s_barrier
	ds_read_b128 v[168:171], v150 offset:49152
	ds_read_b128 v[172:175], v150 offset:50176
	ds_read_b128 v[182:185], v150 offset:51200
	ds_read_b128 v[190:193], v150 offset:52224
	ds_read_b128 v[194:197], v150 offset:53248
	ds_read_b128 v[198:201], v150 offset:54272
	ds_read_b128 v[202:205], v150 offset:55296
	ds_read_b128 v[206:209], v150 offset:56320
	global_load_lds_dwordx4 v[144:145], off
	v_lshl_add_u64 v[144:145], v[228:229], 0, s[6:7]
	s_mov_b32 m0, s43
	s_nop 0
	global_load_lds_dwordx4 v[144:145], off
	s_waitcnt lgkmcnt(0)
	s_barrier
; __device__ __forceinline__ unsigned cvt_pk_bf16(float lo, float hi) { unsigned r; asm volatile("v_cvt_pk_bf16_f32 %0, %1, %2" : "=v"(r) : "v"(lo), "v"(hi)); return r; }
; __device__ __forceinline__ float flogsig16(float x) { return (fminf(x, 0.f) - __logf(1.0f + __expf(-fabsf(x)))) * 0.0625f; }
; #define PG8_WAIT_V(n) asm volatile("s_waitcnt vmcnt(" #n ")" ::: "memory")
; #define PG8_WAIT_L(n) asm volatile("s_waitcnt lgkmcnt(" #n ")" ::: "memory")
;     __device__ __forceinline__ void operator()(const f32x4 (&acc)[2][2][4][2], const Unit& u, int wr, int wc, int fr, int fq) const {
;     ...
;         const int row0 = u.pm * BM + wr * 64 + fr, col0 = u.pn * BM + wc * 32 + 8 * fq, bcol0 = wc * 32 + 8 * fq;
;         f32x4 bv[2][2];
; #pragma unroll
;         for (int bj = 0; bj < 2; ++bj)
; #pragma unroll
;             for (int n = 0; n < 2; ++n) bv[bj][n] = bias ? *(const f32x4*)(bias + bcol0 + bj * HALF + 4 * n) : (f32x4){0.f, 0.f, 0.f, 0.f};
; #pragma unroll
;         for (int ai = 0; ai < 2; ++ai)
; #pragma unroll
;             for (int m = 0; m < 4; ++m) { bf16_t* rowp = O + (size_t)(row0 + ai * HALF + m * 16) * ldc + col0;
; #pragma unroll
;                 for (int bj = 0; bj < 2; ++bj) { f32x4 v0 = acc[ai][bj][m][0] + bv[bj][0], v1 = acc[ai][bj][m][1] + bv[bj][1];
;                     if (act == 1) {
; #pragma unroll
;                         for (int j = 0; j < 1; ++j) { v0 = v0 * sigmoid4(v0); v1 = v1 * sigmoid4(v1); } }
;                     else if (act == 2) {
; #pragma unroll
;                         for (int j = 0; j < 1; ++j) { v0 = sigmoid4(v0); v1 = sigmoid4(v1); } }
;                     else if (act == 3) {
; #pragma unroll
;                         for (int j = 0; j < 4; ++j) { v0[j] = flogsig16(v0[j]); v1[j] = flogsig16(v1[j]); } }
;                     u32x4 w; w.x = cvt_pk_bf16(v0[0], v0[1]); w.y = cvt_pk_bf16(v0[2], v0[3]); w.z = cvt_pk_bf16(v1[0], v1[1]); w.w = cvt_pk_bf16(v1[2], v1[3]);
;                     *(u32x4*)(rowp + bj * HALF) = w; } }
; template <class Epi, class Sched>
; __device__ __forceinline__ void gemm_phase(PG8_LAS unsigned char* lds, const Gemm g, const Sched& S, const Epi& E) {
;     ...
;             PG8_BAR; PG8_WAIT_L(0); PG8_MMA(1, 0, At, B0); PG8_BAR; PG8_SCHED;
;             PG8_STAGE(PG8_SB(1, 1), b3 + hstep, voffB);
;             PG8_WAIT_V(6); PG8_BAR; PG8_MMA(1, 1, At, B1); PG8_BAR;
	v_mfma_f32_16x16x32_bf16 v[60:63], v[152:155], v[168:171], v[60:63]
	v_mfma_f32_16x16x32_bf16 v[56:59], v[160:163], v[168:171], v[56:59]
	v_mfma_f32_16x16x32_bf16 v[48:51], v[152:155], v[182:185], v[48:51]
	v_mfma_f32_16x16x32_bf16 v[40:43], v[160:163], v[182:185], v[40:43]
	v_mfma_f32_16x16x32_bf16 v[32:35], v[152:155], v[194:197], v[32:35]
	v_mfma_f32_16x16x32_bf16 v[24:27], v[160:163], v[194:197], v[24:27]
	v_mfma_f32_16x16x32_bf16 v[16:19], v[152:155], v[202:205], v[16:19]
	v_mfma_f32_16x16x32_bf16 v[8:11], v[160:163], v[202:205], v[8:11]
	v_mfma_f32_16x16x32_bf16 v[60:63], v[156:159], v[172:175], v[60:63]
	v_mfma_f32_16x16x32_bf16 v[56:59], v[164:167], v[172:175], v[56:59]
	v_mfma_f32_16x16x32_bf16 v[48:51], v[156:159], v[190:193], v[48:51]
	v_mfma_f32_16x16x32_bf16 v[40:43], v[164:167], v[190:193], v[40:43]
	v_mfma_f32_16x16x32_bf16 v[32:35], v[156:159], v[198:201], v[32:35]
	v_mfma_f32_16x16x32_bf16 v[24:27], v[164:167], v[198:201], v[24:27]
	v_mfma_f32_16x16x32_bf16 v[16:19], v[156:159], v[206:209], v[16:19]
	v_mfma_f32_16x16x32_bf16 v[8:11], v[164:167], v[206:209], v[8:11]
	s_barrier
	s_add_u32 s26, s26, 0x40080
	s_addc_u32 s27, s27, 0
	s_add_i32 s28, s28, s37
	v_lshl_add_u64 v[144:145], s[26:27], 0, v[130:131]
	s_mov_b32 m0, s28
	s_nop 0
	global_load_lds_dwordx4 v[144:145], off
	v_lshl_add_u64 v[144:145], s[26:27], 0, v[134:135]
	s_add_i32 m0, s28, 0x2000
	s_nop 0
	global_load_lds_dwordx4 v[144:145], off
	s_waitcnt vmcnt(6)
	s_barrier
	v_mfma_f32_16x16x32_bf16 v[52:55], v[210:213], v[168:171], v[52:55]
	v_mfma_f32_16x16x32_bf16 v[44:47], v[218:221], v[168:171], v[44:47]
	v_mfma_f32_16x16x32_bf16 v[36:39], v[210:213], v[182:185], v[36:39]
	v_mfma_f32_16x16x32_bf16 v[28:31], v[218:221], v[182:185], v[28:31]
	v_mfma_f32_16x16x32_bf16 v[20:23], v[210:213], v[194:197], v[20:23]
	v_mfma_f32_16x16x32_bf16 v[12:15], v[218:221], v[194:197], v[12:15]
	v_mfma_f32_16x16x32_bf16 v[4:7], v[210:213], v[202:205], v[4:7]
	v_mfma_f32_16x16x32_bf16 v[0:3], v[218:221], v[202:205], v[0:3]
	v_mfma_f32_16x16x32_bf16 v[52:55], v[214:217], v[172:175], v[52:55]
	v_mfma_f32_16x16x32_bf16 v[44:47], v[222:225], v[172:175], v[44:47]
	v_mfma_f32_16x16x32_bf16 v[36:39], v[214:217], v[190:193], v[36:39]
	v_mfma_f32_16x16x32_bf16 v[28:31], v[222:225], v[190:193], v[28:31]
	v_mfma_f32_16x16x32_bf16 v[20:23], v[214:217], v[198:201], v[20:23]
	v_mfma_f32_16x16x32_bf16 v[12:15], v[222:225], v[198:201], v[12:15]
	v_mfma_f32_16x16x32_bf16 v[4:7], v[214:217], v[206:209], v[4:7]
	v_mfma_f32_16x16x32_bf16 v[0:3], v[222:225], v[206:209], v[0:3]
	s_add_i32 s56, s56, 2
	s_add_u32 s24, s24, 0x100
	s_addc_u32 s25, s25, 0
	s_add_u32 s54, s54, 0x100
	s_addc_u32 s55, s55, 0
	s_cmp_gt_u32 s56, 13
	s_barrier
	s_cbranch_scc0 .LBB0_1083
	v_lshl_add_u32 v152, s22, 8, v146
	v_lshl_or_b32 v144, s51, 8, v148
	v_ashrrev_i32_e32 v153, 31, v152
	v_ashrrev_i32_e32 v145, 31, v144
	v_lshlrev_b64 v[154:155], 11, v[152:153]
	v_lshl_add_u64 v[154:155], s[4:5], 0, v[154:155]
	v_lshlrev_b64 v[156:157], 1, v[144:145]
	v_lshl_add_u64 v[144:145], v[154:155], 0, v[156:157]
	v_pk_add_f32 v[126:127], v[126:127], 0 op_sel_hi:[1,0]
	v_pk_add_f32 v[124:125], v[124:125], 0 op_sel_hi:[1,0]
	v_pk_add_f32 v[154:155], v[122:123], 0 op_sel_hi:[1,0]
	v_pk_add_f32 v[122:123], v[120:121], 0 op_sel_hi:[1,0]
	v_cvt_pk_bf16_f32 v120, v124, v125
	v_cvt_pk_bf16_f32 v121, v126, v127
	v_pk_add_f32 v[116:117], v[116:117], 0 op_sel_hi:[1,0]
	v_cvt_pk_bf16_f32 v122, v122, v123
	v_cvt_pk_bf16_f32 v123, v154, v155
	global_store_dwordx4 v[144:145], v[120:123], off
	v_pk_add_f32 v[118:119], v[118:119], 0 op_sel_hi:[1,0]
	v_pk_add_f32 v[110:111], v[110:111], 0 op_sel_hi:[1,0]
	v_pk_add_f32 v[120:121], v[114:115], 0 op_sel_hi:[1,0]
	v_pk_add_f32 v[114:115], v[112:113], 0 op_sel_hi:[1,0]
	v_cvt_pk_bf16_f32 v112, v116, v117
	v_cvt_pk_bf16_f32 v113, v118, v119
	v_pk_add_f32 v[108:109], v[108:109], 0 op_sel_hi:[1,0]
	v_cvt_pk_bf16_f32 v114, v114, v115
	v_cvt_pk_bf16_f32 v115, v120, v121
	global_store_dwordx4 v[144:145], v[112:115], off offset:256
	v_pk_add_f32 v[100:101], v[100:101], 0 op_sel_hi:[1,0]
	v_pk_add_f32 v[102:103], v[102:103], 0 op_sel_hi:[1,0]
	v_or_b32_e32 v112, 16, v152
	v_ashrrev_i32_e32 v113, 31, v112
	v_lshlrev_b64 v[112:113], 11, v[112:113]
	v_lshl_add_u64 v[112:113], s[4:5], 0, v[112:113]
	v_lshl_add_u64 v[112:113], v[112:113], 0, v[156:157]
	v_pk_add_f32 v[114:115], v[106:107], 0 op_sel_hi:[1,0]
	v_pk_add_f32 v[106:107], v[104:105], 0 op_sel_hi:[1,0]
	v_cvt_pk_bf16_f32 v104, v108, v109
	v_cvt_pk_bf16_f32 v105, v110, v111
	v_pk_add_f32 v[94:95], v[94:95], 0 op_sel_hi:[1,0]
	v_cvt_pk_bf16_f32 v106, v106, v107
	v_cvt_pk_bf16_f32 v107, v114, v115
	global_store_dwordx4 v[112:113], v[104:107], off
	v_pk_add_f32 v[92:93], v[92:93], 0 op_sel_hi:[1,0]
	v_pk_add_f32 v[84:85], v[84:85], 0 op_sel_hi:[1,0]
	v_pk_add_f32 v[104:105], v[98:99], 0 op_sel_hi:[1,0]
	v_pk_add_f32 v[98:99], v[96:97], 0 op_sel_hi:[1,0]
	v_cvt_pk_bf16_f32 v96, v100, v101
	v_cvt_pk_bf16_f32 v97, v102, v103
	v_pk_add_f32 v[86:87], v[86:87], 0 op_sel_hi:[1,0]
	v_cvt_pk_bf16_f32 v98, v98, v99
	v_cvt_pk_bf16_f32 v99, v104, v105
	global_store_dwordx4 v[112:113], v[96:99], off offset:256
	v_pk_add_f32 v[78:79], v[78:79], 0 op_sel_hi:[1,0]
	v_pk_add_f32 v[76:77], v[76:77], 0 op_sel_hi:[1,0]
	v_or_b32_e32 v96, 32, v152
	v_ashrrev_i32_e32 v97, 31, v96
	v_lshlrev_b64 v[96:97], 11, v[96:97]
	v_lshl_add_u64 v[96:97], s[4:5], 0, v[96:97]
; __device__ __forceinline__ unsigned cvt_pk_bf16(float lo, float hi) { unsigned r; asm volatile("v_cvt_pk_bf16_f32 %0, %1, %2" : "=v"(r) : "v"(lo), "v"(hi)); return r; }
; __device__ __forceinline__ float flogsig16(float x) { return (fminf(x, 0.f) - __logf(1.0f + __expf(-fabsf(x)))) * 0.0625f; }
; #define PG8_WAIT_V(n) asm volatile("s_waitcnt vmcnt(" #n ")" ::: "memory")
; #define PG8_BAR __builtin_amdgcn_s_barrier()
;     __device__ __forceinline__ void operator()(const f32x4 (&acc)[2][2][4][2], const Unit& u, int wr, int wc, int fr, int fq) const {
;     ...
;             for (int m = 0; m < 4; ++m) { bf16_t* rowp = O + (size_t)(row0 + ai * HALF + m * 16) * ldc + col0;
; #pragma unroll
;                 for (int bj = 0; bj < 2; ++bj) { f32x4 v0 = acc[ai][bj][m][0] + bv[bj][0], v1 = acc[ai][bj][m][1] + bv[bj][1];
;                     if (act == 1) {
; #pragma unroll
;                         for (int j = 0; j < 1; ++j) { v0 = v0 * sigmoid4(v0); v1 = v1 * sigmoid4(v1); } }
;                     else if (act == 2) {
; #pragma unroll
;                         for (int j = 0; j < 1; ++j) { v0 = sigmoid4(v0); v1 = sigmoid4(v1); } }
;                     else if (act == 3) {
; #pragma unroll
;                         for (int j = 0; j < 4; ++j) { v0[j] = flogsig16(v0[j]); v1[j] = flogsig16(v1[j]); } }
;                     u32x4 w; w.x = cvt_pk_bf16(v0[0], v0[1]); w.y = cvt_pk_bf16(v0[2], v0[3]); w.z = cvt_pk_bf16(v1[0], v1[1]); w.w = cvt_pk_bf16(v1[2], v1[3]);
;                     *(u32x4*)(rowp + bj * HALF) = w; } }
; template <class Epi, class Sched>
; __device__ __forceinline__ void gemm_phase(PG8_LAS unsigned char* lds, const Gemm g, const Sched& S, const Epi& E) {
;     ...
;         if (!has_next) break;
; #pragma unroll
;         for (int a = 0; a < 2; ++a)
; #pragma unroll
;             for (int b = 0; b < 2; ++b)
; #pragma unroll
;                 for (int m = 0; m < 4; ++m)
; #pragma unroll
;                     for (int n = 0; n < 2; ++n) acc[a][b][m][n] = (f32x4){0.f, 0.f, 0.f, 0.f};
;         cur = nxt; cA = nA; cB = nB; ++ui;
;     }
;     PG8_WAIT_V(0);
;     if (wr == 0) PG8_BAR;
;     PG8_BAR;
	v_lshl_add_u64 v[96:97], v[96:97], 0, v[156:157]
	v_pk_add_f32 v[98:99], v[90:91], 0 op_sel_hi:[1,0]
	v_pk_add_f32 v[90:91], v[88:89], 0 op_sel_hi:[1,0]
	v_cvt_pk_bf16_f32 v88, v92, v93
	v_cvt_pk_bf16_f32 v89, v94, v95
	v_pk_add_f32 v[70:71], v[70:71], 0 op_sel_hi:[1,0]
	v_cvt_pk_bf16_f32 v90, v90, v91
	v_cvt_pk_bf16_f32 v91, v98, v99
	global_store_dwordx4 v[96:97], v[88:91], off
	v_pk_add_f32 v[68:69], v[68:69], 0 op_sel_hi:[1,0]
	v_pk_add_f32 v[60:61], v[60:61], 0 op_sel_hi:[1,0]
	v_pk_add_f32 v[88:89], v[82:83], 0 op_sel_hi:[1,0]
	v_pk_add_f32 v[82:83], v[80:81], 0 op_sel_hi:[1,0]
	v_cvt_pk_bf16_f32 v80, v84, v85
	v_cvt_pk_bf16_f32 v81, v86, v87
	v_pk_add_f32 v[62:63], v[62:63], 0 op_sel_hi:[1,0]
	v_cvt_pk_bf16_f32 v82, v82, v83
	v_cvt_pk_bf16_f32 v83, v88, v89
	global_store_dwordx4 v[96:97], v[80:83], off offset:256
	v_pk_add_f32 v[54:55], v[54:55], 0 op_sel_hi:[1,0]
	v_pk_add_f32 v[52:53], v[52:53], 0 op_sel_hi:[1,0]
	v_or_b32_e32 v80, 48, v152
	v_ashrrev_i32_e32 v81, 31, v80
	v_lshlrev_b64 v[80:81], 11, v[80:81]
	v_lshl_add_u64 v[80:81], s[4:5], 0, v[80:81]
	v_lshl_add_u64 v[80:81], v[80:81], 0, v[156:157]
	v_pk_add_f32 v[82:83], v[74:75], 0 op_sel_hi:[1,0]
	v_pk_add_f32 v[74:75], v[72:73], 0 op_sel_hi:[1,0]
	v_cvt_pk_bf16_f32 v72, v76, v77
	v_cvt_pk_bf16_f32 v73, v78, v79
	v_pk_add_f32 v[48:49], v[48:49], 0 op_sel_hi:[1,0]
	v_cvt_pk_bf16_f32 v74, v74, v75
	v_cvt_pk_bf16_f32 v75, v82, v83
	global_store_dwordx4 v[80:81], v[72:75], off
	v_pk_add_f32 v[38:39], v[38:39], 0 op_sel_hi:[1,0]
	v_pk_add_f32 v[36:37], v[36:37], 0 op_sel_hi:[1,0]
	v_pk_add_f32 v[72:73], v[66:67], 0 op_sel_hi:[1,0]
	v_pk_add_f32 v[66:67], v[64:65], 0 op_sel_hi:[1,0]
	v_cvt_pk_bf16_f32 v64, v68, v69
	v_cvt_pk_bf16_f32 v65, v70, v71
	v_pk_add_f32 v[32:33], v[32:33], 0 op_sel_hi:[1,0]
	v_cvt_pk_bf16_f32 v66, v66, v67
	v_cvt_pk_bf16_f32 v67, v72, v73
	global_store_dwordx4 v[80:81], v[64:67], off offset:256
	v_pk_add_f32 v[22:23], v[22:23], 0 op_sel_hi:[1,0]
	v_pk_add_f32 v[20:21], v[20:21], 0 op_sel_hi:[1,0]
	v_pk_add_f32 v[66:67], v[58:59], 0 op_sel_hi:[1,0]
	v_pk_add_f32 v[58:59], v[56:57], 0 op_sel_hi:[1,0]
	v_cvt_pk_bf16_f32 v56, v60, v61
	v_add_co_u32_e32 v60, vcc, s47, v144
	v_cvt_pk_bf16_f32 v57, v62, v63
	v_cvt_pk_bf16_f32 v58, v58, v59
	v_cvt_pk_bf16_f32 v59, v66, v67
	v_lshl_add_u64 v[64:65], v[144:145], 0, s[0:1]
	s_nop 0
	v_addc_co_u32_e32 v61, vcc, 0, v145, vcc
	global_store_dwordx4 v[60:61], v[56:59], off
	v_pk_add_f32 v[16:17], v[16:17], 0 op_sel_hi:[1,0]
	s_mov_b32 s51, s14
	v_pk_add_f32 v[56:57], v[46:47], 0 op_sel_hi:[1,0]
	v_pk_add_f32 v[46:47], v[44:45], 0 op_sel_hi:[1,0]
	v_cvt_pk_bf16_f32 v44, v52, v53
	v_cvt_pk_bf16_f32 v45, v54, v55
	s_mov_b32 s22, s16
	v_cvt_pk_bf16_f32 v46, v46, v47
	v_cvt_pk_bf16_f32 v47, v56, v57
	global_store_dwordx4 v[64:65], v[44:47], off offset:256
	s_mov_b64 s[26:27], s[20:21]
	s_mov_b64 s[24:25], s[18:19]
	v_pk_add_f32 v[46:47], v[50:51], 0 op_sel_hi:[1,0]
	v_pk_add_f32 v[50:51], v[42:43], 0 op_sel_hi:[1,0]
	v_pk_add_f32 v[42:43], v[40:41], 0 op_sel_hi:[1,0]
	v_cvt_pk_bf16_f32 v40, v48, v49
	v_cvt_pk_bf16_f32 v41, v46, v47
	v_add_co_u32_e32 v46, vcc, s48, v144
	v_cvt_pk_bf16_f32 v42, v42, v43
	v_cvt_pk_bf16_f32 v43, v50, v51
	v_lshl_add_u64 v[44:45], v[144:145], 0, s[8:9]
	s_nop 0
	v_addc_co_u32_e32 v47, vcc, 0, v145, vcc
	global_store_dwordx4 v[46:47], v[40:43], off
	v_pk_add_f32 v[6:7], v[6:7], 0 op_sel_hi:[1,0]
	v_pk_add_f32 v[4:5], v[4:5], 0 op_sel_hi:[1,0]
	v_pk_add_f32 v[40:41], v[30:31], 0 op_sel_hi:[1,0]
	v_pk_add_f32 v[30:31], v[28:29], 0 op_sel_hi:[1,0]
	v_cvt_pk_bf16_f32 v28, v36, v37
	v_cvt_pk_bf16_f32 v29, v38, v39
	s_nop 0
	v_cvt_pk_bf16_f32 v30, v30, v31
	v_cvt_pk_bf16_f32 v31, v40, v41
	global_store_dwordx4 v[44:45], v[28:31], off offset:256
	s_nop 1
	v_pk_add_f32 v[30:31], v[34:35], 0 op_sel_hi:[1,0]
	v_pk_add_f32 v[34:35], v[26:27], 0 op_sel_hi:[1,0]
	v_pk_add_f32 v[26:27], v[24:25], 0 op_sel_hi:[1,0]
	v_cvt_pk_bf16_f32 v24, v32, v33
	v_cvt_pk_bf16_f32 v25, v30, v31
	v_add_co_u32_e32 v30, vcc, s49, v144
	v_cvt_pk_bf16_f32 v26, v26, v27
	v_cvt_pk_bf16_f32 v27, v34, v35
	v_lshl_add_u64 v[28:29], v[144:145], 0, s[10:11]
	s_nop 0
	v_addc_co_u32_e32 v31, vcc, 0, v145, vcc
	global_store_dwordx4 v[30:31], v[24:27], off
	s_nop 1
	v_pk_add_f32 v[24:25], v[14:15], 0 op_sel_hi:[1,0]
	v_pk_add_f32 v[14:15], v[12:13], 0 op_sel_hi:[1,0]
	v_cvt_pk_bf16_f32 v12, v20, v21
	v_cvt_pk_bf16_f32 v13, v22, v23
	s_nop 0
	v_cvt_pk_bf16_f32 v14, v14, v15
	v_cvt_pk_bf16_f32 v15, v24, v25
	global_store_dwordx4 v[28:29], v[12:15], off offset:256
	s_nop 1
	v_pk_add_f32 v[14:15], v[18:19], 0 op_sel_hi:[1,0]
	v_pk_add_f32 v[18:19], v[10:11], 0 op_sel_hi:[1,0]
	v_pk_add_f32 v[10:11], v[8:9], 0 op_sel_hi:[1,0]
	v_cvt_pk_bf16_f32 v8, v16, v17
	v_cvt_pk_bf16_f32 v9, v14, v15
	v_add_co_u32_e32 v14, vcc, s50, v144
	v_lshl_add_u64 v[12:13], v[144:145], 0, s[12:13]
	s_nop 0
	v_addc_co_u32_e32 v15, vcc, 0, v145, vcc
	v_cvt_pk_bf16_f32 v10, v10, v11
	v_cvt_pk_bf16_f32 v11, v18, v19
	global_store_dwordx4 v[14:15], v[8:11], off
	s_and_b64 vcc, exec, s[2:3]
	s_nop 0
	v_pk_add_f32 v[8:9], v[2:3], 0 op_sel_hi:[1,0]
	v_pk_add_f32 v[2:3], v[0:1], 0 op_sel_hi:[1,0]
	v_cvt_pk_bf16_f32 v0, v4, v5
	v_cvt_pk_bf16_f32 v1, v6, v7
	s_nop 0
	v_cvt_pk_bf16_f32 v2, v2, v3
	v_cvt_pk_bf16_f32 v3, v8, v9
	global_store_dwordx4 v[12:13], v[0:3], off offset:256
	s_cbranch_vccz .LBB0_1076
	s_waitcnt vmcnt(0)
	s_cmpk_gt_u32 s31, 0xff
	s_cbranch_scc1 .LBB0_1087
	s_barrier

; #define PG8_STAGE(bufoff, gbase, voff) do { _Pragma("unroll") for (int _i = 0; _i < 2; ++_i) \
;         __builtin_amdgcn_global_load_lds((const unsigned*)((const char*)(gbase) + (voff)[_i]), (PG8_LAS unsigned*)(lds + (bufoff) + ldsw + _i * 8192), 16, 0, 0); } while (0)
; #define PG8_LDA(dst, b, h) do { _Pragma("unroll") for (int m = 0; m < 4; ++m) _Pragma("unroll") for (int k = 0; k < 2; ++k) dst[m][k] = *(const PG8_LAS bf16x8*)(lds + PG8_SA(b, h) + aoff + m * 2048 + k * 1024); } while (0)
; #define PG8_LDB(dst, b, h) do { _Pragma("unroll") for (int n = 0; n < 2; ++n) _Pragma("unroll") for (int k = 0; k < 2; ++k) dst[n][k] = *(const PG8_LAS bf16x8*)(lds + PG8_SB(b, h) + boff + n * 2048 + k * 1024); } while (0)
; #define PG8_MMA(ai, bj, At, Bt) do { __builtin_amdgcn_s_setprio(1); _Pragma("unroll") for (int m = 0; m < 4; ++m) _Pragma("unroll") for (int n = 0; n < 2; ++n) _Pragma("unroll") for (int k = 0; k < 2; ++k) \
;         acc[ai][bj][m][n] = __builtin_amdgcn_mfma_f32_16x16x32_bf16(Bt[n][k], At[m][k], acc[ai][bj][m][n], 0, 0, 0); __builtin_amdgcn_s_setprio(0); } while (0)
; #define PG8_WAIT_V(n) asm volatile("s_waitcnt vmcnt(" #n ")" ::: "memory")
; #define PG8_WAIT_L(n) asm volatile("s_waitcnt lgkmcnt(" #n ")" ::: "memory")
; template <class Epi, class Sched>
; __device__ __forceinline__ void gemm_phase(PG8_LAS unsigned char* lds, const Gemm g, const Sched& S, const Epi& E) {
;     ...
;             const bool last = (t == nt - 2);
;             const char* a1 = cA + (size_t)(t + 1) * kstep;
;             const char* a2 = last ? nA : cA + (size_t)(t + 2) * kstep; const char* b2 = last ? nB : cB + (size_t)(t + 2) * kstep;
;             const char* a3 = a2 + kstep; const char* b3 = b2 + kstep;
;             if (last && has_next) S.a_ready(nxt);
;             PG8_LDB(B0, 0, 0); PG8_SCHED; PG8_LDA(At, 0, 0); PG8_STAGE(PG8_SA(1, 1), a1 + hstep, voffA);
;             PG8_WAIT_L(8); PG8_BAR; PG8_WAIT_L(0); PG8_MMA(0, 0, At, B0); PG8_BAR; PG8_SCHED;
;             PG8_LDB(B1, 0, 1); PG8_STAGE(PG8_SB(0, 0), b2, voffB);
;             PG8_BAR; PG8_WAIT_L(0); PG8_MMA(0, 1, At, B1); PG8_BAR;
;             PG8_LDA(At, 0, 1); PG8_STAGE(PG8_SA(0, 0), a2, voffA);
;             PG8_BAR; PG8_WAIT_L(0); PG8_MMA(1, 0, At, B0); PG8_BAR; PG8_SCHED;
;             PG8_STAGE(PG8_SB(0, 1), b2 + hstep, voffB);
;             PG8_WAIT_V(6); PG8_BAR; PG8_MMA(1, 1, At, B1); PG8_BAR;
.LBB0_1202:
	ds_read_b128 v[144:147], v151
	ds_read_b128 v[154:157], v151 offset:1024
	ds_read_b128 v[158:161], v151 offset:2048
	ds_read_b128 v[162:165], v151 offset:3072
	s_add_u32 s18, s16, 0xfffc0080
	s_addc_u32 s19, s17, -1
	s_cmp_eq_u32 s46, 12
	s_cselect_b32 s21, s9, s19
	s_cselect_b32 s20, s42, s18
	s_cselect_b32 s19, s7, s45
	s_cselect_b32 s18, s43, s44
	v_lshl_add_u64 v[174:175], s[16:17], 0, v[136:137]
	s_add_i32 m0, s15, 0xc000
	ds_read_b128 v[166:169], v152
	ds_read_b128 v[170:173], v152 offset:1024
	ds_read_b128 v[182:185], v152 offset:2048
	ds_read_b128 v[190:193], v152 offset:3072
	ds_read_b128 v[194:197], v152 offset:4096
	ds_read_b128 v[198:201], v152 offset:5120
	ds_read_b128 v[202:205], v152 offset:6144
	ds_read_b128 v[206:209], v152 offset:7168
	global_load_lds_dwordx4 v[174:175], off
	v_lshl_add_u64 v[174:175], s[16:17], 0, v[138:139]
	s_add_i32 m0, s15, 0xe000
	s_nop 0
	global_load_lds_dwordx4 v[174:175], off
	s_waitcnt lgkmcnt(0)
	s_barrier
	v_mfma_f32_16x16x32_bf16 v[124:127], v[144:147], v[166:169], v[124:127]
	v_mfma_f32_16x16x32_bf16 v[120:123], v[158:161], v[166:169], v[120:123]
	v_mfma_f32_16x16x32_bf16 v[108:111], v[144:147], v[182:185], v[108:111]
	v_mfma_f32_16x16x32_bf16 v[104:107], v[158:161], v[182:185], v[104:107]
	v_mfma_f32_16x16x32_bf16 v[92:95], v[144:147], v[194:197], v[92:95]
	v_mfma_f32_16x16x32_bf16 v[88:91], v[158:161], v[194:197], v[88:91]
	v_mfma_f32_16x16x32_bf16 v[76:79], v[144:147], v[202:205], v[76:79]
	v_mfma_f32_16x16x32_bf16 v[72:75], v[158:161], v[202:205], v[72:75]
	v_mfma_f32_16x16x32_bf16 v[124:127], v[154:157], v[170:173], v[124:127]
	v_mfma_f32_16x16x32_bf16 v[120:123], v[162:165], v[170:173], v[120:123]
	v_mfma_f32_16x16x32_bf16 v[108:111], v[154:157], v[190:193], v[108:111]
	v_mfma_f32_16x16x32_bf16 v[104:107], v[162:165], v[190:193], v[104:107]
	v_mfma_f32_16x16x32_bf16 v[92:95], v[154:157], v[198:201], v[92:95]
	v_mfma_f32_16x16x32_bf16 v[88:91], v[162:165], v[198:201], v[88:91]
	v_mfma_f32_16x16x32_bf16 v[76:79], v[154:157], v[206:209], v[76:79]
	v_mfma_f32_16x16x32_bf16 v[72:75], v[162:165], v[206:209], v[72:75]
	s_barrier
	s_add_i32 s47, s38, s26
	v_lshl_add_u64 v[174:175], s[18:19], 0, v[132:133]
	s_mov_b32 m0, s47
	ds_read_b128 v[210:213], v153
	ds_read_b128 v[214:217], v153 offset:1024
	ds_read_b128 v[218:221], v153 offset:2048
	ds_read_b128 v[222:225], v153 offset:3072
	global_load_lds_dwordx4 v[174:175], off
	v_lshl_add_u64 v[186:187], s[18:19], 0, v[128:129]
	s_add_i32 m0, s47, 0x2000
	s_nop 0
	global_load_lds_dwordx4 v[186:187], off
	s_waitcnt lgkmcnt(0)
	s_barrier
	v_mfma_f32_16x16x32_bf16 v[116:119], v[210:213], v[166:169], v[116:119]
	v_mfma_f32_16x16x32_bf16 v[112:115], v[218:221], v[166:169], v[112:115]
	v_mfma_f32_16x16x32_bf16 v[100:103], v[210:213], v[182:185], v[100:103]
	v_mfma_f32_16x16x32_bf16 v[96:99], v[218:221], v[182:185], v[96:99]
	v_mfma_f32_16x16x32_bf16 v[84:87], v[210:213], v[194:197], v[84:87]
	v_mfma_f32_16x16x32_bf16 v[80:83], v[218:221], v[194:197], v[80:83]
	v_mfma_f32_16x16x32_bf16 v[68:71], v[210:213], v[202:205], v[68:71]
	v_mfma_f32_16x16x32_bf16 v[64:67], v[218:221], v[202:205], v[64:67]
	v_mfma_f32_16x16x32_bf16 v[116:119], v[214:217], v[170:173], v[116:119]
	v_mfma_f32_16x16x32_bf16 v[112:115], v[222:225], v[170:173], v[112:115]
	v_mfma_f32_16x16x32_bf16 v[100:103], v[214:217], v[190:193], v[100:103]
	v_mfma_f32_16x16x32_bf16 v[96:99], v[222:225], v[190:193], v[96:99]
	v_mfma_f32_16x16x32_bf16 v[84:87], v[214:217], v[198:201], v[84:87]
	v_mfma_f32_16x16x32_bf16 v[80:83], v[222:225], v[198:201], v[80:83]
	v_mfma_f32_16x16x32_bf16 v[68:71], v[214:217], v[206:209], v[68:71]
	v_mfma_f32_16x16x32_bf16 v[64:67], v[222:225], v[206:209], v[64:67]
	s_mov_b32 m0, s15
	v_lshl_add_u64 v[226:227], s[20:21], 0, v[134:135]
	s_barrier
	ds_read_b128 v[166:169], v152 offset:16384
	ds_read_b128 v[170:173], v152 offset:17408
	ds_read_b128 v[182:185], v152 offset:18432
	ds_read_b128 v[190:193], v152 offset:19456
	ds_read_b128 v[194:197], v152 offset:20480
	ds_read_b128 v[198:201], v152 offset:21504
	ds_read_b128 v[202:205], v152 offset:22528
	ds_read_b128 v[206:209], v152 offset:23552
	global_load_lds_dwordx4 v[226:227], off
	v_lshl_add_u64 v[228:229], s[20:21], 0, v[130:131]
	s_mov_b32 m0, s29
	s_nop 0
	global_load_lds_dwordx4 v[228:229], off
	s_waitcnt lgkmcnt(0)
	s_barrier
	v_mfma_f32_16x16x32_bf16 v[60:63], v[144:147], v[166:169], v[60:63]
	v_mfma_f32_16x16x32_bf16 v[56:59], v[158:161], v[166:169], v[56:59]
	v_mfma_f32_16x16x32_bf16 v[44:47], v[144:147], v[182:185], v[44:47]
	v_mfma_f32_16x16x32_bf16 v[40:43], v[158:161], v[182:185], v[40:43]
	v_mfma_f32_16x16x32_bf16 v[28:31], v[144:147], v[194:197], v[28:31]
	v_mfma_f32_16x16x32_bf16 v[24:27], v[158:161], v[194:197], v[24:27]
	v_mfma_f32_16x16x32_bf16 v[12:15], v[144:147], v[202:205], v[12:15]
	v_mfma_f32_16x16x32_bf16 v[8:11], v[158:161], v[202:205], v[8:11]
	v_mfma_f32_16x16x32_bf16 v[60:63], v[154:157], v[170:173], v[60:63]
	v_mfma_f32_16x16x32_bf16 v[56:59], v[162:165], v[170:173], v[56:59]
	v_mfma_f32_16x16x32_bf16 v[44:47], v[154:157], v[190:193], v[44:47]
	v_mfma_f32_16x16x32_bf16 v[40:43], v[162:165], v[190:193], v[40:43]
	v_mfma_f32_16x16x32_bf16 v[28:31], v[154:157], v[198:201], v[28:31]
	v_mfma_f32_16x16x32_bf16 v[24:27], v[162:165], v[198:201], v[24:27]
	v_mfma_f32_16x16x32_bf16 v[12:15], v[154:157], v[206:209], v[12:15]
	v_mfma_f32_16x16x32_bf16 v[8:11], v[162:165], v[206:209], v[8:11]
	s_barrier
	s_add_u32 s48, s18, 0x40000
	s_addc_u32 s49, s19, 0
	s_add_i32 s47, s39, s26
	v_lshl_add_u64 v[144:145], s[48:49], 0, v[132:133]
	s_mov_b32 m0, s47
	s_nop 0
	global_load_lds_dwordx4 v[144:145], off
	v_lshl_add_u64 v[144:145], s[48:49], 0, v[128:129]
	s_add_i32 m0, s47, 0x2000
	s_nop 0
	global_load_lds_dwordx4 v[144:145], off
	s_waitcnt vmcnt(6)
	s_barrier
; #define PG8_STAGE(bufoff, gbase, voff) do { _Pragma("unroll") for (int _i = 0; _i < 2; ++_i) \
;         __builtin_amdgcn_global_load_lds((const unsigned*)((const char*)(gbase) + (voff)[_i]), (PG8_LAS unsigned*)(lds + (bufoff) + ldsw + _i * 8192), 16, 0, 0); } while (0)
; #define PG8_LDA(dst, b, h) do { _Pragma("unroll") for (int m = 0; m < 4; ++m) _Pragma("unroll") for (int k = 0; k < 2; ++k) dst[m][k] = *(const PG8_LAS bf16x8*)(lds + PG8_SA(b, h) + aoff + m * 2048 + k * 1024); } while (0)
; #define PG8_LDB(dst, b, h) do { _Pragma("unroll") for (int n = 0; n < 2; ++n) _Pragma("unroll") for (int k = 0; k < 2; ++k) dst[n][k] = *(const PG8_LAS bf16x8*)(lds + PG8_SB(b, h) + boff + n * 2048 + k * 1024); } while (0)
; #define PG8_MMA(ai, bj, At, Bt) do { __builtin_amdgcn_s_setprio(1); _Pragma("unroll") for (int m = 0; m < 4; ++m) _Pragma("unroll") for (int n = 0; n < 2; ++n) _Pragma("unroll") for (int k = 0; k < 2; ++k) \
;         acc[ai][bj][m][n] = __builtin_amdgcn_mfma_f32_16x16x32_bf16(Bt[n][k], At[m][k], acc[ai][bj][m][n], 0, 0, 0); __builtin_amdgcn_s_setprio(0); } while (0)
; #define PG8_WAIT_V(n) asm volatile("s_waitcnt vmcnt(" #n ")" ::: "memory")
; #define PG8_WAIT_L(n) asm volatile("s_waitcnt lgkmcnt(" #n ")" ::: "memory")
; #define PG8_BAR __builtin_amdgcn_s_barrier()
; #define PG8_SCHED __builtin_amdgcn_sched_barrier(0)
; template <class Epi, class Sched>
; __device__ __forceinline__ void gemm_phase(PG8_LAS unsigned char* lds, const Gemm g, const Sched& S, const Epi& E) {
;     ...
;             PG8_WAIT_V(6); PG8_BAR; PG8_MMA(1, 1, At, B1); PG8_BAR;
;             PG8_LDB(B0, 1, 0); PG8_SCHED; PG8_LDA(At, 1, 0); PG8_STAGE(PG8_SA(0, 1), a2 + hstep, voffA);
;             PG8_WAIT_L(8); PG8_BAR; PG8_WAIT_L(0); PG8_MMA(0, 0, At, B0); PG8_BAR; PG8_SCHED;
;             PG8_LDB(B1, 1, 1); PG8_STAGE(PG8_SB(1, 0), b3, voffB);
;             PG8_BAR; PG8_WAIT_L(0); PG8_MMA(0, 1, At, B1); PG8_BAR;
;             PG8_LDA(At, 1, 1); PG8_STAGE(PG8_SA(1, 0), a3, voffA);
;             PG8_BAR; PG8_WAIT_L(0); PG8_MMA(1, 0, At, B0); PG8_BAR; PG8_SCHED;
;             PG8_STAGE(PG8_SB(1, 1), b3 + hstep, voffB);
	v_mfma_f32_16x16x32_bf16 v[52:55], v[210:213], v[166:169], v[52:55]
	v_mfma_f32_16x16x32_bf16 v[48:51], v[218:221], v[166:169], v[48:51]
	v_mfma_f32_16x16x32_bf16 v[36:39], v[210:213], v[182:185], v[36:39]
	v_mfma_f32_16x16x32_bf16 v[32:35], v[218:221], v[182:185], v[32:35]
	v_mfma_f32_16x16x32_bf16 v[20:23], v[210:213], v[194:197], v[20:23]
	v_mfma_f32_16x16x32_bf16 v[16:19], v[218:221], v[194:197], v[16:19]
	v_mfma_f32_16x16x32_bf16 v[4:7], v[210:213], v[202:205], v[4:7]
	v_mfma_f32_16x16x32_bf16 v[0:3], v[218:221], v[202:205], v[0:3]
	v_mfma_f32_16x16x32_bf16 v[52:55], v[214:217], v[170:173], v[52:55]
	v_mfma_f32_16x16x32_bf16 v[48:51], v[222:225], v[170:173], v[48:51]
	v_mfma_f32_16x16x32_bf16 v[36:39], v[214:217], v[190:193], v[36:39]
	v_mfma_f32_16x16x32_bf16 v[32:35], v[222:225], v[190:193], v[32:35]
	v_mfma_f32_16x16x32_bf16 v[20:23], v[214:217], v[198:201], v[20:23]
	v_mfma_f32_16x16x32_bf16 v[16:19], v[222:225], v[198:201], v[16:19]
	v_mfma_f32_16x16x32_bf16 v[4:7], v[214:217], v[206:209], v[4:7]
	v_mfma_f32_16x16x32_bf16 v[0:3], v[222:225], v[206:209], v[0:3]
	s_add_i32 s47, 0, 0x18000
	v_add_u32_e32 v162, s47, v149
	s_barrier
	ds_read_b128 v[144:147], v162
	ds_read_b128 v[154:157], v162 offset:1024
	ds_read_b128 v[158:161], v162 offset:2048
	ds_read_b128 v[162:165], v162 offset:3072
	s_add_u32 s20, s20, 0x40000
	s_addc_u32 s21, s21, 0
	s_mov_b32 m0, s30
	v_lshl_add_u64 v[210:211], s[20:21], 0, v[134:135]
	ds_read_b128 v[166:169], v152 offset:32768
	ds_read_b128 v[170:173], v152 offset:33792
	ds_read_b128 v[182:185], v152 offset:34816
	ds_read_b128 v[190:193], v152 offset:35840
	ds_read_b128 v[194:197], v152 offset:36864
	ds_read_b128 v[198:201], v152 offset:37888
	ds_read_b128 v[202:205], v152 offset:38912
	ds_read_b128 v[206:209], v152 offset:39936
	global_load_lds_dwordx4 v[210:211], off
	v_lshl_add_u64 v[210:211], s[20:21], 0, v[130:131]
	s_mov_b32 m0, s31
	s_nop 0
	global_load_lds_dwordx4 v[210:211], off
	s_waitcnt lgkmcnt(0)
	s_barrier
	v_mfma_f32_16x16x32_bf16 v[124:127], v[144:147], v[166:169], v[124:127]
	v_mfma_f32_16x16x32_bf16 v[120:123], v[158:161], v[166:169], v[120:123]
	v_mfma_f32_16x16x32_bf16 v[108:111], v[144:147], v[182:185], v[108:111]
	v_mfma_f32_16x16x32_bf16 v[104:107], v[158:161], v[182:185], v[104:107]
	v_mfma_f32_16x16x32_bf16 v[92:95], v[144:147], v[194:197], v[92:95]
	v_mfma_f32_16x16x32_bf16 v[88:91], v[158:161], v[194:197], v[88:91]
	v_mfma_f32_16x16x32_bf16 v[76:79], v[144:147], v[202:205], v[76:79]
	v_mfma_f32_16x16x32_bf16 v[72:75], v[158:161], v[202:205], v[72:75]
	v_mfma_f32_16x16x32_bf16 v[124:127], v[154:157], v[170:173], v[124:127]
	v_mfma_f32_16x16x32_bf16 v[120:123], v[162:165], v[170:173], v[120:123]
	v_mfma_f32_16x16x32_bf16 v[108:111], v[154:157], v[190:193], v[108:111]
	v_mfma_f32_16x16x32_bf16 v[104:107], v[162:165], v[190:193], v[104:107]
	v_mfma_f32_16x16x32_bf16 v[92:95], v[154:157], v[198:201], v[92:95]
	v_mfma_f32_16x16x32_bf16 v[88:91], v[162:165], v[198:201], v[88:91]
	v_mfma_f32_16x16x32_bf16 v[76:79], v[154:157], v[206:209], v[76:79]
	v_mfma_f32_16x16x32_bf16 v[72:75], v[162:165], v[206:209], v[72:75]
	s_barrier
	s_add_i32 s20, 0, 0x1c000
	s_add_i32 s21, s47, s26
	v_add_u32_e32 v179, s20, v149
	v_lshl_add_u64 v[174:175], v[174:175], 0, s[4:5]
	s_mov_b32 m0, s21
	ds_read_b128 v[210:213], v179
	ds_read_b128 v[214:217], v179 offset:1024
	ds_read_b128 v[218:221], v179 offset:2048
	ds_read_b128 v[222:225], v179 offset:3072
	global_load_lds_dwordx4 v[174:175], off
	v_lshl_add_u64 v[174:175], v[186:187], 0, s[4:5]
	s_add_i32 m0, s21, 0x2000
	s_nop 0
	global_load_lds_dwordx4 v[174:175], off
	s_waitcnt lgkmcnt(0)
	s_barrier
	v_mfma_f32_16x16x32_bf16 v[116:119], v[210:213], v[166:169], v[116:119]
	v_mfma_f32_16x16x32_bf16 v[112:115], v[218:221], v[166:169], v[112:115]
	v_mfma_f32_16x16x32_bf16 v[100:103], v[210:213], v[182:185], v[100:103]
	v_mfma_f32_16x16x32_bf16 v[96:99], v[218:221], v[182:185], v[96:99]
	v_mfma_f32_16x16x32_bf16 v[84:87], v[210:213], v[194:197], v[84:87]
	v_mfma_f32_16x16x32_bf16 v[80:83], v[218:221], v[194:197], v[80:83]
	v_mfma_f32_16x16x32_bf16 v[68:71], v[210:213], v[202:205], v[68:71]
	v_mfma_f32_16x16x32_bf16 v[64:67], v[218:221], v[202:205], v[64:67]
	v_mfma_f32_16x16x32_bf16 v[116:119], v[214:217], v[170:173], v[116:119]
	v_mfma_f32_16x16x32_bf16 v[112:115], v[222:225], v[170:173], v[112:115]
	v_mfma_f32_16x16x32_bf16 v[100:103], v[214:217], v[190:193], v[100:103]
	v_mfma_f32_16x16x32_bf16 v[96:99], v[222:225], v[190:193], v[96:99]
	v_mfma_f32_16x16x32_bf16 v[84:87], v[214:217], v[198:201], v[84:87]
	v_mfma_f32_16x16x32_bf16 v[80:83], v[222:225], v[198:201], v[80:83]
	v_mfma_f32_16x16x32_bf16 v[68:71], v[214:217], v[206:209], v[68:71]
	v_mfma_f32_16x16x32_bf16 v[64:67], v[222:225], v[206:209], v[64:67]
	s_mov_b32 m0, s35
	v_lshl_add_u64 v[174:175], v[226:227], 0, s[4:5]
	s_barrier
	ds_read_b128 v[166:169], v152 offset:49152
	ds_read_b128 v[170:173], v152 offset:50176
	ds_read_b128 v[182:185], v152 offset:51200
	ds_read_b128 v[190:193], v152 offset:52224
	ds_read_b128 v[194:197], v152 offset:53248
	ds_read_b128 v[198:201], v152 offset:54272
	ds_read_b128 v[202:205], v152 offset:55296
	ds_read_b128 v[206:209], v152 offset:56320
	global_load_lds_dwordx4 v[174:175], off
	v_lshl_add_u64 v[174:175], v[228:229], 0, s[4:5]
	s_mov_b32 m0, s36
	s_nop 0
	global_load_lds_dwordx4 v[174:175], off
	s_waitcnt lgkmcnt(0)
	s_barrier
; __device__ __forceinline__ unsigned cvt_pk_bf16(float lo, float hi) { unsigned r; asm volatile("v_cvt_pk_bf16_f32 %0, %1, %2" : "=v"(r) : "v"(lo), "v"(hi)); return r; }
; #define PG8_STAGE(bufoff, gbase, voff) do { _Pragma("unroll") for (int _i = 0; _i < 2; ++_i) \
;         __builtin_amdgcn_global_load_lds((const unsigned*)((const char*)(gbase) + (voff)[_i]), (PG8_LAS unsigned*)(lds + (bufoff) + ldsw + _i * 8192), 16, 0, 0); } while (0)
; #define PG8_MMA(ai, bj, At, Bt) do { __builtin_amdgcn_s_setprio(1); _Pragma("unroll") for (int m = 0; m < 4; ++m) _Pragma("unroll") for (int n = 0; n < 2; ++n) _Pragma("unroll") for (int k = 0; k < 2; ++k) \
;         acc[ai][bj][m][n] = __builtin_amdgcn_mfma_f32_16x16x32_bf16(Bt[n][k], At[m][k], acc[ai][bj][m][n], 0, 0, 0); __builtin_amdgcn_s_setprio(0); } while (0)
; __device__ __forceinline__ f32x4 sigmoid4(f32x4 x) {
;     f32x4 d;
; #pragma unroll
;     for (int j = 0; j < 4; ++j) d[j] = 1.0f + __expf(-fmaxf(x[j], -20.0f));
;     const float p01 = d[0] * d[1], p23 = d[2] * d[3], r = __builtin_amdgcn_rcpf(p01 * p23), r01 = r * p23, r23 = r * p01;
;     return (f32x4){r01 * d[1], r01 * d[0], r23 * d[3], r23 * d[2]};
; }
;     __device__ __forceinline__ void operator()(const f32x4 (&acc)[2][2][4][2], const Unit& u, int wr, int wc, int fr, int fq) const {
;         const int row0 = u.pm * BM + wr * 64 + fr, col0 = u.pn * HALF + wc * 32 + 8 * fq;
; #pragma unroll
;         for (int ai = 0; ai < 2; ++ai)
; #pragma unroll
;             for (int m = 0; m < 4; ++m) { bf16_t* rowp = O + (size_t)(row0 + ai * HALF + m * 16) * ldc + col0;
;                 f32x4 v0, v1;
; #pragma unroll
;                 for (int j = 0; j < 1; ++j) { v0 = acc[ai][0][m][0] * sigmoid4(acc[ai][0][m][0]) * acc[ai][1][m][0]; v1 = acc[ai][0][m][1] * sigmoid4(acc[ai][0][m][1]) * acc[ai][1][m][1]; }
;                 u32x4 w; w.x = cvt_pk_bf16(v0[0], v0[1]); w.y = cvt_pk_bf16(v0[2], v0[3]); w.z = cvt_pk_bf16(v1[0], v1[1]); w.w = cvt_pk_bf16(v1[2], v1[3]);
;                 *(u32x4*)rowp = w; }
; template <class Epi, class Sched>
; __device__ __forceinline__ void gemm_phase(PG8_LAS unsigned char* lds, const Gemm g, const Sched& S, const Epi& E) {
;     ...
;             PG8_BAR; PG8_WAIT_L(0); PG8_MMA(1, 0, At, B0); PG8_BAR; PG8_SCHED;
;             PG8_STAGE(PG8_SB(1, 1), b3 + hstep, voffB);
;             PG8_WAIT_V(6); PG8_BAR; PG8_MMA(1, 1, At, B1); PG8_BAR;
	v_mfma_f32_16x16x32_bf16 v[60:63], v[144:147], v[166:169], v[60:63]
	v_mfma_f32_16x16x32_bf16 v[56:59], v[158:161], v[166:169], v[56:59]
	v_mfma_f32_16x16x32_bf16 v[44:47], v[144:147], v[182:185], v[44:47]
	v_mfma_f32_16x16x32_bf16 v[40:43], v[158:161], v[182:185], v[40:43]
	v_mfma_f32_16x16x32_bf16 v[28:31], v[144:147], v[194:197], v[28:31]
	v_mfma_f32_16x16x32_bf16 v[24:27], v[158:161], v[194:197], v[24:27]
	v_mfma_f32_16x16x32_bf16 v[12:15], v[144:147], v[202:205], v[12:15]
	v_mfma_f32_16x16x32_bf16 v[8:11], v[158:161], v[202:205], v[8:11]
	v_mfma_f32_16x16x32_bf16 v[60:63], v[154:157], v[170:173], v[60:63]
	v_mfma_f32_16x16x32_bf16 v[56:59], v[162:165], v[170:173], v[56:59]
	v_mfma_f32_16x16x32_bf16 v[44:47], v[154:157], v[190:193], v[44:47]
	v_mfma_f32_16x16x32_bf16 v[40:43], v[162:165], v[190:193], v[40:43]
	v_mfma_f32_16x16x32_bf16 v[28:31], v[154:157], v[198:201], v[28:31]
	v_mfma_f32_16x16x32_bf16 v[24:27], v[162:165], v[198:201], v[24:27]
	v_mfma_f32_16x16x32_bf16 v[12:15], v[154:157], v[206:209], v[12:15]
	v_mfma_f32_16x16x32_bf16 v[8:11], v[162:165], v[206:209], v[8:11]
	s_barrier
	s_add_u32 s18, s18, 0x40080
	s_addc_u32 s19, s19, 0
	s_add_i32 s20, s20, s26
	v_lshl_add_u64 v[144:145], s[18:19], 0, v[132:133]
	s_mov_b32 m0, s20
	s_nop 0
	global_load_lds_dwordx4 v[144:145], off
	v_lshl_add_u64 v[144:145], s[18:19], 0, v[128:129]
	s_add_i32 m0, s20, 0x2000
	s_nop 0
	global_load_lds_dwordx4 v[144:145], off
	s_waitcnt vmcnt(6)
	s_barrier
	v_mfma_f32_16x16x32_bf16 v[52:55], v[210:213], v[166:169], v[52:55]
	v_mfma_f32_16x16x32_bf16 v[48:51], v[218:221], v[166:169], v[48:51]
	v_mfma_f32_16x16x32_bf16 v[36:39], v[210:213], v[182:185], v[36:39]
	v_mfma_f32_16x16x32_bf16 v[32:35], v[218:221], v[182:185], v[32:35]
	v_mfma_f32_16x16x32_bf16 v[20:23], v[210:213], v[194:197], v[20:23]
	v_mfma_f32_16x16x32_bf16 v[16:19], v[218:221], v[194:197], v[16:19]
	v_mfma_f32_16x16x32_bf16 v[4:7], v[210:213], v[202:205], v[4:7]
	v_mfma_f32_16x16x32_bf16 v[0:3], v[218:221], v[202:205], v[0:3]
	v_mfma_f32_16x16x32_bf16 v[52:55], v[214:217], v[170:173], v[52:55]
	v_mfma_f32_16x16x32_bf16 v[48:51], v[222:225], v[170:173], v[48:51]
	v_mfma_f32_16x16x32_bf16 v[36:39], v[214:217], v[190:193], v[36:39]
	v_mfma_f32_16x16x32_bf16 v[32:35], v[222:225], v[190:193], v[32:35]
	v_mfma_f32_16x16x32_bf16 v[20:23], v[214:217], v[198:201], v[20:23]
	v_mfma_f32_16x16x32_bf16 v[16:19], v[222:225], v[198:201], v[16:19]
	v_mfma_f32_16x16x32_bf16 v[4:7], v[214:217], v[206:209], v[4:7]
	v_mfma_f32_16x16x32_bf16 v[0:3], v[222:225], v[206:209], v[0:3]
	s_add_i32 s46, s46, 2
	s_add_u32 s16, s16, 0x100
	s_addc_u32 s17, s17, 0
	s_add_u32 s44, s44, 0x100
	s_addc_u32 s45, s45, 0
	s_cmp_gt_u32 s46, 13
	s_barrier
	s_cbranch_scc0 .LBB0_1202
	v_max_f32_e32 v144, v124, v124
	v_max_f32_e32 v144, 0xc1a00000, v144
	v_mul_f32_e32 v144, 0xbfb8aa3b, v144
	v_exp_f32_e32 v157, v144
	v_max_f32_e32 v144, v125, v125
	v_max_f32_e32 v144, 0xc1a00000, v144
	v_mul_f32_e32 v144, 0xbfb8aa3b, v144
	v_exp_f32_e32 v156, v144
	v_max_f32_e32 v144, v126, v126
	v_max_f32_e32 v144, 0xc1a00000, v144
	v_mul_f32_e32 v144, 0xbfb8aa3b, v144
	v_exp_f32_e32 v159, v144
	v_max_f32_e32 v144, v127, v127
	v_max_f32_e32 v144, 0xc1a00000, v144
	v_mul_f32_e32 v144, 0xbfb8aa3b, v144
	v_exp_f32_e32 v158, v144
	v_pk_add_f32 v[156:157], v[156:157], 1.0 op_sel_hi:[1,0]
	v_lshl_or_b32 v146, s41, 7, v150
	v_mov_b32_e32 v160, v157
	v_pk_add_f32 v[158:159], v[158:159], 1.0 op_sel_hi:[1,0]
	v_mov_b32_e32 v162, v156
	v_mov_b32_e32 v161, v159
	v_mov_b32_e32 v163, v158
	v_pk_mul_f32 v[160:161], v[160:161], v[162:163]
	v_lshl_add_u32 v154, s14, 8, v148
	v_mul_f32_e32 v155, v160, v161
	v_rcp_f32_e32 v155, v155
	v_ashrrev_i32_e32 v147, 31, v146
	v_mov_b64_e32 v[144:145], s[0:1]
	v_mad_i64_i32 v[162:163], s[16:17], v154, s40, v[144:145]
	v_mul_f32_e32 v164, v161, v155
	v_mul_f32_e32 v160, v160, v155
	v_max_f32_e32 v155, v120, v120
	v_max_f32_e32 v155, 0xc1a00000, v155
	v_mul_f32_e32 v155, 0xbfb8aa3b, v155
	v_pk_mul_f32 v[158:159], v[158:159], v[160:161] op_sel_hi:[1,0]
	v_exp_f32_e32 v161, v155
	v_max_f32_e32 v155, v121, v121
	v_max_f32_e32 v155, 0xc1a00000, v155
	v_mul_f32_e32 v155, 0xbfb8aa3b, v155
	v_exp_f32_e32 v160, v155
	v_max_f32_e32 v155, v122, v122
	v_max_f32_e32 v155, 0xc1a00000, v155
	v_mul_f32_e32 v155, 0xbfb8aa3b, v155
	v_exp_f32_e32 v167, v155
	v_max_f32_e32 v155, v123, v123
	v_max_f32_e32 v155, 0xc1a00000, v155
	v_mul_f32_e32 v155, 0xbfb8aa3b, v155
	v_exp_f32_e32 v166, v155
	v_pk_mul_f32 v[156:157], v[156:157], v[164:165] op_sel_hi:[1,0]
	v_pk_mul_f32 v[126:127], v[126:127], v[158:159]
	v_pk_mul_f32 v[124:125], v[124:125], v[156:157]
	v_pk_add_f32 v[156:157], v[160:161], 1.0 op_sel_hi:[1,0]
	v_pk_add_f32 v[160:161], v[166:167], 1.0 op_sel_hi:[1,0]
	v_mov_b32_e32 v164, v157
	v_mov_b32_e32 v165, v161
	v_mov_b32_e32 v166, v156
	v_mov_b32_e32 v167, v160
	v_pk_mul_f32 v[164:165], v[164:165], v[166:167]
	v_pk_mul_f32 v[118:119], v[126:127], v[118:119]
	v_mul_f32_e32 v155, v164, v165
	v_rcp_f32_e32 v155, v155
	v_pk_mul_f32 v[116:117], v[124:125], v[116:117]
	v_lshlrev_b64 v[146:147], 1, v[146:147]
	v_lshl_add_u64 v[162:163], v[162:163], 0, v[146:147]
	v_mul_f32_e32 v124, v165, v155
	v_mul_f32_e32 v126, v164, v155
	v_pk_mul_f32 v[126:127], v[160:161], v[126:127] op_sel_hi:[1,0]
	v_pk_mul_f32 v[124:125], v[156:157], v[124:125] op_sel_hi:[1,0]
	v_pk_mul_f32 v[122:123], v[122:123], v[126:127]
	v_pk_mul_f32 v[120:121], v[120:121], v[124:125]
	v_pk_mul_f32 v[122:123], v[122:123], v[114:115]
	v_pk_mul_f32 v[114:115], v[120:121], v[112:113]
	v_cvt_pk_bf16_f32 v112, v116, v117
	v_cvt_pk_bf16_f32 v113, v118, v119
	v_max_f32_e32 v116, v108, v108
; __device__ __forceinline__ unsigned cvt_pk_bf16(float lo, float hi) { unsigned r; asm volatile("v_cvt_pk_bf16_f32 %0, %1, %2" : "=v"(r) : "v"(lo), "v"(hi)); return r; }
; __device__ __forceinline__ f32x4 sigmoid4(f32x4 x) {
;     f32x4 d;
; #pragma unroll
;     for (int j = 0; j < 4; ++j) d[j] = 1.0f + __expf(-fmaxf(x[j], -20.0f));
;     const float p01 = d[0] * d[1], p23 = d[2] * d[3], r = __builtin_amdgcn_rcpf(p01 * p23), r01 = r * p23, r23 = r * p01;
;     return (f32x4){r01 * d[1], r01 * d[0], r23 * d[3], r23 * d[2]};
; }
;     __device__ __forceinline__ void operator()(const f32x4 (&acc)[2][2][4][2], const Unit& u, int wr, int wc, int fr, int fq) const {
;         const int row0 = u.pm * BM + wr * 64 + fr, col0 = u.pn * HALF + wc * 32 + 8 * fq;
; #pragma unroll
;         for (int ai = 0; ai < 2; ++ai)
; #pragma unroll
;             for (int m = 0; m < 4; ++m) { bf16_t* rowp = O + (size_t)(row0 + ai * HALF + m * 16) * ldc + col0;
;                 f32x4 v0, v1;
; #pragma unroll
;                 for (int j = 0; j < 1; ++j) { v0 = acc[ai][0][m][0] * sigmoid4(acc[ai][0][m][0]) * acc[ai][1][m][0]; v1 = acc[ai][0][m][1] * sigmoid4(acc[ai][0][m][1]) * acc[ai][1][m][1]; }
;                 u32x4 w; w.x = cvt_pk_bf16(v0[0], v0[1]); w.y = cvt_pk_bf16(v0[2], v0[3]); w.z = cvt_pk_bf16(v1[0], v1[1]); w.w = cvt_pk_bf16(v1[2], v1[3]);
;                 *(u32x4*)rowp = w; }
	v_max_f32_e32 v118, v110, v110
	v_max_f32_e32 v116, 0xc1a00000, v116
	v_max_f32_e32 v118, 0xc1a00000, v118
	v_mul_f32_e32 v116, 0xbfb8aa3b, v116
	v_mul_f32_e32 v118, 0xbfb8aa3b, v118
	v_exp_f32_e32 v117, v116
	v_max_f32_e32 v116, v109, v109
	v_exp_f32_e32 v119, v118
	v_max_f32_e32 v118, v111, v111
	v_max_f32_e32 v116, 0xc1a00000, v116
	v_max_f32_e32 v118, 0xc1a00000, v118
	v_mul_f32_e32 v116, 0xbfb8aa3b, v116
	v_mul_f32_e32 v118, 0xbfb8aa3b, v118
	v_exp_f32_e32 v116, v116
	v_exp_f32_e32 v118, v118
	v_cvt_pk_bf16_f32 v114, v114, v115
	v_cvt_pk_bf16_f32 v115, v122, v123
	global_store_dwordx4 v[162:163], v[112:115], off
	v_or_b32_e32 v120, 16, v154
	s_and_b64 vcc, exec, s[2:3]
	v_pk_add_f32 v[112:113], v[116:117], 1.0 op_sel_hi:[1,0]
	v_pk_add_f32 v[114:115], v[118:119], 1.0 op_sel_hi:[1,0]
	v_mov_b32_e32 v116, v113
	v_mov_b32_e32 v117, v115
	v_mov_b32_e32 v118, v112
	v_mov_b32_e32 v119, v114
	v_pk_mul_f32 v[116:117], v[116:117], v[118:119]
	s_mov_b32 s41, s6
	v_mul_f32_e32 v118, v116, v117
	v_rcp_f32_e32 v121, v118
	v_mad_i64_i32 v[118:119], s[16:17], v120, s40, v[144:145]
	v_lshl_add_u64 v[118:119], v[118:119], 0, v[146:147]
	v_mul_f32_e32 v116, v116, v121
	v_mul_f32_e32 v120, v117, v121
	v_pk_mul_f32 v[114:115], v[114:115], v[116:117] op_sel_hi:[1,0]
	v_max_f32_e32 v116, v104, v104
	v_max_f32_e32 v121, v106, v106
	v_max_f32_e32 v116, 0xc1a00000, v116
	v_max_f32_e32 v121, 0xc1a00000, v121
	v_mul_f32_e32 v116, 0xbfb8aa3b, v116
	v_mul_f32_e32 v121, 0xbfb8aa3b, v121
	v_exp_f32_e32 v117, v116
	v_max_f32_e32 v116, v105, v105
	v_exp_f32_e32 v123, v121
	v_max_f32_e32 v121, v107, v107
	v_max_f32_e32 v116, 0xc1a00000, v116
	v_max_f32_e32 v121, 0xc1a00000, v121
	v_mul_f32_e32 v116, 0xbfb8aa3b, v116
	v_mul_f32_e32 v121, 0xbfb8aa3b, v121
	v_exp_f32_e32 v116, v116
	v_exp_f32_e32 v122, v121
	v_pk_mul_f32 v[112:113], v[112:113], v[120:121] op_sel_hi:[1,0]
	v_pk_mul_f32 v[110:111], v[110:111], v[114:115]
	v_pk_mul_f32 v[108:109], v[108:109], v[112:113]
	v_pk_add_f32 v[112:113], v[116:117], 1.0 op_sel_hi:[1,0]
	v_pk_add_f32 v[116:117], v[122:123], 1.0 op_sel_hi:[1,0]
	v_mov_b32_e32 v120, v113
	v_mov_b32_e32 v121, v117
	v_mov_b32_e32 v122, v112
	v_mov_b32_e32 v123, v116
	v_pk_mul_f32 v[120:121], v[120:121], v[122:123]
	v_pk_mul_f32 v[102:103], v[110:111], v[102:103]
	v_mul_f32_e32 v122, v120, v121
	v_rcp_f32_e32 v122, v122
	v_pk_mul_f32 v[100:101], v[108:109], v[100:101]
	s_mov_b32 s14, s8
	s_mov_b64 s[18:19], s[12:13]
	v_mul_f32_e32 v108, v121, v122
	v_mul_f32_e32 v110, v120, v122
	v_pk_mul_f32 v[110:111], v[116:117], v[110:111] op_sel_hi:[1,0]
	v_pk_mul_f32 v[108:109], v[112:113], v[108:109] op_sel_hi:[1,0]
	v_pk_mul_f32 v[106:107], v[106:107], v[110:111]
	v_pk_mul_f32 v[104:105], v[104:105], v[108:109]
	v_pk_mul_f32 v[106:107], v[106:107], v[98:99]
	v_pk_mul_f32 v[98:99], v[104:105], v[96:97]
	v_cvt_pk_bf16_f32 v96, v100, v101
	v_cvt_pk_bf16_f32 v97, v102, v103
	v_max_f32_e32 v100, v92, v92
	v_max_f32_e32 v102, v94, v94
	v_max_f32_e32 v100, 0xc1a00000, v100
	v_max_f32_e32 v102, 0xc1a00000, v102
	v_mul_f32_e32 v100, 0xbfb8aa3b, v100
	v_mul_f32_e32 v102, 0xbfb8aa3b, v102
	v_exp_f32_e32 v101, v100
	v_max_f32_e32 v100, v93, v93
	v_exp_f32_e32 v103, v102
	v_max_f32_e32 v102, v95, v95
	v_max_f32_e32 v100, 0xc1a00000, v100
	v_max_f32_e32 v102, 0xc1a00000, v102
	v_mul_f32_e32 v100, 0xbfb8aa3b, v100
	v_mul_f32_e32 v102, 0xbfb8aa3b, v102
	v_exp_f32_e32 v100, v100
	v_exp_f32_e32 v102, v102
	v_cvt_pk_bf16_f32 v98, v98, v99
	v_cvt_pk_bf16_f32 v99, v106, v107
	global_store_dwordx4 v[118:119], v[96:99], off
	v_or_b32_e32 v104, 32, v154
	s_nop 0
	v_pk_add_f32 v[96:97], v[100:101], 1.0 op_sel_hi:[1,0]
	v_pk_add_f32 v[98:99], v[102:103], 1.0 op_sel_hi:[1,0]
	v_mov_b32_e32 v100, v97
	v_mov_b32_e32 v101, v99
	v_mov_b32_e32 v102, v96
	v_mov_b32_e32 v103, v98
	v_pk_mul_f32 v[100:101], v[100:101], v[102:103]
	s_nop 0
	v_mul_f32_e32 v102, v100, v101
	v_rcp_f32_e32 v105, v102
	v_mad_i64_i32 v[102:103], s[16:17], v104, s40, v[144:145]
	v_lshl_add_u64 v[102:103], v[102:103], 0, v[146:147]
	v_mul_f32_e32 v100, v100, v105
	v_mul_f32_e32 v104, v101, v105
	v_pk_mul_f32 v[98:99], v[98:99], v[100:101] op_sel_hi:[1,0]
	v_max_f32_e32 v100, v88, v88
	v_max_f32_e32 v105, v90, v90
	v_max_f32_e32 v100, 0xc1a00000, v100
	v_max_f32_e32 v105, 0xc1a00000, v105
	v_mul_f32_e32 v100, 0xbfb8aa3b, v100
	v_mul_f32_e32 v105, 0xbfb8aa3b, v105
	v_exp_f32_e32 v101, v100
	v_max_f32_e32 v100, v89, v89
	v_exp_f32_e32 v107, v105
	v_max_f32_e32 v105, v91, v91
	v_max_f32_e32 v100, 0xc1a00000, v100
	v_max_f32_e32 v105, 0xc1a00000, v105
	v_mul_f32_e32 v100, 0xbfb8aa3b, v100
	v_mul_f32_e32 v105, 0xbfb8aa3b, v105
	v_exp_f32_e32 v100, v100
	v_exp_f32_e32 v106, v105
	v_pk_mul_f32 v[96:97], v[96:97], v[104:105] op_sel_hi:[1,0]
	v_pk_mul_f32 v[94:95], v[94:95], v[98:99]
	v_pk_mul_f32 v[92:93], v[92:93], v[96:97]
	v_pk_add_f32 v[96:97], v[100:101], 1.0 op_sel_hi:[1,0]
	v_pk_add_f32 v[100:101], v[106:107], 1.0 op_sel_hi:[1,0]
	v_mov_b32_e32 v104, v97
	v_mov_b32_e32 v105, v101
	v_mov_b32_e32 v106, v96
	v_mov_b32_e32 v107, v100
	v_pk_mul_f32 v[104:105], v[104:105], v[106:107]
	v_pk_mul_f32 v[86:87], v[94:95], v[86:87]
	v_mul_f32_e32 v106, v104, v105
	v_rcp_f32_e32 v106, v106
	v_pk_mul_f32 v[84:85], v[92:93], v[84:85]
	v_mul_f32_e32 v92, v105, v106
	v_mul_f32_e32 v94, v104, v106
	v_pk_mul_f32 v[94:95], v[100:101], v[94:95] op_sel_hi:[1,0]
	v_pk_mul_f32 v[92:93], v[96:97], v[92:93] op_sel_hi:[1,0]
	v_pk_mul_f32 v[90:91], v[90:91], v[94:95]
	v_pk_mul_f32 v[88:89], v[88:89], v[92:93]
	v_pk_mul_f32 v[90:91], v[90:91], v[82:83]
	v_pk_mul_f32 v[82:83], v[88:89], v[80:81]
	v_cvt_pk_bf16_f32 v80, v84, v85
	v_cvt_pk_bf16_f32 v81, v86, v87
; __device__ __forceinline__ unsigned cvt_pk_bf16(float lo, float hi) { unsigned r; asm volatile("v_cvt_pk_bf16_f32 %0, %1, %2" : "=v"(r) : "v"(lo), "v"(hi)); return r; }
; __device__ __forceinline__ f32x4 sigmoid4(f32x4 x) {
;     f32x4 d;
; #pragma unroll
;     for (int j = 0; j < 4; ++j) d[j] = 1.0f + __expf(-fmaxf(x[j], -20.0f));
;     const float p01 = d[0] * d[1], p23 = d[2] * d[3], r = __builtin_amdgcn_rcpf(p01 * p23), r01 = r * p23, r23 = r * p01;
;     return (f32x4){r01 * d[1], r01 * d[0], r23 * d[3], r23 * d[2]};
; }
;     __device__ __forceinline__ void operator()(const f32x4 (&acc)[2][2][4][2], const Unit& u, int wr, int wc, int fr, int fq) const {
;         const int row0 = u.pm * BM + wr * 64 + fr, col0 = u.pn * HALF + wc * 32 + 8 * fq;
; #pragma unroll
;         for (int ai = 0; ai < 2; ++ai)
; #pragma unroll
;             for (int m = 0; m < 4; ++m) { bf16_t* rowp = O + (size_t)(row0 + ai * HALF + m * 16) * ldc + col0;
;                 f32x4 v0, v1;
; #pragma unroll
;                 for (int j = 0; j < 1; ++j) { v0 = acc[ai][0][m][0] * sigmoid4(acc[ai][0][m][0]) * acc[ai][1][m][0]; v1 = acc[ai][0][m][1] * sigmoid4(acc[ai][0][m][1]) * acc[ai][1][m][1]; }
;                 u32x4 w; w.x = cvt_pk_bf16(v0[0], v0[1]); w.y = cvt_pk_bf16(v0[2], v0[3]); w.z = cvt_pk_bf16(v1[0], v1[1]); w.w = cvt_pk_bf16(v1[2], v1[3]);
;                 *(u32x4*)rowp = w; }
	v_max_f32_e32 v84, v76, v76
	v_max_f32_e32 v86, v78, v78
	v_max_f32_e32 v84, 0xc1a00000, v84
	v_max_f32_e32 v86, 0xc1a00000, v86
	v_mul_f32_e32 v84, 0xbfb8aa3b, v84
	v_mul_f32_e32 v86, 0xbfb8aa3b, v86
	v_exp_f32_e32 v85, v84
	v_max_f32_e32 v84, v77, v77
	v_exp_f32_e32 v87, v86
	v_max_f32_e32 v86, v79, v79
	v_max_f32_e32 v84, 0xc1a00000, v84
	v_max_f32_e32 v86, 0xc1a00000, v86
	v_mul_f32_e32 v84, 0xbfb8aa3b, v84
	v_mul_f32_e32 v86, 0xbfb8aa3b, v86
	v_exp_f32_e32 v84, v84
	v_exp_f32_e32 v86, v86
	v_cvt_pk_bf16_f32 v82, v82, v83
	v_cvt_pk_bf16_f32 v83, v90, v91
	global_store_dwordx4 v[102:103], v[80:83], off
	v_or_b32_e32 v88, 48, v154
	s_nop 0
	v_pk_add_f32 v[80:81], v[84:85], 1.0 op_sel_hi:[1,0]
	v_pk_add_f32 v[82:83], v[86:87], 1.0 op_sel_hi:[1,0]
	v_mov_b32_e32 v84, v81
	v_mov_b32_e32 v85, v83
	v_mov_b32_e32 v86, v80
	v_mov_b32_e32 v87, v82
	v_pk_mul_f32 v[84:85], v[84:85], v[86:87]
	s_nop 0
	v_mul_f32_e32 v86, v84, v85
	v_rcp_f32_e32 v89, v86
	v_mad_i64_i32 v[86:87], s[16:17], v88, s40, v[144:145]
	v_lshl_add_u64 v[86:87], v[86:87], 0, v[146:147]
	v_mul_f32_e32 v84, v84, v89
	v_mul_f32_e32 v88, v85, v89
	v_pk_mul_f32 v[82:83], v[82:83], v[84:85] op_sel_hi:[1,0]
	v_max_f32_e32 v84, v72, v72
	v_max_f32_e32 v89, v74, v74
	v_max_f32_e32 v84, 0xc1a00000, v84
	v_max_f32_e32 v89, 0xc1a00000, v89
	v_mul_f32_e32 v84, 0xbfb8aa3b, v84
	v_mul_f32_e32 v89, 0xbfb8aa3b, v89
	v_exp_f32_e32 v85, v84
	v_max_f32_e32 v84, v73, v73
	v_exp_f32_e32 v91, v89
	v_max_f32_e32 v89, v75, v75
	v_max_f32_e32 v84, 0xc1a00000, v84
	v_max_f32_e32 v89, 0xc1a00000, v89
	v_mul_f32_e32 v84, 0xbfb8aa3b, v84
	v_mul_f32_e32 v89, 0xbfb8aa3b, v89
	v_exp_f32_e32 v84, v84
	v_exp_f32_e32 v90, v89
	v_pk_mul_f32 v[80:81], v[80:81], v[88:89] op_sel_hi:[1,0]
	v_pk_mul_f32 v[78:79], v[78:79], v[82:83]
	v_pk_mul_f32 v[76:77], v[76:77], v[80:81]
	v_pk_add_f32 v[80:81], v[84:85], 1.0 op_sel_hi:[1,0]
	v_pk_add_f32 v[84:85], v[90:91], 1.0 op_sel_hi:[1,0]
	v_mov_b32_e32 v88, v81
	v_mov_b32_e32 v89, v85
	v_mov_b32_e32 v90, v80
	v_mov_b32_e32 v91, v84
	v_pk_mul_f32 v[88:89], v[88:89], v[90:91]
	v_pk_mul_f32 v[70:71], v[78:79], v[70:71]
	v_mul_f32_e32 v90, v88, v89
	v_rcp_f32_e32 v90, v90
	v_pk_mul_f32 v[68:69], v[76:77], v[68:69]
	v_mul_f32_e32 v76, v89, v90
	v_mul_f32_e32 v78, v88, v90
	v_pk_mul_f32 v[78:79], v[84:85], v[78:79] op_sel_hi:[1,0]
	v_pk_mul_f32 v[76:77], v[80:81], v[76:77] op_sel_hi:[1,0]
	v_pk_mul_f32 v[74:75], v[74:75], v[78:79]
	v_pk_mul_f32 v[72:73], v[72:73], v[76:77]
	v_pk_mul_f32 v[74:75], v[74:75], v[66:67]
	v_pk_mul_f32 v[66:67], v[72:73], v[64:65]
	v_cvt_pk_bf16_f32 v64, v68, v69
	v_cvt_pk_bf16_f32 v65, v70, v71
	v_max_f32_e32 v68, v60, v60
	v_max_f32_e32 v70, v62, v62
	v_max_f32_e32 v68, 0xc1a00000, v68
	v_max_f32_e32 v70, 0xc1a00000, v70
	v_mul_f32_e32 v68, 0xbfb8aa3b, v68
	v_mul_f32_e32 v70, 0xbfb8aa3b, v70
	v_exp_f32_e32 v69, v68
	v_max_f32_e32 v68, v61, v61
	v_exp_f32_e32 v71, v70
	v_max_f32_e32 v70, v63, v63
	v_max_f32_e32 v68, 0xc1a00000, v68
	v_max_f32_e32 v70, 0xc1a00000, v70
	v_mul_f32_e32 v68, 0xbfb8aa3b, v68
	v_mul_f32_e32 v70, 0xbfb8aa3b, v70
	v_exp_f32_e32 v68, v68
	v_exp_f32_e32 v70, v70
	v_cvt_pk_bf16_f32 v66, v66, v67
	v_cvt_pk_bf16_f32 v67, v74, v75
	global_store_dwordx4 v[86:87], v[64:67], off
	v_add_u32_e32 v72, 0x80, v154
	s_nop 0
	v_pk_add_f32 v[64:65], v[68:69], 1.0 op_sel_hi:[1,0]
	v_pk_add_f32 v[66:67], v[70:71], 1.0 op_sel_hi:[1,0]
	v_mov_b32_e32 v68, v65
	v_mov_b32_e32 v69, v67
	v_mov_b32_e32 v70, v64
	v_mov_b32_e32 v71, v66
	v_pk_mul_f32 v[68:69], v[68:69], v[70:71]
	s_nop 0
	v_mul_f32_e32 v70, v68, v69
	v_rcp_f32_e32 v73, v70
	v_mad_i64_i32 v[70:71], s[16:17], v72, s40, v[144:145]
	v_lshl_add_u64 v[70:71], v[70:71], 0, v[146:147]
	v_mul_f32_e32 v68, v68, v73
	v_mul_f32_e32 v72, v69, v73
	v_pk_mul_f32 v[66:67], v[66:67], v[68:69] op_sel_hi:[1,0]
	v_max_f32_e32 v68, v56, v56
	v_max_f32_e32 v73, v58, v58
	v_max_f32_e32 v68, 0xc1a00000, v68
	v_max_f32_e32 v73, 0xc1a00000, v73
	v_mul_f32_e32 v68, 0xbfb8aa3b, v68
	v_mul_f32_e32 v73, 0xbfb8aa3b, v73
	v_exp_f32_e32 v69, v68
	v_max_f32_e32 v68, v57, v57
	v_exp_f32_e32 v75, v73
	v_max_f32_e32 v73, v59, v59
	v_max_f32_e32 v68, 0xc1a00000, v68
	v_max_f32_e32 v73, 0xc1a00000, v73
	v_mul_f32_e32 v68, 0xbfb8aa3b, v68
	v_mul_f32_e32 v73, 0xbfb8aa3b, v73
	v_exp_f32_e32 v68, v68
	v_exp_f32_e32 v74, v73
	v_pk_mul_f32 v[64:65], v[64:65], v[72:73] op_sel_hi:[1,0]
	v_pk_mul_f32 v[62:63], v[62:63], v[66:67]
	v_pk_mul_f32 v[60:61], v[60:61], v[64:65]
	v_pk_add_f32 v[64:65], v[68:69], 1.0 op_sel_hi:[1,0]
	v_pk_add_f32 v[68:69], v[74:75], 1.0 op_sel_hi:[1,0]
	v_mov_b32_e32 v72, v65
	v_mov_b32_e32 v73, v69
	v_mov_b32_e32 v74, v64
	v_mov_b32_e32 v75, v68
	v_pk_mul_f32 v[72:73], v[72:73], v[74:75]
	v_pk_mul_f32 v[54:55], v[62:63], v[54:55]
	v_mul_f32_e32 v74, v72, v73
	v_rcp_f32_e32 v74, v74
	v_pk_mul_f32 v[52:53], v[60:61], v[52:53]
	v_mul_f32_e32 v60, v73, v74
	v_mul_f32_e32 v62, v72, v74
	v_pk_mul_f32 v[62:63], v[68:69], v[62:63] op_sel_hi:[1,0]
	v_pk_mul_f32 v[60:61], v[64:65], v[60:61] op_sel_hi:[1,0]
	v_pk_mul_f32 v[58:59], v[58:59], v[62:63]
	v_pk_mul_f32 v[56:57], v[56:57], v[60:61]
	v_pk_mul_f32 v[58:59], v[58:59], v[50:51]
	v_pk_mul_f32 v[50:51], v[56:57], v[48:49]
	v_cvt_pk_bf16_f32 v48, v52, v53
	v_cvt_pk_bf16_f32 v49, v54, v55
	v_max_f32_e32 v52, v44, v44
	v_max_f32_e32 v54, v46, v46
	v_max_f32_e32 v52, 0xc1a00000, v52
	v_max_f32_e32 v54, 0xc1a00000, v54
	v_mul_f32_e32 v52, 0xbfb8aa3b, v52
	v_mul_f32_e32 v54, 0xbfb8aa3b, v54
	v_exp_f32_e32 v53, v52
	v_max_f32_e32 v52, v45, v45
	v_exp_f32_e32 v55, v54
	v_max_f32_e32 v54, v47, v47
	v_max_f32_e32 v52, 0xc1a00000, v52
	v_max_f32_e32 v54, 0xc1a00000, v54
; __device__ __forceinline__ unsigned cvt_pk_bf16(float lo, float hi) { unsigned r; asm volatile("v_cvt_pk_bf16_f32 %0, %1, %2" : "=v"(r) : "v"(lo), "v"(hi)); return r; }
; __device__ __forceinline__ f32x4 sigmoid4(f32x4 x) {
;     f32x4 d;
; #pragma unroll
;     for (int j = 0; j < 4; ++j) d[j] = 1.0f + __expf(-fmaxf(x[j], -20.0f));
;     const float p01 = d[0] * d[1], p23 = d[2] * d[3], r = __builtin_amdgcn_rcpf(p01 * p23), r01 = r * p23, r23 = r * p01;
;     return (f32x4){r01 * d[1], r01 * d[0], r23 * d[3], r23 * d[2]};
; }
;     __device__ __forceinline__ void operator()(const f32x4 (&acc)[2][2][4][2], const Unit& u, int wr, int wc, int fr, int fq) const {
;         const int row0 = u.pm * BM + wr * 64 + fr, col0 = u.pn * HALF + wc * 32 + 8 * fq;
; #pragma unroll
;         for (int ai = 0; ai < 2; ++ai)
; #pragma unroll
;             for (int m = 0; m < 4; ++m) { bf16_t* rowp = O + (size_t)(row0 + ai * HALF + m * 16) * ldc + col0;
;                 f32x4 v0, v1;
; #pragma unroll
;                 for (int j = 0; j < 1; ++j) { v0 = acc[ai][0][m][0] * sigmoid4(acc[ai][0][m][0]) * acc[ai][1][m][0]; v1 = acc[ai][0][m][1] * sigmoid4(acc[ai][0][m][1]) * acc[ai][1][m][1]; }
;                 u32x4 w; w.x = cvt_pk_bf16(v0[0], v0[1]); w.y = cvt_pk_bf16(v0[2], v0[3]); w.z = cvt_pk_bf16(v1[0], v1[1]); w.w = cvt_pk_bf16(v1[2], v1[3]);
;                 *(u32x4*)rowp = w; }
	v_mul_f32_e32 v52, 0xbfb8aa3b, v52
	v_mul_f32_e32 v54, 0xbfb8aa3b, v54
	v_exp_f32_e32 v52, v52
	v_exp_f32_e32 v54, v54
	v_cvt_pk_bf16_f32 v50, v50, v51
	v_cvt_pk_bf16_f32 v51, v58, v59
	global_store_dwordx4 v[70:71], v[48:51], off
	v_add_u32_e32 v56, 0x90, v154
	s_nop 0
	v_pk_add_f32 v[48:49], v[52:53], 1.0 op_sel_hi:[1,0]
	v_pk_add_f32 v[50:51], v[54:55], 1.0 op_sel_hi:[1,0]
	v_mov_b32_e32 v52, v49
	v_mov_b32_e32 v53, v51
	v_mov_b32_e32 v54, v48
	v_mov_b32_e32 v55, v50
	v_pk_mul_f32 v[52:53], v[52:53], v[54:55]
	s_nop 0
	v_mul_f32_e32 v54, v52, v53
	v_rcp_f32_e32 v57, v54
	v_mad_i64_i32 v[54:55], s[16:17], v56, s40, v[144:145]
	v_lshl_add_u64 v[54:55], v[54:55], 0, v[146:147]
	v_mul_f32_e32 v52, v52, v57
	v_mul_f32_e32 v56, v53, v57
	v_pk_mul_f32 v[50:51], v[50:51], v[52:53] op_sel_hi:[1,0]
	v_max_f32_e32 v52, v40, v40
	v_max_f32_e32 v57, v42, v42
	v_max_f32_e32 v52, 0xc1a00000, v52
	v_max_f32_e32 v57, 0xc1a00000, v57
	v_mul_f32_e32 v52, 0xbfb8aa3b, v52
	v_mul_f32_e32 v57, 0xbfb8aa3b, v57
	v_exp_f32_e32 v53, v52
	v_max_f32_e32 v52, v41, v41
	v_exp_f32_e32 v59, v57
	v_max_f32_e32 v57, v43, v43
	v_max_f32_e32 v52, 0xc1a00000, v52
	v_max_f32_e32 v57, 0xc1a00000, v57
	v_mul_f32_e32 v52, 0xbfb8aa3b, v52
	v_mul_f32_e32 v57, 0xbfb8aa3b, v57
	v_exp_f32_e32 v52, v52
	v_exp_f32_e32 v58, v57
	v_pk_mul_f32 v[48:49], v[48:49], v[56:57] op_sel_hi:[1,0]
	v_pk_mul_f32 v[46:47], v[46:47], v[50:51]
	v_pk_mul_f32 v[44:45], v[44:45], v[48:49]
	v_pk_add_f32 v[48:49], v[52:53], 1.0 op_sel_hi:[1,0]
	v_pk_add_f32 v[52:53], v[58:59], 1.0 op_sel_hi:[1,0]
	v_mov_b32_e32 v56, v49
	v_mov_b32_e32 v57, v53
	v_mov_b32_e32 v58, v48
	v_mov_b32_e32 v59, v52
	v_pk_mul_f32 v[56:57], v[56:57], v[58:59]
	v_pk_mul_f32 v[38:39], v[46:47], v[38:39]
	v_mul_f32_e32 v58, v56, v57
	v_rcp_f32_e32 v58, v58
	v_pk_mul_f32 v[36:37], v[44:45], v[36:37]
	v_mul_f32_e32 v44, v57, v58
	v_mul_f32_e32 v46, v56, v58
	v_pk_mul_f32 v[46:47], v[52:53], v[46:47] op_sel_hi:[1,0]
	v_pk_mul_f32 v[44:45], v[48:49], v[44:45] op_sel_hi:[1,0]
	v_pk_mul_f32 v[42:43], v[42:43], v[46:47]
	v_pk_mul_f32 v[40:41], v[40:41], v[44:45]
	v_pk_mul_f32 v[42:43], v[42:43], v[34:35]
	v_pk_mul_f32 v[34:35], v[40:41], v[32:33]
	v_cvt_pk_bf16_f32 v32, v36, v37
	v_cvt_pk_bf16_f32 v33, v38, v39
	v_max_f32_e32 v36, v28, v28
	v_max_f32_e32 v38, v30, v30
	v_max_f32_e32 v36, 0xc1a00000, v36
	v_max_f32_e32 v38, 0xc1a00000, v38
	v_mul_f32_e32 v36, 0xbfb8aa3b, v36
	v_mul_f32_e32 v38, 0xbfb8aa3b, v38
	v_exp_f32_e32 v37, v36
	v_max_f32_e32 v36, v29, v29
	v_exp_f32_e32 v39, v38
	v_max_f32_e32 v38, v31, v31
	v_max_f32_e32 v36, 0xc1a00000, v36
	v_max_f32_e32 v38, 0xc1a00000, v38
	v_mul_f32_e32 v36, 0xbfb8aa3b, v36
	v_mul_f32_e32 v38, 0xbfb8aa3b, v38
	v_exp_f32_e32 v36, v36
	v_exp_f32_e32 v38, v38
	v_cvt_pk_bf16_f32 v34, v34, v35
	v_cvt_pk_bf16_f32 v35, v42, v43
	global_store_dwordx4 v[54:55], v[32:35], off
	v_add_u32_e32 v40, 0xa0, v154
	s_nop 0
	v_pk_add_f32 v[32:33], v[36:37], 1.0 op_sel_hi:[1,0]
	v_pk_add_f32 v[34:35], v[38:39], 1.0 op_sel_hi:[1,0]
	v_mov_b32_e32 v36, v33
	v_mov_b32_e32 v37, v35
	v_mov_b32_e32 v38, v32
	v_mov_b32_e32 v39, v34
	v_pk_mul_f32 v[36:37], v[36:37], v[38:39]
	s_nop 0
	v_mul_f32_e32 v38, v36, v37
	v_rcp_f32_e32 v41, v38
	v_mad_i64_i32 v[38:39], s[16:17], v40, s40, v[144:145]
	v_lshl_add_u64 v[38:39], v[38:39], 0, v[146:147]
	v_mul_f32_e32 v36, v36, v41
	v_mul_f32_e32 v40, v37, v41
	v_pk_mul_f32 v[34:35], v[34:35], v[36:37] op_sel_hi:[1,0]
	v_max_f32_e32 v36, v24, v24
	v_max_f32_e32 v41, v26, v26
	v_max_f32_e32 v36, 0xc1a00000, v36
	v_max_f32_e32 v41, 0xc1a00000, v41
	v_mul_f32_e32 v36, 0xbfb8aa3b, v36
	v_mul_f32_e32 v41, 0xbfb8aa3b, v41
	v_exp_f32_e32 v37, v36
	v_max_f32_e32 v36, v25, v25
	v_exp_f32_e32 v43, v41
	v_max_f32_e32 v41, v27, v27
	v_max_f32_e32 v36, 0xc1a00000, v36
	v_max_f32_e32 v41, 0xc1a00000, v41
	v_mul_f32_e32 v36, 0xbfb8aa3b, v36
; __device__ __forceinline__ unsigned cvt_pk_bf16(float lo, float hi) { unsigned r; asm volatile("v_cvt_pk_bf16_f32 %0, %1, %2" : "=v"(r) : "v"(lo), "v"(hi)); return r; }
; #define PG8_WAIT_V(n) asm volatile("s_waitcnt vmcnt(" #n ")" ::: "memory")
; #define PG8_BAR __builtin_amdgcn_s_barrier()
;     __device__ __forceinline__ void operator()(const f32x4 (&acc)[2][2][4][2], const Unit& u, int wr, int wc, int fr, int fq) const {
;         const int row0 = u.pm * BM + wr * 64 + fr, col0 = u.pn * HALF + wc * 32 + 8 * fq;
; #pragma unroll
;         for (int ai = 0; ai < 2; ++ai)
; #pragma unroll
;             for (int m = 0; m < 4; ++m) { bf16_t* rowp = O + (size_t)(row0 + ai * HALF + m * 16) * ldc + col0;
;                 f32x4 v0, v1;
; #pragma unroll
;                 for (int j = 0; j < 1; ++j) { v0 = acc[ai][0][m][0] * sigmoid4(acc[ai][0][m][0]) * acc[ai][1][m][0]; v1 = acc[ai][0][m][1] * sigmoid4(acc[ai][0][m][1]) * acc[ai][1][m][1]; }
;                 u32x4 w; w.x = cvt_pk_bf16(v0[0], v0[1]); w.y = cvt_pk_bf16(v0[2], v0[3]); w.z = cvt_pk_bf16(v1[0], v1[1]); w.w = cvt_pk_bf16(v1[2], v1[3]);
;                 *(u32x4*)rowp = w; }
; template <class Epi, class Sched>
; __device__ __forceinline__ void gemm_phase(PG8_LAS unsigned char* lds, const Gemm g, const Sched& S, const Epi& E) {
;     ...
;         if (!has_next) break;
; #pragma unroll
;         for (int a = 0; a < 2; ++a)
; #pragma unroll
;             for (int b = 0; b < 2; ++b)
; #pragma unroll
;                 for (int m = 0; m < 4; ++m)
; #pragma unroll
;                     for (int n = 0; n < 2; ++n) acc[a][b][m][n] = (f32x4){0.f, 0.f, 0.f, 0.f};
;         cur = nxt; cA = nA; cB = nB; ++ui;
;     }
;     PG8_WAIT_V(0);
;     if (wr == 0) PG8_BAR;
;     PG8_BAR;
	v_mul_f32_e32 v41, 0xbfb8aa3b, v41
	v_exp_f32_e32 v36, v36
	v_exp_f32_e32 v42, v41
	v_pk_mul_f32 v[32:33], v[32:33], v[40:41] op_sel_hi:[1,0]
	v_pk_mul_f32 v[30:31], v[30:31], v[34:35]
	v_pk_mul_f32 v[28:29], v[28:29], v[32:33]
	v_pk_add_f32 v[32:33], v[36:37], 1.0 op_sel_hi:[1,0]
	v_pk_add_f32 v[36:37], v[42:43], 1.0 op_sel_hi:[1,0]
	v_mov_b32_e32 v40, v33
	v_mov_b32_e32 v41, v37
	v_mov_b32_e32 v42, v32
	v_mov_b32_e32 v43, v36
	v_pk_mul_f32 v[40:41], v[40:41], v[42:43]
	v_pk_mul_f32 v[22:23], v[30:31], v[22:23]
	v_mul_f32_e32 v42, v40, v41
	v_rcp_f32_e32 v42, v42
	v_pk_mul_f32 v[20:21], v[28:29], v[20:21]
	v_mul_f32_e32 v28, v41, v42
	v_mul_f32_e32 v30, v40, v42
	v_pk_mul_f32 v[30:31], v[36:37], v[30:31] op_sel_hi:[1,0]
	v_pk_mul_f32 v[28:29], v[32:33], v[28:29] op_sel_hi:[1,0]
	v_pk_mul_f32 v[26:27], v[26:27], v[30:31]
	v_pk_mul_f32 v[24:25], v[24:25], v[28:29]
	v_pk_mul_f32 v[26:27], v[26:27], v[18:19]
	v_pk_mul_f32 v[18:19], v[24:25], v[16:17]
	v_cvt_pk_bf16_f32 v16, v20, v21
	v_cvt_pk_bf16_f32 v17, v22, v23
	v_max_f32_e32 v20, v12, v12
	v_max_f32_e32 v22, v14, v14
	v_max_f32_e32 v20, 0xc1a00000, v20
	v_max_f32_e32 v22, 0xc1a00000, v22
	v_mul_f32_e32 v20, 0xbfb8aa3b, v20
	v_mul_f32_e32 v22, 0xbfb8aa3b, v22
	v_exp_f32_e32 v21, v20
	v_max_f32_e32 v20, v13, v13
	v_exp_f32_e32 v23, v22
	v_max_f32_e32 v22, v15, v15
	v_max_f32_e32 v20, 0xc1a00000, v20
	v_max_f32_e32 v22, 0xc1a00000, v22
	v_mul_f32_e32 v20, 0xbfb8aa3b, v20
	v_mul_f32_e32 v22, 0xbfb8aa3b, v22
	v_exp_f32_e32 v20, v20
	v_exp_f32_e32 v22, v22
	v_cvt_pk_bf16_f32 v18, v18, v19
	v_cvt_pk_bf16_f32 v19, v26, v27
	global_store_dwordx4 v[38:39], v[16:19], off
	v_add_u32_e32 v24, 0xb0, v154
	s_nop 0
	v_pk_add_f32 v[16:17], v[20:21], 1.0 op_sel_hi:[1,0]
	v_pk_add_f32 v[18:19], v[22:23], 1.0 op_sel_hi:[1,0]
	v_mov_b32_e32 v20, v17
	v_mov_b32_e32 v21, v19
	v_mov_b32_e32 v22, v16
	v_mov_b32_e32 v23, v18
	v_pk_mul_f32 v[20:21], v[20:21], v[22:23]
	s_nop 0
	v_mul_f32_e32 v22, v20, v21
	v_rcp_f32_e32 v25, v22
	v_mad_i64_i32 v[22:23], s[16:17], v24, s40, v[144:145]
	v_lshl_add_u64 v[22:23], v[22:23], 0, v[146:147]
	v_mul_f32_e32 v20, v20, v25
	v_mul_f32_e32 v24, v21, v25
	v_pk_mul_f32 v[18:19], v[18:19], v[20:21] op_sel_hi:[1,0]
	v_max_f32_e32 v20, v8, v8
	v_max_f32_e32 v25, v10, v10
	v_max_f32_e32 v20, 0xc1a00000, v20
	v_max_f32_e32 v25, 0xc1a00000, v25
	v_mul_f32_e32 v20, 0xbfb8aa3b, v20
	v_mul_f32_e32 v25, 0xbfb8aa3b, v25
	v_exp_f32_e32 v21, v20
	v_max_f32_e32 v20, v9, v9
	v_exp_f32_e32 v27, v25
	v_max_f32_e32 v25, v11, v11
	v_max_f32_e32 v20, 0xc1a00000, v20
	v_max_f32_e32 v25, 0xc1a00000, v25
	v_mul_f32_e32 v20, 0xbfb8aa3b, v20
	v_mul_f32_e32 v25, 0xbfb8aa3b, v25
	v_exp_f32_e32 v20, v20
	v_exp_f32_e32 v26, v25
	v_pk_mul_f32 v[16:17], v[16:17], v[24:25] op_sel_hi:[1,0]
	v_pk_mul_f32 v[14:15], v[14:15], v[18:19]
	v_pk_mul_f32 v[12:13], v[12:13], v[16:17]
	v_pk_add_f32 v[16:17], v[20:21], 1.0 op_sel_hi:[1,0]
	v_pk_add_f32 v[20:21], v[26:27], 1.0 op_sel_hi:[1,0]
	v_mov_b32_e32 v24, v17
	v_mov_b32_e32 v25, v21
	v_mov_b32_e32 v26, v16
	v_mov_b32_e32 v27, v20
	v_pk_mul_f32 v[24:25], v[24:25], v[26:27]
	v_pk_mul_f32 v[6:7], v[14:15], v[6:7]
	v_mul_f32_e32 v26, v24, v25
	v_rcp_f32_e32 v26, v26
	v_pk_mul_f32 v[4:5], v[12:13], v[4:5]
	s_mov_b64 s[16:17], s[10:11]
	v_mul_f32_e32 v12, v25, v26
	v_mul_f32_e32 v14, v24, v26
	v_pk_mul_f32 v[14:15], v[20:21], v[14:15] op_sel_hi:[1,0]
	v_pk_mul_f32 v[12:13], v[16:17], v[12:13] op_sel_hi:[1,0]
	v_pk_mul_f32 v[10:11], v[10:11], v[14:15]
	v_pk_mul_f32 v[8:9], v[8:9], v[12:13]
	v_pk_mul_f32 v[10:11], v[10:11], v[2:3]
	v_pk_mul_f32 v[2:3], v[8:9], v[0:1]
	v_cvt_pk_bf16_f32 v0, v4, v5
	v_cvt_pk_bf16_f32 v1, v6, v7
	s_nop 0
	v_cvt_pk_bf16_f32 v2, v2, v3
	v_cvt_pk_bf16_f32 v3, v10, v11
	global_store_dwordx4 v[22:23], v[0:3], off
	s_cbranch_vccz .LBB0_1199
	s_waitcnt vmcnt(0)
	s_cmpk_gt_u32 s23, 0xff
	s_cbranch_scc1 .LBB0_1206
	s_barrier

; #define PG8_STAGE(bufoff, gbase, voff) do { _Pragma("unroll") for (int _i = 0; _i < 2; ++_i) \
;         __builtin_amdgcn_global_load_lds((const unsigned*)((const char*)(gbase) + (voff)[_i]), (PG8_LAS unsigned*)(lds + (bufoff) + ldsw + _i * 8192), 16, 0, 0); } while (0)
; #define PG8_LDA(dst, b, h) do { _Pragma("unroll") for (int m = 0; m < 4; ++m) _Pragma("unroll") for (int k = 0; k < 2; ++k) dst[m][k] = *(const PG8_LAS bf16x8*)(lds + PG8_SA(b, h) + aoff + m * 2048 + k * 1024); } while (0)
; #define PG8_LDB(dst, b, h) do { _Pragma("unroll") for (int n = 0; n < 2; ++n) _Pragma("unroll") for (int k = 0; k < 2; ++k) dst[n][k] = *(const PG8_LAS bf16x8*)(lds + PG8_SB(b, h) + boff + n * 2048 + k * 1024); } while (0)
; #define PG8_MMA(ai, bj, At, Bt) do { __builtin_amdgcn_s_setprio(1); _Pragma("unroll") for (int m = 0; m < 4; ++m) _Pragma("unroll") for (int n = 0; n < 2; ++n) _Pragma("unroll") for (int k = 0; k < 2; ++k) \
;         acc[ai][bj][m][n] = __builtin_amdgcn_mfma_f32_16x16x32_bf16(Bt[n][k], At[m][k], acc[ai][bj][m][n], 0, 0, 0); __builtin_amdgcn_s_setprio(0); } while (0)
; #define PG8_WAIT_V(n) asm volatile("s_waitcnt vmcnt(" #n ")" ::: "memory")
; #define PG8_WAIT_L(n) asm volatile("s_waitcnt lgkmcnt(" #n ")" ::: "memory")
; template <class Epi, class Sched>
; __device__ __forceinline__ void gemm_phase(PG8_LAS unsigned char* lds, const Gemm g, const Sched& S, const Epi& E) {
;     ...
;             const bool last = (t == nt - 2);
;             const char* a1 = cA + (size_t)(t + 1) * kstep;
;             const char* a2 = last ? nA : cA + (size_t)(t + 2) * kstep; const char* b2 = last ? nB : cB + (size_t)(t + 2) * kstep;
;             const char* a3 = a2 + kstep; const char* b3 = b2 + kstep;
;             if (last && has_next) S.a_ready(nxt);
;             PG8_LDB(B0, 0, 0); PG8_SCHED; PG8_LDA(At, 0, 0); PG8_STAGE(PG8_SA(1, 1), a1 + hstep, voffA);
;             PG8_WAIT_L(8); PG8_BAR; PG8_WAIT_L(0); PG8_MMA(0, 0, At, B0); PG8_BAR; PG8_SCHED;
;             PG8_LDB(B1, 0, 1); PG8_STAGE(PG8_SB(0, 0), b2, voffB);
;             PG8_BAR; PG8_WAIT_L(0); PG8_MMA(0, 1, At, B1); PG8_BAR;
;             PG8_LDA(At, 0, 1); PG8_STAGE(PG8_SA(0, 0), a2, voffA);
;             PG8_BAR; PG8_WAIT_L(0); PG8_MMA(1, 0, At, B0); PG8_BAR; PG8_SCHED;
;             PG8_STAGE(PG8_SB(0, 1), b2 + hstep, voffB);
;             PG8_WAIT_V(6); PG8_BAR; PG8_MMA(1, 1, At, B1); PG8_BAR;
.LBB0_1278:
	ds_read_b128 v[152:155], v149
	ds_read_b128 v[156:159], v149 offset:1024
	ds_read_b128 v[160:163], v149 offset:2048
	ds_read_b128 v[164:167], v149 offset:3072
	s_add_u32 s20, s18, 0x100
	s_addc_u32 s21, s19, 0
	s_cmp_eq_u32 s54, 40
	s_cselect_b32 s25, s1, s21
	s_cselect_b32 s24, s0, s20
	s_cselect_b32 s23, s5, s53
	s_cselect_b32 s22, s4, s52
	v_lshl_add_u64 v[144:145], s[18:19], 0, v[136:137]
	s_add_i32 m0, s34, 0xc000
	ds_read_b128 v[168:171], v150
	ds_read_b128 v[172:175], v150 offset:1024
	ds_read_b128 v[182:185], v150 offset:2048
	ds_read_b128 v[190:193], v150 offset:3072
	ds_read_b128 v[194:197], v150 offset:4096
	ds_read_b128 v[198:201], v150 offset:5120
	ds_read_b128 v[202:205], v150 offset:6144
	ds_read_b128 v[206:209], v150 offset:7168
	global_load_lds_dwordx4 v[144:145], off
	v_lshl_add_u64 v[144:145], s[18:19], 0, v[138:139]
	s_add_i32 m0, s34, 0xe000
	s_nop 0
	global_load_lds_dwordx4 v[144:145], off
	s_waitcnt lgkmcnt(0)
	s_barrier
	v_mfma_f32_16x16x32_bf16 v[124:127], v[152:155], v[168:171], v[124:127]
	v_mfma_f32_16x16x32_bf16 v[120:123], v[160:163], v[168:171], v[120:123]
	v_mfma_f32_16x16x32_bf16 v[108:111], v[152:155], v[182:185], v[108:111]
	v_mfma_f32_16x16x32_bf16 v[104:107], v[160:163], v[182:185], v[104:107]
	v_mfma_f32_16x16x32_bf16 v[92:95], v[152:155], v[194:197], v[92:95]
	v_mfma_f32_16x16x32_bf16 v[88:91], v[160:163], v[194:197], v[88:91]
	v_mfma_f32_16x16x32_bf16 v[76:79], v[152:155], v[202:205], v[76:79]
	v_mfma_f32_16x16x32_bf16 v[72:75], v[160:163], v[202:205], v[72:75]
	v_mfma_f32_16x16x32_bf16 v[124:127], v[156:159], v[172:175], v[124:127]
	v_mfma_f32_16x16x32_bf16 v[120:123], v[164:167], v[172:175], v[120:123]
	v_mfma_f32_16x16x32_bf16 v[108:111], v[156:159], v[190:193], v[108:111]
	v_mfma_f32_16x16x32_bf16 v[104:107], v[164:167], v[190:193], v[104:107]
	v_mfma_f32_16x16x32_bf16 v[92:95], v[156:159], v[198:201], v[92:95]
	v_mfma_f32_16x16x32_bf16 v[88:91], v[164:167], v[198:201], v[88:91]
	v_mfma_f32_16x16x32_bf16 v[76:79], v[156:159], v[206:209], v[76:79]
	v_mfma_f32_16x16x32_bf16 v[72:75], v[164:167], v[206:209], v[72:75]
	s_barrier
	s_add_i32 s18, s42, s31
	v_lshl_add_u64 v[144:145], s[22:23], 0, v[130:131]
	s_mov_b32 m0, s18
	ds_read_b128 v[210:213], v151
	ds_read_b128 v[214:217], v151 offset:1024
	ds_read_b128 v[218:221], v151 offset:2048
	ds_read_b128 v[222:225], v151 offset:3072
	global_load_lds_dwordx4 v[144:145], off
	v_lshl_add_u64 v[186:187], s[22:23], 0, v[134:135]
	s_add_i32 m0, s18, 0x2000
	s_nop 0
	global_load_lds_dwordx4 v[186:187], off
	s_waitcnt lgkmcnt(0)
	s_barrier
	v_mfma_f32_16x16x32_bf16 v[116:119], v[210:213], v[168:171], v[116:119]
	v_mfma_f32_16x16x32_bf16 v[112:115], v[218:221], v[168:171], v[112:115]
	v_mfma_f32_16x16x32_bf16 v[100:103], v[210:213], v[182:185], v[100:103]
	v_mfma_f32_16x16x32_bf16 v[96:99], v[218:221], v[182:185], v[96:99]
	v_mfma_f32_16x16x32_bf16 v[84:87], v[210:213], v[194:197], v[84:87]
	v_mfma_f32_16x16x32_bf16 v[80:83], v[218:221], v[194:197], v[80:83]
	v_mfma_f32_16x16x32_bf16 v[68:71], v[210:213], v[202:205], v[68:71]
	v_mfma_f32_16x16x32_bf16 v[64:67], v[218:221], v[202:205], v[64:67]
	v_mfma_f32_16x16x32_bf16 v[116:119], v[214:217], v[172:175], v[116:119]
	v_mfma_f32_16x16x32_bf16 v[112:115], v[222:225], v[172:175], v[112:115]
	v_mfma_f32_16x16x32_bf16 v[100:103], v[214:217], v[190:193], v[100:103]
	v_mfma_f32_16x16x32_bf16 v[96:99], v[222:225], v[190:193], v[96:99]
	v_mfma_f32_16x16x32_bf16 v[84:87], v[214:217], v[198:201], v[84:87]
	v_mfma_f32_16x16x32_bf16 v[80:83], v[222:225], v[198:201], v[80:83]
	v_mfma_f32_16x16x32_bf16 v[68:71], v[214:217], v[206:209], v[68:71]
	v_mfma_f32_16x16x32_bf16 v[64:67], v[222:225], v[206:209], v[64:67]
	s_mov_b32 m0, s34
	v_lshl_add_u64 v[226:227], s[24:25], 0, v[128:129]
	s_barrier
	ds_read_b128 v[168:171], v150 offset:16384
	ds_read_b128 v[172:175], v150 offset:17408
	ds_read_b128 v[182:185], v150 offset:18432
	ds_read_b128 v[190:193], v150 offset:19456
	ds_read_b128 v[194:197], v150 offset:20480
	ds_read_b128 v[198:201], v150 offset:21504
	ds_read_b128 v[202:205], v150 offset:22528
	ds_read_b128 v[206:209], v150 offset:23552
	global_load_lds_dwordx4 v[226:227], off
	v_lshl_add_u64 v[228:229], s[24:25], 0, v[132:133]
	s_mov_b32 m0, s35
	s_nop 0
	global_load_lds_dwordx4 v[228:229], off
	s_waitcnt lgkmcnt(0)
	s_barrier
	v_mfma_f32_16x16x32_bf16 v[60:63], v[152:155], v[168:171], v[60:63]
	v_mfma_f32_16x16x32_bf16 v[56:59], v[160:163], v[168:171], v[56:59]
	v_mfma_f32_16x16x32_bf16 v[48:51], v[152:155], v[182:185], v[48:51]
	v_mfma_f32_16x16x32_bf16 v[40:43], v[160:163], v[182:185], v[40:43]
	v_mfma_f32_16x16x32_bf16 v[32:35], v[152:155], v[194:197], v[32:35]
	v_mfma_f32_16x16x32_bf16 v[24:27], v[160:163], v[194:197], v[24:27]
	v_mfma_f32_16x16x32_bf16 v[16:19], v[152:155], v[202:205], v[16:19]
	v_mfma_f32_16x16x32_bf16 v[8:11], v[160:163], v[202:205], v[8:11]
	v_mfma_f32_16x16x32_bf16 v[60:63], v[156:159], v[172:175], v[60:63]
	v_mfma_f32_16x16x32_bf16 v[56:59], v[164:167], v[172:175], v[56:59]
	v_mfma_f32_16x16x32_bf16 v[48:51], v[156:159], v[190:193], v[48:51]
	v_mfma_f32_16x16x32_bf16 v[40:43], v[164:167], v[190:193], v[40:43]
	v_mfma_f32_16x16x32_bf16 v[32:35], v[156:159], v[198:201], v[32:35]
	v_mfma_f32_16x16x32_bf16 v[24:27], v[164:167], v[198:201], v[24:27]
	v_mfma_f32_16x16x32_bf16 v[16:19], v[156:159], v[206:209], v[16:19]
	v_mfma_f32_16x16x32_bf16 v[8:11], v[164:167], v[206:209], v[8:11]
	s_barrier
	s_add_u32 s18, s22, 0xb0000
	s_addc_u32 s19, s23, 0
	s_add_i32 s55, s43, s31
	v_lshl_add_u64 v[152:153], s[18:19], 0, v[130:131]
	s_mov_b32 m0, s55
	s_nop 0
	global_load_lds_dwordx4 v[152:153], off
	v_lshl_add_u64 v[152:153], s[18:19], 0, v[134:135]
	s_add_i32 m0, s55, 0x2000
	s_nop 0
	global_load_lds_dwordx4 v[152:153], off
	s_waitcnt vmcnt(6)
	s_barrier
; #define PG8_STAGE(bufoff, gbase, voff) do { _Pragma("unroll") for (int _i = 0; _i < 2; ++_i) \
;         __builtin_amdgcn_global_load_lds((const unsigned*)((const char*)(gbase) + (voff)[_i]), (PG8_LAS unsigned*)(lds + (bufoff) + ldsw + _i * 8192), 16, 0, 0); } while (0)
; #define PG8_LDA(dst, b, h) do { _Pragma("unroll") for (int m = 0; m < 4; ++m) _Pragma("unroll") for (int k = 0; k < 2; ++k) dst[m][k] = *(const PG8_LAS bf16x8*)(lds + PG8_SA(b, h) + aoff + m * 2048 + k * 1024); } while (0)
; #define PG8_LDB(dst, b, h) do { _Pragma("unroll") for (int n = 0; n < 2; ++n) _Pragma("unroll") for (int k = 0; k < 2; ++k) dst[n][k] = *(const PG8_LAS bf16x8*)(lds + PG8_SB(b, h) + boff + n * 2048 + k * 1024); } while (0)
; #define PG8_MMA(ai, bj, At, Bt) do { __builtin_amdgcn_s_setprio(1); _Pragma("unroll") for (int m = 0; m < 4; ++m) _Pragma("unroll") for (int n = 0; n < 2; ++n) _Pragma("unroll") for (int k = 0; k < 2; ++k) \
;         acc[ai][bj][m][n] = __builtin_amdgcn_mfma_f32_16x16x32_bf16(Bt[n][k], At[m][k], acc[ai][bj][m][n], 0, 0, 0); __builtin_amdgcn_s_setprio(0); } while (0)
; #define PG8_WAIT_V(n) asm volatile("s_waitcnt vmcnt(" #n ")" ::: "memory")
; #define PG8_WAIT_L(n) asm volatile("s_waitcnt lgkmcnt(" #n ")" ::: "memory")
; #define PG8_BAR __builtin_amdgcn_s_barrier()
; #define PG8_SCHED __builtin_amdgcn_sched_barrier(0)
; template <class Epi, class Sched>
; __device__ __forceinline__ void gemm_phase(PG8_LAS unsigned char* lds, const Gemm g, const Sched& S, const Epi& E) {
;     ...
;             PG8_WAIT_V(6); PG8_BAR; PG8_MMA(1, 1, At, B1); PG8_BAR;
;             PG8_LDB(B0, 1, 0); PG8_SCHED; PG8_LDA(At, 1, 0); PG8_STAGE(PG8_SA(0, 1), a2 + hstep, voffA);
;             PG8_WAIT_L(8); PG8_BAR; PG8_WAIT_L(0); PG8_MMA(0, 0, At, B0); PG8_BAR; PG8_SCHED;
;             PG8_LDB(B1, 1, 1); PG8_STAGE(PG8_SB(1, 0), b3, voffB);
;             PG8_BAR; PG8_WAIT_L(0); PG8_MMA(0, 1, At, B1); PG8_BAR;
;             PG8_LDA(At, 1, 1); PG8_STAGE(PG8_SA(1, 0), a3, voffA);
;             PG8_BAR; PG8_WAIT_L(0); PG8_MMA(1, 0, At, B0); PG8_BAR; PG8_SCHED;
;             PG8_STAGE(PG8_SB(1, 1), b3 + hstep, voffB);
	v_mfma_f32_16x16x32_bf16 v[52:55], v[210:213], v[168:171], v[52:55]
	v_mfma_f32_16x16x32_bf16 v[44:47], v[218:221], v[168:171], v[44:47]
	v_mfma_f32_16x16x32_bf16 v[36:39], v[210:213], v[182:185], v[36:39]
	v_mfma_f32_16x16x32_bf16 v[28:31], v[218:221], v[182:185], v[28:31]
	v_mfma_f32_16x16x32_bf16 v[20:23], v[210:213], v[194:197], v[20:23]
	v_mfma_f32_16x16x32_bf16 v[12:15], v[218:221], v[194:197], v[12:15]
	v_mfma_f32_16x16x32_bf16 v[4:7], v[210:213], v[202:205], v[4:7]
	v_mfma_f32_16x16x32_bf16 v[0:3], v[218:221], v[202:205], v[0:3]
	v_mfma_f32_16x16x32_bf16 v[52:55], v[214:217], v[172:175], v[52:55]
	v_mfma_f32_16x16x32_bf16 v[44:47], v[222:225], v[172:175], v[44:47]
	v_mfma_f32_16x16x32_bf16 v[36:39], v[214:217], v[190:193], v[36:39]
	v_mfma_f32_16x16x32_bf16 v[28:31], v[222:225], v[190:193], v[28:31]
	v_mfma_f32_16x16x32_bf16 v[20:23], v[214:217], v[198:201], v[20:23]
	v_mfma_f32_16x16x32_bf16 v[12:15], v[222:225], v[198:201], v[12:15]
	v_mfma_f32_16x16x32_bf16 v[4:7], v[214:217], v[206:209], v[4:7]
	v_mfma_f32_16x16x32_bf16 v[0:3], v[222:225], v[206:209], v[0:3]
	s_add_i32 s55, 0, 0x18000
	v_add_u32_e32 v164, s55, v147
	s_barrier
	ds_read_b128 v[152:155], v164
	ds_read_b128 v[156:159], v164 offset:1024
	ds_read_b128 v[160:163], v164 offset:2048
	ds_read_b128 v[164:167], v164 offset:3072
	s_add_u32 s18, s24, 0xb0000
	s_addc_u32 s19, s25, 0
	s_mov_b32 m0, s36
	v_lshl_add_u64 v[210:211], s[18:19], 0, v[128:129]
	ds_read_b128 v[168:171], v150 offset:32768
	ds_read_b128 v[172:175], v150 offset:33792
	ds_read_b128 v[182:185], v150 offset:34816
	ds_read_b128 v[190:193], v150 offset:35840
	ds_read_b128 v[194:197], v150 offset:36864
	ds_read_b128 v[198:201], v150 offset:37888
	ds_read_b128 v[202:205], v150 offset:38912
	ds_read_b128 v[206:209], v150 offset:39936
	global_load_lds_dwordx4 v[210:211], off
	v_lshl_add_u64 v[210:211], s[18:19], 0, v[132:133]
	s_mov_b32 m0, s37
	s_nop 0
	global_load_lds_dwordx4 v[210:211], off
	s_waitcnt lgkmcnt(0)
	s_barrier
	v_mfma_f32_16x16x32_bf16 v[124:127], v[152:155], v[168:171], v[124:127]
	v_mfma_f32_16x16x32_bf16 v[120:123], v[160:163], v[168:171], v[120:123]
	v_mfma_f32_16x16x32_bf16 v[108:111], v[152:155], v[182:185], v[108:111]
	v_mfma_f32_16x16x32_bf16 v[104:107], v[160:163], v[182:185], v[104:107]
	v_mfma_f32_16x16x32_bf16 v[92:95], v[152:155], v[194:197], v[92:95]
	v_mfma_f32_16x16x32_bf16 v[88:91], v[160:163], v[194:197], v[88:91]
	v_mfma_f32_16x16x32_bf16 v[76:79], v[152:155], v[202:205], v[76:79]
	v_mfma_f32_16x16x32_bf16 v[72:75], v[160:163], v[202:205], v[72:75]
	v_mfma_f32_16x16x32_bf16 v[124:127], v[156:159], v[172:175], v[124:127]
	v_mfma_f32_16x16x32_bf16 v[120:123], v[164:167], v[172:175], v[120:123]
	v_mfma_f32_16x16x32_bf16 v[108:111], v[156:159], v[190:193], v[108:111]
	v_mfma_f32_16x16x32_bf16 v[104:107], v[164:167], v[190:193], v[104:107]
	v_mfma_f32_16x16x32_bf16 v[92:95], v[156:159], v[198:201], v[92:95]
	v_mfma_f32_16x16x32_bf16 v[88:91], v[164:167], v[198:201], v[88:91]
	v_mfma_f32_16x16x32_bf16 v[76:79], v[156:159], v[206:209], v[76:79]
	v_mfma_f32_16x16x32_bf16 v[72:75], v[164:167], v[206:209], v[72:75]
	s_barrier
	s_add_i32 s24, 0, 0x1c000
	s_add_i32 s18, s55, s31
	v_add_u32_e32 v179, s24, v147
	v_lshl_add_u64 v[144:145], v[144:145], 0, s[8:9]
	s_mov_b32 m0, s18
	ds_read_b128 v[210:213], v179
	ds_read_b128 v[214:217], v179 offset:1024
	ds_read_b128 v[218:221], v179 offset:2048
	ds_read_b128 v[222:225], v179 offset:3072
	global_load_lds_dwordx4 v[144:145], off
	v_lshl_add_u64 v[144:145], v[186:187], 0, s[8:9]
	s_add_i32 m0, s18, 0x2000
	s_nop 0
	global_load_lds_dwordx4 v[144:145], off
	s_waitcnt lgkmcnt(0)
	s_barrier
	v_mfma_f32_16x16x32_bf16 v[116:119], v[210:213], v[168:171], v[116:119]
	v_mfma_f32_16x16x32_bf16 v[112:115], v[218:221], v[168:171], v[112:115]
	v_mfma_f32_16x16x32_bf16 v[100:103], v[210:213], v[182:185], v[100:103]
	v_mfma_f32_16x16x32_bf16 v[96:99], v[218:221], v[182:185], v[96:99]
	v_mfma_f32_16x16x32_bf16 v[84:87], v[210:213], v[194:197], v[84:87]
	v_mfma_f32_16x16x32_bf16 v[80:83], v[218:221], v[194:197], v[80:83]
	v_mfma_f32_16x16x32_bf16 v[68:71], v[210:213], v[202:205], v[68:71]
	v_mfma_f32_16x16x32_bf16 v[64:67], v[218:221], v[202:205], v[64:67]
	v_mfma_f32_16x16x32_bf16 v[116:119], v[214:217], v[172:175], v[116:119]
	v_mfma_f32_16x16x32_bf16 v[112:115], v[222:225], v[172:175], v[112:115]
	v_mfma_f32_16x16x32_bf16 v[100:103], v[214:217], v[190:193], v[100:103]
	v_mfma_f32_16x16x32_bf16 v[96:99], v[222:225], v[190:193], v[96:99]
	v_mfma_f32_16x16x32_bf16 v[84:87], v[214:217], v[198:201], v[84:87]
	v_mfma_f32_16x16x32_bf16 v[80:83], v[222:225], v[198:201], v[80:83]
	v_mfma_f32_16x16x32_bf16 v[68:71], v[214:217], v[206:209], v[68:71]
	v_mfma_f32_16x16x32_bf16 v[64:67], v[222:225], v[206:209], v[64:67]
	s_mov_b32 m0, s39
	v_lshl_add_u64 v[144:145], v[226:227], 0, s[8:9]
	s_barrier
	ds_read_b128 v[168:171], v150 offset:49152
	ds_read_b128 v[172:175], v150 offset:50176
	ds_read_b128 v[182:185], v150 offset:51200
	ds_read_b128 v[190:193], v150 offset:52224
	ds_read_b128 v[194:197], v150 offset:53248
	ds_read_b128 v[198:201], v150 offset:54272
	ds_read_b128 v[202:205], v150 offset:55296
	ds_read_b128 v[206:209], v150 offset:56320
	global_load_lds_dwordx4 v[144:145], off
	v_lshl_add_u64 v[144:145], v[228:229], 0, s[8:9]
	s_mov_b32 m0, s40
	s_nop 0
	global_load_lds_dwordx4 v[144:145], off
	s_waitcnt lgkmcnt(0)
	s_barrier
; __device__ __forceinline__ unsigned cvt_pk_bf16(float lo, float hi) { unsigned r; asm volatile("v_cvt_pk_bf16_f32 %0, %1, %2" : "=v"(r) : "v"(lo), "v"(hi)); return r; }
; __device__ __forceinline__ float flogsig16(float x) { return (fminf(x, 0.f) - __logf(1.0f + __expf(-fabsf(x)))) * 0.0625f; }
; #define PG8_WAIT_V(n) asm volatile("s_waitcnt vmcnt(" #n ")" ::: "memory")
; #define PG8_WAIT_L(n) asm volatile("s_waitcnt lgkmcnt(" #n ")" ::: "memory")
;     __device__ __forceinline__ void operator()(const f32x4 (&acc)[2][2][4][2], const Unit& u, int wr, int wc, int fr, int fq) const {
;     ...
;         const int row0 = u.pm * BM + wr * 64 + fr, col0 = u.pn * BM + wc * 32 + 8 * fq, bcol0 = wc * 32 + 8 * fq;
;         f32x4 bv[2][2];
; #pragma unroll
;         for (int bj = 0; bj < 2; ++bj)
; #pragma unroll
;             for (int n = 0; n < 2; ++n) bv[bj][n] = bias ? *(const f32x4*)(bias + bcol0 + bj * HALF + 4 * n) : (f32x4){0.f, 0.f, 0.f, 0.f};
; #pragma unroll
;         for (int ai = 0; ai < 2; ++ai)
; #pragma unroll
;             for (int m = 0; m < 4; ++m) { bf16_t* rowp = O + (size_t)(row0 + ai * HALF + m * 16) * ldc + col0;
; #pragma unroll
;                 for (int bj = 0; bj < 2; ++bj) { f32x4 v0 = acc[ai][bj][m][0] + bv[bj][0], v1 = acc[ai][bj][m][1] + bv[bj][1];
;                     if (act == 1) {
; #pragma unroll
;                         for (int j = 0; j < 1; ++j) { v0 = v0 * sigmoid4(v0); v1 = v1 * sigmoid4(v1); } }
;                     else if (act == 2) {
; #pragma unroll
;                         for (int j = 0; j < 1; ++j) { v0 = sigmoid4(v0); v1 = sigmoid4(v1); } }
;                     else if (act == 3) {
; #pragma unroll
;                         for (int j = 0; j < 4; ++j) { v0[j] = flogsig16(v0[j]); v1[j] = flogsig16(v1[j]); } }
;                     u32x4 w; w.x = cvt_pk_bf16(v0[0], v0[1]); w.y = cvt_pk_bf16(v0[2], v0[3]); w.z = cvt_pk_bf16(v1[0], v1[1]); w.w = cvt_pk_bf16(v1[2], v1[3]);
;                     *(u32x4*)(rowp + bj * HALF) = w; } }
; template <class Epi, class Sched>
; __device__ __forceinline__ void gemm_phase(PG8_LAS unsigned char* lds, const Gemm g, const Sched& S, const Epi& E) {
;     ...
;             PG8_BAR; PG8_WAIT_L(0); PG8_MMA(1, 0, At, B0); PG8_BAR; PG8_SCHED;
;             PG8_STAGE(PG8_SB(1, 1), b3 + hstep, voffB);
;             PG8_WAIT_V(6); PG8_BAR; PG8_MMA(1, 1, At, B1); PG8_BAR;
	v_mfma_f32_16x16x32_bf16 v[60:63], v[152:155], v[168:171], v[60:63]
	v_mfma_f32_16x16x32_bf16 v[56:59], v[160:163], v[168:171], v[56:59]
	v_mfma_f32_16x16x32_bf16 v[48:51], v[152:155], v[182:185], v[48:51]
	v_mfma_f32_16x16x32_bf16 v[40:43], v[160:163], v[182:185], v[40:43]
	v_mfma_f32_16x16x32_bf16 v[32:35], v[152:155], v[194:197], v[32:35]
	v_mfma_f32_16x16x32_bf16 v[24:27], v[160:163], v[194:197], v[24:27]
	v_mfma_f32_16x16x32_bf16 v[16:19], v[152:155], v[202:205], v[16:19]
	v_mfma_f32_16x16x32_bf16 v[8:11], v[160:163], v[202:205], v[8:11]
	v_mfma_f32_16x16x32_bf16 v[60:63], v[156:159], v[172:175], v[60:63]
	v_mfma_f32_16x16x32_bf16 v[56:59], v[164:167], v[172:175], v[56:59]
	v_mfma_f32_16x16x32_bf16 v[48:51], v[156:159], v[190:193], v[48:51]
	v_mfma_f32_16x16x32_bf16 v[40:43], v[164:167], v[190:193], v[40:43]
	v_mfma_f32_16x16x32_bf16 v[32:35], v[156:159], v[198:201], v[32:35]
	v_mfma_f32_16x16x32_bf16 v[24:27], v[164:167], v[198:201], v[24:27]
	v_mfma_f32_16x16x32_bf16 v[16:19], v[156:159], v[206:209], v[16:19]
	v_mfma_f32_16x16x32_bf16 v[8:11], v[164:167], v[206:209], v[8:11]
	s_barrier
	s_add_u32 s18, s22, 0xb0080
	s_addc_u32 s19, s23, 0
	s_add_i32 s22, s24, s31
	v_lshl_add_u64 v[144:145], s[18:19], 0, v[130:131]
	s_mov_b32 m0, s22
	s_nop 0
	global_load_lds_dwordx4 v[144:145], off
	v_lshl_add_u64 v[144:145], s[18:19], 0, v[134:135]
	s_add_i32 m0, s22, 0x2000
	s_nop 0
	global_load_lds_dwordx4 v[144:145], off
	s_waitcnt vmcnt(6)
	s_barrier
	v_mfma_f32_16x16x32_bf16 v[52:55], v[210:213], v[168:171], v[52:55]
	v_mfma_f32_16x16x32_bf16 v[44:47], v[218:221], v[168:171], v[44:47]
	v_mfma_f32_16x16x32_bf16 v[36:39], v[210:213], v[182:185], v[36:39]
	v_mfma_f32_16x16x32_bf16 v[28:31], v[218:221], v[182:185], v[28:31]
	v_mfma_f32_16x16x32_bf16 v[20:23], v[210:213], v[194:197], v[20:23]
	v_mfma_f32_16x16x32_bf16 v[12:15], v[218:221], v[194:197], v[12:15]
	v_mfma_f32_16x16x32_bf16 v[4:7], v[210:213], v[202:205], v[4:7]
	v_mfma_f32_16x16x32_bf16 v[0:3], v[218:221], v[202:205], v[0:3]
	v_mfma_f32_16x16x32_bf16 v[52:55], v[214:217], v[172:175], v[52:55]
	v_mfma_f32_16x16x32_bf16 v[44:47], v[222:225], v[172:175], v[44:47]
	v_mfma_f32_16x16x32_bf16 v[36:39], v[214:217], v[190:193], v[36:39]
	v_mfma_f32_16x16x32_bf16 v[28:31], v[222:225], v[190:193], v[28:31]
	v_mfma_f32_16x16x32_bf16 v[20:23], v[214:217], v[198:201], v[20:23]
	v_mfma_f32_16x16x32_bf16 v[12:15], v[222:225], v[198:201], v[12:15]
	v_mfma_f32_16x16x32_bf16 v[4:7], v[214:217], v[206:209], v[4:7]
	v_mfma_f32_16x16x32_bf16 v[0:3], v[222:225], v[206:209], v[0:3]
	s_add_i32 s54, s54, 2
	s_add_u32 s52, s52, 0x100
	s_addc_u32 s53, s53, 0
	s_cmp_gt_u32 s54, 41
	s_mov_b64 s[18:19], s[20:21]
	s_barrier
	s_cbranch_scc0 .LBB0_1278
	v_lshl_add_u32 v152, s50, 8, v146
	v_lshl_or_b32 v144, s51, 8, v148
	v_ashrrev_i32_e32 v153, 31, v152
	v_ashrrev_i32_e32 v145, 31, v144
	v_lshlrev_b64 v[154:155], 11, v[152:153]
	v_lshl_add_u64 v[154:155], s[6:7], 0, v[154:155]
	v_lshlrev_b64 v[156:157], 1, v[144:145]
	v_lshl_add_u64 v[144:145], v[154:155], 0, v[156:157]
	v_pk_add_f32 v[126:127], v[126:127], 0 op_sel_hi:[1,0]
	v_pk_add_f32 v[124:125], v[124:125], 0 op_sel_hi:[1,0]
	v_pk_add_f32 v[154:155], v[122:123], 0 op_sel_hi:[1,0]
	v_pk_add_f32 v[122:123], v[120:121], 0 op_sel_hi:[1,0]
	v_cvt_pk_bf16_f32 v120, v124, v125
	v_cvt_pk_bf16_f32 v121, v126, v127
	v_pk_add_f32 v[116:117], v[116:117], 0 op_sel_hi:[1,0]
	v_cvt_pk_bf16_f32 v122, v122, v123
	v_cvt_pk_bf16_f32 v123, v154, v155
	global_store_dwordx4 v[144:145], v[120:123], off
	v_pk_add_f32 v[118:119], v[118:119], 0 op_sel_hi:[1,0]
	v_pk_add_f32 v[110:111], v[110:111], 0 op_sel_hi:[1,0]
	v_pk_add_f32 v[120:121], v[114:115], 0 op_sel_hi:[1,0]
	v_pk_add_f32 v[114:115], v[112:113], 0 op_sel_hi:[1,0]
	v_cvt_pk_bf16_f32 v112, v116, v117
	v_cvt_pk_bf16_f32 v113, v118, v119
	v_pk_add_f32 v[108:109], v[108:109], 0 op_sel_hi:[1,0]
	v_cvt_pk_bf16_f32 v114, v114, v115
	v_cvt_pk_bf16_f32 v115, v120, v121
	global_store_dwordx4 v[144:145], v[112:115], off offset:256
	v_pk_add_f32 v[100:101], v[100:101], 0 op_sel_hi:[1,0]
	v_pk_add_f32 v[102:103], v[102:103], 0 op_sel_hi:[1,0]
	v_or_b32_e32 v112, 16, v152
	v_ashrrev_i32_e32 v113, 31, v112
	v_lshlrev_b64 v[112:113], 11, v[112:113]
	v_lshl_add_u64 v[112:113], s[6:7], 0, v[112:113]
	v_lshl_add_u64 v[112:113], v[112:113], 0, v[156:157]
	v_pk_add_f32 v[114:115], v[106:107], 0 op_sel_hi:[1,0]
	v_pk_add_f32 v[106:107], v[104:105], 0 op_sel_hi:[1,0]
	v_cvt_pk_bf16_f32 v104, v108, v109
	v_cvt_pk_bf16_f32 v105, v110, v111
	v_pk_add_f32 v[94:95], v[94:95], 0 op_sel_hi:[1,0]
	v_cvt_pk_bf16_f32 v106, v106, v107
	v_cvt_pk_bf16_f32 v107, v114, v115
	global_store_dwordx4 v[112:113], v[104:107], off
	v_pk_add_f32 v[92:93], v[92:93], 0 op_sel_hi:[1,0]
	v_pk_add_f32 v[84:85], v[84:85], 0 op_sel_hi:[1,0]
	v_pk_add_f32 v[104:105], v[98:99], 0 op_sel_hi:[1,0]
	v_pk_add_f32 v[98:99], v[96:97], 0 op_sel_hi:[1,0]
	v_cvt_pk_bf16_f32 v96, v100, v101
	v_cvt_pk_bf16_f32 v97, v102, v103
	v_pk_add_f32 v[86:87], v[86:87], 0 op_sel_hi:[1,0]
	v_cvt_pk_bf16_f32 v98, v98, v99
	v_cvt_pk_bf16_f32 v99, v104, v105
	global_store_dwordx4 v[112:113], v[96:99], off offset:256
	v_pk_add_f32 v[78:79], v[78:79], 0 op_sel_hi:[1,0]
	v_pk_add_f32 v[76:77], v[76:77], 0 op_sel_hi:[1,0]
	v_or_b32_e32 v96, 32, v152
	v_ashrrev_i32_e32 v97, 31, v96
	v_lshlrev_b64 v[96:97], 11, v[96:97]
	v_lshl_add_u64 v[96:97], s[6:7], 0, v[96:97]
	v_lshl_add_u64 v[96:97], v[96:97], 0, v[156:157]
; __device__ __forceinline__ unsigned cvt_pk_bf16(float lo, float hi) { unsigned r; asm volatile("v_cvt_pk_bf16_f32 %0, %1, %2" : "=v"(r) : "v"(lo), "v"(hi)); return r; }
; __device__ __forceinline__ float flogsig16(float x) { return (fminf(x, 0.f) - __logf(1.0f + __expf(-fabsf(x)))) * 0.0625f; }
; #define PG8_WAIT_V(n) asm volatile("s_waitcnt vmcnt(" #n ")" ::: "memory")
; #define PG8_BAR __builtin_amdgcn_s_barrier()
;     __device__ __forceinline__ void operator()(const f32x4 (&acc)[2][2][4][2], const Unit& u, int wr, int wc, int fr, int fq) const {
;     ...
;             for (int m = 0; m < 4; ++m) { bf16_t* rowp = O + (size_t)(row0 + ai * HALF + m * 16) * ldc + col0;
; #pragma unroll
;                 for (int bj = 0; bj < 2; ++bj) { f32x4 v0 = acc[ai][bj][m][0] + bv[bj][0], v1 = acc[ai][bj][m][1] + bv[bj][1];
;                     if (act == 1) {
; #pragma unroll
;                         for (int j = 0; j < 1; ++j) { v0 = v0 * sigmoid4(v0); v1 = v1 * sigmoid4(v1); } }
;                     else if (act == 2) {
; #pragma unroll
;                         for (int j = 0; j < 1; ++j) { v0 = sigmoid4(v0); v1 = sigmoid4(v1); } }
;                     else if (act == 3) {
; #pragma unroll
;                         for (int j = 0; j < 4; ++j) { v0[j] = flogsig16(v0[j]); v1[j] = flogsig16(v1[j]); } }
;                     u32x4 w; w.x = cvt_pk_bf16(v0[0], v0[1]); w.y = cvt_pk_bf16(v0[2], v0[3]); w.z = cvt_pk_bf16(v1[0], v1[1]); w.w = cvt_pk_bf16(v1[2], v1[3]);
;                     *(u32x4*)(rowp + bj * HALF) = w; } }
; template <class Epi, class Sched>
; __device__ __forceinline__ void gemm_phase(PG8_LAS unsigned char* lds, const Gemm g, const Sched& S, const Epi& E) {
;     ...
;         if (!has_next) break;
; #pragma unroll
;         for (int a = 0; a < 2; ++a)
; #pragma unroll
;             for (int b = 0; b < 2; ++b)
; #pragma unroll
;                 for (int m = 0; m < 4; ++m)
; #pragma unroll
;                     for (int n = 0; n < 2; ++n) acc[a][b][m][n] = (f32x4){0.f, 0.f, 0.f, 0.f};
;         cur = nxt; cA = nA; cB = nB; ++ui;
;     }
;     PG8_WAIT_V(0);
;     if (wr == 0) PG8_BAR;
;     PG8_BAR;
	v_pk_add_f32 v[98:99], v[90:91], 0 op_sel_hi:[1,0]
	v_pk_add_f32 v[90:91], v[88:89], 0 op_sel_hi:[1,0]
	v_cvt_pk_bf16_f32 v88, v92, v93
	v_cvt_pk_bf16_f32 v89, v94, v95
	v_pk_add_f32 v[70:71], v[70:71], 0 op_sel_hi:[1,0]
	v_cvt_pk_bf16_f32 v90, v90, v91
	v_cvt_pk_bf16_f32 v91, v98, v99
	global_store_dwordx4 v[96:97], v[88:91], off
	v_pk_add_f32 v[68:69], v[68:69], 0 op_sel_hi:[1,0]
	v_pk_add_f32 v[60:61], v[60:61], 0 op_sel_hi:[1,0]
	v_pk_add_f32 v[88:89], v[82:83], 0 op_sel_hi:[1,0]
	v_pk_add_f32 v[82:83], v[80:81], 0 op_sel_hi:[1,0]
	v_cvt_pk_bf16_f32 v80, v84, v85
	v_cvt_pk_bf16_f32 v81, v86, v87
	v_pk_add_f32 v[62:63], v[62:63], 0 op_sel_hi:[1,0]
	v_cvt_pk_bf16_f32 v82, v82, v83
	v_cvt_pk_bf16_f32 v83, v88, v89
	global_store_dwordx4 v[96:97], v[80:83], off offset:256
	v_pk_add_f32 v[54:55], v[54:55], 0 op_sel_hi:[1,0]
	v_pk_add_f32 v[52:53], v[52:53], 0 op_sel_hi:[1,0]
	v_or_b32_e32 v80, 48, v152
	v_ashrrev_i32_e32 v81, 31, v80
	v_lshlrev_b64 v[80:81], 11, v[80:81]
	v_lshl_add_u64 v[80:81], s[6:7], 0, v[80:81]
	v_lshl_add_u64 v[80:81], v[80:81], 0, v[156:157]
	v_pk_add_f32 v[82:83], v[74:75], 0 op_sel_hi:[1,0]
	v_pk_add_f32 v[74:75], v[72:73], 0 op_sel_hi:[1,0]
	v_cvt_pk_bf16_f32 v72, v76, v77
	v_cvt_pk_bf16_f32 v73, v78, v79
	v_pk_add_f32 v[48:49], v[48:49], 0 op_sel_hi:[1,0]
	v_cvt_pk_bf16_f32 v74, v74, v75
	v_cvt_pk_bf16_f32 v75, v82, v83
	global_store_dwordx4 v[80:81], v[72:75], off
	v_pk_add_f32 v[38:39], v[38:39], 0 op_sel_hi:[1,0]
	v_pk_add_f32 v[36:37], v[36:37], 0 op_sel_hi:[1,0]
	v_pk_add_f32 v[72:73], v[66:67], 0 op_sel_hi:[1,0]
	v_pk_add_f32 v[66:67], v[64:65], 0 op_sel_hi:[1,0]
	v_cvt_pk_bf16_f32 v64, v68, v69
	v_cvt_pk_bf16_f32 v65, v70, v71
	v_pk_add_f32 v[32:33], v[32:33], 0 op_sel_hi:[1,0]
	v_cvt_pk_bf16_f32 v66, v66, v67
	v_cvt_pk_bf16_f32 v67, v72, v73
	global_store_dwordx4 v[80:81], v[64:67], off offset:256
	v_pk_add_f32 v[22:23], v[22:23], 0 op_sel_hi:[1,0]
	v_pk_add_f32 v[20:21], v[20:21], 0 op_sel_hi:[1,0]
	v_pk_add_f32 v[66:67], v[58:59], 0 op_sel_hi:[1,0]
	v_pk_add_f32 v[58:59], v[56:57], 0 op_sel_hi:[1,0]
	v_cvt_pk_bf16_f32 v56, v60, v61
	v_add_co_u32_e32 v60, vcc, s44, v144
	v_cvt_pk_bf16_f32 v57, v62, v63
	v_cvt_pk_bf16_f32 v58, v58, v59
	v_cvt_pk_bf16_f32 v59, v66, v67
	v_lshl_add_u64 v[64:65], v[144:145], 0, s[10:11]
	s_nop 0
	v_addc_co_u32_e32 v61, vcc, 0, v145, vcc
	global_store_dwordx4 v[60:61], v[56:59], off
	v_pk_add_f32 v[16:17], v[16:17], 0 op_sel_hi:[1,0]
	s_mov_b32 s51, s48
	v_pk_add_f32 v[56:57], v[46:47], 0 op_sel_hi:[1,0]
	v_pk_add_f32 v[46:47], v[44:45], 0 op_sel_hi:[1,0]
	v_cvt_pk_bf16_f32 v44, v52, v53
	v_cvt_pk_bf16_f32 v45, v54, v55
	s_mov_b32 s50, s49
	v_cvt_pk_bf16_f32 v46, v46, v47
	v_cvt_pk_bf16_f32 v47, v56, v57
	global_store_dwordx4 v[64:65], v[44:47], off offset:256
	s_mov_b64 s[20:21], s[4:5]
	s_mov_b64 s[18:19], s[0:1]
	v_pk_add_f32 v[46:47], v[50:51], 0 op_sel_hi:[1,0]
	v_pk_add_f32 v[50:51], v[42:43], 0 op_sel_hi:[1,0]
	v_pk_add_f32 v[42:43], v[40:41], 0 op_sel_hi:[1,0]
	v_cvt_pk_bf16_f32 v40, v48, v49
	v_cvt_pk_bf16_f32 v41, v46, v47
	v_add_co_u32_e32 v46, vcc, s45, v144
	v_cvt_pk_bf16_f32 v42, v42, v43
	v_cvt_pk_bf16_f32 v43, v50, v51
	v_lshl_add_u64 v[44:45], v[144:145], 0, s[12:13]
	s_nop 0
	v_addc_co_u32_e32 v47, vcc, 0, v145, vcc
	global_store_dwordx4 v[46:47], v[40:43], off
	v_pk_add_f32 v[6:7], v[6:7], 0 op_sel_hi:[1,0]
	v_pk_add_f32 v[4:5], v[4:5], 0 op_sel_hi:[1,0]
	v_pk_add_f32 v[40:41], v[30:31], 0 op_sel_hi:[1,0]
	v_pk_add_f32 v[30:31], v[28:29], 0 op_sel_hi:[1,0]
	v_cvt_pk_bf16_f32 v28, v36, v37
	v_cvt_pk_bf16_f32 v29, v38, v39
	s_nop 0
	v_cvt_pk_bf16_f32 v30, v30, v31
	v_cvt_pk_bf16_f32 v31, v40, v41
	global_store_dwordx4 v[44:45], v[28:31], off offset:256
	s_nop 1
	v_pk_add_f32 v[30:31], v[34:35], 0 op_sel_hi:[1,0]
	v_pk_add_f32 v[34:35], v[26:27], 0 op_sel_hi:[1,0]
	v_pk_add_f32 v[26:27], v[24:25], 0 op_sel_hi:[1,0]
	v_cvt_pk_bf16_f32 v24, v32, v33
	v_cvt_pk_bf16_f32 v25, v30, v31
	v_add_co_u32_e32 v30, vcc, s46, v144
	v_cvt_pk_bf16_f32 v26, v26, v27
	v_cvt_pk_bf16_f32 v27, v34, v35
	v_lshl_add_u64 v[28:29], v[144:145], 0, s[14:15]
	s_nop 0
	v_addc_co_u32_e32 v31, vcc, 0, v145, vcc
	global_store_dwordx4 v[30:31], v[24:27], off
	s_nop 1
	v_pk_add_f32 v[24:25], v[14:15], 0 op_sel_hi:[1,0]
	v_pk_add_f32 v[14:15], v[12:13], 0 op_sel_hi:[1,0]
	v_cvt_pk_bf16_f32 v12, v20, v21
	v_cvt_pk_bf16_f32 v13, v22, v23
	s_nop 0
	v_cvt_pk_bf16_f32 v14, v14, v15
	v_cvt_pk_bf16_f32 v15, v24, v25
	global_store_dwordx4 v[28:29], v[12:15], off offset:256
	s_nop 1
	v_pk_add_f32 v[14:15], v[18:19], 0 op_sel_hi:[1,0]
	v_pk_add_f32 v[18:19], v[10:11], 0 op_sel_hi:[1,0]
	v_pk_add_f32 v[10:11], v[8:9], 0 op_sel_hi:[1,0]
	v_cvt_pk_bf16_f32 v8, v16, v17
	v_cvt_pk_bf16_f32 v9, v14, v15
	v_add_co_u32_e32 v14, vcc, s47, v144
	v_lshl_add_u64 v[12:13], v[144:145], 0, s[16:17]
	s_nop 0
	v_addc_co_u32_e32 v15, vcc, 0, v145, vcc
	v_cvt_pk_bf16_f32 v10, v10, v11
	v_cvt_pk_bf16_f32 v11, v18, v19
	global_store_dwordx4 v[14:15], v[8:11], off
	s_and_b64 vcc, exec, s[2:3]
	s_nop 0
	v_pk_add_f32 v[8:9], v[2:3], 0 op_sel_hi:[1,0]
	v_pk_add_f32 v[2:3], v[0:1], 0 op_sel_hi:[1,0]
	v_cvt_pk_bf16_f32 v0, v4, v5
	v_cvt_pk_bf16_f32 v1, v6, v7
	s_nop 0
	v_cvt_pk_bf16_f32 v2, v2, v3
	v_cvt_pk_bf16_f32 v3, v8, v9
	global_store_dwordx4 v[12:13], v[0:3], off offset:256
	s_cbranch_vccz .LBB0_1267
	s_waitcnt vmcnt(0)
	s_cmpk_gt_u32 s27, 0xff
	s_cbranch_scc1 .LBB0_1282
	s_barrier
